# K-loop segment boundaries: setprio 1 hoisted before the pre-MFMA barrier, redundant lgkmcnt(0) after it dropped, post-MFMA setprio 0 moved after the barrier
# speedup vs baseline: 1.0259x; 1.0259x over previous
; template <class Epi, class Sched, bool ALIGN_EPI = false, bool SP2 = false, bool A_TILED = false>
; __device__ __forceinline__ void gemm_phase(PG8_LAS unsigned char* lds, const Gemm g, const Sched& S, const Epi& E, const int wave_s) {
;     ...
;         const bool has_next = Epi::AFTER_DRAIN ? false : S.next(ui + 1, nxt);
;         const char* nA = has_next ? (const char*)g.A + (size_t)nxt.pm * tstepA : cA; const char* nB = has_next ? (const char*)g.Bt + (size_t)nxt.pn * tstep : cB;
;         constexpr bool PEEL = SP2 && !Epi::AFTER_DRAIN;
;         if constexpr (PEEL) {
;             const char* a1 = cA + kstepA; const char* a2 = cA + 2 * kstepA; const char* b2 = cB + 2 * kstep; const char* a3 = a2 + kstepA; const char* b3 = b2 + kstep;
;             PG8_ITER(PG8_MMAZ)
.LBB0_776:
	s_ashr_i32 s73, s72, 31
	ds_read_b128 v[0:3], v149
	ds_read_b128 v[4:7], v149 offset:1024
	ds_read_b128 v[8:11], v149 offset:2048
	ds_read_b128 v[12:15], v149 offset:3072
	ds_read_b128 v[16:19], v150
	ds_read_b128 v[20:23], v150 offset:1024
	ds_read_b128 v[24:27], v150 offset:2048
	ds_read_b128 v[28:31], v150 offset:3072
	s_lshl_b64 s[52:53], s[72:73], 20
	s_add_u32 s74, s7, s52
	s_addc_u32 s75, s8, s53
	s_and_b64 s[52:53], s[0:1], exec
	s_cselect_b32 s51, s75, s83
	s_cselect_b32 s52, s74, s82
	s_ashr_i32 s71, s70, 31
	s_lshl_b64 s[54:55], s[70:71], 20
	s_add_u32 s76, s9, s54
	s_addc_u32 s77, s14, s55
	s_and_b64 s[54:55], s[0:1], exec
	s_cselect_b32 s53, s77, s81
	s_cselect_b32 s54, s76, s80
	s_add_u32 s56, s82, 0x80080
	s_addc_u32 s57, s83, 0
	s_mov_b32 m0, s48
	v_lshl_add_u64 v[64:65], s[56:57], 0, v[134:135]
	ds_read_b128 v[32:35], v151
	ds_read_b128 v[36:39], v151 offset:1024
	ds_read_b128 v[40:43], v151 offset:2048
	ds_read_b128 v[44:47], v151 offset:3072
	ds_read_b128 v[48:51], v151 offset:4096
	ds_read_b128 v[52:55], v151 offset:5120
	ds_read_b128 v[56:59], v151 offset:6144
	ds_read_b128 v[60:63], v151 offset:7168
	global_load_lds_dwordx4 v[64:65], off
	v_lshl_add_u64 v[64:65], s[56:57], 0, v[132:133]
	s_mov_b32 m0, s49
	s_nop 0
	global_load_lds_dwordx4 v[64:65], off
	s_waitcnt vmcnt(8) lgkmcnt(0)
	s_setprio 1
	s_barrier
	v_mfma_f32_16x16x32_bf16 v[88:91], v[0:3], v[56:59], 0
	v_mfma_f32_16x16x32_bf16 v[64:67], v[0:3], v[32:35], 0
	v_mfma_f32_16x16x32_bf16 v[68:71], v[8:11], v[32:35], 0
	v_mfma_f32_16x16x32_bf16 v[72:75], v[0:3], v[40:43], 0
	v_mfma_f32_16x16x32_bf16 v[76:79], v[8:11], v[40:43], 0
	v_mfma_f32_16x16x32_bf16 v[80:83], v[0:3], v[48:51], 0
	v_mfma_f32_16x16x32_bf16 v[84:87], v[8:11], v[48:51], 0
	v_mfma_f32_16x16x32_bf16 v[92:95], v[4:7], v[60:63], v[88:91]
	v_mfma_f32_16x16x32_bf16 v[88:91], v[8:11], v[56:59], 0
	v_mfma_f32_16x16x32_bf16 v[64:67], v[4:7], v[36:39], v[64:67]
	v_mfma_f32_16x16x32_bf16 v[68:71], v[12:15], v[36:39], v[68:71]
	v_mfma_f32_16x16x32_bf16 v[72:75], v[4:7], v[44:47], v[72:75]
	v_mfma_f32_16x16x32_bf16 v[76:79], v[12:15], v[44:47], v[76:79]
	v_mfma_f32_16x16x32_bf16 v[80:83], v[4:7], v[52:55], v[80:83]
	v_mfma_f32_16x16x32_bf16 v[84:87], v[12:15], v[52:55], v[84:87]
	v_mfma_f32_16x16x32_bf16 v[100:103], v[12:15], v[60:63], v[88:91]
	s_setprio 0
	s_setprio 1
	v_mfma_f32_16x16x32_bf16 v[88:91], v[16:19], v[32:35], 0
	v_mfma_f32_16x16x32_bf16 v[32:35], v[24:27], v[32:35], 0
	v_mfma_f32_16x16x32_bf16 v[108:111], v[20:23], v[36:39], v[88:91]
	v_mfma_f32_16x16x32_bf16 v[32:35], v[28:31], v[36:39], v[32:35]
	v_mfma_f32_16x16x32_bf16 v[36:39], v[16:19], v[40:43], 0
	v_mfma_f32_16x16x32_bf16 v[40:43], v[24:27], v[40:43], 0
	v_mfma_f32_16x16x32_bf16 v[36:39], v[20:23], v[44:47], v[36:39]
	v_mfma_f32_16x16x32_bf16 v[40:43], v[28:31], v[44:47], v[40:43]
	v_mfma_f32_16x16x32_bf16 v[44:47], v[16:19], v[48:51], 0
	v_mfma_f32_16x16x32_bf16 v[48:51], v[24:27], v[48:51], 0
	v_mfma_f32_16x16x32_bf16 v[44:47], v[20:23], v[52:55], v[44:47]
	v_mfma_f32_16x16x32_bf16 v[52:55], v[28:31], v[52:55], v[48:51]
	v_mfma_f32_16x16x32_bf16 v[48:51], v[16:19], v[56:59], 0
	v_mfma_f32_16x16x32_bf16 v[152:155], v[20:23], v[60:63], v[48:51]
	v_mfma_f32_16x16x32_bf16 v[48:51], v[24:27], v[56:59], 0
	v_mfma_f32_16x16x32_bf16 v[156:159], v[28:31], v[60:63], v[48:51]
	s_barrier
	s_setprio 0
	s_add_i32 s55, s45, s15
	v_lshl_add_u64 v[146:147], s[80:81], 0, v[128:129]
	s_add_i32 s56, s55, 0x2000
	v_lshl_add_u64 v[120:121], v[146:147], 0, s[68:69]
	s_mov_b32 m0, s55
	v_lshl_add_u64 v[252:253], s[80:81], 0, v[130:131]
	s_add_u32 s58, s80, 0x80100
	ds_read_b128 v[48:51], v151 offset:16384
	ds_read_b128 v[56:59], v151 offset:17408
	ds_read_b128 v[60:63], v151 offset:18432
	ds_read_b128 v[88:91], v151 offset:19456
	ds_read_b128 v[96:99], v151 offset:20480
	ds_read_b128 v[104:107], v151 offset:21504
	ds_read_b128 v[112:115], v151 offset:22528
	ds_read_b128 v[116:119], v151 offset:23552
	global_load_lds_dwordx4 v[120:121], off
	v_lshl_add_u64 v[120:121], v[252:253], 0, s[68:69]
	s_mov_b32 m0, s56
	s_addc_u32 s59, s81, 0
	s_add_i32 s57, s46, s15
	global_load_lds_dwordx4 v[120:121], off
	v_lshl_add_u64 v[120:121], s[58:59], 0, v[128:129]
	s_mov_b32 m0, s57
	v_lshl_add_u64 v[140:141], s[82:83], 0, v[134:135]
	global_load_lds_dwordx4 v[120:121], off
	v_lshl_add_u64 v[120:121], s[58:59], 0, v[130:131]
	s_add_i32 s58, s57, 0x2000
	s_mov_b32 m0, s58
	v_lshl_add_u64 v[142:143], s[82:83], 0, v[132:133]
	global_load_lds_dwordx4 v[120:121], off
	v_lshl_add_u64 v[120:121], v[140:141], 0, s[68:69]
	s_mov_b32 m0, s23
	s_nop 0
	global_load_lds_dwordx4 v[120:121], off
	v_lshl_add_u64 v[120:121], v[142:143], 0, s[68:69]
	s_mov_b32 m0, s36
	s_nop 0
	global_load_lds_dwordx4 v[120:121], off
	s_waitcnt vmcnt(8) lgkmcnt(0)
	s_setprio 1
	s_barrier
	v_mfma_f32_16x16x32_bf16 v[120:123], v[0:3], v[48:51], 0
	v_mfma_f32_16x16x32_bf16 v[160:163], v[4:7], v[56:59], v[120:123]
	v_mfma_f32_16x16x32_bf16 v[120:123], v[8:11], v[48:51], 0
	v_mfma_f32_16x16x32_bf16 v[164:167], v[12:15], v[56:59], v[120:123]
	v_mfma_f32_16x16x32_bf16 v[120:123], v[0:3], v[60:63], 0
	v_mfma_f32_16x16x32_bf16 v[168:171], v[4:7], v[88:91], v[120:123]
	v_mfma_f32_16x16x32_bf16 v[120:123], v[8:11], v[60:63], 0
	v_mfma_f32_16x16x32_bf16 v[172:175], v[12:15], v[88:91], v[120:123]
	v_mfma_f32_16x16x32_bf16 v[120:123], v[0:3], v[96:99], 0
	v_mfma_f32_16x16x32_bf16 v[0:3], v[0:3], v[112:115], 0
	v_mfma_f32_16x16x32_bf16 v[176:179], v[4:7], v[104:107], v[120:123]
	v_mfma_f32_16x16x32_bf16 v[0:3], v[4:7], v[116:119], v[0:3]
	v_mfma_f32_16x16x32_bf16 v[4:7], v[8:11], v[112:115], 0
	v_mfma_f32_16x16x32_bf16 v[120:123], v[8:11], v[96:99], 0
	v_mfma_f32_16x16x32_bf16 v[4:7], v[12:15], v[116:119], v[4:7]
	v_mfma_f32_16x16x32_bf16 v[180:183], v[12:15], v[104:107], v[120:123]
	s_setprio 0
	s_setprio 1
	v_mfma_f32_16x16x32_bf16 v[8:11], v[16:19], v[48:51], 0
	v_mfma_f32_16x16x32_bf16 v[12:15], v[20:23], v[56:59], v[8:11]
	v_mfma_f32_16x16x32_bf16 v[8:11], v[24:27], v[48:51], 0
	v_mfma_f32_16x16x32_bf16 v[184:187], v[28:31], v[56:59], v[8:11]
	v_mfma_f32_16x16x32_bf16 v[8:11], v[16:19], v[60:63], 0
	v_mfma_f32_16x16x32_bf16 v[188:191], v[20:23], v[88:91], v[8:11]
	v_mfma_f32_16x16x32_bf16 v[8:11], v[24:27], v[60:63], 0
	v_mfma_f32_16x16x32_bf16 v[192:195], v[28:31], v[88:91], v[8:11]
	v_mfma_f32_16x16x32_bf16 v[8:11], v[16:19], v[96:99], 0
	v_mfma_f32_16x16x32_bf16 v[196:199], v[20:23], v[104:107], v[8:11]
	v_mfma_f32_16x16x32_bf16 v[8:11], v[24:27], v[96:99], 0
	v_mfma_f32_16x16x32_bf16 v[200:203], v[28:31], v[104:107], v[8:11]
	v_mfma_f32_16x16x32_bf16 v[8:11], v[16:19], v[112:115], 0
	v_mfma_f32_16x16x32_bf16 v[204:207], v[20:23], v[116:119], v[8:11]
	v_mfma_f32_16x16x32_bf16 v[8:11], v[24:27], v[112:115], 0
	v_mfma_f32_16x16x32_bf16 v[208:211], v[28:31], v[116:119], v[8:11]
	s_barrier
	s_setprio 0
	s_add_i32 s59, 0, 0x18000
	s_add_i32 s73, 0, 0x1c000
	v_add_u32_e32 v144, s59, v148
	v_add_u32_e32 v145, s73, v148
	s_nop 0
	ds_read_b128 v[8:11], v144
	ds_read_b128 v[20:23], v144 offset:1024
	ds_read_b128 v[28:31], v144 offset:2048
	ds_read_b128 v[212:215], v144 offset:3072
	ds_read_b128 v[216:219], v145
	ds_read_b128 v[220:223], v145 offset:1024
	ds_read_b128 v[224:227], v145 offset:2048
	ds_read_b128 v[228:231], v145 offset:3072
	s_add_u32 s84, s82, 0x80100
	s_addc_u32 s85, s83, 0
	s_mov_b32 m0, s37
	v_lshl_add_u64 v[48:49], s[84:85], 0, v[134:135]
	ds_read_b128 v[16:19], v151 offset:32768
	ds_read_b128 v[24:27], v151 offset:33792
	ds_read_b128 v[60:63], v151 offset:34816
	ds_read_b128 v[232:235], v151 offset:35840
	ds_read_b128 v[236:239], v151 offset:36864
	ds_read_b128 v[240:243], v151 offset:37888
	ds_read_b128 v[244:247], v151 offset:38912
	ds_read_b128 v[248:251], v151 offset:39936
	global_load_lds_dwordx4 v[48:49], off
	v_lshl_add_u64 v[48:49], s[84:85], 0, v[132:133]
	s_mov_b32 m0, s38
	s_nop 0
	global_load_lds_dwordx4 v[48:49], off
	s_waitcnt vmcnt(8) lgkmcnt(0)
	s_setprio 1
	s_barrier
	v_mfma_f32_16x16x32_bf16 v[48:51], v[8:11], v[16:19], v[64:67]
	v_mfma_f32_16x16x32_bf16 v[120:123], v[20:23], v[24:27], v[48:51]
	v_mfma_f32_16x16x32_bf16 v[48:51], v[28:31], v[16:19], v[68:71]
	v_mfma_f32_16x16x32_bf16 v[112:115], v[212:215], v[24:27], v[48:51]
	v_mfma_f32_16x16x32_bf16 v[48:51], v[8:11], v[60:63], v[72:75]
	v_mfma_f32_16x16x32_bf16 v[104:107], v[20:23], v[232:235], v[48:51]
	v_mfma_f32_16x16x32_bf16 v[48:51], v[28:31], v[60:63], v[76:79]
	v_mfma_f32_16x16x32_bf16 v[96:99], v[212:215], v[232:235], v[48:51]
	v_mfma_f32_16x16x32_bf16 v[48:51], v[8:11], v[236:239], v[80:83]
	v_mfma_f32_16x16x32_bf16 v[88:91], v[20:23], v[240:243], v[48:51]
	v_mfma_f32_16x16x32_bf16 v[48:51], v[28:31], v[236:239], v[84:87]
	v_mfma_f32_16x16x32_bf16 v[80:83], v[212:215], v[240:243], v[48:51]
	v_mfma_f32_16x16x32_bf16 v[48:51], v[8:11], v[244:247], v[92:95]
	v_mfma_f32_16x16x32_bf16 v[56:59], v[20:23], v[248:251], v[48:51]
	v_mfma_f32_16x16x32_bf16 v[48:51], v[28:31], v[244:247], v[100:103]
	v_mfma_f32_16x16x32_bf16 v[48:51], v[212:215], v[248:251], v[48:51]
	s_setprio 0
	s_setprio 1
	v_mfma_f32_16x16x32_bf16 v[64:67], v[216:219], v[16:19], v[108:111]
	v_mfma_f32_16x16x32_bf16 v[16:19], v[224:227], v[16:19], v[32:35]
	v_mfma_f32_16x16x32_bf16 v[116:119], v[228:231], v[24:27], v[16:19]
	v_mfma_f32_16x16x32_bf16 v[16:19], v[216:219], v[60:63], v[36:39]
	v_mfma_f32_16x16x32_bf16 v[108:111], v[220:223], v[232:235], v[16:19]
	v_mfma_f32_16x16x32_bf16 v[16:19], v[224:227], v[60:63], v[40:43]
	v_mfma_f32_16x16x32_bf16 v[100:103], v[228:231], v[232:235], v[16:19]
	v_mfma_f32_16x16x32_bf16 v[16:19], v[216:219], v[236:239], v[44:47]
	v_mfma_f32_16x16x32_bf16 v[92:95], v[220:223], v[240:243], v[16:19]
	v_mfma_f32_16x16x32_bf16 v[16:19], v[224:227], v[236:239], v[52:55]
	v_mfma_f32_16x16x32_bf16 v[84:87], v[228:231], v[240:243], v[16:19]
	v_mfma_f32_16x16x32_bf16 v[16:19], v[216:219], v[244:247], v[152:155]
	v_mfma_f32_16x16x32_bf16 v[60:63], v[220:223], v[248:251], v[16:19]
	v_mfma_f32_16x16x32_bf16 v[16:19], v[224:227], v[244:247], v[156:159]
	v_mfma_f32_16x16x32_bf16 v[124:127], v[220:223], v[24:27], v[64:67]
	v_mfma_f32_16x16x32_bf16 v[52:55], v[228:231], v[248:251], v[16:19]
	s_barrier
; #define PG8_MMA(ai, bj, At, Bt) do { __builtin_amdgcn_s_setprio(1); _Pragma("unroll") for (int m = 0; m < 4; ++m) _Pragma("unroll") for (int n = 0; n < 2; ++n) _Pragma("unroll") for (int k = 0; k < 2; ++k) \
;         acc[ai][bj][m][n] = __builtin_amdgcn_mfma_f32_16x16x32_bf16(Bt[n][k], At[m][k], acc[ai][bj][m][n], 0, 0, 0); __builtin_amdgcn_s_setprio(0); } while (0)
; template <class Epi, class Sched, bool ALIGN_EPI = false, bool SP2 = false, bool A_TILED = false>
; __device__ __forceinline__ void gemm_phase(PG8_LAS unsigned char* lds, const Gemm g, const Sched& S, const Epi& E, const int wave_s) {
;     ...
;         for (int t = PEEL ? 2 : 0; t < nt; t += 2) {
;             const bool last = (t == nt - 2);
;             const char* a1 = cA + (size_t)(t + 1) * kstepA;
;             const char* a2 = last ? nA : cA + (size_t)(t + 2) * kstepA; const char* b2 = last ? nB : cB + (size_t)(t + 2) * kstep;
;             const char* a3 = a2 + kstepA; const char* b3 = b2 + kstep;
;             if (last && has_next) S.a_ready(nxt);
;             if constexpr (SP2) {
;             PG8_ITER(PG8_MMA)
	s_setprio 0
	s_add_i32 s59, s59, s15
	s_add_i32 s71, s59, 0x2000
	s_nop 1
	v_lshl_add_u64 v[16:17], v[146:147], 0, s[66:67]
	s_mov_b32 m0, s59
	s_add_u32 s84, s80, 0x80180
	ds_read_b128 v[36:39], v151 offset:49152
	ds_read_b128 v[44:47], v151 offset:50176
	ds_read_b128 v[152:155], v151 offset:51200
	ds_read_b128 v[156:159], v151 offset:52224
	ds_read_b128 v[232:235], v151 offset:53248
	ds_read_b128 v[236:239], v151 offset:54272
	ds_read_b128 v[240:243], v151 offset:55296
	ds_read_b128 v[244:247], v151 offset:56320
	global_load_lds_dwordx4 v[16:17], off
	v_lshl_add_u64 v[16:17], v[252:253], 0, s[66:67]
	s_mov_b32 m0, s71
	s_addc_u32 s85, s81, 0
	s_add_i32 s73, s73, s15
	global_load_lds_dwordx4 v[16:17], off
	v_lshl_add_u64 v[16:17], s[84:85], 0, v[128:129]
	s_mov_b32 m0, s73
	s_add_i32 s79, s73, 0x2000
	global_load_lds_dwordx4 v[16:17], off
	v_lshl_add_u64 v[16:17], s[84:85], 0, v[130:131]
	s_mov_b32 m0, s79
	s_nop 0
	global_load_lds_dwordx4 v[16:17], off
	v_lshl_add_u64 v[16:17], v[140:141], 0, s[66:67]
	s_mov_b32 m0, s43
	s_nop 0
	global_load_lds_dwordx4 v[16:17], off
	v_lshl_add_u64 v[16:17], v[142:143], 0, s[66:67]
	s_mov_b32 m0, s44
	s_nop 0
	global_load_lds_dwordx4 v[16:17], off
	s_waitcnt vmcnt(8) lgkmcnt(0)
	s_setprio 1
	s_barrier
	v_mfma_f32_16x16x32_bf16 v[16:19], v[8:11], v[36:39], v[160:163]
	v_mfma_f32_16x16x32_bf16 v[72:75], v[20:23], v[44:47], v[16:19]
	v_mfma_f32_16x16x32_bf16 v[16:19], v[28:31], v[36:39], v[164:167]
	v_mfma_f32_16x16x32_bf16 v[64:67], v[212:215], v[44:47], v[16:19]
	v_mfma_f32_16x16x32_bf16 v[16:19], v[8:11], v[152:155], v[168:171]
	v_mfma_f32_16x16x32_bf16 v[40:43], v[20:23], v[156:159], v[16:19]
	v_mfma_f32_16x16x32_bf16 v[16:19], v[28:31], v[152:155], v[172:175]
	v_mfma_f32_16x16x32_bf16 v[32:35], v[212:215], v[156:159], v[16:19]
	v_mfma_f32_16x16x32_bf16 v[16:19], v[8:11], v[232:235], v[176:179]
	v_mfma_f32_16x16x32_bf16 v[0:3], v[8:11], v[240:243], v[0:3]
	v_mfma_f32_16x16x32_bf16 v[24:27], v[20:23], v[236:239], v[16:19]
	v_mfma_f32_16x16x32_bf16 v[16:19], v[28:31], v[232:235], v[180:183]
	v_mfma_f32_16x16x32_bf16 v[8:11], v[20:23], v[244:247], v[0:3]
	v_mfma_f32_16x16x32_bf16 v[0:3], v[28:31], v[240:243], v[4:7]
	v_mfma_f32_16x16x32_bf16 v[16:19], v[212:215], v[236:239], v[16:19]
	v_mfma_f32_16x16x32_bf16 v[0:3], v[212:215], v[244:247], v[0:3]
	s_setprio 0
	s_setprio 1
	v_mfma_f32_16x16x32_bf16 v[4:7], v[216:219], v[36:39], v[12:15]
	v_mfma_f32_16x16x32_bf16 v[76:79], v[220:223], v[44:47], v[4:7]
	v_mfma_f32_16x16x32_bf16 v[4:7], v[224:227], v[36:39], v[184:187]
	v_mfma_f32_16x16x32_bf16 v[68:71], v[228:231], v[44:47], v[4:7]
	v_mfma_f32_16x16x32_bf16 v[4:7], v[216:219], v[152:155], v[188:191]
	v_mfma_f32_16x16x32_bf16 v[44:47], v[220:223], v[156:159], v[4:7]
	v_mfma_f32_16x16x32_bf16 v[4:7], v[224:227], v[152:155], v[192:195]
	v_mfma_f32_16x16x32_bf16 v[36:39], v[228:231], v[156:159], v[4:7]
	v_mfma_f32_16x16x32_bf16 v[4:7], v[216:219], v[232:235], v[196:199]
	v_mfma_f32_16x16x32_bf16 v[28:31], v[220:223], v[236:239], v[4:7]
	v_mfma_f32_16x16x32_bf16 v[4:7], v[224:227], v[232:235], v[200:203]
	v_mfma_f32_16x16x32_bf16 v[20:23], v[228:231], v[236:239], v[4:7]
	v_mfma_f32_16x16x32_bf16 v[4:7], v[216:219], v[240:243], v[204:207]
	v_mfma_f32_16x16x32_bf16 v[12:15], v[220:223], v[244:247], v[4:7]
	v_mfma_f32_16x16x32_bf16 v[4:7], v[224:227], v[240:243], v[208:211]
	v_mfma_f32_16x16x32_bf16 v[4:7], v[228:231], v[244:247], v[4:7]
	s_barrier
	s_setprio 0
	s_add_u32 s88, s80, 0x200
	s_addc_u32 s89, s81, 0
	s_add_u32 s80, s82, 0x80180
	s_addc_u32 s81, s83, 0
	s_mov_b32 s90, 0
.LBB0_777:
	ds_read_b128 v[152:155], v149
	ds_read_b128 v[156:159], v149 offset:1024
	ds_read_b128 v[160:163], v149 offset:2048
	ds_read_b128 v[164:167], v149 offset:3072
	ds_read_b128 v[168:171], v150
	ds_read_b128 v[172:175], v150 offset:1024
	ds_read_b128 v[176:179], v150 offset:2048
	ds_read_b128 v[180:183], v150 offset:3072
	s_add_u32 s82, s80, 0xfff80080
	s_addc_u32 s83, s81, -1
	s_cmp_eq_u32 s90, 28
	s_cselect_b32 s85, s51, s83
	s_cselect_b32 s84, s52, s82
	s_cselect_b32 s83, s53, s89
	s_cselect_b32 s82, s54, s88
	s_mov_b32 m0, s48
	v_lshl_add_u64 v[140:141], s[80:81], 0, v[138:139]
	ds_read_b128 v[184:187], v151
	ds_read_b128 v[188:191], v151 offset:1024
	ds_read_b128 v[192:195], v151 offset:2048
	ds_read_b128 v[196:199], v151 offset:3072
	ds_read_b128 v[200:203], v151 offset:4096
	ds_read_b128 v[204:207], v151 offset:5120
	ds_read_b128 v[208:211], v151 offset:6144
	ds_read_b128 v[212:215], v151 offset:7168
	global_load_lds_dwordx4 v[140:141], off
	v_lshl_add_u64 v[140:141], s[80:81], 0, v[136:137]
	s_mov_b32 m0, s49
	s_nop 0
	global_load_lds_dwordx4 v[140:141], off
	s_waitcnt vmcnt(8) lgkmcnt(0)
	s_setprio 1
	s_barrier
	v_mfma_f32_16x16x32_bf16 v[120:123], v[152:155], v[184:187], v[120:123]
	v_mfma_f32_16x16x32_bf16 v[112:115], v[160:163], v[184:187], v[112:115]
	v_mfma_f32_16x16x32_bf16 v[104:107], v[152:155], v[192:195], v[104:107]
	v_mfma_f32_16x16x32_bf16 v[96:99], v[160:163], v[192:195], v[96:99]
	v_mfma_f32_16x16x32_bf16 v[88:91], v[152:155], v[200:203], v[88:91]
	v_mfma_f32_16x16x32_bf16 v[80:83], v[160:163], v[200:203], v[80:83]
	v_mfma_f32_16x16x32_bf16 v[56:59], v[152:155], v[208:211], v[56:59]
	v_mfma_f32_16x16x32_bf16 v[48:51], v[160:163], v[208:211], v[48:51]
	v_mfma_f32_16x16x32_bf16 v[120:123], v[156:159], v[188:191], v[120:123]
	v_mfma_f32_16x16x32_bf16 v[112:115], v[164:167], v[188:191], v[112:115]
	v_mfma_f32_16x16x32_bf16 v[104:107], v[156:159], v[196:199], v[104:107]
	v_mfma_f32_16x16x32_bf16 v[96:99], v[164:167], v[196:199], v[96:99]
	v_mfma_f32_16x16x32_bf16 v[88:91], v[156:159], v[204:207], v[88:91]
	v_mfma_f32_16x16x32_bf16 v[80:83], v[164:167], v[204:207], v[80:83]
	v_mfma_f32_16x16x32_bf16 v[56:59], v[156:159], v[212:215], v[56:59]
	v_mfma_f32_16x16x32_bf16 v[48:51], v[164:167], v[212:215], v[48:51]
	s_setprio 0
	s_setprio 1
	v_mfma_f32_16x16x32_bf16 v[124:127], v[168:171], v[184:187], v[124:127]
	v_mfma_f32_16x16x32_bf16 v[116:119], v[176:179], v[184:187], v[116:119]
	v_mfma_f32_16x16x32_bf16 v[108:111], v[168:171], v[192:195], v[108:111]
	v_mfma_f32_16x16x32_bf16 v[100:103], v[176:179], v[192:195], v[100:103]
	v_mfma_f32_16x16x32_bf16 v[92:95], v[168:171], v[200:203], v[92:95]
	v_mfma_f32_16x16x32_bf16 v[84:87], v[176:179], v[200:203], v[84:87]
	v_mfma_f32_16x16x32_bf16 v[60:63], v[168:171], v[208:211], v[60:63]
	v_mfma_f32_16x16x32_bf16 v[52:55], v[176:179], v[208:211], v[52:55]
	v_mfma_f32_16x16x32_bf16 v[124:127], v[172:175], v[188:191], v[124:127]
	v_mfma_f32_16x16x32_bf16 v[116:119], v[180:183], v[188:191], v[116:119]
	v_mfma_f32_16x16x32_bf16 v[108:111], v[172:175], v[196:199], v[108:111]
	v_mfma_f32_16x16x32_bf16 v[100:103], v[180:183], v[196:199], v[100:103]
	v_mfma_f32_16x16x32_bf16 v[92:95], v[172:175], v[204:207], v[92:95]
	v_mfma_f32_16x16x32_bf16 v[84:87], v[180:183], v[204:207], v[84:87]
	v_mfma_f32_16x16x32_bf16 v[60:63], v[172:175], v[212:215], v[60:63]
	v_mfma_f32_16x16x32_bf16 v[52:55], v[180:183], v[212:215], v[52:55]
	s_barrier
	s_setprio 0
	s_mov_b32 m0, s55
	v_lshl_add_u64 v[140:141], s[82:83], 0, v[128:129]
	s_add_u32 s94, s82, 0x80000
	ds_read_b128 v[184:187], v151 offset:16384
	ds_read_b128 v[188:191], v151 offset:17408
	ds_read_b128 v[192:195], v151 offset:18432
	ds_read_b128 v[196:199], v151 offset:19456
	ds_read_b128 v[200:203], v151 offset:20480
	ds_read_b128 v[204:207], v151 offset:21504
	ds_read_b128 v[208:211], v151 offset:22528
	ds_read_b128 v[212:215], v151 offset:23552
	global_load_lds_dwordx4 v[140:141], off
	v_lshl_add_u64 v[142:143], s[82:83], 0, v[130:131]
	s_mov_b32 m0, s56
	s_addc_u32 s95, s83, 0
	global_load_lds_dwordx4 v[142:143], off
	v_lshl_add_u64 v[146:147], s[94:95], 0, v[128:129]
	s_mov_b32 m0, s57
	v_lshl_add_u64 v[216:217], s[84:85], 0, v[132:133]
	global_load_lds_dwordx4 v[146:147], off
	v_lshl_add_u64 v[146:147], s[94:95], 0, v[130:131]
	s_mov_b32 m0, s58
	s_nop 0
	global_load_lds_dwordx4 v[146:147], off
	v_lshl_add_u64 v[146:147], s[84:85], 0, v[134:135]
	s_mov_b32 m0, s23
	s_nop 0
	global_load_lds_dwordx4 v[146:147], off
	s_mov_b32 m0, s36
	s_nop 0
	global_load_lds_dwordx4 v[216:217], off
	s_waitcnt vmcnt(8) lgkmcnt(0)
	s_setprio 1
	s_barrier
	v_mfma_f32_16x16x32_bf16 v[72:75], v[152:155], v[184:187], v[72:75]
	v_mfma_f32_16x16x32_bf16 v[64:67], v[160:163], v[184:187], v[64:67]
	v_mfma_f32_16x16x32_bf16 v[40:43], v[152:155], v[192:195], v[40:43]
	v_mfma_f32_16x16x32_bf16 v[32:35], v[160:163], v[192:195], v[32:35]
	v_mfma_f32_16x16x32_bf16 v[24:27], v[152:155], v[200:203], v[24:27]
	v_mfma_f32_16x16x32_bf16 v[16:19], v[160:163], v[200:203], v[16:19]
	v_mfma_f32_16x16x32_bf16 v[8:11], v[152:155], v[208:211], v[8:11]
	v_mfma_f32_16x16x32_bf16 v[0:3], v[160:163], v[208:211], v[0:3]
	v_mfma_f32_16x16x32_bf16 v[72:75], v[156:159], v[188:191], v[72:75]
	v_mfma_f32_16x16x32_bf16 v[64:67], v[164:167], v[188:191], v[64:67]
	v_mfma_f32_16x16x32_bf16 v[40:43], v[156:159], v[196:199], v[40:43]
	v_mfma_f32_16x16x32_bf16 v[32:35], v[164:167], v[196:199], v[32:35]
	v_mfma_f32_16x16x32_bf16 v[24:27], v[156:159], v[204:207], v[24:27]
	v_mfma_f32_16x16x32_bf16 v[16:19], v[164:167], v[204:207], v[16:19]
	v_mfma_f32_16x16x32_bf16 v[8:11], v[156:159], v[212:215], v[8:11]
	v_mfma_f32_16x16x32_bf16 v[0:3], v[164:167], v[212:215], v[0:3]
	s_setprio 0
	s_setprio 1
	v_mfma_f32_16x16x32_bf16 v[76:79], v[168:171], v[184:187], v[76:79]
	v_mfma_f32_16x16x32_bf16 v[68:71], v[176:179], v[184:187], v[68:71]
	v_mfma_f32_16x16x32_bf16 v[44:47], v[168:171], v[192:195], v[44:47]
	v_mfma_f32_16x16x32_bf16 v[36:39], v[176:179], v[192:195], v[36:39]
	v_mfma_f32_16x16x32_bf16 v[28:31], v[168:171], v[200:203], v[28:31]
	v_mfma_f32_16x16x32_bf16 v[20:23], v[176:179], v[200:203], v[20:23]
	v_mfma_f32_16x16x32_bf16 v[12:15], v[168:171], v[208:211], v[12:15]
	v_mfma_f32_16x16x32_bf16 v[4:7], v[176:179], v[208:211], v[4:7]
	v_mfma_f32_16x16x32_bf16 v[76:79], v[172:175], v[188:191], v[76:79]
	v_mfma_f32_16x16x32_bf16 v[68:71], v[180:183], v[188:191], v[68:71]
	v_mfma_f32_16x16x32_bf16 v[44:47], v[172:175], v[196:199], v[44:47]
	v_mfma_f32_16x16x32_bf16 v[36:39], v[180:183], v[196:199], v[36:39]
	v_mfma_f32_16x16x32_bf16 v[28:31], v[172:175], v[204:207], v[28:31]
	v_mfma_f32_16x16x32_bf16 v[20:23], v[180:183], v[204:207], v[20:23]
	v_mfma_f32_16x16x32_bf16 v[12:15], v[172:175], v[212:215], v[12:15]
	v_mfma_f32_16x16x32_bf16 v[4:7], v[180:183], v[212:215], v[4:7]
	s_barrier
; #define PG8_BAR __builtin_amdgcn_s_barrier()
; template <class Epi, class Sched, bool ALIGN_EPI = false, bool SP2 = false, bool A_TILED = false>
; __device__ __forceinline__ void gemm_phase(PG8_LAS unsigned char* lds, const Gemm g, const Sched& S, const Epi& E, const int wave_s) {
;     ...
;         if constexpr (ALIGN_EPI) { if (wr == 0) PG8_BAR; }
	s_setprio 0
	ds_read_b128 v[152:155], v144
	ds_read_b128 v[156:159], v144 offset:1024
	ds_read_b128 v[160:163], v144 offset:2048
	ds_read_b128 v[164:167], v144 offset:3072
	ds_read_b128 v[168:171], v145
	ds_read_b128 v[172:175], v145 offset:1024
	ds_read_b128 v[176:179], v145 offset:2048
	ds_read_b128 v[180:183], v145 offset:3072
	s_add_u32 s84, s84, 0x80000
	s_addc_u32 s85, s85, 0
	s_mov_b32 m0, s37
	v_lshl_add_u64 v[218:219], s[84:85], 0, v[134:135]
	ds_read_b128 v[184:187], v151 offset:32768
	ds_read_b128 v[188:191], v151 offset:33792
	ds_read_b128 v[192:195], v151 offset:34816
	ds_read_b128 v[196:199], v151 offset:35840
	ds_read_b128 v[200:203], v151 offset:36864
	ds_read_b128 v[204:207], v151 offset:37888
	ds_read_b128 v[208:211], v151 offset:38912
	ds_read_b128 v[212:215], v151 offset:39936
	global_load_lds_dwordx4 v[218:219], off
	v_lshl_add_u64 v[218:219], s[84:85], 0, v[132:133]
	s_mov_b32 m0, s38
	s_nop 0
	global_load_lds_dwordx4 v[218:219], off
	s_waitcnt vmcnt(8) lgkmcnt(0)
	s_setprio 1
	s_barrier
	v_mfma_f32_16x16x32_bf16 v[120:123], v[152:155], v[184:187], v[120:123]
	v_mfma_f32_16x16x32_bf16 v[112:115], v[160:163], v[184:187], v[112:115]
	v_mfma_f32_16x16x32_bf16 v[104:107], v[152:155], v[192:195], v[104:107]
	v_mfma_f32_16x16x32_bf16 v[96:99], v[160:163], v[192:195], v[96:99]
	v_mfma_f32_16x16x32_bf16 v[88:91], v[152:155], v[200:203], v[88:91]
	v_mfma_f32_16x16x32_bf16 v[80:83], v[160:163], v[200:203], v[80:83]
	v_mfma_f32_16x16x32_bf16 v[56:59], v[152:155], v[208:211], v[56:59]
	v_mfma_f32_16x16x32_bf16 v[48:51], v[160:163], v[208:211], v[48:51]
	v_mfma_f32_16x16x32_bf16 v[120:123], v[156:159], v[188:191], v[120:123]
	v_mfma_f32_16x16x32_bf16 v[112:115], v[164:167], v[188:191], v[112:115]
	v_mfma_f32_16x16x32_bf16 v[104:107], v[156:159], v[196:199], v[104:107]
	v_mfma_f32_16x16x32_bf16 v[96:99], v[164:167], v[196:199], v[96:99]
	v_mfma_f32_16x16x32_bf16 v[88:91], v[156:159], v[204:207], v[88:91]
	v_mfma_f32_16x16x32_bf16 v[80:83], v[164:167], v[204:207], v[80:83]
	v_mfma_f32_16x16x32_bf16 v[56:59], v[156:159], v[212:215], v[56:59]
	v_mfma_f32_16x16x32_bf16 v[48:51], v[164:167], v[212:215], v[48:51]
	s_setprio 0
	s_setprio 1
	v_mfma_f32_16x16x32_bf16 v[124:127], v[168:171], v[184:187], v[124:127]
	v_mfma_f32_16x16x32_bf16 v[116:119], v[176:179], v[184:187], v[116:119]
	v_mfma_f32_16x16x32_bf16 v[108:111], v[168:171], v[192:195], v[108:111]
	v_mfma_f32_16x16x32_bf16 v[100:103], v[176:179], v[192:195], v[100:103]
	v_mfma_f32_16x16x32_bf16 v[92:95], v[168:171], v[200:203], v[92:95]
	v_mfma_f32_16x16x32_bf16 v[84:87], v[176:179], v[200:203], v[84:87]
	v_mfma_f32_16x16x32_bf16 v[60:63], v[168:171], v[208:211], v[60:63]
	v_mfma_f32_16x16x32_bf16 v[52:55], v[176:179], v[208:211], v[52:55]
	v_mfma_f32_16x16x32_bf16 v[124:127], v[172:175], v[188:191], v[124:127]
	v_mfma_f32_16x16x32_bf16 v[116:119], v[180:183], v[188:191], v[116:119]
	v_mfma_f32_16x16x32_bf16 v[108:111], v[172:175], v[196:199], v[108:111]
	v_mfma_f32_16x16x32_bf16 v[100:103], v[180:183], v[196:199], v[100:103]
	v_mfma_f32_16x16x32_bf16 v[92:95], v[172:175], v[204:207], v[92:95]
	v_mfma_f32_16x16x32_bf16 v[84:87], v[180:183], v[204:207], v[84:87]
	v_mfma_f32_16x16x32_bf16 v[60:63], v[172:175], v[212:215], v[60:63]
	v_mfma_f32_16x16x32_bf16 v[52:55], v[180:183], v[212:215], v[52:55]
	s_barrier
	s_setprio 0
	s_mov_b32 m0, s59
	v_lshl_add_u64 v[140:141], v[140:141], 0, s[62:63]
	s_add_u32 s82, s82, 0x80080
	ds_read_b128 v[184:187], v151 offset:49152
	ds_read_b128 v[188:191], v151 offset:50176
	ds_read_b128 v[192:195], v151 offset:51200
	ds_read_b128 v[196:199], v151 offset:52224
	ds_read_b128 v[200:203], v151 offset:53248
	ds_read_b128 v[204:207], v151 offset:54272
	ds_read_b128 v[208:211], v151 offset:55296
	ds_read_b128 v[212:215], v151 offset:56320
	global_load_lds_dwordx4 v[140:141], off
	v_lshl_add_u64 v[140:141], v[142:143], 0, s[62:63]
	s_mov_b32 m0, s71
	s_addc_u32 s83, s83, 0
	global_load_lds_dwordx4 v[140:141], off
	v_lshl_add_u64 v[140:141], s[82:83], 0, v[128:129]
	s_mov_b32 m0, s73
	s_nop 0
	global_load_lds_dwordx4 v[140:141], off
	v_lshl_add_u64 v[140:141], s[82:83], 0, v[130:131]
	s_mov_b32 m0, s79
	s_nop 0
	global_load_lds_dwordx4 v[140:141], off
	v_lshl_add_u64 v[140:141], v[146:147], 0, s[62:63]
	s_mov_b32 m0, s43
	s_nop 0
	global_load_lds_dwordx4 v[140:141], off
	v_lshl_add_u64 v[140:141], v[216:217], 0, s[62:63]
	s_mov_b32 m0, s44
	s_nop 0
	global_load_lds_dwordx4 v[140:141], off
	s_waitcnt vmcnt(8) lgkmcnt(0)
	s_setprio 1
	s_barrier
	v_mfma_f32_16x16x32_bf16 v[72:75], v[152:155], v[184:187], v[72:75]
	v_mfma_f32_16x16x32_bf16 v[64:67], v[160:163], v[184:187], v[64:67]
	v_mfma_f32_16x16x32_bf16 v[40:43], v[152:155], v[192:195], v[40:43]
	v_mfma_f32_16x16x32_bf16 v[32:35], v[160:163], v[192:195], v[32:35]
	v_mfma_f32_16x16x32_bf16 v[24:27], v[152:155], v[200:203], v[24:27]
	v_mfma_f32_16x16x32_bf16 v[16:19], v[160:163], v[200:203], v[16:19]
	v_mfma_f32_16x16x32_bf16 v[8:11], v[152:155], v[208:211], v[8:11]
	v_mfma_f32_16x16x32_bf16 v[0:3], v[160:163], v[208:211], v[0:3]
	v_mfma_f32_16x16x32_bf16 v[72:75], v[156:159], v[188:191], v[72:75]
	v_mfma_f32_16x16x32_bf16 v[64:67], v[164:167], v[188:191], v[64:67]
	v_mfma_f32_16x16x32_bf16 v[40:43], v[156:159], v[196:199], v[40:43]
	v_mfma_f32_16x16x32_bf16 v[32:35], v[164:167], v[196:199], v[32:35]
	v_mfma_f32_16x16x32_bf16 v[24:27], v[156:159], v[204:207], v[24:27]
	v_mfma_f32_16x16x32_bf16 v[16:19], v[164:167], v[204:207], v[16:19]
	v_mfma_f32_16x16x32_bf16 v[8:11], v[156:159], v[212:215], v[8:11]
	v_mfma_f32_16x16x32_bf16 v[0:3], v[164:167], v[212:215], v[0:3]
	s_setprio 0
	s_setprio 1
	v_mfma_f32_16x16x32_bf16 v[76:79], v[168:171], v[184:187], v[76:79]
	v_mfma_f32_16x16x32_bf16 v[68:71], v[176:179], v[184:187], v[68:71]
	v_mfma_f32_16x16x32_bf16 v[44:47], v[168:171], v[192:195], v[44:47]
	v_mfma_f32_16x16x32_bf16 v[36:39], v[176:179], v[192:195], v[36:39]
	v_mfma_f32_16x16x32_bf16 v[28:31], v[168:171], v[200:203], v[28:31]
	v_mfma_f32_16x16x32_bf16 v[20:23], v[176:179], v[200:203], v[20:23]
	v_mfma_f32_16x16x32_bf16 v[12:15], v[168:171], v[208:211], v[12:15]
	v_mfma_f32_16x16x32_bf16 v[4:7], v[176:179], v[208:211], v[4:7]
	v_mfma_f32_16x16x32_bf16 v[76:79], v[172:175], v[188:191], v[76:79]
	v_mfma_f32_16x16x32_bf16 v[68:71], v[180:183], v[188:191], v[68:71]
	v_mfma_f32_16x16x32_bf16 v[44:47], v[172:175], v[196:199], v[44:47]
	v_mfma_f32_16x16x32_bf16 v[36:39], v[180:183], v[196:199], v[36:39]
	v_mfma_f32_16x16x32_bf16 v[28:31], v[172:175], v[204:207], v[28:31]
	v_mfma_f32_16x16x32_bf16 v[20:23], v[180:183], v[204:207], v[20:23]
	v_mfma_f32_16x16x32_bf16 v[12:15], v[172:175], v[212:215], v[12:15]
	v_mfma_f32_16x16x32_bf16 v[4:7], v[180:183], v[212:215], v[4:7]
	s_barrier
	s_setprio 0
	s_add_i32 s90, s90, 2
	s_add_u32 s88, s88, 0x100
	s_addc_u32 s89, s89, 0
	s_add_u32 s80, s80, 0x100
	s_addc_u32 s81, s81, 0
	s_cmp_gt_u32 s90, 29
	s_cbranch_scc0 .LBB0_777
	s_and_b64 vcc, exec, s[64:65]
	s_cbranch_vccz .LBB0_780
	s_barrier

; #define PG8_MMA(ai, bj, At, Bt) do { __builtin_amdgcn_s_setprio(1); _Pragma("unroll") for (int m = 0; m < 4; ++m) _Pragma("unroll") for (int n = 0; n < 2; ++n) _Pragma("unroll") for (int k = 0; k < 2; ++k) \
;         acc[ai][bj][m][n] = __builtin_amdgcn_mfma_f32_16x16x32_bf16(Bt[n][k], At[m][k], acc[ai][bj][m][n], 0, 0, 0); __builtin_amdgcn_s_setprio(0); } while (0)
; template <class Epi, class Sched, bool ALIGN_EPI = false, bool SP2 = false, bool A_TILED = false>
; __device__ __forceinline__ void gemm_phase(PG8_LAS unsigned char* lds, const Gemm g, const Sched& S, const Epi& E, const int wave_s) {
;     ...
;         for (int t = PEEL ? 2 : 0; t < nt; t += 2) {
;             const bool last = (t == nt - 2);
;             const char* a1 = cA + (size_t)(t + 1) * kstepA;
;             const char* a2 = last ? nA : cA + (size_t)(t + 2) * kstepA; const char* b2 = last ? nB : cB + (size_t)(t + 2) * kstep;
;             const char* a3 = a2 + kstepA; const char* b3 = b2 + kstep;
;             if (last && has_next) S.a_ready(nxt);
;             if constexpr (SP2) {
;             PG8_ITER(PG8_MMA)
.LBB0_1043:
	ds_read_b128 v[146:149], v140
	ds_read_b128 v[150:153], v140 offset:1024
	ds_read_b128 v[154:157], v140 offset:2048
	ds_read_b128 v[158:161], v140 offset:3072
	ds_read_b128 v[162:165], v141
	ds_read_b128 v[166:169], v141 offset:1024
	ds_read_b128 v[170:173], v141 offset:2048
	ds_read_b128 v[174:177], v141 offset:3072
	s_add_u32 s52, s62, s39
	s_addc_u32 s53, s63, s40
	s_add_u32 s54, s62, s37
	s_addc_u32 s55, s63, s38
	s_cmp_eq_u32 s41, 28
	s_cselect_b32 s73, s5, s53
	s_cselect_b32 s72, s4, s52
	s_cselect_b32 s71, s1, s55
	s_cselect_b32 s70, s0, s54
	s_mov_b32 m0, s42
	v_lshl_add_u64 v[210:211], s[62:63], 0, v[138:139]
	ds_read_b128 v[178:181], v142
	ds_read_b128 v[182:185], v142 offset:1024
	ds_read_b128 v[186:189], v142 offset:2048
	ds_read_b128 v[190:193], v142 offset:3072
	ds_read_b128 v[194:197], v142 offset:4096
	ds_read_b128 v[198:201], v142 offset:5120
	ds_read_b128 v[202:205], v142 offset:6144
	ds_read_b128 v[206:209], v142 offset:7168
	global_load_lds_dwordx4 v[210:211], off
	v_lshl_add_u64 v[210:211], s[62:63], 0, v[136:137]
	s_mov_b32 m0, s43
	s_nop 0
	global_load_lds_dwordx4 v[210:211], off
	s_waitcnt vmcnt(8) lgkmcnt(0)
	s_setprio 1
	s_barrier
	v_mfma_f32_16x16x32_bf16 v[8:11], v[146:149], v[178:181], v[8:11]
	v_mfma_f32_16x16x32_bf16 v[12:15], v[154:157], v[178:181], v[12:15]
	v_mfma_f32_16x16x32_bf16 v[36:39], v[146:149], v[186:189], v[36:39]
	v_mfma_f32_16x16x32_bf16 v[32:35], v[154:157], v[186:189], v[32:35]
	v_mfma_f32_16x16x32_bf16 v[60:63], v[146:149], v[194:197], v[60:63]
	v_mfma_f32_16x16x32_bf16 v[56:59], v[154:157], v[194:197], v[56:59]
	v_mfma_f32_16x16x32_bf16 v[80:83], v[146:149], v[202:205], v[80:83]
	v_mfma_f32_16x16x32_bf16 v[72:75], v[154:157], v[202:205], v[72:75]
	v_mfma_f32_16x16x32_bf16 v[8:11], v[150:153], v[182:185], v[8:11]
	v_mfma_f32_16x16x32_bf16 v[12:15], v[158:161], v[182:185], v[12:15]
	v_mfma_f32_16x16x32_bf16 v[36:39], v[150:153], v[190:193], v[36:39]
	v_mfma_f32_16x16x32_bf16 v[32:35], v[158:161], v[190:193], v[32:35]
	v_mfma_f32_16x16x32_bf16 v[60:63], v[150:153], v[198:201], v[60:63]
	v_mfma_f32_16x16x32_bf16 v[56:59], v[158:161], v[198:201], v[56:59]
	v_mfma_f32_16x16x32_bf16 v[80:83], v[150:153], v[206:209], v[80:83]
	v_mfma_f32_16x16x32_bf16 v[72:75], v[158:161], v[206:209], v[72:75]
	s_setprio 0
	s_setprio 1
	v_mfma_f32_16x16x32_bf16 v[44:47], v[162:165], v[178:181], v[44:47]
	v_mfma_f32_16x16x32_bf16 v[40:43], v[170:173], v[178:181], v[40:43]
	v_mfma_f32_16x16x32_bf16 v[52:55], v[162:165], v[186:189], v[52:55]
	v_mfma_f32_16x16x32_bf16 v[48:51], v[170:173], v[186:189], v[48:51]
	v_mfma_f32_16x16x32_bf16 v[68:71], v[162:165], v[194:197], v[68:71]
	v_mfma_f32_16x16x32_bf16 v[64:67], v[170:173], v[194:197], v[64:67]
	v_mfma_f32_16x16x32_bf16 v[100:103], v[162:165], v[202:205], v[100:103]
	v_mfma_f32_16x16x32_bf16 v[96:99], v[170:173], v[202:205], v[96:99]
	v_mfma_f32_16x16x32_bf16 v[44:47], v[166:169], v[182:185], v[44:47]
	v_mfma_f32_16x16x32_bf16 v[40:43], v[174:177], v[182:185], v[40:43]
	v_mfma_f32_16x16x32_bf16 v[52:55], v[166:169], v[190:193], v[52:55]
	v_mfma_f32_16x16x32_bf16 v[48:51], v[174:177], v[190:193], v[48:51]
	v_mfma_f32_16x16x32_bf16 v[68:71], v[166:169], v[198:201], v[68:71]
	v_mfma_f32_16x16x32_bf16 v[64:67], v[174:177], v[198:201], v[64:67]
	v_mfma_f32_16x16x32_bf16 v[100:103], v[166:169], v[206:209], v[100:103]
	v_mfma_f32_16x16x32_bf16 v[96:99], v[174:177], v[206:209], v[96:99]
	s_barrier
	s_setprio 0
	s_mov_b32 m0, s44
	v_lshl_add_u64 v[210:211], s[70:71], 0, v[130:131]
	s_add_u32 s52, s70, 0x80000
	ds_read_b128 v[178:181], v142 offset:16384
	ds_read_b128 v[182:185], v142 offset:17408
	ds_read_b128 v[186:189], v142 offset:18432
	ds_read_b128 v[190:193], v142 offset:19456
	ds_read_b128 v[194:197], v142 offset:20480
	ds_read_b128 v[198:201], v142 offset:21504
	ds_read_b128 v[202:205], v142 offset:22528
	ds_read_b128 v[206:209], v142 offset:23552
	global_load_lds_dwordx4 v[210:211], off
	v_lshl_add_u64 v[212:213], s[70:71], 0, v[134:135]
	s_mov_b32 m0, s45
	s_addc_u32 s53, s71, 0
	global_load_lds_dwordx4 v[212:213], off
	v_lshl_add_u64 v[214:215], s[52:53], 0, v[130:131]
	s_mov_b32 m0, s46
	v_lshl_add_u64 v[216:217], s[72:73], 0, v[132:133]
	global_load_lds_dwordx4 v[214:215], off
	v_lshl_add_u64 v[214:215], s[52:53], 0, v[134:135]
	s_mov_b32 m0, s47
	s_nop 0
	global_load_lds_dwordx4 v[214:215], off
	v_lshl_add_u64 v[214:215], s[72:73], 0, v[128:129]
	s_mov_b32 m0, s14
	s_nop 0
	global_load_lds_dwordx4 v[214:215], off
	s_mov_b32 m0, s15
	s_nop 0
	global_load_lds_dwordx4 v[216:217], off
	s_waitcnt vmcnt(8) lgkmcnt(0)
	s_setprio 1
	s_barrier
	v_mfma_f32_16x16x32_bf16 v[108:111], v[146:149], v[178:181], v[108:111]
	v_mfma_f32_16x16x32_bf16 v[104:107], v[154:157], v[178:181], v[104:107]
	v_mfma_f32_16x16x32_bf16 v[124:127], v[146:149], v[186:189], v[124:127]
	v_mfma_f32_16x16x32_bf16 v[120:123], v[154:157], v[186:189], v[120:123]
	v_mfma_f32_16x16x32_bf16 v[84:87], v[146:149], v[194:197], v[84:87]
	v_mfma_f32_16x16x32_bf16 v[76:79], v[154:157], v[194:197], v[76:79]
	v_mfma_f32_16x16x32_bf16 v[20:23], v[146:149], v[202:205], v[20:23]
	v_mfma_f32_16x16x32_bf16 v[16:19], v[154:157], v[202:205], v[16:19]
	v_mfma_f32_16x16x32_bf16 v[108:111], v[150:153], v[182:185], v[108:111]
	v_mfma_f32_16x16x32_bf16 v[104:107], v[158:161], v[182:185], v[104:107]
	v_mfma_f32_16x16x32_bf16 v[124:127], v[150:153], v[190:193], v[124:127]
	v_mfma_f32_16x16x32_bf16 v[120:123], v[158:161], v[190:193], v[120:123]
	v_mfma_f32_16x16x32_bf16 v[84:87], v[150:153], v[198:201], v[84:87]
	v_mfma_f32_16x16x32_bf16 v[76:79], v[158:161], v[198:201], v[76:79]
	v_mfma_f32_16x16x32_bf16 v[20:23], v[150:153], v[206:209], v[20:23]
	v_mfma_f32_16x16x32_bf16 v[16:19], v[158:161], v[206:209], v[16:19]
	s_setprio 0
	s_setprio 1
	v_mfma_f32_16x16x32_bf16 v[116:119], v[162:165], v[178:181], v[116:119]
	v_mfma_f32_16x16x32_bf16 v[112:115], v[170:173], v[178:181], v[112:115]
	v_mfma_f32_16x16x32_bf16 v[92:95], v[162:165], v[186:189], v[92:95]
	v_mfma_f32_16x16x32_bf16 v[88:91], v[170:173], v[186:189], v[88:91]
	v_mfma_f32_16x16x32_bf16 v[28:31], v[162:165], v[194:197], v[28:31]
	v_mfma_f32_16x16x32_bf16 v[24:27], v[170:173], v[194:197], v[24:27]
	v_mfma_f32_16x16x32_bf16 v[4:7], v[162:165], v[202:205], v[4:7]
	v_mfma_f32_16x16x32_bf16 v[0:3], v[170:173], v[202:205], v[0:3]
	v_mfma_f32_16x16x32_bf16 v[116:119], v[166:169], v[182:185], v[116:119]
	v_mfma_f32_16x16x32_bf16 v[112:115], v[174:177], v[182:185], v[112:115]
	v_mfma_f32_16x16x32_bf16 v[92:95], v[166:169], v[190:193], v[92:95]
	v_mfma_f32_16x16x32_bf16 v[88:91], v[174:177], v[190:193], v[88:91]
	v_mfma_f32_16x16x32_bf16 v[28:31], v[166:169], v[198:201], v[28:31]
	v_mfma_f32_16x16x32_bf16 v[24:27], v[174:177], v[198:201], v[24:27]
	v_mfma_f32_16x16x32_bf16 v[4:7], v[166:169], v[206:209], v[4:7]
	v_mfma_f32_16x16x32_bf16 v[0:3], v[174:177], v[206:209], v[0:3]
	s_barrier
	s_setprio 0
	ds_read_b128 v[146:149], v143
	ds_read_b128 v[150:153], v143 offset:1024
	ds_read_b128 v[154:157], v143 offset:2048
	ds_read_b128 v[158:161], v143 offset:3072
	ds_read_b128 v[162:165], v144
	ds_read_b128 v[166:169], v144 offset:1024
	ds_read_b128 v[170:173], v144 offset:2048
	ds_read_b128 v[174:177], v144 offset:3072
	s_add_u32 s52, s72, 0x80000
	s_addc_u32 s53, s73, 0
	s_mov_b32 m0, s21
	v_lshl_add_u64 v[218:219], s[52:53], 0, v[128:129]
	ds_read_b128 v[178:181], v142 offset:32768
	ds_read_b128 v[182:185], v142 offset:33792
	ds_read_b128 v[186:189], v142 offset:34816
	ds_read_b128 v[190:193], v142 offset:35840
	ds_read_b128 v[194:197], v142 offset:36864
	ds_read_b128 v[198:201], v142 offset:37888
	ds_read_b128 v[202:205], v142 offset:38912
	ds_read_b128 v[206:209], v142 offset:39936
	global_load_lds_dwordx4 v[218:219], off
	v_lshl_add_u64 v[218:219], s[52:53], 0, v[132:133]
	s_mov_b32 m0, s22
	s_nop 0
	global_load_lds_dwordx4 v[218:219], off
	s_waitcnt vmcnt(8) lgkmcnt(0)
	s_setprio 1
	s_barrier
	v_mfma_f32_16x16x32_bf16 v[8:11], v[146:149], v[178:181], v[8:11]
	v_mfma_f32_16x16x32_bf16 v[12:15], v[154:157], v[178:181], v[12:15]
	v_mfma_f32_16x16x32_bf16 v[36:39], v[146:149], v[186:189], v[36:39]
	v_mfma_f32_16x16x32_bf16 v[32:35], v[154:157], v[186:189], v[32:35]
	v_mfma_f32_16x16x32_bf16 v[60:63], v[146:149], v[194:197], v[60:63]
	v_mfma_f32_16x16x32_bf16 v[56:59], v[154:157], v[194:197], v[56:59]
	v_mfma_f32_16x16x32_bf16 v[80:83], v[146:149], v[202:205], v[80:83]
	v_mfma_f32_16x16x32_bf16 v[72:75], v[154:157], v[202:205], v[72:75]
	v_mfma_f32_16x16x32_bf16 v[8:11], v[150:153], v[182:185], v[8:11]
	v_mfma_f32_16x16x32_bf16 v[12:15], v[158:161], v[182:185], v[12:15]
	v_mfma_f32_16x16x32_bf16 v[36:39], v[150:153], v[190:193], v[36:39]
	v_mfma_f32_16x16x32_bf16 v[32:35], v[158:161], v[190:193], v[32:35]
	v_mfma_f32_16x16x32_bf16 v[60:63], v[150:153], v[198:201], v[60:63]
	v_mfma_f32_16x16x32_bf16 v[56:59], v[158:161], v[198:201], v[56:59]
	v_mfma_f32_16x16x32_bf16 v[80:83], v[150:153], v[206:209], v[80:83]
	v_mfma_f32_16x16x32_bf16 v[72:75], v[158:161], v[206:209], v[72:75]
	s_setprio 0
	s_setprio 1
	v_mfma_f32_16x16x32_bf16 v[44:47], v[162:165], v[178:181], v[44:47]
	v_mfma_f32_16x16x32_bf16 v[40:43], v[170:173], v[178:181], v[40:43]
	v_mfma_f32_16x16x32_bf16 v[52:55], v[162:165], v[186:189], v[52:55]
	v_mfma_f32_16x16x32_bf16 v[48:51], v[170:173], v[186:189], v[48:51]
	v_mfma_f32_16x16x32_bf16 v[68:71], v[162:165], v[194:197], v[68:71]
	v_mfma_f32_16x16x32_bf16 v[64:67], v[170:173], v[194:197], v[64:67]
	v_mfma_f32_16x16x32_bf16 v[100:103], v[162:165], v[202:205], v[100:103]
	v_mfma_f32_16x16x32_bf16 v[96:99], v[170:173], v[202:205], v[96:99]
	v_mfma_f32_16x16x32_bf16 v[44:47], v[166:169], v[182:185], v[44:47]
	v_mfma_f32_16x16x32_bf16 v[40:43], v[174:177], v[182:185], v[40:43]
	v_mfma_f32_16x16x32_bf16 v[52:55], v[166:169], v[190:193], v[52:55]
	v_mfma_f32_16x16x32_bf16 v[48:51], v[174:177], v[190:193], v[48:51]
	v_mfma_f32_16x16x32_bf16 v[68:71], v[166:169], v[198:201], v[68:71]
	v_mfma_f32_16x16x32_bf16 v[64:67], v[174:177], v[198:201], v[64:67]
	v_mfma_f32_16x16x32_bf16 v[100:103], v[166:169], v[206:209], v[100:103]
	v_mfma_f32_16x16x32_bf16 v[96:99], v[174:177], v[206:209], v[96:99]
	s_barrier
; #define PG8_WAIT_V(n) asm volatile("s_waitcnt vmcnt(" #n ")" ::: "memory")
; #define PG8_BAR __builtin_amdgcn_s_barrier()
; template <class Epi, class Sched, bool ALIGN_EPI = false, bool SP2 = false, bool A_TILED = false>
; __device__ __forceinline__ void gemm_phase(PG8_LAS unsigned char* lds, const Gemm g, const Sched& S, const Epi& E, const int wave_s) {
;     ...
;     PG8_WAIT_V(0);
;     if constexpr (!ALIGN_EPI) { if (wr == 0) PG8_BAR; }
	s_setprio 0
	s_mov_b32 m0, s48
	v_lshl_add_u64 v[210:211], v[210:211], 0, s[66:67]
	s_add_u32 s52, s70, 0x80080
	ds_read_b128 v[178:181], v142 offset:49152
	ds_read_b128 v[182:185], v142 offset:50176
	ds_read_b128 v[186:189], v142 offset:51200
	ds_read_b128 v[190:193], v142 offset:52224
	ds_read_b128 v[194:197], v142 offset:53248
	ds_read_b128 v[198:201], v142 offset:54272
	ds_read_b128 v[202:205], v142 offset:55296
	ds_read_b128 v[206:209], v142 offset:56320
	global_load_lds_dwordx4 v[210:211], off
	v_lshl_add_u64 v[210:211], v[212:213], 0, s[66:67]
	s_mov_b32 m0, s49
	s_addc_u32 s53, s71, 0
	global_load_lds_dwordx4 v[210:211], off
	v_lshl_add_u64 v[210:211], s[52:53], 0, v[130:131]
	s_mov_b32 m0, s50
	s_nop 0
	global_load_lds_dwordx4 v[210:211], off
	v_lshl_add_u64 v[210:211], s[52:53], 0, v[134:135]
	s_mov_b32 m0, s51
	s_nop 0
	global_load_lds_dwordx4 v[210:211], off
	v_lshl_add_u64 v[210:211], v[214:215], 0, s[66:67]
	s_mov_b32 m0, s23
	s_nop 0
	global_load_lds_dwordx4 v[210:211], off
	v_lshl_add_u64 v[210:211], v[216:217], 0, s[66:67]
	s_mov_b32 m0, s36
	s_nop 0
	global_load_lds_dwordx4 v[210:211], off
	s_waitcnt vmcnt(8) lgkmcnt(0)
	s_setprio 1
	s_barrier
	v_mfma_f32_16x16x32_bf16 v[108:111], v[146:149], v[178:181], v[108:111]
	v_mfma_f32_16x16x32_bf16 v[104:107], v[154:157], v[178:181], v[104:107]
	v_mfma_f32_16x16x32_bf16 v[124:127], v[146:149], v[186:189], v[124:127]
	v_mfma_f32_16x16x32_bf16 v[120:123], v[154:157], v[186:189], v[120:123]
	v_mfma_f32_16x16x32_bf16 v[84:87], v[146:149], v[194:197], v[84:87]
	v_mfma_f32_16x16x32_bf16 v[76:79], v[154:157], v[194:197], v[76:79]
	v_mfma_f32_16x16x32_bf16 v[20:23], v[146:149], v[202:205], v[20:23]
	v_mfma_f32_16x16x32_bf16 v[16:19], v[154:157], v[202:205], v[16:19]
	v_mfma_f32_16x16x32_bf16 v[108:111], v[150:153], v[182:185], v[108:111]
	v_mfma_f32_16x16x32_bf16 v[104:107], v[158:161], v[182:185], v[104:107]
	v_mfma_f32_16x16x32_bf16 v[124:127], v[150:153], v[190:193], v[124:127]
	v_mfma_f32_16x16x32_bf16 v[120:123], v[158:161], v[190:193], v[120:123]
	v_mfma_f32_16x16x32_bf16 v[84:87], v[150:153], v[198:201], v[84:87]
	v_mfma_f32_16x16x32_bf16 v[76:79], v[158:161], v[198:201], v[76:79]
	v_mfma_f32_16x16x32_bf16 v[20:23], v[150:153], v[206:209], v[20:23]
	v_mfma_f32_16x16x32_bf16 v[16:19], v[158:161], v[206:209], v[16:19]
	s_setprio 0
	s_setprio 1
	v_mfma_f32_16x16x32_bf16 v[116:119], v[162:165], v[178:181], v[116:119]
	v_mfma_f32_16x16x32_bf16 v[112:115], v[170:173], v[178:181], v[112:115]
	v_mfma_f32_16x16x32_bf16 v[92:95], v[162:165], v[186:189], v[92:95]
	v_mfma_f32_16x16x32_bf16 v[88:91], v[170:173], v[186:189], v[88:91]
	v_mfma_f32_16x16x32_bf16 v[28:31], v[162:165], v[194:197], v[28:31]
	v_mfma_f32_16x16x32_bf16 v[24:27], v[170:173], v[194:197], v[24:27]
	v_mfma_f32_16x16x32_bf16 v[4:7], v[162:165], v[202:205], v[4:7]
	v_mfma_f32_16x16x32_bf16 v[0:3], v[170:173], v[202:205], v[0:3]
	v_mfma_f32_16x16x32_bf16 v[116:119], v[166:169], v[182:185], v[116:119]
	v_mfma_f32_16x16x32_bf16 v[112:115], v[174:177], v[182:185], v[112:115]
	v_mfma_f32_16x16x32_bf16 v[92:95], v[166:169], v[190:193], v[92:95]
	v_mfma_f32_16x16x32_bf16 v[88:91], v[174:177], v[190:193], v[88:91]
	v_mfma_f32_16x16x32_bf16 v[28:31], v[166:169], v[198:201], v[28:31]
	v_mfma_f32_16x16x32_bf16 v[24:27], v[174:177], v[198:201], v[24:27]
	v_mfma_f32_16x16x32_bf16 v[4:7], v[166:169], v[206:209], v[4:7]
	v_mfma_f32_16x16x32_bf16 v[0:3], v[174:177], v[206:209], v[0:3]
	s_barrier
	s_setprio 0
	s_add_i32 s41, s41, 2
	s_add_u32 s37, s37, 0x100
	s_addc_u32 s38, s38, 0
	s_add_u32 s39, s39, 0x100
	s_addc_u32 s40, s40, 0
	v_lshl_add_u64 v[136:137], v[136:137], 0, s[68:69]
	s_cmp_gt_u32 s41, 29
	v_lshl_add_u64 v[138:139], v[138:139], 0, s[68:69]
	s_cbranch_scc0 .LBB0_1043
	s_waitcnt vmcnt(0)
	s_cmpk_lt_u32 s6, 0x100
	s_cbranch_scc0 .LBB0_1046
	s_barrier

; template <class Epi, class Sched, bool ALIGN_EPI = false, bool SP2 = false, bool A_TILED = false>
; __device__ __forceinline__ void gemm_phase(PG8_LAS unsigned char* lds, const Gemm g, const Sched& S, const Epi& E, const int wave_s) {
;     ...
;         const bool has_next = Epi::AFTER_DRAIN ? false : S.next(ui + 1, nxt);
;         const char* nA = has_next ? (const char*)g.A + (size_t)nxt.pm * tstepA : cA; const char* nB = has_next ? (const char*)g.Bt + (size_t)nxt.pn * tstep : cB;
;         constexpr bool PEEL = SP2 && !Epi::AFTER_DRAIN;
;         if constexpr (PEEL) {
;             const char* a1 = cA + kstepA; const char* a2 = cA + 2 * kstepA; const char* b2 = cB + 2 * kstep; const char* a3 = a2 + kstepA; const char* b3 = b2 + kstep;
;             PG8_ITER(PG8_MMAZ)
.LBB0_1154:
	s_ashr_i32 s69, s68, 31
	s_lshl_b64 s[50:51], s[68:69], 20
	s_add_u32 s70, s7, s50
	ds_read_b128 v[0:3], v145
	ds_read_b128 v[4:7], v145 offset:1024
	ds_read_b128 v[8:11], v145 offset:2048
	ds_read_b128 v[12:15], v145 offset:3072
	ds_read_b128 v[16:19], v146
	ds_read_b128 v[20:23], v146 offset:1024
	ds_read_b128 v[24:27], v146 offset:2048
	ds_read_b128 v[28:31], v146 offset:3072
	s_addc_u32 s71, s8, s51
	s_ashr_i32 s67, s66, 31
	s_lshl_b64 s[50:51], s[66:67], 20
	s_add_u32 s72, s9, s50
	s_addc_u32 s73, s14, s51
	s_and_b64 s[50:51], s[0:1], exec
	s_cselect_b32 s50, s71, s79
	s_cselect_b32 s51, s70, s78
	s_cselect_b32 s52, s73, s77
	s_cselect_b32 s53, s72, s76
	s_add_u32 s56, s78, 0x80080
	s_addc_u32 s57, s79, 0
	s_add_i32 s54, s22, 0xc000
	v_lshl_add_u64 v[64:65], s[56:57], 0, v[134:135]
	s_mov_b32 m0, s54
	s_add_i32 s55, s22, 0xe000
	ds_read_b128 v[32:35], v147
	ds_read_b128 v[36:39], v147 offset:1024
	ds_read_b128 v[40:43], v147 offset:2048
	ds_read_b128 v[44:47], v147 offset:3072
	ds_read_b128 v[48:51], v147 offset:4096
	ds_read_b128 v[52:55], v147 offset:5120
	ds_read_b128 v[56:59], v147 offset:6144
	ds_read_b128 v[60:63], v147 offset:7168
	global_load_lds_dwordx4 v[64:65], off
	v_lshl_add_u64 v[64:65], s[56:57], 0, v[132:133]
	s_mov_b32 m0, s55
	s_nop 0
	global_load_lds_dwordx4 v[64:65], off
	s_waitcnt vmcnt(8) lgkmcnt(0)
	s_setprio 1
	s_barrier
	v_mfma_f32_16x16x32_bf16 v[88:91], v[0:3], v[56:59], 0
	v_mfma_f32_16x16x32_bf16 v[64:67], v[0:3], v[32:35], 0
	v_mfma_f32_16x16x32_bf16 v[68:71], v[8:11], v[32:35], 0
	v_mfma_f32_16x16x32_bf16 v[72:75], v[0:3], v[40:43], 0
	v_mfma_f32_16x16x32_bf16 v[76:79], v[8:11], v[40:43], 0
	v_mfma_f32_16x16x32_bf16 v[80:83], v[0:3], v[48:51], 0
	v_mfma_f32_16x16x32_bf16 v[84:87], v[8:11], v[48:51], 0
	v_mfma_f32_16x16x32_bf16 v[96:99], v[4:7], v[60:63], v[88:91]
	v_mfma_f32_16x16x32_bf16 v[88:91], v[8:11], v[56:59], 0
	v_mfma_f32_16x16x32_bf16 v[64:67], v[4:7], v[36:39], v[64:67]
	v_mfma_f32_16x16x32_bf16 v[68:71], v[12:15], v[36:39], v[68:71]
	v_mfma_f32_16x16x32_bf16 v[72:75], v[4:7], v[44:47], v[72:75]
	v_mfma_f32_16x16x32_bf16 v[76:79], v[12:15], v[44:47], v[76:79]
	v_mfma_f32_16x16x32_bf16 v[80:83], v[4:7], v[52:55], v[80:83]
	v_mfma_f32_16x16x32_bf16 v[84:87], v[12:15], v[52:55], v[84:87]
	v_mfma_f32_16x16x32_bf16 v[100:103], v[12:15], v[60:63], v[88:91]
	s_setprio 0
	s_setprio 1
	v_mfma_f32_16x16x32_bf16 v[88:91], v[16:19], v[32:35], 0
	v_mfma_f32_16x16x32_bf16 v[32:35], v[24:27], v[32:35], 0
	v_mfma_f32_16x16x32_bf16 v[112:115], v[20:23], v[36:39], v[88:91]
	v_mfma_f32_16x16x32_bf16 v[32:35], v[28:31], v[36:39], v[32:35]
	v_mfma_f32_16x16x32_bf16 v[36:39], v[16:19], v[40:43], 0
	v_mfma_f32_16x16x32_bf16 v[40:43], v[24:27], v[40:43], 0
	v_mfma_f32_16x16x32_bf16 v[36:39], v[20:23], v[44:47], v[36:39]
	v_mfma_f32_16x16x32_bf16 v[40:43], v[28:31], v[44:47], v[40:43]
	v_mfma_f32_16x16x32_bf16 v[44:47], v[16:19], v[48:51], 0
	v_mfma_f32_16x16x32_bf16 v[48:51], v[24:27], v[48:51], 0
	v_mfma_f32_16x16x32_bf16 v[44:47], v[20:23], v[52:55], v[44:47]
	v_mfma_f32_16x16x32_bf16 v[48:51], v[28:31], v[52:55], v[48:51]
	v_mfma_f32_16x16x32_bf16 v[52:55], v[16:19], v[56:59], 0
	v_mfma_f32_16x16x32_bf16 v[56:59], v[24:27], v[56:59], 0
	v_mfma_f32_16x16x32_bf16 v[52:55], v[20:23], v[60:63], v[52:55]
	v_mfma_f32_16x16x32_bf16 v[56:59], v[28:31], v[60:63], v[56:59]
	s_barrier
	s_setprio 0
	s_add_i32 s56, s47, s15
	v_lshl_add_u64 v[242:243], s[76:77], 0, v[128:129]
	s_add_i32 s57, s56, 0x2000
	v_lshl_add_u64 v[148:149], v[242:243], 0, s[62:63]
	s_mov_b32 m0, s56
	v_lshl_add_u64 v[244:245], s[76:77], 0, v[130:131]
	s_add_u32 s80, s76, 0x80100
	ds_read_b128 v[60:63], v147 offset:16384
	ds_read_b128 v[88:91], v147 offset:17408
	ds_read_b128 v[92:95], v147 offset:18432
	ds_read_b128 v[104:107], v147 offset:19456
	ds_read_b128 v[108:111], v147 offset:20480
	ds_read_b128 v[116:119], v147 offset:21504
	ds_read_b128 v[120:123], v147 offset:22528
	ds_read_b128 v[124:127], v147 offset:23552
	global_load_lds_dwordx4 v[148:149], off
	v_lshl_add_u64 v[148:149], v[244:245], 0, s[62:63]
	s_mov_b32 m0, s57
	s_addc_u32 s81, s77, 0
	s_add_i32 s58, s48, s15
	global_load_lds_dwordx4 v[148:149], off
	v_lshl_add_u64 v[148:149], s[80:81], 0, v[128:129]
	s_mov_b32 m0, s58
	s_add_i32 s59, s58, 0x2000
	global_load_lds_dwordx4 v[148:149], off
	v_lshl_add_u64 v[148:149], s[80:81], 0, v[130:131]
	s_mov_b32 m0, s59
	v_lshl_add_u64 v[246:247], s[78:79], 0, v[134:135]
	global_load_lds_dwordx4 v[148:149], off
	v_lshl_add_u64 v[148:149], v[246:247], 0, s[62:63]
	s_mov_b32 m0, s22
	v_lshl_add_u64 v[248:249], s[78:79], 0, v[132:133]
	global_load_lds_dwordx4 v[148:149], off
	v_lshl_add_u64 v[148:149], v[248:249], 0, s[62:63]
	s_mov_b32 m0, s23
	s_nop 0
	global_load_lds_dwordx4 v[148:149], off
	s_waitcnt vmcnt(8) lgkmcnt(0)
	s_setprio 1
	s_barrier
	v_mfma_f32_16x16x32_bf16 v[148:151], v[0:3], v[60:63], 0
	v_mfma_f32_16x16x32_bf16 v[158:161], v[0:3], v[92:95], 0
	v_mfma_f32_16x16x32_bf16 v[166:169], v[0:3], v[108:111], 0
	v_mfma_f32_16x16x32_bf16 v[0:3], v[0:3], v[120:123], 0
	v_mfma_f32_16x16x32_bf16 v[150:153], v[4:7], v[88:91], v[148:151]
	v_mfma_f32_16x16x32_bf16 v[158:161], v[4:7], v[104:107], v[158:161]
	v_mfma_f32_16x16x32_bf16 v[166:169], v[4:7], v[116:119], v[166:169]
	v_mfma_f32_16x16x32_bf16 v[0:3], v[4:7], v[124:127], v[0:3]
	v_mfma_f32_16x16x32_bf16 v[4:7], v[8:11], v[120:123], 0
	v_mfma_f32_16x16x32_bf16 v[154:157], v[8:11], v[60:63], 0
	v_mfma_f32_16x16x32_bf16 v[162:165], v[8:11], v[92:95], 0
	v_mfma_f32_16x16x32_bf16 v[170:173], v[8:11], v[108:111], 0
	v_mfma_f32_16x16x32_bf16 v[4:7], v[12:15], v[124:127], v[4:7]
	v_mfma_f32_16x16x32_bf16 v[154:157], v[12:15], v[88:91], v[154:157]
	v_mfma_f32_16x16x32_bf16 v[162:165], v[12:15], v[104:107], v[162:165]
	v_mfma_f32_16x16x32_bf16 v[170:173], v[12:15], v[116:119], v[170:173]
	s_setprio 0
	s_setprio 1
	v_mfma_f32_16x16x32_bf16 v[8:11], v[16:19], v[60:63], 0
	v_mfma_f32_16x16x32_bf16 v[174:177], v[20:23], v[88:91], v[8:11]
	v_mfma_f32_16x16x32_bf16 v[8:11], v[24:27], v[60:63], 0
	v_mfma_f32_16x16x32_bf16 v[60:63], v[28:31], v[88:91], v[8:11]
	v_mfma_f32_16x16x32_bf16 v[8:11], v[16:19], v[92:95], 0
	v_mfma_f32_16x16x32_bf16 v[178:181], v[20:23], v[104:107], v[8:11]
	v_mfma_f32_16x16x32_bf16 v[8:11], v[24:27], v[92:95], 0
	v_mfma_f32_16x16x32_bf16 v[182:185], v[28:31], v[104:107], v[8:11]
	v_mfma_f32_16x16x32_bf16 v[8:11], v[16:19], v[108:111], 0
	v_mfma_f32_16x16x32_bf16 v[186:189], v[20:23], v[116:119], v[8:11]
	v_mfma_f32_16x16x32_bf16 v[8:11], v[24:27], v[108:111], 0
	v_mfma_f32_16x16x32_bf16 v[190:193], v[28:31], v[116:119], v[8:11]
	v_mfma_f32_16x16x32_bf16 v[8:11], v[16:19], v[120:123], 0
	v_mfma_f32_16x16x32_bf16 v[194:197], v[20:23], v[124:127], v[8:11]
	v_mfma_f32_16x16x32_bf16 v[8:11], v[24:27], v[120:123], 0
	v_mfma_f32_16x16x32_bf16 v[198:201], v[28:31], v[124:127], v[8:11]
	s_barrier
	s_setprio 0
	s_add_i32 s67, 0, 0x18000
	s_add_i32 s75, 0, 0x1c000
	v_add_u32_e32 v148, s67, v144
	v_add_u32_e32 v149, s75, v144
	s_nop 0
	ds_read_b128 v[8:11], v148
	ds_read_b128 v[12:15], v148 offset:1024
	ds_read_b128 v[16:19], v148 offset:2048
	ds_read_b128 v[20:23], v148 offset:3072
	ds_read_b128 v[202:205], v149
	ds_read_b128 v[206:209], v149 offset:1024
	ds_read_b128 v[210:213], v149 offset:2048
	ds_read_b128 v[214:217], v149 offset:3072
	s_add_u32 s80, s78, 0x80100
	s_addc_u32 s81, s79, 0
	s_mov_b32 m0, s36
	v_lshl_add_u64 v[88:89], s[80:81], 0, v[134:135]
	ds_read_b128 v[24:27], v147 offset:32768
	ds_read_b128 v[28:31], v147 offset:33792
	ds_read_b128 v[218:221], v147 offset:34816
	ds_read_b128 v[222:225], v147 offset:35840
	ds_read_b128 v[226:229], v147 offset:36864
	ds_read_b128 v[230:233], v147 offset:37888
	ds_read_b128 v[234:237], v147 offset:38912
	ds_read_b128 v[238:241], v147 offset:39936
	global_load_lds_dwordx4 v[88:89], off
	v_lshl_add_u64 v[88:89], s[80:81], 0, v[132:133]
	s_mov_b32 m0, s37
	s_nop 0
	global_load_lds_dwordx4 v[88:89], off
	s_waitcnt vmcnt(8) lgkmcnt(0)
	s_setprio 1
	s_barrier
	v_mfma_f32_16x16x32_bf16 v[64:67], v[8:11], v[24:27], v[64:67]
	v_mfma_f32_16x16x32_bf16 v[120:123], v[12:15], v[28:31], v[64:67]
	v_mfma_f32_16x16x32_bf16 v[64:67], v[16:19], v[24:27], v[68:71]
	v_mfma_f32_16x16x32_bf16 v[124:127], v[20:23], v[28:31], v[64:67]
	v_mfma_f32_16x16x32_bf16 v[64:67], v[8:11], v[218:221], v[72:75]
	v_mfma_f32_16x16x32_bf16 v[104:107], v[12:15], v[222:225], v[64:67]
	v_mfma_f32_16x16x32_bf16 v[64:67], v[16:19], v[218:221], v[76:79]
	v_mfma_f32_16x16x32_bf16 v[108:111], v[20:23], v[222:225], v[64:67]
	v_mfma_f32_16x16x32_bf16 v[64:67], v[8:11], v[226:229], v[80:83]
	v_mfma_f32_16x16x32_bf16 v[88:91], v[12:15], v[230:233], v[64:67]
	v_mfma_f32_16x16x32_bf16 v[64:67], v[16:19], v[226:229], v[84:87]
	v_mfma_f32_16x16x32_bf16 v[92:95], v[20:23], v[230:233], v[64:67]
	v_mfma_f32_16x16x32_bf16 v[64:67], v[8:11], v[234:237], v[96:99]
	v_mfma_f32_16x16x32_bf16 v[68:71], v[16:19], v[234:237], v[100:103]
	v_mfma_f32_16x16x32_bf16 v[64:67], v[12:15], v[238:241], v[64:67]
	v_mfma_f32_16x16x32_bf16 v[68:71], v[20:23], v[238:241], v[68:71]
	s_setprio 0
	s_setprio 1
	v_mfma_f32_16x16x32_bf16 v[72:75], v[202:205], v[24:27], v[112:115]
	v_mfma_f32_16x16x32_bf16 v[24:27], v[210:213], v[24:27], v[32:35]
	v_mfma_f32_16x16x32_bf16 v[116:119], v[214:217], v[28:31], v[24:27]
	v_mfma_f32_16x16x32_bf16 v[24:27], v[202:205], v[218:221], v[36:39]
	v_mfma_f32_16x16x32_bf16 v[96:99], v[206:209], v[222:225], v[24:27]
	v_mfma_f32_16x16x32_bf16 v[24:27], v[210:213], v[218:221], v[40:43]
	v_mfma_f32_16x16x32_bf16 v[100:103], v[214:217], v[222:225], v[24:27]
	v_mfma_f32_16x16x32_bf16 v[24:27], v[202:205], v[226:229], v[44:47]
	v_mfma_f32_16x16x32_bf16 v[80:83], v[206:209], v[230:233], v[24:27]
	v_mfma_f32_16x16x32_bf16 v[24:27], v[210:213], v[226:229], v[48:51]
	v_mfma_f32_16x16x32_bf16 v[84:87], v[214:217], v[230:233], v[24:27]
	v_mfma_f32_16x16x32_bf16 v[24:27], v[202:205], v[234:237], v[52:55]
	v_mfma_f32_16x16x32_bf16 v[48:51], v[206:209], v[238:241], v[24:27]
	v_mfma_f32_16x16x32_bf16 v[24:27], v[210:213], v[234:237], v[56:59]
	v_mfma_f32_16x16x32_bf16 v[112:115], v[206:209], v[28:31], v[72:75]
	v_mfma_f32_16x16x32_bf16 v[52:55], v[214:217], v[238:241], v[24:27]
	s_barrier
; #define PG8_MMA(ai, bj, At, Bt) do { __builtin_amdgcn_s_setprio(1); _Pragma("unroll") for (int m = 0; m < 4; ++m) _Pragma("unroll") for (int n = 0; n < 2; ++n) _Pragma("unroll") for (int k = 0; k < 2; ++k) \
;         acc[ai][bj][m][n] = __builtin_amdgcn_mfma_f32_16x16x32_bf16(Bt[n][k], At[m][k], acc[ai][bj][m][n], 0, 0, 0); __builtin_amdgcn_s_setprio(0); } while (0)
; template <class Epi, class Sched, bool ALIGN_EPI = false, bool SP2 = false, bool A_TILED = false>
; __device__ __forceinline__ void gemm_phase(PG8_LAS unsigned char* lds, const Gemm g, const Sched& S, const Epi& E, const int wave_s) {
;     ...
;         for (int t = PEEL ? 2 : 0; t < nt; t += 2) {
;             const bool last = (t == nt - 2);
;             const char* a1 = cA + (size_t)(t + 1) * kstepA;
;             const char* a2 = last ? nA : cA + (size_t)(t + 2) * kstepA; const char* b2 = last ? nB : cB + (size_t)(t + 2) * kstep;
;             const char* a3 = a2 + kstepA; const char* b3 = b2 + kstep;
;             if (last && has_next) S.a_ready(nxt);
;             if constexpr (SP2) {
;             PG8_ITER(PG8_MMA)
	s_setprio 0
	s_add_i32 s67, s67, s15
	s_add_i32 s69, s67, 0x2000
	s_nop 1
	v_lshl_add_u64 v[24:25], v[242:243], 0, s[64:65]
	s_mov_b32 m0, s67
	s_add_u32 s80, s76, 0x80180
	ds_read_b128 v[32:35], v147 offset:49152
	ds_read_b128 v[36:39], v147 offset:50176
	ds_read_b128 v[218:221], v147 offset:51200
	ds_read_b128 v[222:225], v147 offset:52224
	ds_read_b128 v[226:229], v147 offset:53248
	ds_read_b128 v[230:233], v147 offset:54272
	ds_read_b128 v[234:237], v147 offset:55296
	ds_read_b128 v[238:241], v147 offset:56320
	global_load_lds_dwordx4 v[24:25], off
	v_lshl_add_u64 v[24:25], v[244:245], 0, s[64:65]
	s_mov_b32 m0, s69
	s_addc_u32 s81, s77, 0
	s_add_i32 s75, s75, s15
	global_load_lds_dwordx4 v[24:25], off
	v_lshl_add_u64 v[24:25], s[80:81], 0, v[128:129]
	s_mov_b32 m0, s75
	s_add_i32 s82, s75, 0x2000
	global_load_lds_dwordx4 v[24:25], off
	v_lshl_add_u64 v[24:25], s[80:81], 0, v[130:131]
	s_mov_b32 m0, s82
	s_nop 0
	global_load_lds_dwordx4 v[24:25], off
	v_lshl_add_u64 v[24:25], v[246:247], 0, s[64:65]
	s_mov_b32 m0, s43
	s_nop 0
	global_load_lds_dwordx4 v[24:25], off
	v_lshl_add_u64 v[24:25], v[248:249], 0, s[64:65]
	s_mov_b32 m0, s44
	s_nop 0
	global_load_lds_dwordx4 v[24:25], off
	s_waitcnt vmcnt(8) lgkmcnt(0)
	s_setprio 1
	s_barrier
	v_mfma_f32_16x16x32_bf16 v[24:27], v[8:11], v[32:35], v[150:153]
	v_mfma_f32_16x16x32_bf16 v[72:75], v[12:15], v[36:39], v[24:27]
	v_mfma_f32_16x16x32_bf16 v[24:27], v[16:19], v[32:35], v[154:157]
	v_mfma_f32_16x16x32_bf16 v[76:79], v[20:23], v[36:39], v[24:27]
	v_mfma_f32_16x16x32_bf16 v[24:27], v[8:11], v[218:221], v[158:161]
	v_mfma_f32_16x16x32_bf16 v[40:43], v[12:15], v[222:225], v[24:27]
	v_mfma_f32_16x16x32_bf16 v[24:27], v[16:19], v[218:221], v[162:165]
	v_mfma_f32_16x16x32_bf16 v[0:3], v[8:11], v[234:237], v[0:3]
	v_mfma_f32_16x16x32_bf16 v[44:47], v[20:23], v[222:225], v[24:27]
	v_mfma_f32_16x16x32_bf16 v[24:27], v[8:11], v[226:229], v[166:169]
	v_mfma_f32_16x16x32_bf16 v[28:31], v[16:19], v[226:229], v[170:173]
	v_mfma_f32_16x16x32_bf16 v[8:11], v[12:15], v[238:241], v[0:3]
	v_mfma_f32_16x16x32_bf16 v[0:3], v[16:19], v[234:237], v[4:7]
	v_mfma_f32_16x16x32_bf16 v[24:27], v[12:15], v[230:233], v[24:27]
	v_mfma_f32_16x16x32_bf16 v[28:31], v[20:23], v[230:233], v[28:31]
	v_mfma_f32_16x16x32_bf16 v[12:15], v[20:23], v[238:241], v[0:3]
	s_setprio 0
	s_setprio 1
	v_mfma_f32_16x16x32_bf16 v[0:3], v[202:205], v[32:35], v[174:177]
	v_mfma_f32_16x16x32_bf16 v[56:59], v[206:209], v[36:39], v[0:3]
	v_mfma_f32_16x16x32_bf16 v[0:3], v[210:213], v[32:35], v[60:63]
	v_mfma_f32_16x16x32_bf16 v[60:63], v[214:217], v[36:39], v[0:3]
	v_mfma_f32_16x16x32_bf16 v[0:3], v[202:205], v[218:221], v[178:181]
	v_mfma_f32_16x16x32_bf16 v[32:35], v[206:209], v[222:225], v[0:3]
	v_mfma_f32_16x16x32_bf16 v[0:3], v[210:213], v[218:221], v[182:185]
	v_mfma_f32_16x16x32_bf16 v[36:39], v[214:217], v[222:225], v[0:3]
	v_mfma_f32_16x16x32_bf16 v[0:3], v[202:205], v[226:229], v[186:189]
	v_mfma_f32_16x16x32_bf16 v[16:19], v[206:209], v[230:233], v[0:3]
	v_mfma_f32_16x16x32_bf16 v[0:3], v[210:213], v[226:229], v[190:193]
	v_mfma_f32_16x16x32_bf16 v[20:23], v[214:217], v[230:233], v[0:3]
	v_mfma_f32_16x16x32_bf16 v[0:3], v[202:205], v[234:237], v[194:197]
	v_mfma_f32_16x16x32_bf16 v[4:7], v[210:213], v[234:237], v[198:201]
	v_mfma_f32_16x16x32_bf16 v[0:3], v[206:209], v[238:241], v[0:3]
	v_mfma_f32_16x16x32_bf16 v[4:7], v[214:217], v[238:241], v[4:7]
	s_barrier
	s_setprio 0
	s_add_u32 s83, s76, 0x200
	s_addc_u32 s84, s77, 0
	s_add_u32 s76, s78, 0x80180
	s_addc_u32 s77, s79, 0
	s_mov_b32 s85, 0
.LBB0_1155:
	ds_read_b128 v[150:153], v145
	ds_read_b128 v[154:157], v145 offset:1024
	ds_read_b128 v[158:161], v145 offset:2048
	ds_read_b128 v[162:165], v145 offset:3072
	ds_read_b128 v[166:169], v146
	ds_read_b128 v[170:173], v146 offset:1024
	ds_read_b128 v[174:177], v146 offset:2048
	ds_read_b128 v[178:181], v146 offset:3072
	s_add_u32 s78, s76, 0xfff80080
	s_addc_u32 s79, s77, -1
	s_cmp_eq_u32 s85, 28
	s_cselect_b32 s81, s50, s79
	s_cselect_b32 s80, s51, s78
	s_cselect_b32 s79, s52, s84
	s_cselect_b32 s78, s53, s83
	s_mov_b32 m0, s54
	v_lshl_add_u64 v[214:215], s[76:77], 0, v[138:139]
	ds_read_b128 v[182:185], v147
	ds_read_b128 v[186:189], v147 offset:1024
	ds_read_b128 v[190:193], v147 offset:2048
	ds_read_b128 v[194:197], v147 offset:3072
	ds_read_b128 v[198:201], v147 offset:4096
	ds_read_b128 v[202:205], v147 offset:5120
	ds_read_b128 v[206:209], v147 offset:6144
	ds_read_b128 v[210:213], v147 offset:7168
	global_load_lds_dwordx4 v[214:215], off
	v_lshl_add_u64 v[214:215], s[76:77], 0, v[136:137]
	s_mov_b32 m0, s55
	s_nop 0
	global_load_lds_dwordx4 v[214:215], off
	s_waitcnt vmcnt(8) lgkmcnt(0)
	s_setprio 1
	s_barrier
	v_mfma_f32_16x16x32_bf16 v[120:123], v[150:153], v[182:185], v[120:123]
	v_mfma_f32_16x16x32_bf16 v[124:127], v[158:161], v[182:185], v[124:127]
	v_mfma_f32_16x16x32_bf16 v[104:107], v[150:153], v[190:193], v[104:107]
	v_mfma_f32_16x16x32_bf16 v[108:111], v[158:161], v[190:193], v[108:111]
	v_mfma_f32_16x16x32_bf16 v[88:91], v[150:153], v[198:201], v[88:91]
	v_mfma_f32_16x16x32_bf16 v[92:95], v[158:161], v[198:201], v[92:95]
	v_mfma_f32_16x16x32_bf16 v[64:67], v[150:153], v[206:209], v[64:67]
	v_mfma_f32_16x16x32_bf16 v[68:71], v[158:161], v[206:209], v[68:71]
	v_mfma_f32_16x16x32_bf16 v[120:123], v[154:157], v[186:189], v[120:123]
	v_mfma_f32_16x16x32_bf16 v[124:127], v[162:165], v[186:189], v[124:127]
	v_mfma_f32_16x16x32_bf16 v[104:107], v[154:157], v[194:197], v[104:107]
	v_mfma_f32_16x16x32_bf16 v[108:111], v[162:165], v[194:197], v[108:111]
	v_mfma_f32_16x16x32_bf16 v[88:91], v[154:157], v[202:205], v[88:91]
	v_mfma_f32_16x16x32_bf16 v[92:95], v[162:165], v[202:205], v[92:95]
	v_mfma_f32_16x16x32_bf16 v[64:67], v[154:157], v[210:213], v[64:67]
	v_mfma_f32_16x16x32_bf16 v[68:71], v[162:165], v[210:213], v[68:71]
	s_setprio 0
	s_setprio 1
	v_mfma_f32_16x16x32_bf16 v[112:115], v[166:169], v[182:185], v[112:115]
	v_mfma_f32_16x16x32_bf16 v[116:119], v[174:177], v[182:185], v[116:119]
	v_mfma_f32_16x16x32_bf16 v[96:99], v[166:169], v[190:193], v[96:99]
	v_mfma_f32_16x16x32_bf16 v[100:103], v[174:177], v[190:193], v[100:103]
	v_mfma_f32_16x16x32_bf16 v[80:83], v[166:169], v[198:201], v[80:83]
	v_mfma_f32_16x16x32_bf16 v[84:87], v[174:177], v[198:201], v[84:87]
	v_mfma_f32_16x16x32_bf16 v[48:51], v[166:169], v[206:209], v[48:51]
	v_mfma_f32_16x16x32_bf16 v[52:55], v[174:177], v[206:209], v[52:55]
	v_mfma_f32_16x16x32_bf16 v[112:115], v[170:173], v[186:189], v[112:115]
	v_mfma_f32_16x16x32_bf16 v[116:119], v[178:181], v[186:189], v[116:119]
	v_mfma_f32_16x16x32_bf16 v[96:99], v[170:173], v[194:197], v[96:99]
	v_mfma_f32_16x16x32_bf16 v[100:103], v[178:181], v[194:197], v[100:103]
	v_mfma_f32_16x16x32_bf16 v[80:83], v[170:173], v[202:205], v[80:83]
	v_mfma_f32_16x16x32_bf16 v[84:87], v[178:181], v[202:205], v[84:87]
	v_mfma_f32_16x16x32_bf16 v[48:51], v[170:173], v[210:213], v[48:51]
	v_mfma_f32_16x16x32_bf16 v[52:55], v[178:181], v[210:213], v[52:55]
	s_barrier
	s_setprio 0
	s_mov_b32 m0, s56
	v_lshl_add_u64 v[214:215], s[78:79], 0, v[128:129]
	s_add_u32 s88, s78, 0x80000
	ds_read_b128 v[182:185], v147 offset:16384
	ds_read_b128 v[186:189], v147 offset:17408
	ds_read_b128 v[190:193], v147 offset:18432
	ds_read_b128 v[194:197], v147 offset:19456
	ds_read_b128 v[198:201], v147 offset:20480
	ds_read_b128 v[202:205], v147 offset:21504
	ds_read_b128 v[206:209], v147 offset:22528
	ds_read_b128 v[210:213], v147 offset:23552
	global_load_lds_dwordx4 v[214:215], off
	v_lshl_add_u64 v[216:217], s[78:79], 0, v[130:131]
	s_mov_b32 m0, s57
	s_addc_u32 s89, s79, 0
	global_load_lds_dwordx4 v[216:217], off
	v_lshl_add_u64 v[218:219], s[88:89], 0, v[128:129]
	s_mov_b32 m0, s58
	v_lshl_add_u64 v[220:221], s[80:81], 0, v[132:133]
	global_load_lds_dwordx4 v[218:219], off
	v_lshl_add_u64 v[218:219], s[88:89], 0, v[130:131]
	s_mov_b32 m0, s59
	s_nop 0
	global_load_lds_dwordx4 v[218:219], off
	v_lshl_add_u64 v[218:219], s[80:81], 0, v[134:135]
	s_mov_b32 m0, s22
	s_nop 0
	global_load_lds_dwordx4 v[218:219], off
	s_mov_b32 m0, s23
	s_nop 0
	global_load_lds_dwordx4 v[220:221], off
	s_waitcnt vmcnt(8) lgkmcnt(0)
	s_setprio 1
	s_barrier
	v_mfma_f32_16x16x32_bf16 v[72:75], v[150:153], v[182:185], v[72:75]
	v_mfma_f32_16x16x32_bf16 v[76:79], v[158:161], v[182:185], v[76:79]
	v_mfma_f32_16x16x32_bf16 v[40:43], v[150:153], v[190:193], v[40:43]
	v_mfma_f32_16x16x32_bf16 v[44:47], v[158:161], v[190:193], v[44:47]
	v_mfma_f32_16x16x32_bf16 v[24:27], v[150:153], v[198:201], v[24:27]
	v_mfma_f32_16x16x32_bf16 v[28:31], v[158:161], v[198:201], v[28:31]
	v_mfma_f32_16x16x32_bf16 v[8:11], v[150:153], v[206:209], v[8:11]
	v_mfma_f32_16x16x32_bf16 v[12:15], v[158:161], v[206:209], v[12:15]
	v_mfma_f32_16x16x32_bf16 v[72:75], v[154:157], v[186:189], v[72:75]
	v_mfma_f32_16x16x32_bf16 v[76:79], v[162:165], v[186:189], v[76:79]
	v_mfma_f32_16x16x32_bf16 v[40:43], v[154:157], v[194:197], v[40:43]
	v_mfma_f32_16x16x32_bf16 v[44:47], v[162:165], v[194:197], v[44:47]
	v_mfma_f32_16x16x32_bf16 v[24:27], v[154:157], v[202:205], v[24:27]
	v_mfma_f32_16x16x32_bf16 v[28:31], v[162:165], v[202:205], v[28:31]
	v_mfma_f32_16x16x32_bf16 v[8:11], v[154:157], v[210:213], v[8:11]
	v_mfma_f32_16x16x32_bf16 v[12:15], v[162:165], v[210:213], v[12:15]
	s_setprio 0
	s_setprio 1
	v_mfma_f32_16x16x32_bf16 v[56:59], v[166:169], v[182:185], v[56:59]
	v_mfma_f32_16x16x32_bf16 v[60:63], v[174:177], v[182:185], v[60:63]
	v_mfma_f32_16x16x32_bf16 v[32:35], v[166:169], v[190:193], v[32:35]
	v_mfma_f32_16x16x32_bf16 v[36:39], v[174:177], v[190:193], v[36:39]
	v_mfma_f32_16x16x32_bf16 v[16:19], v[166:169], v[198:201], v[16:19]
	v_mfma_f32_16x16x32_bf16 v[20:23], v[174:177], v[198:201], v[20:23]
	v_mfma_f32_16x16x32_bf16 v[0:3], v[166:169], v[206:209], v[0:3]
	v_mfma_f32_16x16x32_bf16 v[4:7], v[174:177], v[206:209], v[4:7]
	v_mfma_f32_16x16x32_bf16 v[56:59], v[170:173], v[186:189], v[56:59]
	v_mfma_f32_16x16x32_bf16 v[60:63], v[178:181], v[186:189], v[60:63]
	v_mfma_f32_16x16x32_bf16 v[32:35], v[170:173], v[194:197], v[32:35]
	v_mfma_f32_16x16x32_bf16 v[36:39], v[178:181], v[194:197], v[36:39]
	v_mfma_f32_16x16x32_bf16 v[16:19], v[170:173], v[202:205], v[16:19]
	v_mfma_f32_16x16x32_bf16 v[20:23], v[178:181], v[202:205], v[20:23]
	v_mfma_f32_16x16x32_bf16 v[0:3], v[170:173], v[210:213], v[0:3]
	v_mfma_f32_16x16x32_bf16 v[4:7], v[178:181], v[210:213], v[4:7]
	s_barrier
; #define PG8_BAR __builtin_amdgcn_s_barrier()
; template <class Epi, class Sched, bool ALIGN_EPI = false, bool SP2 = false, bool A_TILED = false>
; __device__ __forceinline__ void gemm_phase(PG8_LAS unsigned char* lds, const Gemm g, const Sched& S, const Epi& E, const int wave_s) {
;     ...
;         if constexpr (ALIGN_EPI) { if (wr == 0) PG8_BAR; }
	s_setprio 0
	ds_read_b128 v[150:153], v148
	ds_read_b128 v[154:157], v148 offset:1024
	ds_read_b128 v[158:161], v148 offset:2048
	ds_read_b128 v[162:165], v148 offset:3072
	ds_read_b128 v[166:169], v149
	ds_read_b128 v[170:173], v149 offset:1024
	ds_read_b128 v[174:177], v149 offset:2048
	ds_read_b128 v[178:181], v149 offset:3072
	s_add_u32 s80, s80, 0x80000
	s_addc_u32 s81, s81, 0
	s_mov_b32 m0, s36
	v_lshl_add_u64 v[222:223], s[80:81], 0, v[134:135]
	ds_read_b128 v[182:185], v147 offset:32768
	ds_read_b128 v[186:189], v147 offset:33792
	ds_read_b128 v[190:193], v147 offset:34816
	ds_read_b128 v[194:197], v147 offset:35840
	ds_read_b128 v[198:201], v147 offset:36864
	ds_read_b128 v[202:205], v147 offset:37888
	ds_read_b128 v[206:209], v147 offset:38912
	ds_read_b128 v[210:213], v147 offset:39936
	global_load_lds_dwordx4 v[222:223], off
	v_lshl_add_u64 v[222:223], s[80:81], 0, v[132:133]
	s_mov_b32 m0, s37
	s_nop 0
	global_load_lds_dwordx4 v[222:223], off
	s_waitcnt vmcnt(8) lgkmcnt(0)
	s_setprio 1
	s_barrier
	v_mfma_f32_16x16x32_bf16 v[120:123], v[150:153], v[182:185], v[120:123]
	v_mfma_f32_16x16x32_bf16 v[124:127], v[158:161], v[182:185], v[124:127]
	v_mfma_f32_16x16x32_bf16 v[104:107], v[150:153], v[190:193], v[104:107]
	v_mfma_f32_16x16x32_bf16 v[108:111], v[158:161], v[190:193], v[108:111]
	v_mfma_f32_16x16x32_bf16 v[88:91], v[150:153], v[198:201], v[88:91]
	v_mfma_f32_16x16x32_bf16 v[92:95], v[158:161], v[198:201], v[92:95]
	v_mfma_f32_16x16x32_bf16 v[64:67], v[150:153], v[206:209], v[64:67]
	v_mfma_f32_16x16x32_bf16 v[68:71], v[158:161], v[206:209], v[68:71]
	v_mfma_f32_16x16x32_bf16 v[120:123], v[154:157], v[186:189], v[120:123]
	v_mfma_f32_16x16x32_bf16 v[124:127], v[162:165], v[186:189], v[124:127]
	v_mfma_f32_16x16x32_bf16 v[104:107], v[154:157], v[194:197], v[104:107]
	v_mfma_f32_16x16x32_bf16 v[108:111], v[162:165], v[194:197], v[108:111]
	v_mfma_f32_16x16x32_bf16 v[88:91], v[154:157], v[202:205], v[88:91]
	v_mfma_f32_16x16x32_bf16 v[92:95], v[162:165], v[202:205], v[92:95]
	v_mfma_f32_16x16x32_bf16 v[64:67], v[154:157], v[210:213], v[64:67]
	v_mfma_f32_16x16x32_bf16 v[68:71], v[162:165], v[210:213], v[68:71]
	s_setprio 0
	s_setprio 1
	v_mfma_f32_16x16x32_bf16 v[112:115], v[166:169], v[182:185], v[112:115]
	v_mfma_f32_16x16x32_bf16 v[116:119], v[174:177], v[182:185], v[116:119]
	v_mfma_f32_16x16x32_bf16 v[96:99], v[166:169], v[190:193], v[96:99]
	v_mfma_f32_16x16x32_bf16 v[100:103], v[174:177], v[190:193], v[100:103]
	v_mfma_f32_16x16x32_bf16 v[80:83], v[166:169], v[198:201], v[80:83]
	v_mfma_f32_16x16x32_bf16 v[84:87], v[174:177], v[198:201], v[84:87]
	v_mfma_f32_16x16x32_bf16 v[48:51], v[166:169], v[206:209], v[48:51]
	v_mfma_f32_16x16x32_bf16 v[52:55], v[174:177], v[206:209], v[52:55]
	v_mfma_f32_16x16x32_bf16 v[112:115], v[170:173], v[186:189], v[112:115]
	v_mfma_f32_16x16x32_bf16 v[116:119], v[178:181], v[186:189], v[116:119]
	v_mfma_f32_16x16x32_bf16 v[96:99], v[170:173], v[194:197], v[96:99]
	v_mfma_f32_16x16x32_bf16 v[100:103], v[178:181], v[194:197], v[100:103]
	v_mfma_f32_16x16x32_bf16 v[80:83], v[170:173], v[202:205], v[80:83]
	v_mfma_f32_16x16x32_bf16 v[84:87], v[178:181], v[202:205], v[84:87]
	v_mfma_f32_16x16x32_bf16 v[48:51], v[170:173], v[210:213], v[48:51]
	v_mfma_f32_16x16x32_bf16 v[52:55], v[178:181], v[210:213], v[52:55]
	s_barrier
	s_setprio 0
	s_mov_b32 m0, s67
	v_lshl_add_u64 v[214:215], v[214:215], 0, s[12:13]
	s_add_u32 s78, s78, 0x80080
	ds_read_b128 v[182:185], v147 offset:49152
	ds_read_b128 v[186:189], v147 offset:50176
	ds_read_b128 v[190:193], v147 offset:51200
	ds_read_b128 v[194:197], v147 offset:52224
	ds_read_b128 v[198:201], v147 offset:53248
	ds_read_b128 v[202:205], v147 offset:54272
	ds_read_b128 v[206:209], v147 offset:55296
	ds_read_b128 v[210:213], v147 offset:56320
	global_load_lds_dwordx4 v[214:215], off
	v_lshl_add_u64 v[214:215], v[216:217], 0, s[12:13]
	s_mov_b32 m0, s69
	s_addc_u32 s79, s79, 0
	global_load_lds_dwordx4 v[214:215], off
	v_lshl_add_u64 v[214:215], s[78:79], 0, v[128:129]
	s_mov_b32 m0, s75
	s_nop 0
	global_load_lds_dwordx4 v[214:215], off
	v_lshl_add_u64 v[214:215], s[78:79], 0, v[130:131]
	s_mov_b32 m0, s82
	s_nop 0
	global_load_lds_dwordx4 v[214:215], off
	v_lshl_add_u64 v[214:215], v[218:219], 0, s[12:13]
	s_mov_b32 m0, s43
	s_nop 0
	global_load_lds_dwordx4 v[214:215], off
	v_lshl_add_u64 v[214:215], v[220:221], 0, s[12:13]
	s_mov_b32 m0, s44
	s_nop 0
	global_load_lds_dwordx4 v[214:215], off
	s_waitcnt vmcnt(8) lgkmcnt(0)
	s_setprio 1
	s_barrier
	v_mfma_f32_16x16x32_bf16 v[72:75], v[150:153], v[182:185], v[72:75]
	v_mfma_f32_16x16x32_bf16 v[76:79], v[158:161], v[182:185], v[76:79]
	v_mfma_f32_16x16x32_bf16 v[40:43], v[150:153], v[190:193], v[40:43]
	v_mfma_f32_16x16x32_bf16 v[44:47], v[158:161], v[190:193], v[44:47]
	v_mfma_f32_16x16x32_bf16 v[24:27], v[150:153], v[198:201], v[24:27]
	v_mfma_f32_16x16x32_bf16 v[28:31], v[158:161], v[198:201], v[28:31]
	v_mfma_f32_16x16x32_bf16 v[8:11], v[150:153], v[206:209], v[8:11]
	v_mfma_f32_16x16x32_bf16 v[12:15], v[158:161], v[206:209], v[12:15]
	v_mfma_f32_16x16x32_bf16 v[72:75], v[154:157], v[186:189], v[72:75]
	v_mfma_f32_16x16x32_bf16 v[76:79], v[162:165], v[186:189], v[76:79]
	v_mfma_f32_16x16x32_bf16 v[40:43], v[154:157], v[194:197], v[40:43]
	v_mfma_f32_16x16x32_bf16 v[44:47], v[162:165], v[194:197], v[44:47]
	v_mfma_f32_16x16x32_bf16 v[24:27], v[154:157], v[202:205], v[24:27]
	v_mfma_f32_16x16x32_bf16 v[28:31], v[162:165], v[202:205], v[28:31]
	v_mfma_f32_16x16x32_bf16 v[8:11], v[154:157], v[210:213], v[8:11]
	v_mfma_f32_16x16x32_bf16 v[12:15], v[162:165], v[210:213], v[12:15]
	s_setprio 0
	s_setprio 1
	v_mfma_f32_16x16x32_bf16 v[56:59], v[166:169], v[182:185], v[56:59]
	v_mfma_f32_16x16x32_bf16 v[60:63], v[174:177], v[182:185], v[60:63]
	v_mfma_f32_16x16x32_bf16 v[32:35], v[166:169], v[190:193], v[32:35]
	v_mfma_f32_16x16x32_bf16 v[36:39], v[174:177], v[190:193], v[36:39]
	v_mfma_f32_16x16x32_bf16 v[16:19], v[166:169], v[198:201], v[16:19]
	v_mfma_f32_16x16x32_bf16 v[20:23], v[174:177], v[198:201], v[20:23]
	v_mfma_f32_16x16x32_bf16 v[0:3], v[166:169], v[206:209], v[0:3]
	v_mfma_f32_16x16x32_bf16 v[4:7], v[174:177], v[206:209], v[4:7]
	v_mfma_f32_16x16x32_bf16 v[56:59], v[170:173], v[186:189], v[56:59]
	v_mfma_f32_16x16x32_bf16 v[60:63], v[178:181], v[186:189], v[60:63]
	v_mfma_f32_16x16x32_bf16 v[32:35], v[170:173], v[194:197], v[32:35]
	v_mfma_f32_16x16x32_bf16 v[36:39], v[178:181], v[194:197], v[36:39]
	v_mfma_f32_16x16x32_bf16 v[16:19], v[170:173], v[202:205], v[16:19]
	v_mfma_f32_16x16x32_bf16 v[20:23], v[178:181], v[202:205], v[20:23]
	v_mfma_f32_16x16x32_bf16 v[0:3], v[170:173], v[210:213], v[0:3]
	v_mfma_f32_16x16x32_bf16 v[4:7], v[178:181], v[210:213], v[4:7]
	s_barrier
	s_setprio 0
	s_add_i32 s85, s85, 2
	s_add_u32 s83, s83, 0x100
	s_addc_u32 s84, s84, 0
	s_add_u32 s76, s76, 0x100
	s_addc_u32 s77, s77, 0
	s_cmp_gt_u32 s85, 29
	s_cbranch_scc0 .LBB0_1155
	s_and_b64 vcc, exec, s[60:61]
	s_cbranch_vccz .LBB0_1158
	s_barrier

; #define PG8_MMA(ai, bj, At, Bt) do { __builtin_amdgcn_s_setprio(1); _Pragma("unroll") for (int m = 0; m < 4; ++m) _Pragma("unroll") for (int n = 0; n < 2; ++n) _Pragma("unroll") for (int k = 0; k < 2; ++k) \
;         acc[ai][bj][m][n] = __builtin_amdgcn_mfma_f32_16x16x32_bf16(Bt[n][k], At[m][k], acc[ai][bj][m][n], 0, 0, 0); __builtin_amdgcn_s_setprio(0); } while (0)
; template <class Epi, class Sched, bool ALIGN_EPI = false, bool SP2 = false, bool A_TILED = false>
; __device__ __forceinline__ void gemm_phase(PG8_LAS unsigned char* lds, const Gemm g, const Sched& S, const Epi& E, const int wave_s) {
;     ...
;         for (int t = PEEL ? 2 : 0; t < nt; t += 2) {
;             const bool last = (t == nt - 2);
;             const char* a1 = cA + (size_t)(t + 1) * kstepA;
;             const char* a2 = last ? nA : cA + (size_t)(t + 2) * kstepA; const char* b2 = last ? nB : cB + (size_t)(t + 2) * kstep;
;             const char* a3 = a2 + kstepA; const char* b3 = b2 + kstep;
;             if (last && has_next) S.a_ready(nxt);
;             if constexpr (SP2) {
;             PG8_ITER(PG8_MMA)
.LBB0_1228:
	ds_read_b128 v[146:149], v140
	ds_read_b128 v[150:153], v140 offset:1024
	ds_read_b128 v[154:157], v140 offset:2048
	ds_read_b128 v[158:161], v140 offset:3072
	ds_read_b128 v[162:165], v141
	ds_read_b128 v[166:169], v141 offset:1024
	ds_read_b128 v[170:173], v141 offset:2048
	ds_read_b128 v[174:177], v141 offset:3072
	s_add_u32 s52, s12, s39
	s_addc_u32 s53, s13, s40
	s_add_u32 s54, s12, s37
	s_addc_u32 s55, s13, s38
	s_cmpk_eq_i32 s41, 0x7c
	s_cselect_b32 s72, s4, s52
	s_cselect_b32 s73, s5, s53
	s_cselect_b32 s70, s0, s54
	s_cselect_b32 s71, s1, s55
	s_add_u32 s68, s72, 0x8000
	s_addc_u32 s69, s73, 0
	s_mov_b32 m0, s42
	v_lshl_add_u64 v[210:211], s[12:13], 0, v[138:139]
	ds_read_b128 v[178:181], v142
	ds_read_b128 v[182:185], v142 offset:1024
	ds_read_b128 v[186:189], v142 offset:2048
	ds_read_b128 v[190:193], v142 offset:3072
	ds_read_b128 v[194:197], v142 offset:4096
	ds_read_b128 v[198:201], v142 offset:5120
	ds_read_b128 v[202:205], v142 offset:6144
	ds_read_b128 v[206:209], v142 offset:7168
	global_load_lds_dwordx4 v[210:211], off
	v_lshl_add_u64 v[210:211], s[12:13], 0, v[136:137]
	s_mov_b32 m0, s43
	s_nop 0
	global_load_lds_dwordx4 v[210:211], off
	s_waitcnt vmcnt(8) lgkmcnt(0)
	s_setprio 1
	s_barrier
	v_mfma_f32_16x16x32_bf16 v[8:11], v[146:149], v[178:181], v[8:11]
	v_mfma_f32_16x16x32_bf16 v[12:15], v[154:157], v[178:181], v[12:15]
	v_mfma_f32_16x16x32_bf16 v[60:63], v[146:149], v[186:189], v[60:63]
	v_mfma_f32_16x16x32_bf16 v[20:23], v[154:157], v[186:189], v[20:23]
	v_mfma_f32_16x16x32_bf16 v[76:79], v[146:149], v[194:197], v[76:79]
	v_mfma_f32_16x16x32_bf16 v[52:55], v[154:157], v[194:197], v[52:55]
	v_mfma_f32_16x16x32_bf16 v[128:131], v[146:149], v[202:205], v[128:131]
	v_mfma_f32_16x16x32_bf16 v[68:71], v[154:157], v[202:205], v[68:71]
	v_mfma_f32_16x16x32_bf16 v[8:11], v[150:153], v[182:185], v[8:11]
	v_mfma_f32_16x16x32_bf16 v[12:15], v[158:161], v[182:185], v[12:15]
	v_mfma_f32_16x16x32_bf16 v[60:63], v[150:153], v[190:193], v[60:63]
	v_mfma_f32_16x16x32_bf16 v[20:23], v[158:161], v[190:193], v[20:23]
	v_mfma_f32_16x16x32_bf16 v[76:79], v[150:153], v[198:201], v[76:79]
	v_mfma_f32_16x16x32_bf16 v[52:55], v[158:161], v[198:201], v[52:55]
	v_mfma_f32_16x16x32_bf16 v[128:131], v[150:153], v[206:209], v[128:131]
	v_mfma_f32_16x16x32_bf16 v[68:71], v[158:161], v[206:209], v[68:71]
	s_setprio 0
	s_setprio 1
	v_mfma_f32_16x16x32_bf16 v[28:31], v[162:165], v[178:181], v[28:31]
	v_mfma_f32_16x16x32_bf16 v[16:19], v[170:173], v[178:181], v[16:19]
	v_mfma_f32_16x16x32_bf16 v[56:59], v[162:165], v[186:189], v[56:59]
	v_mfma_f32_16x16x32_bf16 v[48:51], v[170:173], v[186:189], v[48:51]
	v_mfma_f32_16x16x32_bf16 v[72:75], v[162:165], v[194:197], v[72:75]
	v_mfma_f32_16x16x32_bf16 v[64:67], v[170:173], v[194:197], v[64:67]
	v_mfma_f32_16x16x32_bf16 v[108:111], v[162:165], v[202:205], v[108:111]
	v_mfma_f32_16x16x32_bf16 v[96:99], v[170:173], v[202:205], v[96:99]
	v_mfma_f32_16x16x32_bf16 v[28:31], v[166:169], v[182:185], v[28:31]
	v_mfma_f32_16x16x32_bf16 v[16:19], v[174:177], v[182:185], v[16:19]
	v_mfma_f32_16x16x32_bf16 v[56:59], v[166:169], v[190:193], v[56:59]
	v_mfma_f32_16x16x32_bf16 v[48:51], v[174:177], v[190:193], v[48:51]
	v_mfma_f32_16x16x32_bf16 v[72:75], v[166:169], v[198:201], v[72:75]
	v_mfma_f32_16x16x32_bf16 v[64:67], v[174:177], v[198:201], v[64:67]
	v_mfma_f32_16x16x32_bf16 v[108:111], v[166:169], v[206:209], v[108:111]
	v_mfma_f32_16x16x32_bf16 v[96:99], v[174:177], v[206:209], v[96:99]
	s_barrier
	s_setprio 0
	s_mov_b32 m0, s44
	v_lshl_add_u64 v[210:211], s[70:71], 0, v[34:35]
	s_add_u32 s52, s70, 0x200000
	ds_read_b128 v[178:181], v142 offset:16384
	ds_read_b128 v[182:185], v142 offset:17408
	ds_read_b128 v[186:189], v142 offset:18432
	ds_read_b128 v[190:193], v142 offset:19456
	ds_read_b128 v[194:197], v142 offset:20480
	ds_read_b128 v[198:201], v142 offset:21504
	ds_read_b128 v[202:205], v142 offset:22528
	ds_read_b128 v[206:209], v142 offset:23552
	global_load_lds_dwordx4 v[210:211], off
	v_lshl_add_u64 v[212:213], s[70:71], 0, v[134:135]
	s_mov_b32 m0, s45
	s_addc_u32 s53, s71, 0
	global_load_lds_dwordx4 v[212:213], off
	v_lshl_add_u64 v[214:215], s[52:53], 0, v[34:35]
	s_mov_b32 m0, s46
	s_nop 0
	global_load_lds_dwordx4 v[214:215], off
	v_lshl_add_u64 v[214:215], s[52:53], 0, v[134:135]
	s_mov_b32 m0, s47
	s_nop 0
	global_load_lds_dwordx4 v[214:215], off
	v_lshl_add_u64 v[214:215], s[72:73], 0, v[32:33]
	s_mov_b32 m0, s14
	s_nop 0
	global_load_lds_dwordx4 v[214:215], off
	v_lshl_add_u64 v[214:215], s[72:73], 0, v[132:133]
	s_mov_b32 m0, s15
	s_nop 0
	global_load_lds_dwordx4 v[214:215], off
	s_waitcnt vmcnt(8) lgkmcnt(0)
	s_setprio 1
	s_barrier
	v_mfma_f32_16x16x32_bf16 v[100:103], v[146:149], v[178:181], v[100:103]
	v_mfma_f32_16x16x32_bf16 v[104:107], v[154:157], v[178:181], v[104:107]
	v_mfma_f32_16x16x32_bf16 v[116:119], v[146:149], v[186:189], v[116:119]
	v_mfma_f32_16x16x32_bf16 v[120:123], v[154:157], v[186:189], v[120:123]
	v_mfma_f32_16x16x32_bf16 v[84:87], v[146:149], v[194:197], v[84:87]
	v_mfma_f32_16x16x32_bf16 v[80:83], v[154:157], v[194:197], v[80:83]
	v_mfma_f32_16x16x32_bf16 v[36:39], v[146:149], v[202:205], v[36:39]
	v_mfma_f32_16x16x32_bf16 v[24:27], v[154:157], v[202:205], v[24:27]
	v_mfma_f32_16x16x32_bf16 v[100:103], v[150:153], v[182:185], v[100:103]
	v_mfma_f32_16x16x32_bf16 v[104:107], v[158:161], v[182:185], v[104:107]
	v_mfma_f32_16x16x32_bf16 v[116:119], v[150:153], v[190:193], v[116:119]
	v_mfma_f32_16x16x32_bf16 v[120:123], v[158:161], v[190:193], v[120:123]
	v_mfma_f32_16x16x32_bf16 v[84:87], v[150:153], v[198:201], v[84:87]
	v_mfma_f32_16x16x32_bf16 v[80:83], v[158:161], v[198:201], v[80:83]
	v_mfma_f32_16x16x32_bf16 v[36:39], v[150:153], v[206:209], v[36:39]
	v_mfma_f32_16x16x32_bf16 v[24:27], v[158:161], v[206:209], v[24:27]
	s_setprio 0
	s_setprio 1
	v_mfma_f32_16x16x32_bf16 v[124:127], v[162:165], v[178:181], v[124:127]
	v_mfma_f32_16x16x32_bf16 v[112:115], v[170:173], v[178:181], v[112:115]
	v_mfma_f32_16x16x32_bf16 v[92:95], v[162:165], v[186:189], v[92:95]
	v_mfma_f32_16x16x32_bf16 v[88:91], v[170:173], v[186:189], v[88:91]
	v_mfma_f32_16x16x32_bf16 v[44:47], v[162:165], v[194:197], v[44:47]
	v_mfma_f32_16x16x32_bf16 v[40:43], v[170:173], v[194:197], v[40:43]
	v_mfma_f32_16x16x32_bf16 v[4:7], v[162:165], v[202:205], v[4:7]
	v_mfma_f32_16x16x32_bf16 v[0:3], v[170:173], v[202:205], v[0:3]
	v_mfma_f32_16x16x32_bf16 v[124:127], v[166:169], v[182:185], v[124:127]
	v_mfma_f32_16x16x32_bf16 v[112:115], v[174:177], v[182:185], v[112:115]
	v_mfma_f32_16x16x32_bf16 v[92:95], v[166:169], v[190:193], v[92:95]
	v_mfma_f32_16x16x32_bf16 v[88:91], v[174:177], v[190:193], v[88:91]
	v_mfma_f32_16x16x32_bf16 v[44:47], v[166:169], v[198:201], v[44:47]
	v_mfma_f32_16x16x32_bf16 v[40:43], v[174:177], v[198:201], v[40:43]
	v_mfma_f32_16x16x32_bf16 v[4:7], v[166:169], v[206:209], v[4:7]
	v_mfma_f32_16x16x32_bf16 v[0:3], v[174:177], v[206:209], v[0:3]
	s_barrier
	s_setprio 0
	ds_read_b128 v[146:149], v143
	ds_read_b128 v[150:153], v143 offset:1024
	ds_read_b128 v[154:157], v143 offset:2048
	ds_read_b128 v[158:161], v143 offset:3072
	ds_read_b128 v[162:165], v144
	ds_read_b128 v[166:169], v144 offset:1024
	ds_read_b128 v[170:173], v144 offset:2048
	ds_read_b128 v[174:177], v144 offset:3072
	s_add_u32 s52, s72, 0x4000
	s_addc_u32 s53, s73, 0
	s_mov_b32 m0, s21
	v_lshl_add_u64 v[214:215], s[52:53], 0, v[32:33]
	ds_read_b128 v[178:181], v142 offset:32768
	ds_read_b128 v[182:185], v142 offset:33792
	ds_read_b128 v[186:189], v142 offset:34816
	ds_read_b128 v[190:193], v142 offset:35840
	ds_read_b128 v[194:197], v142 offset:36864
	ds_read_b128 v[198:201], v142 offset:37888
	ds_read_b128 v[202:205], v142 offset:38912
	ds_read_b128 v[206:209], v142 offset:39936
	global_load_lds_dwordx4 v[214:215], off
	v_lshl_add_u64 v[214:215], s[52:53], 0, v[132:133]
	s_mov_b32 m0, s22
	s_nop 0
	global_load_lds_dwordx4 v[214:215], off
	s_waitcnt vmcnt(8) lgkmcnt(0)
	s_setprio 1
	s_barrier
	v_mfma_f32_16x16x32_bf16 v[8:11], v[146:149], v[178:181], v[8:11]
	v_mfma_f32_16x16x32_bf16 v[12:15], v[154:157], v[178:181], v[12:15]
	v_mfma_f32_16x16x32_bf16 v[60:63], v[146:149], v[186:189], v[60:63]
	v_mfma_f32_16x16x32_bf16 v[20:23], v[154:157], v[186:189], v[20:23]
	v_mfma_f32_16x16x32_bf16 v[76:79], v[146:149], v[194:197], v[76:79]
	v_mfma_f32_16x16x32_bf16 v[52:55], v[154:157], v[194:197], v[52:55]
	v_mfma_f32_16x16x32_bf16 v[128:131], v[146:149], v[202:205], v[128:131]
	v_mfma_f32_16x16x32_bf16 v[68:71], v[154:157], v[202:205], v[68:71]
	v_mfma_f32_16x16x32_bf16 v[8:11], v[150:153], v[182:185], v[8:11]
	v_mfma_f32_16x16x32_bf16 v[12:15], v[158:161], v[182:185], v[12:15]
	v_mfma_f32_16x16x32_bf16 v[60:63], v[150:153], v[190:193], v[60:63]
	v_mfma_f32_16x16x32_bf16 v[20:23], v[158:161], v[190:193], v[20:23]
	v_mfma_f32_16x16x32_bf16 v[76:79], v[150:153], v[198:201], v[76:79]
	v_mfma_f32_16x16x32_bf16 v[52:55], v[158:161], v[198:201], v[52:55]
	v_mfma_f32_16x16x32_bf16 v[128:131], v[150:153], v[206:209], v[128:131]
	v_mfma_f32_16x16x32_bf16 v[68:71], v[158:161], v[206:209], v[68:71]
	s_setprio 0
	s_setprio 1
	v_mfma_f32_16x16x32_bf16 v[28:31], v[162:165], v[178:181], v[28:31]
	v_mfma_f32_16x16x32_bf16 v[16:19], v[170:173], v[178:181], v[16:19]
	v_mfma_f32_16x16x32_bf16 v[56:59], v[162:165], v[186:189], v[56:59]
	v_mfma_f32_16x16x32_bf16 v[48:51], v[170:173], v[186:189], v[48:51]
	v_mfma_f32_16x16x32_bf16 v[72:75], v[162:165], v[194:197], v[72:75]
	v_mfma_f32_16x16x32_bf16 v[64:67], v[170:173], v[194:197], v[64:67]
	v_mfma_f32_16x16x32_bf16 v[108:111], v[162:165], v[202:205], v[108:111]
	v_mfma_f32_16x16x32_bf16 v[96:99], v[170:173], v[202:205], v[96:99]
	v_mfma_f32_16x16x32_bf16 v[28:31], v[166:169], v[182:185], v[28:31]
	v_mfma_f32_16x16x32_bf16 v[16:19], v[174:177], v[182:185], v[16:19]
	v_mfma_f32_16x16x32_bf16 v[56:59], v[166:169], v[190:193], v[56:59]
	v_mfma_f32_16x16x32_bf16 v[48:51], v[174:177], v[190:193], v[48:51]
	v_mfma_f32_16x16x32_bf16 v[72:75], v[166:169], v[198:201], v[72:75]
	v_mfma_f32_16x16x32_bf16 v[64:67], v[174:177], v[198:201], v[64:67]
	v_mfma_f32_16x16x32_bf16 v[108:111], v[166:169], v[206:209], v[108:111]
	v_mfma_f32_16x16x32_bf16 v[96:99], v[174:177], v[206:209], v[96:99]
	s_barrier
; #define PG8_WAIT_V(n) asm volatile("s_waitcnt vmcnt(" #n ")" ::: "memory")
; #define PG8_BAR __builtin_amdgcn_s_barrier()
; template <class Epi, class Sched, bool ALIGN_EPI = false, bool SP2 = false, bool A_TILED = false>
; __device__ __forceinline__ void gemm_phase(PG8_LAS unsigned char* lds, const Gemm g, const Sched& S, const Epi& E, const int wave_s) {
;     ...
;     PG8_WAIT_V(0);
;     if constexpr (!ALIGN_EPI) { if (wr == 0) PG8_BAR; }
	s_setprio 0
	s_mov_b32 m0, s48
	v_lshl_add_u64 v[210:211], v[210:211], 0, s[64:65]
	s_add_u32 s52, s70, 0x200080
	ds_read_b128 v[178:181], v142 offset:49152
	ds_read_b128 v[182:185], v142 offset:50176
	ds_read_b128 v[186:189], v142 offset:51200
	ds_read_b128 v[190:193], v142 offset:52224
	ds_read_b128 v[194:197], v142 offset:53248
	ds_read_b128 v[198:201], v142 offset:54272
	ds_read_b128 v[202:205], v142 offset:55296
	ds_read_b128 v[206:209], v142 offset:56320
	global_load_lds_dwordx4 v[210:211], off
	v_lshl_add_u64 v[210:211], v[212:213], 0, s[64:65]
	s_mov_b32 m0, s49
	s_addc_u32 s53, s71, 0
	global_load_lds_dwordx4 v[210:211], off
	v_lshl_add_u64 v[210:211], s[52:53], 0, v[34:35]
	s_mov_b32 m0, s50
	s_nop 0
	global_load_lds_dwordx4 v[210:211], off
	v_lshl_add_u64 v[210:211], s[52:53], 0, v[134:135]
	s_mov_b32 m0, s51
	s_nop 0
	global_load_lds_dwordx4 v[210:211], off
	v_lshl_add_u64 v[210:211], s[68:69], 0, v[32:33]
	s_mov_b32 m0, s23
	s_nop 0
	global_load_lds_dwordx4 v[210:211], off
	v_lshl_add_u64 v[210:211], s[68:69], 0, v[132:133]
	s_mov_b32 m0, s36
	s_nop 0
	global_load_lds_dwordx4 v[210:211], off
	s_waitcnt vmcnt(8) lgkmcnt(0)
	s_setprio 1
	s_barrier
	v_mfma_f32_16x16x32_bf16 v[100:103], v[146:149], v[178:181], v[100:103]
	v_mfma_f32_16x16x32_bf16 v[104:107], v[154:157], v[178:181], v[104:107]
	v_mfma_f32_16x16x32_bf16 v[116:119], v[146:149], v[186:189], v[116:119]
	v_mfma_f32_16x16x32_bf16 v[120:123], v[154:157], v[186:189], v[120:123]
	v_mfma_f32_16x16x32_bf16 v[84:87], v[146:149], v[194:197], v[84:87]
	v_mfma_f32_16x16x32_bf16 v[80:83], v[154:157], v[194:197], v[80:83]
	v_mfma_f32_16x16x32_bf16 v[36:39], v[146:149], v[202:205], v[36:39]
	v_mfma_f32_16x16x32_bf16 v[24:27], v[154:157], v[202:205], v[24:27]
	v_mfma_f32_16x16x32_bf16 v[100:103], v[150:153], v[182:185], v[100:103]
	v_mfma_f32_16x16x32_bf16 v[104:107], v[158:161], v[182:185], v[104:107]
	v_mfma_f32_16x16x32_bf16 v[116:119], v[150:153], v[190:193], v[116:119]
	v_mfma_f32_16x16x32_bf16 v[120:123], v[158:161], v[190:193], v[120:123]
	v_mfma_f32_16x16x32_bf16 v[84:87], v[150:153], v[198:201], v[84:87]
	v_mfma_f32_16x16x32_bf16 v[80:83], v[158:161], v[198:201], v[80:83]
	v_mfma_f32_16x16x32_bf16 v[36:39], v[150:153], v[206:209], v[36:39]
	v_mfma_f32_16x16x32_bf16 v[24:27], v[158:161], v[206:209], v[24:27]
	s_setprio 0
	s_setprio 1
	v_mfma_f32_16x16x32_bf16 v[124:127], v[162:165], v[178:181], v[124:127]
	v_mfma_f32_16x16x32_bf16 v[112:115], v[170:173], v[178:181], v[112:115]
	v_mfma_f32_16x16x32_bf16 v[92:95], v[162:165], v[186:189], v[92:95]
	v_mfma_f32_16x16x32_bf16 v[88:91], v[170:173], v[186:189], v[88:91]
	v_mfma_f32_16x16x32_bf16 v[44:47], v[162:165], v[194:197], v[44:47]
	v_mfma_f32_16x16x32_bf16 v[40:43], v[170:173], v[194:197], v[40:43]
	v_mfma_f32_16x16x32_bf16 v[4:7], v[162:165], v[202:205], v[4:7]
	v_mfma_f32_16x16x32_bf16 v[0:3], v[170:173], v[202:205], v[0:3]
	v_mfma_f32_16x16x32_bf16 v[124:127], v[166:169], v[182:185], v[124:127]
	v_mfma_f32_16x16x32_bf16 v[112:115], v[174:177], v[182:185], v[112:115]
	v_mfma_f32_16x16x32_bf16 v[92:95], v[166:169], v[190:193], v[92:95]
	v_mfma_f32_16x16x32_bf16 v[88:91], v[174:177], v[190:193], v[88:91]
	v_mfma_f32_16x16x32_bf16 v[44:47], v[166:169], v[198:201], v[44:47]
	v_mfma_f32_16x16x32_bf16 v[40:43], v[174:177], v[198:201], v[40:43]
	v_mfma_f32_16x16x32_bf16 v[4:7], v[166:169], v[206:209], v[4:7]
	v_mfma_f32_16x16x32_bf16 v[0:3], v[174:177], v[206:209], v[0:3]
	s_barrier
	s_setprio 0
	s_add_i32 s41, s41, 2
	s_add_u32 s37, s37, 0x100
	s_addc_u32 s38, s38, 0
	s_add_u32 s39, s39, 0x10000
	s_addc_u32 s40, s40, 0
	v_lshl_add_u64 v[136:137], v[136:137], 0, s[66:67]
	s_cmpk_gt_u32 s41, 0x7d
	v_lshl_add_u64 v[138:139], v[138:139], 0, s[66:67]
	s_cbranch_scc0 .LBB0_1228
	s_waitcnt vmcnt(0)
	s_cmpk_lt_u32 s8, 0x100
	s_cbranch_scc0 .LBB0_1231
	s_barrier

; template <class Epi, class Sched, bool ALIGN_EPI = false, bool SP2 = false, bool A_TILED = false>
; __device__ __forceinline__ void gemm_phase(PG8_LAS unsigned char* lds, const Gemm g, const Sched& S, const Epi& E, const int wave_s) {
;     ...
;         const bool has_next = Epi::AFTER_DRAIN ? false : S.next(ui + 1, nxt);
;         const char* nA = has_next ? (const char*)g.A + (size_t)nxt.pm * tstepA : cA; const char* nB = has_next ? (const char*)g.Bt + (size_t)nxt.pn * tstep : cB;
;         constexpr bool PEEL = SP2 && !Epi::AFTER_DRAIN;
;         if constexpr (PEEL) {
;             const char* a1 = cA + kstepA; const char* a2 = cA + 2 * kstepA; const char* b2 = cB + 2 * kstep; const char* a3 = a2 + kstepA; const char* b3 = b2 + kstep;
;             PG8_ITER(PG8_MMAZ)
.LBB0_1618:
	s_ashr_i32 s71, s70, 31
	s_lshl_b64 s[52:53], s[70:71], 20
	s_add_u32 s72, s1, s52
	ds_read_b128 v[0:3], v149
	ds_read_b128 v[4:7], v149 offset:1024
	ds_read_b128 v[8:11], v149 offset:2048
	ds_read_b128 v[12:15], v149 offset:3072
	ds_read_b128 v[16:19], v150
	ds_read_b128 v[20:23], v150 offset:1024
	ds_read_b128 v[24:27], v150 offset:2048
	ds_read_b128 v[28:31], v150 offset:3072
	s_addc_u32 s73, s8, s53
	s_ashr_i32 s69, s68, 31
	s_lshl_b64 s[52:53], s[68:69], 20
	s_add_u32 s74, s9, s52
	s_addc_u32 s75, s14, s53
	s_and_b64 s[52:53], s[2:3], exec
	s_cselect_b32 s51, s73, s81
	s_cselect_b32 s52, s72, s80
	s_cselect_b32 s53, s75, s79
	s_cselect_b32 s54, s74, s78
	s_add_u32 s56, s80, 0x80080
	s_addc_u32 s57, s81, 0
	s_add_i32 s55, s23, 0xc000
	v_lshl_add_u64 v[64:65], s[56:57], 0, v[134:135]
	s_mov_b32 m0, s55
	ds_read_b128 v[32:35], v151
	ds_read_b128 v[36:39], v151 offset:1024
	ds_read_b128 v[40:43], v151 offset:2048
	ds_read_b128 v[44:47], v151 offset:3072
	ds_read_b128 v[48:51], v151 offset:4096
	ds_read_b128 v[52:55], v151 offset:5120
	ds_read_b128 v[56:59], v151 offset:6144
	ds_read_b128 v[60:63], v151 offset:7168
	global_load_lds_dwordx4 v[64:65], off
	v_lshl_add_u64 v[64:65], s[56:57], 0, v[132:133]
	s_add_i32 s56, s23, 0xe000
	s_mov_b32 m0, s56
	s_nop 0
	global_load_lds_dwordx4 v[64:65], off
	s_waitcnt vmcnt(8) lgkmcnt(0)
	s_setprio 1
	s_barrier
	v_mfma_f32_16x16x32_bf16 v[88:91], v[0:3], v[56:59], 0
	v_mfma_f32_16x16x32_bf16 v[64:67], v[0:3], v[32:35], 0
	v_mfma_f32_16x16x32_bf16 v[68:71], v[8:11], v[32:35], 0
	v_mfma_f32_16x16x32_bf16 v[72:75], v[0:3], v[40:43], 0
	v_mfma_f32_16x16x32_bf16 v[76:79], v[8:11], v[40:43], 0
	v_mfma_f32_16x16x32_bf16 v[80:83], v[0:3], v[48:51], 0
	v_mfma_f32_16x16x32_bf16 v[84:87], v[8:11], v[48:51], 0
	v_mfma_f32_16x16x32_bf16 v[96:99], v[4:7], v[60:63], v[88:91]
	v_mfma_f32_16x16x32_bf16 v[88:91], v[8:11], v[56:59], 0
	v_mfma_f32_16x16x32_bf16 v[64:67], v[4:7], v[36:39], v[64:67]
	v_mfma_f32_16x16x32_bf16 v[68:71], v[12:15], v[36:39], v[68:71]
	v_mfma_f32_16x16x32_bf16 v[72:75], v[4:7], v[44:47], v[72:75]
	v_mfma_f32_16x16x32_bf16 v[76:79], v[12:15], v[44:47], v[76:79]
	v_mfma_f32_16x16x32_bf16 v[80:83], v[4:7], v[52:55], v[80:83]
	v_mfma_f32_16x16x32_bf16 v[84:87], v[12:15], v[52:55], v[84:87]
	v_mfma_f32_16x16x32_bf16 v[100:103], v[12:15], v[60:63], v[88:91]
	s_setprio 0
	s_setprio 1
	v_mfma_f32_16x16x32_bf16 v[88:91], v[16:19], v[32:35], 0
	v_mfma_f32_16x16x32_bf16 v[32:35], v[24:27], v[32:35], 0
	v_mfma_f32_16x16x32_bf16 v[112:115], v[20:23], v[36:39], v[88:91]
	v_mfma_f32_16x16x32_bf16 v[32:35], v[28:31], v[36:39], v[32:35]
	v_mfma_f32_16x16x32_bf16 v[36:39], v[16:19], v[40:43], 0
	v_mfma_f32_16x16x32_bf16 v[40:43], v[24:27], v[40:43], 0
	v_mfma_f32_16x16x32_bf16 v[36:39], v[20:23], v[44:47], v[36:39]
	v_mfma_f32_16x16x32_bf16 v[40:43], v[28:31], v[44:47], v[40:43]
	v_mfma_f32_16x16x32_bf16 v[44:47], v[16:19], v[48:51], 0
	v_mfma_f32_16x16x32_bf16 v[48:51], v[24:27], v[48:51], 0
	v_mfma_f32_16x16x32_bf16 v[44:47], v[20:23], v[52:55], v[44:47]
	v_mfma_f32_16x16x32_bf16 v[48:51], v[28:31], v[52:55], v[48:51]
	v_mfma_f32_16x16x32_bf16 v[52:55], v[16:19], v[56:59], 0
	v_mfma_f32_16x16x32_bf16 v[56:59], v[24:27], v[56:59], 0
	v_mfma_f32_16x16x32_bf16 v[52:55], v[20:23], v[60:63], v[52:55]
	v_mfma_f32_16x16x32_bf16 v[56:59], v[28:31], v[60:63], v[56:59]
	s_barrier
	s_setprio 0
	s_add_i32 s57, s46, s15
	v_lshl_add_u64 v[250:251], s[78:79], 0, v[128:129]
	s_add_i32 s58, s57, 0x2000
	v_lshl_add_u64 v[144:145], v[250:251], 0, s[64:65]
	s_mov_b32 m0, s57
	v_lshl_add_u64 v[252:253], s[78:79], 0, v[130:131]
	s_add_u32 s82, s78, 0x80100
	ds_read_b128 v[60:63], v151 offset:16384
	ds_read_b128 v[88:91], v151 offset:17408
	ds_read_b128 v[92:95], v151 offset:18432
	ds_read_b128 v[104:107], v151 offset:19456
	ds_read_b128 v[108:111], v151 offset:20480
	ds_read_b128 v[116:119], v151 offset:21504
	ds_read_b128 v[120:123], v151 offset:22528
	ds_read_b128 v[124:127], v151 offset:23552
	global_load_lds_dwordx4 v[144:145], off
	v_lshl_add_u64 v[144:145], v[252:253], 0, s[64:65]
	s_mov_b32 m0, s58
	s_addc_u32 s83, s79, 0
	s_add_i32 s59, s47, s15
	global_load_lds_dwordx4 v[144:145], off
	v_lshl_add_u64 v[144:145], s[82:83], 0, v[128:129]
	s_mov_b32 m0, s59
	s_add_i32 s69, s59, 0x2000
	global_load_lds_dwordx4 v[144:145], off
	v_lshl_add_u64 v[144:145], s[82:83], 0, v[130:131]
	s_mov_b32 m0, s69
	v_lshl_add_u64 v[140:141], s[80:81], 0, v[134:135]
	global_load_lds_dwordx4 v[144:145], off
	v_lshl_add_u64 v[144:145], v[140:141], 0, s[64:65]
	s_mov_b32 m0, s23
	v_lshl_add_u64 v[142:143], s[80:81], 0, v[132:133]
	global_load_lds_dwordx4 v[144:145], off
	v_lshl_add_u64 v[144:145], v[142:143], 0, s[64:65]
	s_mov_b32 m0, s36
	s_nop 0
	global_load_lds_dwordx4 v[144:145], off
	s_waitcnt vmcnt(8) lgkmcnt(0)
	s_setprio 1
	s_barrier
	v_mfma_f32_16x16x32_bf16 v[144:147], v[0:3], v[60:63], 0
	v_mfma_f32_16x16x32_bf16 v[154:157], v[4:7], v[88:91], v[144:147]
	v_mfma_f32_16x16x32_bf16 v[144:147], v[8:11], v[60:63], 0
	v_mfma_f32_16x16x32_bf16 v[158:161], v[12:15], v[88:91], v[144:147]
	v_mfma_f32_16x16x32_bf16 v[144:147], v[0:3], v[92:95], 0
	v_mfma_f32_16x16x32_bf16 v[162:165], v[4:7], v[104:107], v[144:147]
	v_mfma_f32_16x16x32_bf16 v[144:147], v[8:11], v[92:95], 0
	v_mfma_f32_16x16x32_bf16 v[166:169], v[12:15], v[104:107], v[144:147]
	v_mfma_f32_16x16x32_bf16 v[144:147], v[0:3], v[108:111], 0
	v_mfma_f32_16x16x32_bf16 v[0:3], v[0:3], v[120:123], 0
	v_mfma_f32_16x16x32_bf16 v[170:173], v[4:7], v[116:119], v[144:147]
	v_mfma_f32_16x16x32_bf16 v[0:3], v[4:7], v[124:127], v[0:3]
	v_mfma_f32_16x16x32_bf16 v[4:7], v[8:11], v[120:123], 0
	v_mfma_f32_16x16x32_bf16 v[144:147], v[8:11], v[108:111], 0
	v_mfma_f32_16x16x32_bf16 v[4:7], v[12:15], v[124:127], v[4:7]
	v_mfma_f32_16x16x32_bf16 v[174:177], v[12:15], v[116:119], v[144:147]
	s_setprio 0
	s_setprio 1
	v_mfma_f32_16x16x32_bf16 v[8:11], v[16:19], v[60:63], 0
	v_mfma_f32_16x16x32_bf16 v[178:181], v[20:23], v[88:91], v[8:11]
	v_mfma_f32_16x16x32_bf16 v[8:11], v[24:27], v[60:63], 0
	v_mfma_f32_16x16x32_bf16 v[182:185], v[28:31], v[88:91], v[8:11]
	v_mfma_f32_16x16x32_bf16 v[8:11], v[16:19], v[92:95], 0
	v_mfma_f32_16x16x32_bf16 v[186:189], v[20:23], v[104:107], v[8:11]
	v_mfma_f32_16x16x32_bf16 v[8:11], v[24:27], v[92:95], 0
	v_mfma_f32_16x16x32_bf16 v[190:193], v[28:31], v[104:107], v[8:11]
	v_mfma_f32_16x16x32_bf16 v[8:11], v[16:19], v[108:111], 0
	v_mfma_f32_16x16x32_bf16 v[194:197], v[20:23], v[116:119], v[8:11]
	v_mfma_f32_16x16x32_bf16 v[8:11], v[24:27], v[108:111], 0
	v_mfma_f32_16x16x32_bf16 v[198:201], v[28:31], v[116:119], v[8:11]
	v_mfma_f32_16x16x32_bf16 v[8:11], v[16:19], v[120:123], 0
	v_mfma_f32_16x16x32_bf16 v[202:205], v[20:23], v[124:127], v[8:11]
	v_mfma_f32_16x16x32_bf16 v[8:11], v[24:27], v[120:123], 0
	v_mfma_f32_16x16x32_bf16 v[206:209], v[28:31], v[124:127], v[8:11]
	s_barrier
	s_setprio 0
	s_add_i32 s71, 0, 0x18000
	s_add_i32 s88, 0, 0x1c000
	v_add_u32_e32 v144, s71, v148
	v_add_u32_e32 v145, s88, v148
	s_nop 0
	ds_read_b128 v[8:11], v144
	ds_read_b128 v[12:15], v144 offset:1024
	ds_read_b128 v[16:19], v144 offset:2048
	ds_read_b128 v[20:23], v144 offset:3072
	ds_read_b128 v[210:213], v145
	ds_read_b128 v[214:217], v145 offset:1024
	ds_read_b128 v[218:221], v145 offset:2048
	ds_read_b128 v[222:225], v145 offset:3072
	s_add_u32 s82, s80, 0x80100
	s_addc_u32 s83, s81, 0
	s_mov_b32 m0, s37
	v_lshl_add_u64 v[88:89], s[82:83], 0, v[134:135]
	ds_read_b128 v[24:27], v151 offset:32768
	ds_read_b128 v[28:31], v151 offset:33792
	ds_read_b128 v[60:63], v151 offset:34816
	ds_read_b128 v[226:229], v151 offset:35840
	ds_read_b128 v[230:233], v151 offset:36864
	ds_read_b128 v[234:237], v151 offset:37888
	ds_read_b128 v[238:241], v151 offset:38912
	ds_read_b128 v[242:245], v151 offset:39936
	global_load_lds_dwordx4 v[88:89], off
	v_lshl_add_u64 v[88:89], s[82:83], 0, v[132:133]
	s_mov_b32 m0, s38
	s_nop 0
	global_load_lds_dwordx4 v[88:89], off
	s_waitcnt vmcnt(8) lgkmcnt(0)
	s_setprio 1
	s_barrier
	v_mfma_f32_16x16x32_bf16 v[64:67], v[8:11], v[24:27], v[64:67]
	v_mfma_f32_16x16x32_bf16 v[124:127], v[12:15], v[28:31], v[64:67]
	v_mfma_f32_16x16x32_bf16 v[64:67], v[16:19], v[24:27], v[68:71]
	v_mfma_f32_16x16x32_bf16 v[120:123], v[20:23], v[28:31], v[64:67]
	v_mfma_f32_16x16x32_bf16 v[64:67], v[8:11], v[60:63], v[72:75]
	v_mfma_f32_16x16x32_bf16 v[108:111], v[12:15], v[226:229], v[64:67]
	v_mfma_f32_16x16x32_bf16 v[64:67], v[16:19], v[60:63], v[76:79]
	v_mfma_f32_16x16x32_bf16 v[104:107], v[20:23], v[226:229], v[64:67]
	v_mfma_f32_16x16x32_bf16 v[64:67], v[8:11], v[230:233], v[80:83]
	v_mfma_f32_16x16x32_bf16 v[92:95], v[12:15], v[234:237], v[64:67]
	v_mfma_f32_16x16x32_bf16 v[64:67], v[16:19], v[230:233], v[84:87]
	v_mfma_f32_16x16x32_bf16 v[88:91], v[20:23], v[234:237], v[64:67]
	v_mfma_f32_16x16x32_bf16 v[64:67], v[8:11], v[238:241], v[96:99]
	v_mfma_f32_16x16x32_bf16 v[76:79], v[12:15], v[242:245], v[64:67]
	v_mfma_f32_16x16x32_bf16 v[64:67], v[16:19], v[238:241], v[100:103]
	v_mfma_f32_16x16x32_bf16 v[72:75], v[20:23], v[242:245], v[64:67]
	s_setprio 0
	s_setprio 1
	v_mfma_f32_16x16x32_bf16 v[64:67], v[210:213], v[24:27], v[112:115]
	v_mfma_f32_16x16x32_bf16 v[24:27], v[218:221], v[24:27], v[32:35]
	v_mfma_f32_16x16x32_bf16 v[112:115], v[222:225], v[28:31], v[24:27]
	v_mfma_f32_16x16x32_bf16 v[24:27], v[210:213], v[60:63], v[36:39]
	v_mfma_f32_16x16x32_bf16 v[100:103], v[214:217], v[226:229], v[24:27]
	v_mfma_f32_16x16x32_bf16 v[24:27], v[218:221], v[60:63], v[40:43]
	v_mfma_f32_16x16x32_bf16 v[96:99], v[222:225], v[226:229], v[24:27]
	v_mfma_f32_16x16x32_bf16 v[24:27], v[210:213], v[230:233], v[44:47]
	v_mfma_f32_16x16x32_bf16 v[84:87], v[214:217], v[234:237], v[24:27]
	v_mfma_f32_16x16x32_bf16 v[24:27], v[218:221], v[230:233], v[48:51]
	v_mfma_f32_16x16x32_bf16 v[80:83], v[222:225], v[234:237], v[24:27]
	v_mfma_f32_16x16x32_bf16 v[24:27], v[210:213], v[238:241], v[52:55]
	v_mfma_f32_16x16x32_bf16 v[68:71], v[214:217], v[242:245], v[24:27]
	v_mfma_f32_16x16x32_bf16 v[24:27], v[218:221], v[238:241], v[56:59]
	v_mfma_f32_16x16x32_bf16 v[116:119], v[214:217], v[28:31], v[64:67]
	v_mfma_f32_16x16x32_bf16 v[64:67], v[222:225], v[242:245], v[24:27]
	s_barrier
; #define PG8_MMA(ai, bj, At, Bt) do { __builtin_amdgcn_s_setprio(1); _Pragma("unroll") for (int m = 0; m < 4; ++m) _Pragma("unroll") for (int n = 0; n < 2; ++n) _Pragma("unroll") for (int k = 0; k < 2; ++k) \
;         acc[ai][bj][m][n] = __builtin_amdgcn_mfma_f32_16x16x32_bf16(Bt[n][k], At[m][k], acc[ai][bj][m][n], 0, 0, 0); __builtin_amdgcn_s_setprio(0); } while (0)
; template <class Epi, class Sched, bool ALIGN_EPI = false, bool SP2 = false, bool A_TILED = false>
; __device__ __forceinline__ void gemm_phase(PG8_LAS unsigned char* lds, const Gemm g, const Sched& S, const Epi& E, const int wave_s) {
;     ...
;         for (int t = PEEL ? 2 : 0; t < nt; t += 2) {
;             const bool last = (t == nt - 2);
;             const char* a1 = cA + (size_t)(t + 1) * kstepA;
;             const char* a2 = last ? nA : cA + (size_t)(t + 2) * kstepA; const char* b2 = last ? nB : cB + (size_t)(t + 2) * kstep;
;             const char* a3 = a2 + kstepA; const char* b3 = b2 + kstep;
;             if (last && has_next) S.a_ready(nxt);
;             if constexpr (SP2) {
;             PG8_ITER(PG8_MMA)
	s_setprio 0
	s_add_i32 s71, s71, s15
	s_add_i32 s77, s71, 0x2000
	s_nop 1
	v_lshl_add_u64 v[24:25], v[250:251], 0, s[66:67]
	s_mov_b32 m0, s71
	s_add_u32 s82, s78, 0x80180
	ds_read_b128 v[32:35], v151 offset:49152
	ds_read_b128 v[36:39], v151 offset:50176
	ds_read_b128 v[226:229], v151 offset:51200
	ds_read_b128 v[230:233], v151 offset:52224
	ds_read_b128 v[234:237], v151 offset:53248
	ds_read_b128 v[238:241], v151 offset:54272
	ds_read_b128 v[242:245], v151 offset:55296
	ds_read_b128 v[246:249], v151 offset:56320
	global_load_lds_dwordx4 v[24:25], off
	v_lshl_add_u64 v[24:25], v[252:253], 0, s[66:67]
	s_mov_b32 m0, s77
	s_addc_u32 s83, s79, 0
	s_add_i32 s88, s88, s15
	global_load_lds_dwordx4 v[24:25], off
	v_lshl_add_u64 v[24:25], s[82:83], 0, v[128:129]
	s_mov_b32 m0, s88
	s_add_i32 s89, s88, 0x2000
	global_load_lds_dwordx4 v[24:25], off
	v_lshl_add_u64 v[24:25], s[82:83], 0, v[130:131]
	s_mov_b32 m0, s89
	s_nop 0
	global_load_lds_dwordx4 v[24:25], off
	v_lshl_add_u64 v[24:25], v[140:141], 0, s[66:67]
	s_mov_b32 m0, s43
	s_nop 0
	global_load_lds_dwordx4 v[24:25], off
	v_lshl_add_u64 v[24:25], v[142:143], 0, s[66:67]
	s_mov_b32 m0, s44
	s_nop 0
	global_load_lds_dwordx4 v[24:25], off
	s_waitcnt vmcnt(8) lgkmcnt(0)
	s_setprio 1
	s_barrier
	v_mfma_f32_16x16x32_bf16 v[24:27], v[8:11], v[32:35], v[154:157]
	v_mfma_f32_16x16x32_bf16 v[60:63], v[12:15], v[36:39], v[24:27]
	v_mfma_f32_16x16x32_bf16 v[24:27], v[16:19], v[32:35], v[158:161]
	v_mfma_f32_16x16x32_bf16 v[56:59], v[20:23], v[36:39], v[24:27]
	v_mfma_f32_16x16x32_bf16 v[24:27], v[8:11], v[226:229], v[162:165]
	v_mfma_f32_16x16x32_bf16 v[44:47], v[12:15], v[230:233], v[24:27]
	v_mfma_f32_16x16x32_bf16 v[24:27], v[16:19], v[226:229], v[166:169]
	v_mfma_f32_16x16x32_bf16 v[40:43], v[20:23], v[230:233], v[24:27]
	v_mfma_f32_16x16x32_bf16 v[24:27], v[8:11], v[234:237], v[170:173]
	v_mfma_f32_16x16x32_bf16 v[0:3], v[8:11], v[242:245], v[0:3]
	v_mfma_f32_16x16x32_bf16 v[28:31], v[12:15], v[238:241], v[24:27]
	v_mfma_f32_16x16x32_bf16 v[24:27], v[16:19], v[234:237], v[174:177]
	v_mfma_f32_16x16x32_bf16 v[12:15], v[12:15], v[246:249], v[0:3]
	v_mfma_f32_16x16x32_bf16 v[0:3], v[16:19], v[242:245], v[4:7]
	v_mfma_f32_16x16x32_bf16 v[24:27], v[20:23], v[238:241], v[24:27]
	v_mfma_f32_16x16x32_bf16 v[8:11], v[20:23], v[246:249], v[0:3]
	s_setprio 0
	s_setprio 1
	v_mfma_f32_16x16x32_bf16 v[0:3], v[210:213], v[32:35], v[178:181]
	v_mfma_f32_16x16x32_bf16 v[52:55], v[214:217], v[36:39], v[0:3]
	v_mfma_f32_16x16x32_bf16 v[0:3], v[218:221], v[32:35], v[182:185]
	v_mfma_f32_16x16x32_bf16 v[48:51], v[222:225], v[36:39], v[0:3]
	v_mfma_f32_16x16x32_bf16 v[0:3], v[210:213], v[226:229], v[186:189]
	v_mfma_f32_16x16x32_bf16 v[36:39], v[214:217], v[230:233], v[0:3]
	v_mfma_f32_16x16x32_bf16 v[0:3], v[218:221], v[226:229], v[190:193]
	v_mfma_f32_16x16x32_bf16 v[32:35], v[222:225], v[230:233], v[0:3]
	v_mfma_f32_16x16x32_bf16 v[0:3], v[210:213], v[234:237], v[194:197]
	v_mfma_f32_16x16x32_bf16 v[20:23], v[214:217], v[238:241], v[0:3]
	v_mfma_f32_16x16x32_bf16 v[0:3], v[218:221], v[234:237], v[198:201]
	v_mfma_f32_16x16x32_bf16 v[16:19], v[222:225], v[238:241], v[0:3]
	v_mfma_f32_16x16x32_bf16 v[0:3], v[210:213], v[242:245], v[202:205]
	v_mfma_f32_16x16x32_bf16 v[4:7], v[214:217], v[246:249], v[0:3]
	v_mfma_f32_16x16x32_bf16 v[0:3], v[218:221], v[242:245], v[206:209]
	v_mfma_f32_16x16x32_bf16 v[0:3], v[222:225], v[246:249], v[0:3]
	s_barrier
	s_setprio 0
	s_add_u32 s90, s78, 0x200
	s_addc_u32 s85, s79, 0
	s_add_u32 s78, s80, 0x80180
	s_addc_u32 s79, s81, 0
	s_mov_b32 s91, 0
.LBB0_1619:
	ds_read_b128 v[154:157], v149
	ds_read_b128 v[158:161], v149 offset:1024
	ds_read_b128 v[162:165], v149 offset:2048
	ds_read_b128 v[166:169], v149 offset:3072
	ds_read_b128 v[170:173], v150
	ds_read_b128 v[174:177], v150 offset:1024
	ds_read_b128 v[178:181], v150 offset:2048
	ds_read_b128 v[182:185], v150 offset:3072
	s_add_u32 s80, s78, 0xfff80080
	s_addc_u32 s81, s79, -1
	s_cmp_eq_u32 s91, 28
	s_cselect_b32 s83, s51, s81
	s_cselect_b32 s82, s52, s80
	s_cselect_b32 s81, s53, s85
	s_cselect_b32 s80, s54, s90
	s_mov_b32 m0, s55
	v_lshl_add_u64 v[140:141], s[78:79], 0, v[138:139]
	ds_read_b128 v[186:189], v151
	ds_read_b128 v[190:193], v151 offset:1024
	ds_read_b128 v[194:197], v151 offset:2048
	ds_read_b128 v[198:201], v151 offset:3072
	ds_read_b128 v[202:205], v151 offset:4096
	ds_read_b128 v[206:209], v151 offset:5120
	ds_read_b128 v[210:213], v151 offset:6144
	ds_read_b128 v[214:217], v151 offset:7168
	global_load_lds_dwordx4 v[140:141], off
	v_lshl_add_u64 v[140:141], s[78:79], 0, v[136:137]
	s_mov_b32 m0, s56
	s_nop 0
	global_load_lds_dwordx4 v[140:141], off
	s_waitcnt vmcnt(8) lgkmcnt(0)
	s_setprio 1
	s_barrier
	v_mfma_f32_16x16x32_bf16 v[124:127], v[154:157], v[186:189], v[124:127]
	v_mfma_f32_16x16x32_bf16 v[120:123], v[162:165], v[186:189], v[120:123]
	v_mfma_f32_16x16x32_bf16 v[108:111], v[154:157], v[194:197], v[108:111]
	v_mfma_f32_16x16x32_bf16 v[104:107], v[162:165], v[194:197], v[104:107]
	v_mfma_f32_16x16x32_bf16 v[92:95], v[154:157], v[202:205], v[92:95]
	v_mfma_f32_16x16x32_bf16 v[88:91], v[162:165], v[202:205], v[88:91]
	v_mfma_f32_16x16x32_bf16 v[76:79], v[154:157], v[210:213], v[76:79]
	v_mfma_f32_16x16x32_bf16 v[72:75], v[162:165], v[210:213], v[72:75]
	v_mfma_f32_16x16x32_bf16 v[124:127], v[158:161], v[190:193], v[124:127]
	v_mfma_f32_16x16x32_bf16 v[120:123], v[166:169], v[190:193], v[120:123]
	v_mfma_f32_16x16x32_bf16 v[108:111], v[158:161], v[198:201], v[108:111]
	v_mfma_f32_16x16x32_bf16 v[104:107], v[166:169], v[198:201], v[104:107]
	v_mfma_f32_16x16x32_bf16 v[92:95], v[158:161], v[206:209], v[92:95]
	v_mfma_f32_16x16x32_bf16 v[88:91], v[166:169], v[206:209], v[88:91]
	v_mfma_f32_16x16x32_bf16 v[76:79], v[158:161], v[214:217], v[76:79]
	v_mfma_f32_16x16x32_bf16 v[72:75], v[166:169], v[214:217], v[72:75]
	s_setprio 0
	s_setprio 1
	v_mfma_f32_16x16x32_bf16 v[116:119], v[170:173], v[186:189], v[116:119]
	v_mfma_f32_16x16x32_bf16 v[112:115], v[178:181], v[186:189], v[112:115]
	v_mfma_f32_16x16x32_bf16 v[100:103], v[170:173], v[194:197], v[100:103]
	v_mfma_f32_16x16x32_bf16 v[96:99], v[178:181], v[194:197], v[96:99]
	v_mfma_f32_16x16x32_bf16 v[84:87], v[170:173], v[202:205], v[84:87]
	v_mfma_f32_16x16x32_bf16 v[80:83], v[178:181], v[202:205], v[80:83]
	v_mfma_f32_16x16x32_bf16 v[68:71], v[170:173], v[210:213], v[68:71]
	v_mfma_f32_16x16x32_bf16 v[64:67], v[178:181], v[210:213], v[64:67]
	v_mfma_f32_16x16x32_bf16 v[116:119], v[174:177], v[190:193], v[116:119]
	v_mfma_f32_16x16x32_bf16 v[112:115], v[182:185], v[190:193], v[112:115]
	v_mfma_f32_16x16x32_bf16 v[100:103], v[174:177], v[198:201], v[100:103]
	v_mfma_f32_16x16x32_bf16 v[96:99], v[182:185], v[198:201], v[96:99]
	v_mfma_f32_16x16x32_bf16 v[84:87], v[174:177], v[206:209], v[84:87]
	v_mfma_f32_16x16x32_bf16 v[80:83], v[182:185], v[206:209], v[80:83]
	v_mfma_f32_16x16x32_bf16 v[68:71], v[174:177], v[214:217], v[68:71]
	v_mfma_f32_16x16x32_bf16 v[64:67], v[182:185], v[214:217], v[64:67]
	s_barrier
	s_setprio 0
	s_mov_b32 m0, s57
	v_lshl_add_u64 v[140:141], s[80:81], 0, v[128:129]
	s_add_u32 s94, s80, 0x80000
	ds_read_b128 v[186:189], v151 offset:16384
	ds_read_b128 v[190:193], v151 offset:17408
	ds_read_b128 v[194:197], v151 offset:18432
	ds_read_b128 v[198:201], v151 offset:19456
	ds_read_b128 v[202:205], v151 offset:20480
	ds_read_b128 v[206:209], v151 offset:21504
	ds_read_b128 v[210:213], v151 offset:22528
	ds_read_b128 v[214:217], v151 offset:23552
	global_load_lds_dwordx4 v[140:141], off
	v_lshl_add_u64 v[142:143], s[80:81], 0, v[130:131]
	s_mov_b32 m0, s58
	s_addc_u32 s95, s81, 0
	global_load_lds_dwordx4 v[142:143], off
	v_lshl_add_u64 v[146:147], s[94:95], 0, v[128:129]
	s_mov_b32 m0, s59
	v_lshl_add_u64 v[218:219], s[82:83], 0, v[132:133]
	global_load_lds_dwordx4 v[146:147], off
	v_lshl_add_u64 v[146:147], s[94:95], 0, v[130:131]
	s_mov_b32 m0, s69
	s_nop 0
	global_load_lds_dwordx4 v[146:147], off
	v_lshl_add_u64 v[146:147], s[82:83], 0, v[134:135]
	s_mov_b32 m0, s23
	s_nop 0
	global_load_lds_dwordx4 v[146:147], off
	s_mov_b32 m0, s36
	s_nop 0
	global_load_lds_dwordx4 v[218:219], off
	s_waitcnt vmcnt(8) lgkmcnt(0)
	s_setprio 1
	s_barrier
	v_mfma_f32_16x16x32_bf16 v[60:63], v[154:157], v[186:189], v[60:63]
	v_mfma_f32_16x16x32_bf16 v[56:59], v[162:165], v[186:189], v[56:59]
	v_mfma_f32_16x16x32_bf16 v[44:47], v[154:157], v[194:197], v[44:47]
	v_mfma_f32_16x16x32_bf16 v[40:43], v[162:165], v[194:197], v[40:43]
	v_mfma_f32_16x16x32_bf16 v[28:31], v[154:157], v[202:205], v[28:31]
	v_mfma_f32_16x16x32_bf16 v[24:27], v[162:165], v[202:205], v[24:27]
	v_mfma_f32_16x16x32_bf16 v[12:15], v[154:157], v[210:213], v[12:15]
	v_mfma_f32_16x16x32_bf16 v[8:11], v[162:165], v[210:213], v[8:11]
	v_mfma_f32_16x16x32_bf16 v[60:63], v[158:161], v[190:193], v[60:63]
	v_mfma_f32_16x16x32_bf16 v[56:59], v[166:169], v[190:193], v[56:59]
	v_mfma_f32_16x16x32_bf16 v[44:47], v[158:161], v[198:201], v[44:47]
	v_mfma_f32_16x16x32_bf16 v[40:43], v[166:169], v[198:201], v[40:43]
	v_mfma_f32_16x16x32_bf16 v[28:31], v[158:161], v[206:209], v[28:31]
	v_mfma_f32_16x16x32_bf16 v[24:27], v[166:169], v[206:209], v[24:27]
	v_mfma_f32_16x16x32_bf16 v[12:15], v[158:161], v[214:217], v[12:15]
	v_mfma_f32_16x16x32_bf16 v[8:11], v[166:169], v[214:217], v[8:11]
	s_setprio 0
	s_setprio 1
	v_mfma_f32_16x16x32_bf16 v[52:55], v[170:173], v[186:189], v[52:55]
	v_mfma_f32_16x16x32_bf16 v[48:51], v[178:181], v[186:189], v[48:51]
	v_mfma_f32_16x16x32_bf16 v[36:39], v[170:173], v[194:197], v[36:39]
	v_mfma_f32_16x16x32_bf16 v[32:35], v[178:181], v[194:197], v[32:35]
	v_mfma_f32_16x16x32_bf16 v[20:23], v[170:173], v[202:205], v[20:23]
	v_mfma_f32_16x16x32_bf16 v[16:19], v[178:181], v[202:205], v[16:19]
	v_mfma_f32_16x16x32_bf16 v[4:7], v[170:173], v[210:213], v[4:7]
	v_mfma_f32_16x16x32_bf16 v[0:3], v[178:181], v[210:213], v[0:3]
	v_mfma_f32_16x16x32_bf16 v[52:55], v[174:177], v[190:193], v[52:55]
	v_mfma_f32_16x16x32_bf16 v[48:51], v[182:185], v[190:193], v[48:51]
	v_mfma_f32_16x16x32_bf16 v[36:39], v[174:177], v[198:201], v[36:39]
	v_mfma_f32_16x16x32_bf16 v[32:35], v[182:185], v[198:201], v[32:35]
	v_mfma_f32_16x16x32_bf16 v[20:23], v[174:177], v[206:209], v[20:23]
	v_mfma_f32_16x16x32_bf16 v[16:19], v[182:185], v[206:209], v[16:19]
	v_mfma_f32_16x16x32_bf16 v[4:7], v[174:177], v[214:217], v[4:7]
	v_mfma_f32_16x16x32_bf16 v[0:3], v[182:185], v[214:217], v[0:3]
	s_barrier
; #define PG8_BAR __builtin_amdgcn_s_barrier()
; template <class Epi, class Sched, bool ALIGN_EPI = false, bool SP2 = false, bool A_TILED = false>
; __device__ __forceinline__ void gemm_phase(PG8_LAS unsigned char* lds, const Gemm g, const Sched& S, const Epi& E, const int wave_s) {
;     ...
;         if constexpr (ALIGN_EPI) { if (wr == 0) PG8_BAR; }
	s_setprio 0
	ds_read_b128 v[154:157], v144
	ds_read_b128 v[158:161], v144 offset:1024
	ds_read_b128 v[162:165], v144 offset:2048
	ds_read_b128 v[166:169], v144 offset:3072
	ds_read_b128 v[170:173], v145
	ds_read_b128 v[174:177], v145 offset:1024
	ds_read_b128 v[178:181], v145 offset:2048
	ds_read_b128 v[182:185], v145 offset:3072
	s_add_u32 s82, s82, 0x80000
	s_addc_u32 s83, s83, 0
	s_mov_b32 m0, s37
	v_lshl_add_u64 v[220:221], s[82:83], 0, v[134:135]
	ds_read_b128 v[186:189], v151 offset:32768
	ds_read_b128 v[190:193], v151 offset:33792
	ds_read_b128 v[194:197], v151 offset:34816
	ds_read_b128 v[198:201], v151 offset:35840
	ds_read_b128 v[202:205], v151 offset:36864
	ds_read_b128 v[206:209], v151 offset:37888
	ds_read_b128 v[210:213], v151 offset:38912
	ds_read_b128 v[214:217], v151 offset:39936
	global_load_lds_dwordx4 v[220:221], off
	v_lshl_add_u64 v[220:221], s[82:83], 0, v[132:133]
	s_mov_b32 m0, s38
	s_nop 0
	global_load_lds_dwordx4 v[220:221], off
	s_waitcnt vmcnt(8) lgkmcnt(0)
	s_setprio 1
	s_barrier
	v_mfma_f32_16x16x32_bf16 v[124:127], v[154:157], v[186:189], v[124:127]
	v_mfma_f32_16x16x32_bf16 v[120:123], v[162:165], v[186:189], v[120:123]
	v_mfma_f32_16x16x32_bf16 v[108:111], v[154:157], v[194:197], v[108:111]
	v_mfma_f32_16x16x32_bf16 v[104:107], v[162:165], v[194:197], v[104:107]
	v_mfma_f32_16x16x32_bf16 v[92:95], v[154:157], v[202:205], v[92:95]
	v_mfma_f32_16x16x32_bf16 v[88:91], v[162:165], v[202:205], v[88:91]
	v_mfma_f32_16x16x32_bf16 v[76:79], v[154:157], v[210:213], v[76:79]
	v_mfma_f32_16x16x32_bf16 v[72:75], v[162:165], v[210:213], v[72:75]
	v_mfma_f32_16x16x32_bf16 v[124:127], v[158:161], v[190:193], v[124:127]
	v_mfma_f32_16x16x32_bf16 v[120:123], v[166:169], v[190:193], v[120:123]
	v_mfma_f32_16x16x32_bf16 v[108:111], v[158:161], v[198:201], v[108:111]
	v_mfma_f32_16x16x32_bf16 v[104:107], v[166:169], v[198:201], v[104:107]
	v_mfma_f32_16x16x32_bf16 v[92:95], v[158:161], v[206:209], v[92:95]
	v_mfma_f32_16x16x32_bf16 v[88:91], v[166:169], v[206:209], v[88:91]
	v_mfma_f32_16x16x32_bf16 v[76:79], v[158:161], v[214:217], v[76:79]
	v_mfma_f32_16x16x32_bf16 v[72:75], v[166:169], v[214:217], v[72:75]
	s_setprio 0
	s_setprio 1
	v_mfma_f32_16x16x32_bf16 v[116:119], v[170:173], v[186:189], v[116:119]
	v_mfma_f32_16x16x32_bf16 v[112:115], v[178:181], v[186:189], v[112:115]
	v_mfma_f32_16x16x32_bf16 v[100:103], v[170:173], v[194:197], v[100:103]
	v_mfma_f32_16x16x32_bf16 v[96:99], v[178:181], v[194:197], v[96:99]
	v_mfma_f32_16x16x32_bf16 v[84:87], v[170:173], v[202:205], v[84:87]
	v_mfma_f32_16x16x32_bf16 v[80:83], v[178:181], v[202:205], v[80:83]
	v_mfma_f32_16x16x32_bf16 v[68:71], v[170:173], v[210:213], v[68:71]
	v_mfma_f32_16x16x32_bf16 v[64:67], v[178:181], v[210:213], v[64:67]
	v_mfma_f32_16x16x32_bf16 v[116:119], v[174:177], v[190:193], v[116:119]
	v_mfma_f32_16x16x32_bf16 v[112:115], v[182:185], v[190:193], v[112:115]
	v_mfma_f32_16x16x32_bf16 v[100:103], v[174:177], v[198:201], v[100:103]
	v_mfma_f32_16x16x32_bf16 v[96:99], v[182:185], v[198:201], v[96:99]
	v_mfma_f32_16x16x32_bf16 v[84:87], v[174:177], v[206:209], v[84:87]
	v_mfma_f32_16x16x32_bf16 v[80:83], v[182:185], v[206:209], v[80:83]
	v_mfma_f32_16x16x32_bf16 v[68:71], v[174:177], v[214:217], v[68:71]
	v_mfma_f32_16x16x32_bf16 v[64:67], v[182:185], v[214:217], v[64:67]
	s_barrier
	s_setprio 0
	s_mov_b32 m0, s71
	v_lshl_add_u64 v[140:141], v[140:141], 0, s[60:61]
	s_add_u32 s80, s80, 0x80080
	ds_read_b128 v[186:189], v151 offset:49152
	ds_read_b128 v[190:193], v151 offset:50176
	ds_read_b128 v[194:197], v151 offset:51200
	ds_read_b128 v[198:201], v151 offset:52224
	ds_read_b128 v[202:205], v151 offset:53248
	ds_read_b128 v[206:209], v151 offset:54272
	ds_read_b128 v[210:213], v151 offset:55296
	ds_read_b128 v[214:217], v151 offset:56320
	global_load_lds_dwordx4 v[140:141], off
	v_lshl_add_u64 v[140:141], v[142:143], 0, s[60:61]
	s_mov_b32 m0, s77
	s_addc_u32 s81, s81, 0
	global_load_lds_dwordx4 v[140:141], off
	v_lshl_add_u64 v[140:141], s[80:81], 0, v[128:129]
	s_mov_b32 m0, s88
	s_nop 0
	global_load_lds_dwordx4 v[140:141], off
	v_lshl_add_u64 v[140:141], s[80:81], 0, v[130:131]
	s_mov_b32 m0, s89
	s_nop 0
	global_load_lds_dwordx4 v[140:141], off
	v_lshl_add_u64 v[140:141], v[146:147], 0, s[60:61]
	s_mov_b32 m0, s43
	s_nop 0
	global_load_lds_dwordx4 v[140:141], off
	v_lshl_add_u64 v[140:141], v[218:219], 0, s[60:61]
	s_mov_b32 m0, s44
	s_nop 0
	global_load_lds_dwordx4 v[140:141], off
	s_waitcnt vmcnt(8) lgkmcnt(0)
	s_setprio 1
	s_barrier
	v_mfma_f32_16x16x32_bf16 v[60:63], v[154:157], v[186:189], v[60:63]
	v_mfma_f32_16x16x32_bf16 v[56:59], v[162:165], v[186:189], v[56:59]
	v_mfma_f32_16x16x32_bf16 v[44:47], v[154:157], v[194:197], v[44:47]
	v_mfma_f32_16x16x32_bf16 v[40:43], v[162:165], v[194:197], v[40:43]
	v_mfma_f32_16x16x32_bf16 v[28:31], v[154:157], v[202:205], v[28:31]
	v_mfma_f32_16x16x32_bf16 v[24:27], v[162:165], v[202:205], v[24:27]
	v_mfma_f32_16x16x32_bf16 v[12:15], v[154:157], v[210:213], v[12:15]
	v_mfma_f32_16x16x32_bf16 v[8:11], v[162:165], v[210:213], v[8:11]
	v_mfma_f32_16x16x32_bf16 v[60:63], v[158:161], v[190:193], v[60:63]
	v_mfma_f32_16x16x32_bf16 v[56:59], v[166:169], v[190:193], v[56:59]
	v_mfma_f32_16x16x32_bf16 v[44:47], v[158:161], v[198:201], v[44:47]
	v_mfma_f32_16x16x32_bf16 v[40:43], v[166:169], v[198:201], v[40:43]
	v_mfma_f32_16x16x32_bf16 v[28:31], v[158:161], v[206:209], v[28:31]
	v_mfma_f32_16x16x32_bf16 v[24:27], v[166:169], v[206:209], v[24:27]
	v_mfma_f32_16x16x32_bf16 v[12:15], v[158:161], v[214:217], v[12:15]
	v_mfma_f32_16x16x32_bf16 v[8:11], v[166:169], v[214:217], v[8:11]
	s_setprio 0
	s_setprio 1
	v_mfma_f32_16x16x32_bf16 v[52:55], v[170:173], v[186:189], v[52:55]
	v_mfma_f32_16x16x32_bf16 v[48:51], v[178:181], v[186:189], v[48:51]
	v_mfma_f32_16x16x32_bf16 v[36:39], v[170:173], v[194:197], v[36:39]
	v_mfma_f32_16x16x32_bf16 v[32:35], v[178:181], v[194:197], v[32:35]
	v_mfma_f32_16x16x32_bf16 v[20:23], v[170:173], v[202:205], v[20:23]
	v_mfma_f32_16x16x32_bf16 v[16:19], v[178:181], v[202:205], v[16:19]
	v_mfma_f32_16x16x32_bf16 v[4:7], v[170:173], v[210:213], v[4:7]
	v_mfma_f32_16x16x32_bf16 v[0:3], v[178:181], v[210:213], v[0:3]
	v_mfma_f32_16x16x32_bf16 v[52:55], v[174:177], v[190:193], v[52:55]
	v_mfma_f32_16x16x32_bf16 v[48:51], v[182:185], v[190:193], v[48:51]
	v_mfma_f32_16x16x32_bf16 v[36:39], v[174:177], v[198:201], v[36:39]
	v_mfma_f32_16x16x32_bf16 v[32:35], v[182:185], v[198:201], v[32:35]
	v_mfma_f32_16x16x32_bf16 v[20:23], v[174:177], v[206:209], v[20:23]
	v_mfma_f32_16x16x32_bf16 v[16:19], v[182:185], v[206:209], v[16:19]
	v_mfma_f32_16x16x32_bf16 v[4:7], v[174:177], v[214:217], v[4:7]
	v_mfma_f32_16x16x32_bf16 v[0:3], v[182:185], v[214:217], v[0:3]
	s_barrier
	s_setprio 0
	s_add_i32 s91, s91, 2
	s_add_u32 s90, s90, 0x100
	s_addc_u32 s85, s85, 0
	s_add_u32 s78, s78, 0x100
	s_addc_u32 s79, s79, 0
	s_cmp_gt_u32 s91, 29
	s_cbranch_scc0 .LBB0_1619
	s_and_b64 vcc, exec, s[62:63]
	s_cbranch_vccz .LBB0_1622
	s_barrier

; #define PG8_MMA(ai, bj, At, Bt) do { __builtin_amdgcn_s_setprio(1); _Pragma("unroll") for (int m = 0; m < 4; ++m) _Pragma("unroll") for (int n = 0; n < 2; ++n) _Pragma("unroll") for (int k = 0; k < 2; ++k) \
;         acc[ai][bj][m][n] = __builtin_amdgcn_mfma_f32_16x16x32_bf16(Bt[n][k], At[m][k], acc[ai][bj][m][n], 0, 0, 0); __builtin_amdgcn_s_setprio(0); } while (0)
; template <class Epi, class Sched, bool ALIGN_EPI = false, bool SP2 = false, bool A_TILED = false>
; __device__ __forceinline__ void gemm_phase(PG8_LAS unsigned char* lds, const Gemm g, const Sched& S, const Epi& E, const int wave_s) {
;     ...
;         for (int t = PEEL ? 2 : 0; t < nt; t += 2) {
;             const bool last = (t == nt - 2);
;             const char* a1 = cA + (size_t)(t + 1) * kstepA;
;             const char* a2 = last ? nA : cA + (size_t)(t + 2) * kstepA; const char* b2 = last ? nB : cB + (size_t)(t + 2) * kstep;
;             const char* a3 = a2 + kstepA; const char* b3 = b2 + kstep;
;             if (last && has_next) S.a_ready(nxt);
;             if constexpr (SP2) {
;             PG8_ITER(PG8_MMA)
.LBB0_1841:
	ds_read_b128 v[146:149], v140
	ds_read_b128 v[150:153], v140 offset:1024
	ds_read_b128 v[154:157], v140 offset:2048
	ds_read_b128 v[158:161], v140 offset:3072
	ds_read_b128 v[162:165], v141
	ds_read_b128 v[166:169], v141 offset:1024
	ds_read_b128 v[170:173], v141 offset:2048
	ds_read_b128 v[174:177], v141 offset:3072
	s_add_u32 s52, s60, s39
	s_addc_u32 s53, s61, s40
	s_add_u32 s54, s60, s37
	s_addc_u32 s55, s61, s38
	s_cmp_eq_u32 s41, 28
	s_cselect_b32 s71, s7, s53
	s_cselect_b32 s70, s6, s52
	s_cselect_b32 s69, s3, s55
	s_cselect_b32 s68, s2, s54
	s_mov_b32 m0, s42
	v_lshl_add_u64 v[210:211], s[60:61], 0, v[138:139]
	ds_read_b128 v[178:181], v142
	ds_read_b128 v[182:185], v142 offset:1024
	ds_read_b128 v[186:189], v142 offset:2048
	ds_read_b128 v[190:193], v142 offset:3072
	ds_read_b128 v[194:197], v142 offset:4096
	ds_read_b128 v[198:201], v142 offset:5120
	ds_read_b128 v[202:205], v142 offset:6144
	ds_read_b128 v[206:209], v142 offset:7168
	global_load_lds_dwordx4 v[210:211], off
	v_lshl_add_u64 v[210:211], s[60:61], 0, v[136:137]
	s_mov_b32 m0, s43
	s_nop 0
	global_load_lds_dwordx4 v[210:211], off
	s_waitcnt vmcnt(8) lgkmcnt(0)
	s_setprio 1
	s_barrier
	v_mfma_f32_16x16x32_bf16 v[8:11], v[146:149], v[178:181], v[8:11]
	v_mfma_f32_16x16x32_bf16 v[12:15], v[154:157], v[178:181], v[12:15]
	v_mfma_f32_16x16x32_bf16 v[60:63], v[146:149], v[186:189], v[60:63]
	v_mfma_f32_16x16x32_bf16 v[20:23], v[154:157], v[186:189], v[20:23]
	v_mfma_f32_16x16x32_bf16 v[76:79], v[146:149], v[194:197], v[76:79]
	v_mfma_f32_16x16x32_bf16 v[52:55], v[154:157], v[194:197], v[52:55]
	v_mfma_f32_16x16x32_bf16 v[128:131], v[146:149], v[202:205], v[128:131]
	v_mfma_f32_16x16x32_bf16 v[68:71], v[154:157], v[202:205], v[68:71]
	v_mfma_f32_16x16x32_bf16 v[8:11], v[150:153], v[182:185], v[8:11]
	v_mfma_f32_16x16x32_bf16 v[12:15], v[158:161], v[182:185], v[12:15]
	v_mfma_f32_16x16x32_bf16 v[60:63], v[150:153], v[190:193], v[60:63]
	v_mfma_f32_16x16x32_bf16 v[20:23], v[158:161], v[190:193], v[20:23]
	v_mfma_f32_16x16x32_bf16 v[76:79], v[150:153], v[198:201], v[76:79]
	v_mfma_f32_16x16x32_bf16 v[52:55], v[158:161], v[198:201], v[52:55]
	v_mfma_f32_16x16x32_bf16 v[128:131], v[150:153], v[206:209], v[128:131]
	v_mfma_f32_16x16x32_bf16 v[68:71], v[158:161], v[206:209], v[68:71]
	s_setprio 0
	s_setprio 1
	v_mfma_f32_16x16x32_bf16 v[24:27], v[162:165], v[178:181], v[24:27]
	v_mfma_f32_16x16x32_bf16 v[16:19], v[170:173], v[178:181], v[16:19]
	v_mfma_f32_16x16x32_bf16 v[56:59], v[162:165], v[186:189], v[56:59]
	v_mfma_f32_16x16x32_bf16 v[48:51], v[170:173], v[186:189], v[48:51]
	v_mfma_f32_16x16x32_bf16 v[72:75], v[162:165], v[194:197], v[72:75]
	v_mfma_f32_16x16x32_bf16 v[64:67], v[170:173], v[194:197], v[64:67]
	v_mfma_f32_16x16x32_bf16 v[108:111], v[162:165], v[202:205], v[108:111]
	v_mfma_f32_16x16x32_bf16 v[96:99], v[170:173], v[202:205], v[96:99]
	v_mfma_f32_16x16x32_bf16 v[24:27], v[166:169], v[182:185], v[24:27]
	v_mfma_f32_16x16x32_bf16 v[16:19], v[174:177], v[182:185], v[16:19]
	v_mfma_f32_16x16x32_bf16 v[56:59], v[166:169], v[190:193], v[56:59]
	v_mfma_f32_16x16x32_bf16 v[48:51], v[174:177], v[190:193], v[48:51]
	v_mfma_f32_16x16x32_bf16 v[72:75], v[166:169], v[198:201], v[72:75]
	v_mfma_f32_16x16x32_bf16 v[64:67], v[174:177], v[198:201], v[64:67]
	v_mfma_f32_16x16x32_bf16 v[108:111], v[166:169], v[206:209], v[108:111]
	v_mfma_f32_16x16x32_bf16 v[96:99], v[174:177], v[206:209], v[96:99]
	s_barrier
	s_setprio 0
	s_mov_b32 m0, s44
	v_lshl_add_u64 v[210:211], s[68:69], 0, v[34:35]
	s_add_u32 s52, s68, 0x80000
	ds_read_b128 v[178:181], v142 offset:16384
	ds_read_b128 v[182:185], v142 offset:17408
	ds_read_b128 v[186:189], v142 offset:18432
	ds_read_b128 v[190:193], v142 offset:19456
	ds_read_b128 v[194:197], v142 offset:20480
	ds_read_b128 v[198:201], v142 offset:21504
	ds_read_b128 v[202:205], v142 offset:22528
	ds_read_b128 v[206:209], v142 offset:23552
	global_load_lds_dwordx4 v[210:211], off
	v_lshl_add_u64 v[212:213], s[68:69], 0, v[134:135]
	s_mov_b32 m0, s45
	s_addc_u32 s53, s69, 0
	global_load_lds_dwordx4 v[212:213], off
	v_lshl_add_u64 v[214:215], s[52:53], 0, v[34:35]
	s_mov_b32 m0, s46
	v_lshl_add_u64 v[216:217], s[70:71], 0, v[132:133]
	global_load_lds_dwordx4 v[214:215], off
	v_lshl_add_u64 v[214:215], s[52:53], 0, v[134:135]
	s_mov_b32 m0, s47
	s_nop 0
	global_load_lds_dwordx4 v[214:215], off
	v_lshl_add_u64 v[214:215], s[70:71], 0, v[32:33]
	s_mov_b32 m0, s14
	s_nop 0
	global_load_lds_dwordx4 v[214:215], off
	s_mov_b32 m0, s15
	s_nop 0
	global_load_lds_dwordx4 v[216:217], off
	s_waitcnt vmcnt(8) lgkmcnt(0)
	s_setprio 1
	s_barrier
	v_mfma_f32_16x16x32_bf16 v[100:103], v[146:149], v[178:181], v[100:103]
	v_mfma_f32_16x16x32_bf16 v[104:107], v[154:157], v[178:181], v[104:107]
	v_mfma_f32_16x16x32_bf16 v[116:119], v[146:149], v[186:189], v[116:119]
	v_mfma_f32_16x16x32_bf16 v[120:123], v[154:157], v[186:189], v[120:123]
	v_mfma_f32_16x16x32_bf16 v[84:87], v[146:149], v[194:197], v[84:87]
	v_mfma_f32_16x16x32_bf16 v[80:83], v[154:157], v[194:197], v[80:83]
	v_mfma_f32_16x16x32_bf16 v[36:39], v[146:149], v[202:205], v[36:39]
	v_mfma_f32_16x16x32_bf16 v[28:31], v[154:157], v[202:205], v[28:31]
	v_mfma_f32_16x16x32_bf16 v[100:103], v[150:153], v[182:185], v[100:103]
	v_mfma_f32_16x16x32_bf16 v[104:107], v[158:161], v[182:185], v[104:107]
	v_mfma_f32_16x16x32_bf16 v[116:119], v[150:153], v[190:193], v[116:119]
	v_mfma_f32_16x16x32_bf16 v[120:123], v[158:161], v[190:193], v[120:123]
	v_mfma_f32_16x16x32_bf16 v[84:87], v[150:153], v[198:201], v[84:87]
	v_mfma_f32_16x16x32_bf16 v[80:83], v[158:161], v[198:201], v[80:83]
	v_mfma_f32_16x16x32_bf16 v[36:39], v[150:153], v[206:209], v[36:39]
	v_mfma_f32_16x16x32_bf16 v[28:31], v[158:161], v[206:209], v[28:31]
	s_setprio 0
	s_setprio 1
	v_mfma_f32_16x16x32_bf16 v[124:127], v[162:165], v[178:181], v[124:127]
	v_mfma_f32_16x16x32_bf16 v[112:115], v[170:173], v[178:181], v[112:115]
	v_mfma_f32_16x16x32_bf16 v[92:95], v[162:165], v[186:189], v[92:95]
	v_mfma_f32_16x16x32_bf16 v[88:91], v[170:173], v[186:189], v[88:91]
	v_mfma_f32_16x16x32_bf16 v[44:47], v[162:165], v[194:197], v[44:47]
	v_mfma_f32_16x16x32_bf16 v[40:43], v[170:173], v[194:197], v[40:43]
	v_mfma_f32_16x16x32_bf16 v[4:7], v[162:165], v[202:205], v[4:7]
	v_mfma_f32_16x16x32_bf16 v[0:3], v[170:173], v[202:205], v[0:3]
	v_mfma_f32_16x16x32_bf16 v[124:127], v[166:169], v[182:185], v[124:127]
	v_mfma_f32_16x16x32_bf16 v[112:115], v[174:177], v[182:185], v[112:115]
	v_mfma_f32_16x16x32_bf16 v[92:95], v[166:169], v[190:193], v[92:95]
	v_mfma_f32_16x16x32_bf16 v[88:91], v[174:177], v[190:193], v[88:91]
	v_mfma_f32_16x16x32_bf16 v[44:47], v[166:169], v[198:201], v[44:47]
	v_mfma_f32_16x16x32_bf16 v[40:43], v[174:177], v[198:201], v[40:43]
	v_mfma_f32_16x16x32_bf16 v[4:7], v[166:169], v[206:209], v[4:7]
	v_mfma_f32_16x16x32_bf16 v[0:3], v[174:177], v[206:209], v[0:3]
	s_barrier
	s_setprio 0
	ds_read_b128 v[146:149], v143
	ds_read_b128 v[150:153], v143 offset:1024
	ds_read_b128 v[154:157], v143 offset:2048
	ds_read_b128 v[158:161], v143 offset:3072
	ds_read_b128 v[162:165], v144
	ds_read_b128 v[166:169], v144 offset:1024
	ds_read_b128 v[170:173], v144 offset:2048
	ds_read_b128 v[174:177], v144 offset:3072
	s_add_u32 s52, s70, 0x80000
	s_addc_u32 s53, s71, 0
	s_mov_b32 m0, s21
	v_lshl_add_u64 v[218:219], s[52:53], 0, v[32:33]
	ds_read_b128 v[178:181], v142 offset:32768
	ds_read_b128 v[182:185], v142 offset:33792
	ds_read_b128 v[186:189], v142 offset:34816
	ds_read_b128 v[190:193], v142 offset:35840
	ds_read_b128 v[194:197], v142 offset:36864
	ds_read_b128 v[198:201], v142 offset:37888
	ds_read_b128 v[202:205], v142 offset:38912
	ds_read_b128 v[206:209], v142 offset:39936
	global_load_lds_dwordx4 v[218:219], off
	v_lshl_add_u64 v[218:219], s[52:53], 0, v[132:133]
	s_mov_b32 m0, s22
	s_nop 0
	global_load_lds_dwordx4 v[218:219], off
	s_waitcnt vmcnt(8) lgkmcnt(0)
	s_setprio 1
	s_barrier
	v_mfma_f32_16x16x32_bf16 v[8:11], v[146:149], v[178:181], v[8:11]
	v_mfma_f32_16x16x32_bf16 v[12:15], v[154:157], v[178:181], v[12:15]
	v_mfma_f32_16x16x32_bf16 v[60:63], v[146:149], v[186:189], v[60:63]
	v_mfma_f32_16x16x32_bf16 v[20:23], v[154:157], v[186:189], v[20:23]
	v_mfma_f32_16x16x32_bf16 v[76:79], v[146:149], v[194:197], v[76:79]
	v_mfma_f32_16x16x32_bf16 v[52:55], v[154:157], v[194:197], v[52:55]
	v_mfma_f32_16x16x32_bf16 v[128:131], v[146:149], v[202:205], v[128:131]
	v_mfma_f32_16x16x32_bf16 v[68:71], v[154:157], v[202:205], v[68:71]
	v_mfma_f32_16x16x32_bf16 v[8:11], v[150:153], v[182:185], v[8:11]
	v_mfma_f32_16x16x32_bf16 v[12:15], v[158:161], v[182:185], v[12:15]
	v_mfma_f32_16x16x32_bf16 v[60:63], v[150:153], v[190:193], v[60:63]
	v_mfma_f32_16x16x32_bf16 v[20:23], v[158:161], v[190:193], v[20:23]
	v_mfma_f32_16x16x32_bf16 v[76:79], v[150:153], v[198:201], v[76:79]
	v_mfma_f32_16x16x32_bf16 v[52:55], v[158:161], v[198:201], v[52:55]
	v_mfma_f32_16x16x32_bf16 v[128:131], v[150:153], v[206:209], v[128:131]
	v_mfma_f32_16x16x32_bf16 v[68:71], v[158:161], v[206:209], v[68:71]
	s_setprio 0
	s_setprio 1
	v_mfma_f32_16x16x32_bf16 v[24:27], v[162:165], v[178:181], v[24:27]
	v_mfma_f32_16x16x32_bf16 v[16:19], v[170:173], v[178:181], v[16:19]
	v_mfma_f32_16x16x32_bf16 v[56:59], v[162:165], v[186:189], v[56:59]
	v_mfma_f32_16x16x32_bf16 v[48:51], v[170:173], v[186:189], v[48:51]
	v_mfma_f32_16x16x32_bf16 v[72:75], v[162:165], v[194:197], v[72:75]
	v_mfma_f32_16x16x32_bf16 v[64:67], v[170:173], v[194:197], v[64:67]
	v_mfma_f32_16x16x32_bf16 v[108:111], v[162:165], v[202:205], v[108:111]
	v_mfma_f32_16x16x32_bf16 v[96:99], v[170:173], v[202:205], v[96:99]
	v_mfma_f32_16x16x32_bf16 v[24:27], v[166:169], v[182:185], v[24:27]
	v_mfma_f32_16x16x32_bf16 v[16:19], v[174:177], v[182:185], v[16:19]
	v_mfma_f32_16x16x32_bf16 v[56:59], v[166:169], v[190:193], v[56:59]
	v_mfma_f32_16x16x32_bf16 v[48:51], v[174:177], v[190:193], v[48:51]
	v_mfma_f32_16x16x32_bf16 v[72:75], v[166:169], v[198:201], v[72:75]
	v_mfma_f32_16x16x32_bf16 v[64:67], v[174:177], v[198:201], v[64:67]
	v_mfma_f32_16x16x32_bf16 v[108:111], v[166:169], v[206:209], v[108:111]
	v_mfma_f32_16x16x32_bf16 v[96:99], v[174:177], v[206:209], v[96:99]
	s_barrier
; #define PG8_WAIT_V(n) asm volatile("s_waitcnt vmcnt(" #n ")" ::: "memory")
; #define PG8_BAR __builtin_amdgcn_s_barrier()
; template <class Epi, class Sched, bool ALIGN_EPI = false, bool SP2 = false, bool A_TILED = false>
; __device__ __forceinline__ void gemm_phase(PG8_LAS unsigned char* lds, const Gemm g, const Sched& S, const Epi& E, const int wave_s) {
;     ...
;     PG8_WAIT_V(0);
;     if constexpr (!ALIGN_EPI) { if (wr == 0) PG8_BAR; }
	s_setprio 0
	s_mov_b32 m0, s48
	v_lshl_add_u64 v[210:211], v[210:211], 0, s[64:65]
	s_add_u32 s52, s68, 0x80080
	ds_read_b128 v[178:181], v142 offset:49152
	ds_read_b128 v[182:185], v142 offset:50176
	ds_read_b128 v[186:189], v142 offset:51200
	ds_read_b128 v[190:193], v142 offset:52224
	ds_read_b128 v[194:197], v142 offset:53248
	ds_read_b128 v[198:201], v142 offset:54272
	ds_read_b128 v[202:205], v142 offset:55296
	ds_read_b128 v[206:209], v142 offset:56320
	global_load_lds_dwordx4 v[210:211], off
	v_lshl_add_u64 v[210:211], v[212:213], 0, s[64:65]
	s_mov_b32 m0, s49
	s_addc_u32 s53, s69, 0
	global_load_lds_dwordx4 v[210:211], off
	v_lshl_add_u64 v[210:211], s[52:53], 0, v[34:35]
	s_mov_b32 m0, s50
	s_nop 0
	global_load_lds_dwordx4 v[210:211], off
	v_lshl_add_u64 v[210:211], s[52:53], 0, v[134:135]
	s_mov_b32 m0, s51
	s_nop 0
	global_load_lds_dwordx4 v[210:211], off
	v_lshl_add_u64 v[210:211], v[214:215], 0, s[64:65]
	s_mov_b32 m0, s23
	s_nop 0
	global_load_lds_dwordx4 v[210:211], off
	v_lshl_add_u64 v[210:211], v[216:217], 0, s[64:65]
	s_mov_b32 m0, s36
	s_nop 0
	global_load_lds_dwordx4 v[210:211], off
	s_waitcnt vmcnt(8) lgkmcnt(0)
	s_setprio 1
	s_barrier
	v_mfma_f32_16x16x32_bf16 v[100:103], v[146:149], v[178:181], v[100:103]
	v_mfma_f32_16x16x32_bf16 v[104:107], v[154:157], v[178:181], v[104:107]
	v_mfma_f32_16x16x32_bf16 v[116:119], v[146:149], v[186:189], v[116:119]
	v_mfma_f32_16x16x32_bf16 v[120:123], v[154:157], v[186:189], v[120:123]
	v_mfma_f32_16x16x32_bf16 v[84:87], v[146:149], v[194:197], v[84:87]
	v_mfma_f32_16x16x32_bf16 v[80:83], v[154:157], v[194:197], v[80:83]
	v_mfma_f32_16x16x32_bf16 v[36:39], v[146:149], v[202:205], v[36:39]
	v_mfma_f32_16x16x32_bf16 v[28:31], v[154:157], v[202:205], v[28:31]
	v_mfma_f32_16x16x32_bf16 v[100:103], v[150:153], v[182:185], v[100:103]
	v_mfma_f32_16x16x32_bf16 v[104:107], v[158:161], v[182:185], v[104:107]
	v_mfma_f32_16x16x32_bf16 v[116:119], v[150:153], v[190:193], v[116:119]
	v_mfma_f32_16x16x32_bf16 v[120:123], v[158:161], v[190:193], v[120:123]
	v_mfma_f32_16x16x32_bf16 v[84:87], v[150:153], v[198:201], v[84:87]
	v_mfma_f32_16x16x32_bf16 v[80:83], v[158:161], v[198:201], v[80:83]
	v_mfma_f32_16x16x32_bf16 v[36:39], v[150:153], v[206:209], v[36:39]
	v_mfma_f32_16x16x32_bf16 v[28:31], v[158:161], v[206:209], v[28:31]
	s_setprio 0
	s_setprio 1
	v_mfma_f32_16x16x32_bf16 v[124:127], v[162:165], v[178:181], v[124:127]
	v_mfma_f32_16x16x32_bf16 v[112:115], v[170:173], v[178:181], v[112:115]
	v_mfma_f32_16x16x32_bf16 v[92:95], v[162:165], v[186:189], v[92:95]
	v_mfma_f32_16x16x32_bf16 v[88:91], v[170:173], v[186:189], v[88:91]
	v_mfma_f32_16x16x32_bf16 v[44:47], v[162:165], v[194:197], v[44:47]
	v_mfma_f32_16x16x32_bf16 v[40:43], v[170:173], v[194:197], v[40:43]
	v_mfma_f32_16x16x32_bf16 v[4:7], v[162:165], v[202:205], v[4:7]
	v_mfma_f32_16x16x32_bf16 v[0:3], v[170:173], v[202:205], v[0:3]
	v_mfma_f32_16x16x32_bf16 v[124:127], v[166:169], v[182:185], v[124:127]
	v_mfma_f32_16x16x32_bf16 v[112:115], v[174:177], v[182:185], v[112:115]
	v_mfma_f32_16x16x32_bf16 v[92:95], v[166:169], v[190:193], v[92:95]
	v_mfma_f32_16x16x32_bf16 v[88:91], v[174:177], v[190:193], v[88:91]
	v_mfma_f32_16x16x32_bf16 v[44:47], v[166:169], v[198:201], v[44:47]
	v_mfma_f32_16x16x32_bf16 v[40:43], v[174:177], v[198:201], v[40:43]
	v_mfma_f32_16x16x32_bf16 v[4:7], v[166:169], v[206:209], v[4:7]
	v_mfma_f32_16x16x32_bf16 v[0:3], v[174:177], v[206:209], v[0:3]
	s_barrier
	s_setprio 0
	s_add_i32 s41, s41, 2
	s_add_u32 s37, s37, 0x100
	s_addc_u32 s38, s38, 0
	s_add_u32 s39, s39, 0x100
	s_addc_u32 s40, s40, 0
	v_lshl_add_u64 v[136:137], v[136:137], 0, s[66:67]
	s_cmp_gt_u32 s41, 29
	v_lshl_add_u64 v[138:139], v[138:139], 0, s[66:67]
	s_cbranch_scc0 .LBB0_1841
	s_waitcnt vmcnt(0)
	s_cmpk_lt_u32 s0, 0x100
	s_cbranch_scc0 .LBB0_1844
	s_barrier

; template <class Epi, class Sched, bool ALIGN_EPI = false, bool SP2 = false, bool A_TILED = false>
; __device__ __forceinline__ void gemm_phase(PG8_LAS unsigned char* lds, const Gemm g, const Sched& S, const Epi& E, const int wave_s) {
;     ...
;         const bool has_next = Epi::AFTER_DRAIN ? false : S.next(ui + 1, nxt);
;         const char* nA = has_next ? (const char*)g.A + (size_t)nxt.pm * tstepA : cA; const char* nB = has_next ? (const char*)g.Bt + (size_t)nxt.pn * tstep : cB;
.LBB0_1952:
	s_ashr_i32 s69, s68, 31
	s_lshl_b64 s[50:51], s[68:69], 20
	s_add_u32 s70, s1, s50
	ds_read_b128 v[0:3], v145
	ds_read_b128 v[4:7], v145 offset:1024
	ds_read_b128 v[8:11], v145 offset:2048
	ds_read_b128 v[12:15], v145 offset:3072
	ds_read_b128 v[16:19], v146
	ds_read_b128 v[20:23], v146 offset:1024
	ds_read_b128 v[24:27], v146 offset:2048
	ds_read_b128 v[28:31], v146 offset:3072
	s_addc_u32 s71, s8, s51
	s_ashr_i32 s67, s66, 31
	s_lshl_b64 s[50:51], s[66:67], 20
	s_add_u32 s72, s9, s50
	s_addc_u32 s73, s14, s51
	s_and_b64 s[50:51], s[2:3], exec
	s_cselect_b32 s50, s71, s79
	s_cselect_b32 s51, s70, s78
	s_cselect_b32 s52, s73, s77
	s_cselect_b32 s53, s72, s76
	s_add_u32 s56, s78, 0x80080
	s_addc_u32 s57, s79, 0
	s_add_i32 s54, s22, 0xc000
	v_lshl_add_u64 v[64:65], s[56:57], 0, v[134:135]
	s_mov_b32 m0, s54
	s_add_i32 s55, s22, 0xe000
	ds_read_b128 v[32:35], v147
	ds_read_b128 v[36:39], v147 offset:1024
	ds_read_b128 v[40:43], v147 offset:2048
	ds_read_b128 v[44:47], v147 offset:3072
	ds_read_b128 v[48:51], v147 offset:4096
	ds_read_b128 v[52:55], v147 offset:5120
	ds_read_b128 v[56:59], v147 offset:6144
	ds_read_b128 v[60:63], v147 offset:7168
	global_load_lds_dwordx4 v[64:65], off
	v_lshl_add_u64 v[64:65], s[56:57], 0, v[132:133]
	s_mov_b32 m0, s55
	s_nop 0
	global_load_lds_dwordx4 v[64:65], off
	s_waitcnt vmcnt(8) lgkmcnt(0)
	s_setprio 1
	s_barrier
	v_mfma_f32_16x16x32_bf16 v[88:91], v[0:3], v[56:59], 0
	v_mfma_f32_16x16x32_bf16 v[64:67], v[0:3], v[32:35], 0
	v_mfma_f32_16x16x32_bf16 v[68:71], v[8:11], v[32:35], 0
	v_mfma_f32_16x16x32_bf16 v[72:75], v[0:3], v[40:43], 0
	v_mfma_f32_16x16x32_bf16 v[76:79], v[8:11], v[40:43], 0
	v_mfma_f32_16x16x32_bf16 v[80:83], v[0:3], v[48:51], 0
	v_mfma_f32_16x16x32_bf16 v[84:87], v[8:11], v[48:51], 0
	v_mfma_f32_16x16x32_bf16 v[96:99], v[4:7], v[60:63], v[88:91]
	v_mfma_f32_16x16x32_bf16 v[88:91], v[8:11], v[56:59], 0
	v_mfma_f32_16x16x32_bf16 v[64:67], v[4:7], v[36:39], v[64:67]
	v_mfma_f32_16x16x32_bf16 v[68:71], v[12:15], v[36:39], v[68:71]
	v_mfma_f32_16x16x32_bf16 v[72:75], v[4:7], v[44:47], v[72:75]
	v_mfma_f32_16x16x32_bf16 v[76:79], v[12:15], v[44:47], v[76:79]
	v_mfma_f32_16x16x32_bf16 v[80:83], v[4:7], v[52:55], v[80:83]
	v_mfma_f32_16x16x32_bf16 v[84:87], v[12:15], v[52:55], v[84:87]
	v_mfma_f32_16x16x32_bf16 v[100:103], v[12:15], v[60:63], v[88:91]
	s_setprio 0
	s_setprio 1
	v_mfma_f32_16x16x32_bf16 v[88:91], v[16:19], v[32:35], 0
	v_mfma_f32_16x16x32_bf16 v[32:35], v[24:27], v[32:35], 0
	v_mfma_f32_16x16x32_bf16 v[112:115], v[20:23], v[36:39], v[88:91]
	v_mfma_f32_16x16x32_bf16 v[32:35], v[28:31], v[36:39], v[32:35]
	v_mfma_f32_16x16x32_bf16 v[36:39], v[16:19], v[40:43], 0
	v_mfma_f32_16x16x32_bf16 v[40:43], v[24:27], v[40:43], 0
	v_mfma_f32_16x16x32_bf16 v[36:39], v[20:23], v[44:47], v[36:39]
	v_mfma_f32_16x16x32_bf16 v[40:43], v[28:31], v[44:47], v[40:43]
	v_mfma_f32_16x16x32_bf16 v[44:47], v[16:19], v[48:51], 0
	v_mfma_f32_16x16x32_bf16 v[48:51], v[24:27], v[48:51], 0
	v_mfma_f32_16x16x32_bf16 v[44:47], v[20:23], v[52:55], v[44:47]
	v_mfma_f32_16x16x32_bf16 v[48:51], v[28:31], v[52:55], v[48:51]
	v_mfma_f32_16x16x32_bf16 v[52:55], v[16:19], v[56:59], 0
	v_mfma_f32_16x16x32_bf16 v[56:59], v[24:27], v[56:59], 0
	v_mfma_f32_16x16x32_bf16 v[52:55], v[20:23], v[60:63], v[52:55]
	v_mfma_f32_16x16x32_bf16 v[56:59], v[28:31], v[60:63], v[56:59]
	s_barrier
	s_setprio 0
	s_add_i32 s56, s47, s15
	v_lshl_add_u64 v[242:243], s[76:77], 0, v[128:129]
	s_add_i32 s57, s56, 0x2000
	v_lshl_add_u64 v[148:149], v[242:243], 0, s[62:63]
	s_mov_b32 m0, s56
	v_lshl_add_u64 v[244:245], s[76:77], 0, v[130:131]
	s_add_u32 s80, s76, 0x80100
	ds_read_b128 v[60:63], v147 offset:16384
	ds_read_b128 v[88:91], v147 offset:17408
	ds_read_b128 v[92:95], v147 offset:18432
	ds_read_b128 v[104:107], v147 offset:19456
	ds_read_b128 v[108:111], v147 offset:20480
	ds_read_b128 v[116:119], v147 offset:21504
	ds_read_b128 v[120:123], v147 offset:22528
	ds_read_b128 v[124:127], v147 offset:23552
	global_load_lds_dwordx4 v[148:149], off
	v_lshl_add_u64 v[148:149], v[244:245], 0, s[62:63]
	s_mov_b32 m0, s57
	s_addc_u32 s81, s77, 0
	s_add_i32 s58, s48, s15
	global_load_lds_dwordx4 v[148:149], off
	v_lshl_add_u64 v[148:149], s[80:81], 0, v[128:129]
	s_mov_b32 m0, s58
	s_add_i32 s59, s58, 0x2000
	global_load_lds_dwordx4 v[148:149], off
	v_lshl_add_u64 v[148:149], s[80:81], 0, v[130:131]
	s_mov_b32 m0, s59
	v_lshl_add_u64 v[246:247], s[78:79], 0, v[134:135]
	global_load_lds_dwordx4 v[148:149], off
	v_lshl_add_u64 v[148:149], v[246:247], 0, s[62:63]
	s_mov_b32 m0, s22
	v_lshl_add_u64 v[248:249], s[78:79], 0, v[132:133]
	global_load_lds_dwordx4 v[148:149], off
	v_lshl_add_u64 v[148:149], v[248:249], 0, s[62:63]
	s_mov_b32 m0, s23
	s_nop 0
	global_load_lds_dwordx4 v[148:149], off
	s_waitcnt vmcnt(8) lgkmcnt(0)
	s_setprio 1
	s_barrier
	v_mfma_f32_16x16x32_bf16 v[148:151], v[0:3], v[60:63], 0
	v_mfma_f32_16x16x32_bf16 v[158:161], v[0:3], v[92:95], 0
	v_mfma_f32_16x16x32_bf16 v[166:169], v[0:3], v[108:111], 0
	v_mfma_f32_16x16x32_bf16 v[0:3], v[0:3], v[120:123], 0
	v_mfma_f32_16x16x32_bf16 v[150:153], v[4:7], v[88:91], v[148:151]
	v_mfma_f32_16x16x32_bf16 v[158:161], v[4:7], v[104:107], v[158:161]
	v_mfma_f32_16x16x32_bf16 v[166:169], v[4:7], v[116:119], v[166:169]
	v_mfma_f32_16x16x32_bf16 v[0:3], v[4:7], v[124:127], v[0:3]
	v_mfma_f32_16x16x32_bf16 v[4:7], v[8:11], v[120:123], 0
	v_mfma_f32_16x16x32_bf16 v[154:157], v[8:11], v[60:63], 0
	v_mfma_f32_16x16x32_bf16 v[162:165], v[8:11], v[92:95], 0
	v_mfma_f32_16x16x32_bf16 v[170:173], v[8:11], v[108:111], 0
	v_mfma_f32_16x16x32_bf16 v[4:7], v[12:15], v[124:127], v[4:7]
	v_mfma_f32_16x16x32_bf16 v[154:157], v[12:15], v[88:91], v[154:157]
	v_mfma_f32_16x16x32_bf16 v[162:165], v[12:15], v[104:107], v[162:165]
	v_mfma_f32_16x16x32_bf16 v[170:173], v[12:15], v[116:119], v[170:173]
	s_setprio 0
	s_setprio 1
	v_mfma_f32_16x16x32_bf16 v[8:11], v[16:19], v[60:63], 0
	v_mfma_f32_16x16x32_bf16 v[174:177], v[20:23], v[88:91], v[8:11]
	v_mfma_f32_16x16x32_bf16 v[8:11], v[24:27], v[60:63], 0
	v_mfma_f32_16x16x32_bf16 v[60:63], v[28:31], v[88:91], v[8:11]
	v_mfma_f32_16x16x32_bf16 v[8:11], v[16:19], v[92:95], 0
	v_mfma_f32_16x16x32_bf16 v[178:181], v[20:23], v[104:107], v[8:11]
	v_mfma_f32_16x16x32_bf16 v[8:11], v[24:27], v[92:95], 0
	v_mfma_f32_16x16x32_bf16 v[182:185], v[28:31], v[104:107], v[8:11]
	v_mfma_f32_16x16x32_bf16 v[8:11], v[16:19], v[108:111], 0
	v_mfma_f32_16x16x32_bf16 v[186:189], v[20:23], v[116:119], v[8:11]
	v_mfma_f32_16x16x32_bf16 v[8:11], v[24:27], v[108:111], 0
	v_mfma_f32_16x16x32_bf16 v[190:193], v[28:31], v[116:119], v[8:11]
	v_mfma_f32_16x16x32_bf16 v[8:11], v[16:19], v[120:123], 0
	v_mfma_f32_16x16x32_bf16 v[194:197], v[20:23], v[124:127], v[8:11]
	v_mfma_f32_16x16x32_bf16 v[8:11], v[24:27], v[120:123], 0
	v_mfma_f32_16x16x32_bf16 v[198:201], v[28:31], v[124:127], v[8:11]
	s_barrier
	s_setprio 0
	s_add_i32 s67, 0, 0x18000
	s_add_i32 s75, 0, 0x1c000
	v_add_u32_e32 v148, s67, v144
	v_add_u32_e32 v149, s75, v144
	s_nop 0
	ds_read_b128 v[8:11], v148
	ds_read_b128 v[12:15], v148 offset:1024
	ds_read_b128 v[16:19], v148 offset:2048
	ds_read_b128 v[20:23], v148 offset:3072
	ds_read_b128 v[202:205], v149
	ds_read_b128 v[206:209], v149 offset:1024
	ds_read_b128 v[210:213], v149 offset:2048
	ds_read_b128 v[214:217], v149 offset:3072
	s_add_u32 s80, s78, 0x80100
	s_addc_u32 s81, s79, 0
	s_mov_b32 m0, s36
	v_lshl_add_u64 v[88:89], s[80:81], 0, v[134:135]
	ds_read_b128 v[24:27], v147 offset:32768
	ds_read_b128 v[28:31], v147 offset:33792
	ds_read_b128 v[218:221], v147 offset:34816
	ds_read_b128 v[222:225], v147 offset:35840
	ds_read_b128 v[226:229], v147 offset:36864
	ds_read_b128 v[230:233], v147 offset:37888
	ds_read_b128 v[234:237], v147 offset:38912
	ds_read_b128 v[238:241], v147 offset:39936
	global_load_lds_dwordx4 v[88:89], off
	v_lshl_add_u64 v[88:89], s[80:81], 0, v[132:133]
	s_mov_b32 m0, s37
	s_nop 0
	global_load_lds_dwordx4 v[88:89], off
	s_waitcnt vmcnt(8) lgkmcnt(0)
	s_setprio 1
	s_barrier
	v_mfma_f32_16x16x32_bf16 v[64:67], v[8:11], v[24:27], v[64:67]
	v_mfma_f32_16x16x32_bf16 v[120:123], v[12:15], v[28:31], v[64:67]
	v_mfma_f32_16x16x32_bf16 v[64:67], v[16:19], v[24:27], v[68:71]
	v_mfma_f32_16x16x32_bf16 v[124:127], v[20:23], v[28:31], v[64:67]
	v_mfma_f32_16x16x32_bf16 v[64:67], v[8:11], v[218:221], v[72:75]
	v_mfma_f32_16x16x32_bf16 v[104:107], v[12:15], v[222:225], v[64:67]
	v_mfma_f32_16x16x32_bf16 v[64:67], v[16:19], v[218:221], v[76:79]
	v_mfma_f32_16x16x32_bf16 v[108:111], v[20:23], v[222:225], v[64:67]
	v_mfma_f32_16x16x32_bf16 v[64:67], v[8:11], v[226:229], v[80:83]
	v_mfma_f32_16x16x32_bf16 v[88:91], v[12:15], v[230:233], v[64:67]
	v_mfma_f32_16x16x32_bf16 v[64:67], v[16:19], v[226:229], v[84:87]
	v_mfma_f32_16x16x32_bf16 v[92:95], v[20:23], v[230:233], v[64:67]
	v_mfma_f32_16x16x32_bf16 v[64:67], v[8:11], v[234:237], v[96:99]
	v_mfma_f32_16x16x32_bf16 v[68:71], v[16:19], v[234:237], v[100:103]
	v_mfma_f32_16x16x32_bf16 v[64:67], v[12:15], v[238:241], v[64:67]
	v_mfma_f32_16x16x32_bf16 v[68:71], v[20:23], v[238:241], v[68:71]
	s_setprio 0
	s_setprio 1
	v_mfma_f32_16x16x32_bf16 v[72:75], v[202:205], v[24:27], v[112:115]
	v_mfma_f32_16x16x32_bf16 v[24:27], v[210:213], v[24:27], v[32:35]
	v_mfma_f32_16x16x32_bf16 v[116:119], v[214:217], v[28:31], v[24:27]
	v_mfma_f32_16x16x32_bf16 v[24:27], v[202:205], v[218:221], v[36:39]
	v_mfma_f32_16x16x32_bf16 v[96:99], v[206:209], v[222:225], v[24:27]
	v_mfma_f32_16x16x32_bf16 v[24:27], v[210:213], v[218:221], v[40:43]
	v_mfma_f32_16x16x32_bf16 v[100:103], v[214:217], v[222:225], v[24:27]
	v_mfma_f32_16x16x32_bf16 v[24:27], v[202:205], v[226:229], v[44:47]
	v_mfma_f32_16x16x32_bf16 v[80:83], v[206:209], v[230:233], v[24:27]
	v_mfma_f32_16x16x32_bf16 v[24:27], v[210:213], v[226:229], v[48:51]
	v_mfma_f32_16x16x32_bf16 v[84:87], v[214:217], v[230:233], v[24:27]
	v_mfma_f32_16x16x32_bf16 v[24:27], v[202:205], v[234:237], v[52:55]
	v_mfma_f32_16x16x32_bf16 v[48:51], v[206:209], v[238:241], v[24:27]
	v_mfma_f32_16x16x32_bf16 v[24:27], v[210:213], v[234:237], v[56:59]
	v_mfma_f32_16x16x32_bf16 v[112:115], v[206:209], v[28:31], v[72:75]
	v_mfma_f32_16x16x32_bf16 v[52:55], v[214:217], v[238:241], v[24:27]
	s_barrier
; template <class Epi, class Sched, bool ALIGN_EPI = false, bool SP2 = false, bool A_TILED = false>
; __device__ __forceinline__ void gemm_phase(PG8_LAS unsigned char* lds, const Gemm g, const Sched& S, const Epi& E, const int wave_s) {
;     ...
;         for (int t = PEEL ? 2 : 0; t < nt; t += 2) {
;             const bool last = (t == nt - 2);
;             const char* a1 = cA + (size_t)(t + 1) * kstepA;
;             const char* a2 = last ? nA : cA + (size_t)(t + 2) * kstepA; const char* b2 = last ? nB : cB + (size_t)(t + 2) * kstep;
;             const char* a3 = a2 + kstepA; const char* b3 = b2 + kstep;
	s_setprio 0
	s_add_i32 s67, s67, s15
	s_add_i32 s69, s67, 0x2000
	s_nop 1
	v_lshl_add_u64 v[24:25], v[242:243], 0, s[64:65]
	s_mov_b32 m0, s67
	s_add_u32 s80, s76, 0x80180
	ds_read_b128 v[32:35], v147 offset:49152
	ds_read_b128 v[36:39], v147 offset:50176
	ds_read_b128 v[218:221], v147 offset:51200
	ds_read_b128 v[222:225], v147 offset:52224
	ds_read_b128 v[226:229], v147 offset:53248
	ds_read_b128 v[230:233], v147 offset:54272
	ds_read_b128 v[234:237], v147 offset:55296
	ds_read_b128 v[238:241], v147 offset:56320
	global_load_lds_dwordx4 v[24:25], off
	v_lshl_add_u64 v[24:25], v[244:245], 0, s[64:65]
	s_mov_b32 m0, s69
	s_addc_u32 s81, s77, 0
	s_add_i32 s75, s75, s15
	global_load_lds_dwordx4 v[24:25], off
	v_lshl_add_u64 v[24:25], s[80:81], 0, v[128:129]
	s_mov_b32 m0, s75
	s_add_i32 s82, s75, 0x2000
	global_load_lds_dwordx4 v[24:25], off
	v_lshl_add_u64 v[24:25], s[80:81], 0, v[130:131]
	s_mov_b32 m0, s82
	s_nop 0
	global_load_lds_dwordx4 v[24:25], off
	v_lshl_add_u64 v[24:25], v[246:247], 0, s[64:65]
	s_mov_b32 m0, s43
	s_nop 0
	global_load_lds_dwordx4 v[24:25], off
	v_lshl_add_u64 v[24:25], v[248:249], 0, s[64:65]
	s_mov_b32 m0, s44
	s_nop 0
	global_load_lds_dwordx4 v[24:25], off
	s_waitcnt vmcnt(8) lgkmcnt(0)
	s_setprio 1
	s_barrier
	v_mfma_f32_16x16x32_bf16 v[24:27], v[8:11], v[32:35], v[150:153]
	v_mfma_f32_16x16x32_bf16 v[72:75], v[12:15], v[36:39], v[24:27]
	v_mfma_f32_16x16x32_bf16 v[24:27], v[16:19], v[32:35], v[154:157]
	v_mfma_f32_16x16x32_bf16 v[76:79], v[20:23], v[36:39], v[24:27]
	v_mfma_f32_16x16x32_bf16 v[24:27], v[8:11], v[218:221], v[158:161]
	v_mfma_f32_16x16x32_bf16 v[40:43], v[12:15], v[222:225], v[24:27]
	v_mfma_f32_16x16x32_bf16 v[24:27], v[16:19], v[218:221], v[162:165]
	v_mfma_f32_16x16x32_bf16 v[0:3], v[8:11], v[234:237], v[0:3]
	v_mfma_f32_16x16x32_bf16 v[44:47], v[20:23], v[222:225], v[24:27]
	v_mfma_f32_16x16x32_bf16 v[24:27], v[8:11], v[226:229], v[166:169]
	v_mfma_f32_16x16x32_bf16 v[28:31], v[16:19], v[226:229], v[170:173]
	v_mfma_f32_16x16x32_bf16 v[8:11], v[12:15], v[238:241], v[0:3]
	v_mfma_f32_16x16x32_bf16 v[0:3], v[16:19], v[234:237], v[4:7]
	v_mfma_f32_16x16x32_bf16 v[24:27], v[12:15], v[230:233], v[24:27]
	v_mfma_f32_16x16x32_bf16 v[28:31], v[20:23], v[230:233], v[28:31]
	v_mfma_f32_16x16x32_bf16 v[12:15], v[20:23], v[238:241], v[0:3]
	s_setprio 0
	s_setprio 1
	v_mfma_f32_16x16x32_bf16 v[0:3], v[202:205], v[32:35], v[174:177]
	v_mfma_f32_16x16x32_bf16 v[56:59], v[206:209], v[36:39], v[0:3]
	v_mfma_f32_16x16x32_bf16 v[0:3], v[210:213], v[32:35], v[60:63]
	v_mfma_f32_16x16x32_bf16 v[60:63], v[214:217], v[36:39], v[0:3]
	v_mfma_f32_16x16x32_bf16 v[0:3], v[202:205], v[218:221], v[178:181]
	v_mfma_f32_16x16x32_bf16 v[32:35], v[206:209], v[222:225], v[0:3]
	v_mfma_f32_16x16x32_bf16 v[0:3], v[210:213], v[218:221], v[182:185]
	v_mfma_f32_16x16x32_bf16 v[36:39], v[214:217], v[222:225], v[0:3]
	v_mfma_f32_16x16x32_bf16 v[0:3], v[202:205], v[226:229], v[186:189]
	v_mfma_f32_16x16x32_bf16 v[16:19], v[206:209], v[230:233], v[0:3]
	v_mfma_f32_16x16x32_bf16 v[0:3], v[210:213], v[226:229], v[190:193]
	v_mfma_f32_16x16x32_bf16 v[20:23], v[214:217], v[230:233], v[0:3]
	v_mfma_f32_16x16x32_bf16 v[0:3], v[202:205], v[234:237], v[194:197]
	v_mfma_f32_16x16x32_bf16 v[4:7], v[210:213], v[234:237], v[198:201]
	v_mfma_f32_16x16x32_bf16 v[0:3], v[206:209], v[238:241], v[0:3]
	v_mfma_f32_16x16x32_bf16 v[4:7], v[214:217], v[238:241], v[4:7]
	s_barrier
	s_setprio 0
	s_add_u32 s83, s76, 0x200
	s_addc_u32 s85, s77, 0
	s_add_u32 s76, s78, 0x80180
	s_addc_u32 s77, s79, 0
	s_mov_b32 s88, 0
.LBB0_1953:
	ds_read_b128 v[150:153], v145
	ds_read_b128 v[154:157], v145 offset:1024
	ds_read_b128 v[158:161], v145 offset:2048
	ds_read_b128 v[162:165], v145 offset:3072
	ds_read_b128 v[166:169], v146
	ds_read_b128 v[170:173], v146 offset:1024
	ds_read_b128 v[174:177], v146 offset:2048
	ds_read_b128 v[178:181], v146 offset:3072
	s_add_u32 s78, s76, 0xfff80080
	s_addc_u32 s79, s77, -1
	s_cmp_eq_u32 s88, 28
	s_cselect_b32 s81, s50, s79
	s_cselect_b32 s80, s51, s78
	s_cselect_b32 s79, s52, s85
	s_cselect_b32 s78, s53, s83
	s_mov_b32 m0, s54
	v_lshl_add_u64 v[214:215], s[76:77], 0, v[138:139]
	ds_read_b128 v[182:185], v147
	ds_read_b128 v[186:189], v147 offset:1024
	ds_read_b128 v[190:193], v147 offset:2048
	ds_read_b128 v[194:197], v147 offset:3072
	ds_read_b128 v[198:201], v147 offset:4096
	ds_read_b128 v[202:205], v147 offset:5120
	ds_read_b128 v[206:209], v147 offset:6144
	ds_read_b128 v[210:213], v147 offset:7168
	global_load_lds_dwordx4 v[214:215], off
	v_lshl_add_u64 v[214:215], s[76:77], 0, v[136:137]
	s_mov_b32 m0, s55
	s_nop 0
	global_load_lds_dwordx4 v[214:215], off
	s_waitcnt vmcnt(8) lgkmcnt(0)
	s_setprio 1
	s_barrier
	v_mfma_f32_16x16x32_bf16 v[120:123], v[150:153], v[182:185], v[120:123]
	v_mfma_f32_16x16x32_bf16 v[124:127], v[158:161], v[182:185], v[124:127]
	v_mfma_f32_16x16x32_bf16 v[104:107], v[150:153], v[190:193], v[104:107]
	v_mfma_f32_16x16x32_bf16 v[108:111], v[158:161], v[190:193], v[108:111]
	v_mfma_f32_16x16x32_bf16 v[88:91], v[150:153], v[198:201], v[88:91]
	v_mfma_f32_16x16x32_bf16 v[92:95], v[158:161], v[198:201], v[92:95]
	v_mfma_f32_16x16x32_bf16 v[64:67], v[150:153], v[206:209], v[64:67]
	v_mfma_f32_16x16x32_bf16 v[68:71], v[158:161], v[206:209], v[68:71]
	v_mfma_f32_16x16x32_bf16 v[120:123], v[154:157], v[186:189], v[120:123]
	v_mfma_f32_16x16x32_bf16 v[124:127], v[162:165], v[186:189], v[124:127]
	v_mfma_f32_16x16x32_bf16 v[104:107], v[154:157], v[194:197], v[104:107]
	v_mfma_f32_16x16x32_bf16 v[108:111], v[162:165], v[194:197], v[108:111]
	v_mfma_f32_16x16x32_bf16 v[88:91], v[154:157], v[202:205], v[88:91]
	v_mfma_f32_16x16x32_bf16 v[92:95], v[162:165], v[202:205], v[92:95]
	v_mfma_f32_16x16x32_bf16 v[64:67], v[154:157], v[210:213], v[64:67]
	v_mfma_f32_16x16x32_bf16 v[68:71], v[162:165], v[210:213], v[68:71]
	s_setprio 0
	s_setprio 1
	v_mfma_f32_16x16x32_bf16 v[112:115], v[166:169], v[182:185], v[112:115]
	v_mfma_f32_16x16x32_bf16 v[116:119], v[174:177], v[182:185], v[116:119]
	v_mfma_f32_16x16x32_bf16 v[96:99], v[166:169], v[190:193], v[96:99]
	v_mfma_f32_16x16x32_bf16 v[100:103], v[174:177], v[190:193], v[100:103]
	v_mfma_f32_16x16x32_bf16 v[80:83], v[166:169], v[198:201], v[80:83]
	v_mfma_f32_16x16x32_bf16 v[84:87], v[174:177], v[198:201], v[84:87]
	v_mfma_f32_16x16x32_bf16 v[48:51], v[166:169], v[206:209], v[48:51]
	v_mfma_f32_16x16x32_bf16 v[52:55], v[174:177], v[206:209], v[52:55]
	v_mfma_f32_16x16x32_bf16 v[112:115], v[170:173], v[186:189], v[112:115]
	v_mfma_f32_16x16x32_bf16 v[116:119], v[178:181], v[186:189], v[116:119]
	v_mfma_f32_16x16x32_bf16 v[96:99], v[170:173], v[194:197], v[96:99]
	v_mfma_f32_16x16x32_bf16 v[100:103], v[178:181], v[194:197], v[100:103]
	v_mfma_f32_16x16x32_bf16 v[80:83], v[170:173], v[202:205], v[80:83]
	v_mfma_f32_16x16x32_bf16 v[84:87], v[178:181], v[202:205], v[84:87]
	v_mfma_f32_16x16x32_bf16 v[48:51], v[170:173], v[210:213], v[48:51]
	v_mfma_f32_16x16x32_bf16 v[52:55], v[178:181], v[210:213], v[52:55]
	s_barrier
	s_setprio 0
	s_mov_b32 m0, s56
	v_lshl_add_u64 v[214:215], s[78:79], 0, v[128:129]
	s_add_u32 s90, s78, 0x80000
	ds_read_b128 v[182:185], v147 offset:16384
	ds_read_b128 v[186:189], v147 offset:17408
	ds_read_b128 v[190:193], v147 offset:18432
	ds_read_b128 v[194:197], v147 offset:19456
	ds_read_b128 v[198:201], v147 offset:20480
	ds_read_b128 v[202:205], v147 offset:21504
	ds_read_b128 v[206:209], v147 offset:22528
	ds_read_b128 v[210:213], v147 offset:23552
	global_load_lds_dwordx4 v[214:215], off
	v_lshl_add_u64 v[216:217], s[78:79], 0, v[130:131]
	s_mov_b32 m0, s57
	s_addc_u32 s91, s79, 0
	global_load_lds_dwordx4 v[216:217], off
	v_lshl_add_u64 v[218:219], s[90:91], 0, v[128:129]
	s_mov_b32 m0, s58
	v_lshl_add_u64 v[220:221], s[80:81], 0, v[132:133]
	global_load_lds_dwordx4 v[218:219], off
	v_lshl_add_u64 v[218:219], s[90:91], 0, v[130:131]
	s_mov_b32 m0, s59
	s_nop 0
	global_load_lds_dwordx4 v[218:219], off
	v_lshl_add_u64 v[218:219], s[80:81], 0, v[134:135]
	s_mov_b32 m0, s22
	s_nop 0
	global_load_lds_dwordx4 v[218:219], off
	s_mov_b32 m0, s23
	s_nop 0
	global_load_lds_dwordx4 v[220:221], off
	s_waitcnt vmcnt(8) lgkmcnt(0)
	s_setprio 1
	s_barrier
	v_mfma_f32_16x16x32_bf16 v[72:75], v[150:153], v[182:185], v[72:75]
	v_mfma_f32_16x16x32_bf16 v[76:79], v[158:161], v[182:185], v[76:79]
	v_mfma_f32_16x16x32_bf16 v[40:43], v[150:153], v[190:193], v[40:43]
	v_mfma_f32_16x16x32_bf16 v[44:47], v[158:161], v[190:193], v[44:47]
	v_mfma_f32_16x16x32_bf16 v[24:27], v[150:153], v[198:201], v[24:27]
	v_mfma_f32_16x16x32_bf16 v[28:31], v[158:161], v[198:201], v[28:31]
	v_mfma_f32_16x16x32_bf16 v[8:11], v[150:153], v[206:209], v[8:11]
	v_mfma_f32_16x16x32_bf16 v[12:15], v[158:161], v[206:209], v[12:15]
	v_mfma_f32_16x16x32_bf16 v[72:75], v[154:157], v[186:189], v[72:75]
	v_mfma_f32_16x16x32_bf16 v[76:79], v[162:165], v[186:189], v[76:79]
	v_mfma_f32_16x16x32_bf16 v[40:43], v[154:157], v[194:197], v[40:43]
	v_mfma_f32_16x16x32_bf16 v[44:47], v[162:165], v[194:197], v[44:47]
	v_mfma_f32_16x16x32_bf16 v[24:27], v[154:157], v[202:205], v[24:27]
	v_mfma_f32_16x16x32_bf16 v[28:31], v[162:165], v[202:205], v[28:31]
	v_mfma_f32_16x16x32_bf16 v[8:11], v[154:157], v[210:213], v[8:11]
	v_mfma_f32_16x16x32_bf16 v[12:15], v[162:165], v[210:213], v[12:15]
	s_setprio 0
	s_setprio 1
	v_mfma_f32_16x16x32_bf16 v[56:59], v[166:169], v[182:185], v[56:59]
	v_mfma_f32_16x16x32_bf16 v[60:63], v[174:177], v[182:185], v[60:63]
	v_mfma_f32_16x16x32_bf16 v[32:35], v[166:169], v[190:193], v[32:35]
	v_mfma_f32_16x16x32_bf16 v[36:39], v[174:177], v[190:193], v[36:39]
	v_mfma_f32_16x16x32_bf16 v[16:19], v[166:169], v[198:201], v[16:19]
	v_mfma_f32_16x16x32_bf16 v[20:23], v[174:177], v[198:201], v[20:23]
	v_mfma_f32_16x16x32_bf16 v[0:3], v[166:169], v[206:209], v[0:3]
	v_mfma_f32_16x16x32_bf16 v[4:7], v[174:177], v[206:209], v[4:7]
	v_mfma_f32_16x16x32_bf16 v[56:59], v[170:173], v[186:189], v[56:59]
	v_mfma_f32_16x16x32_bf16 v[60:63], v[178:181], v[186:189], v[60:63]
	v_mfma_f32_16x16x32_bf16 v[32:35], v[170:173], v[194:197], v[32:35]
	v_mfma_f32_16x16x32_bf16 v[36:39], v[178:181], v[194:197], v[36:39]
	v_mfma_f32_16x16x32_bf16 v[16:19], v[170:173], v[202:205], v[16:19]
	v_mfma_f32_16x16x32_bf16 v[20:23], v[178:181], v[202:205], v[20:23]
	v_mfma_f32_16x16x32_bf16 v[0:3], v[170:173], v[210:213], v[0:3]
	v_mfma_f32_16x16x32_bf16 v[4:7], v[178:181], v[210:213], v[4:7]
	s_barrier
	s_setprio 0
	ds_read_b128 v[150:153], v148
	ds_read_b128 v[154:157], v148 offset:1024
	ds_read_b128 v[158:161], v148 offset:2048
	ds_read_b128 v[162:165], v148 offset:3072
	ds_read_b128 v[166:169], v149
	ds_read_b128 v[170:173], v149 offset:1024
	ds_read_b128 v[174:177], v149 offset:2048
	ds_read_b128 v[178:181], v149 offset:3072
	s_add_u32 s80, s80, 0x80000
	s_addc_u32 s81, s81, 0
	s_mov_b32 m0, s36
	v_lshl_add_u64 v[222:223], s[80:81], 0, v[134:135]
	ds_read_b128 v[182:185], v147 offset:32768
	ds_read_b128 v[186:189], v147 offset:33792
	ds_read_b128 v[190:193], v147 offset:34816
	ds_read_b128 v[194:197], v147 offset:35840
	ds_read_b128 v[198:201], v147 offset:36864
	ds_read_b128 v[202:205], v147 offset:37888
	ds_read_b128 v[206:209], v147 offset:38912
	ds_read_b128 v[210:213], v147 offset:39936
	global_load_lds_dwordx4 v[222:223], off
	v_lshl_add_u64 v[222:223], s[80:81], 0, v[132:133]
	s_mov_b32 m0, s37
	s_nop 0
	global_load_lds_dwordx4 v[222:223], off
	s_waitcnt vmcnt(8) lgkmcnt(0)
	s_setprio 1
	s_barrier
	v_mfma_f32_16x16x32_bf16 v[120:123], v[150:153], v[182:185], v[120:123]
	v_mfma_f32_16x16x32_bf16 v[124:127], v[158:161], v[182:185], v[124:127]
	v_mfma_f32_16x16x32_bf16 v[104:107], v[150:153], v[190:193], v[104:107]
	v_mfma_f32_16x16x32_bf16 v[108:111], v[158:161], v[190:193], v[108:111]
	v_mfma_f32_16x16x32_bf16 v[88:91], v[150:153], v[198:201], v[88:91]
	v_mfma_f32_16x16x32_bf16 v[92:95], v[158:161], v[198:201], v[92:95]
	v_mfma_f32_16x16x32_bf16 v[64:67], v[150:153], v[206:209], v[64:67]
	v_mfma_f32_16x16x32_bf16 v[68:71], v[158:161], v[206:209], v[68:71]
	v_mfma_f32_16x16x32_bf16 v[120:123], v[154:157], v[186:189], v[120:123]
	v_mfma_f32_16x16x32_bf16 v[124:127], v[162:165], v[186:189], v[124:127]
	v_mfma_f32_16x16x32_bf16 v[104:107], v[154:157], v[194:197], v[104:107]
	v_mfma_f32_16x16x32_bf16 v[108:111], v[162:165], v[194:197], v[108:111]
	v_mfma_f32_16x16x32_bf16 v[88:91], v[154:157], v[202:205], v[88:91]
	v_mfma_f32_16x16x32_bf16 v[92:95], v[162:165], v[202:205], v[92:95]
	v_mfma_f32_16x16x32_bf16 v[64:67], v[154:157], v[210:213], v[64:67]
	v_mfma_f32_16x16x32_bf16 v[68:71], v[162:165], v[210:213], v[68:71]
	s_setprio 0
	s_setprio 1
	v_mfma_f32_16x16x32_bf16 v[112:115], v[166:169], v[182:185], v[112:115]
	v_mfma_f32_16x16x32_bf16 v[116:119], v[174:177], v[182:185], v[116:119]
	v_mfma_f32_16x16x32_bf16 v[96:99], v[166:169], v[190:193], v[96:99]
	v_mfma_f32_16x16x32_bf16 v[100:103], v[174:177], v[190:193], v[100:103]
	v_mfma_f32_16x16x32_bf16 v[80:83], v[166:169], v[198:201], v[80:83]
	v_mfma_f32_16x16x32_bf16 v[84:87], v[174:177], v[198:201], v[84:87]
	v_mfma_f32_16x16x32_bf16 v[48:51], v[166:169], v[206:209], v[48:51]
	v_mfma_f32_16x16x32_bf16 v[52:55], v[174:177], v[206:209], v[52:55]
	v_mfma_f32_16x16x32_bf16 v[112:115], v[170:173], v[186:189], v[112:115]
	v_mfma_f32_16x16x32_bf16 v[116:119], v[178:181], v[186:189], v[116:119]
	v_mfma_f32_16x16x32_bf16 v[96:99], v[170:173], v[194:197], v[96:99]
	v_mfma_f32_16x16x32_bf16 v[100:103], v[178:181], v[194:197], v[100:103]
	v_mfma_f32_16x16x32_bf16 v[80:83], v[170:173], v[202:205], v[80:83]
	v_mfma_f32_16x16x32_bf16 v[84:87], v[178:181], v[202:205], v[84:87]
	v_mfma_f32_16x16x32_bf16 v[48:51], v[170:173], v[210:213], v[48:51]
	v_mfma_f32_16x16x32_bf16 v[52:55], v[178:181], v[210:213], v[52:55]
	s_barrier
	s_setprio 0
	s_mov_b32 m0, s67
	v_lshl_add_u64 v[214:215], v[214:215], 0, s[12:13]
	s_add_u32 s78, s78, 0x80080
	ds_read_b128 v[182:185], v147 offset:49152
	ds_read_b128 v[186:189], v147 offset:50176
	ds_read_b128 v[190:193], v147 offset:51200
	ds_read_b128 v[194:197], v147 offset:52224
	ds_read_b128 v[198:201], v147 offset:53248
	ds_read_b128 v[202:205], v147 offset:54272
	ds_read_b128 v[206:209], v147 offset:55296
	ds_read_b128 v[210:213], v147 offset:56320
	global_load_lds_dwordx4 v[214:215], off
	v_lshl_add_u64 v[214:215], v[216:217], 0, s[12:13]
	s_mov_b32 m0, s69
	s_addc_u32 s79, s79, 0
	global_load_lds_dwordx4 v[214:215], off
	v_lshl_add_u64 v[214:215], s[78:79], 0, v[128:129]
	s_mov_b32 m0, s75
	s_nop 0
	global_load_lds_dwordx4 v[214:215], off
	v_lshl_add_u64 v[214:215], s[78:79], 0, v[130:131]
	s_mov_b32 m0, s82
	s_nop 0
	global_load_lds_dwordx4 v[214:215], off
	v_lshl_add_u64 v[214:215], v[218:219], 0, s[12:13]
	s_mov_b32 m0, s43
	s_nop 0
	global_load_lds_dwordx4 v[214:215], off
	v_lshl_add_u64 v[214:215], v[220:221], 0, s[12:13]
	s_mov_b32 m0, s44
	s_nop 0
	global_load_lds_dwordx4 v[214:215], off
	s_waitcnt vmcnt(8) lgkmcnt(0)
	s_setprio 1
	s_barrier
	v_mfma_f32_16x16x32_bf16 v[72:75], v[150:153], v[182:185], v[72:75]
	v_mfma_f32_16x16x32_bf16 v[76:79], v[158:161], v[182:185], v[76:79]
	v_mfma_f32_16x16x32_bf16 v[40:43], v[150:153], v[190:193], v[40:43]
	v_mfma_f32_16x16x32_bf16 v[44:47], v[158:161], v[190:193], v[44:47]
	v_mfma_f32_16x16x32_bf16 v[24:27], v[150:153], v[198:201], v[24:27]
	v_mfma_f32_16x16x32_bf16 v[28:31], v[158:161], v[198:201], v[28:31]
	v_mfma_f32_16x16x32_bf16 v[8:11], v[150:153], v[206:209], v[8:11]
	v_mfma_f32_16x16x32_bf16 v[12:15], v[158:161], v[206:209], v[12:15]
	v_mfma_f32_16x16x32_bf16 v[72:75], v[154:157], v[186:189], v[72:75]
	v_mfma_f32_16x16x32_bf16 v[76:79], v[162:165], v[186:189], v[76:79]
	v_mfma_f32_16x16x32_bf16 v[40:43], v[154:157], v[194:197], v[40:43]
	v_mfma_f32_16x16x32_bf16 v[44:47], v[162:165], v[194:197], v[44:47]
	v_mfma_f32_16x16x32_bf16 v[24:27], v[154:157], v[202:205], v[24:27]
	v_mfma_f32_16x16x32_bf16 v[28:31], v[162:165], v[202:205], v[28:31]
	v_mfma_f32_16x16x32_bf16 v[8:11], v[154:157], v[210:213], v[8:11]
	v_mfma_f32_16x16x32_bf16 v[12:15], v[162:165], v[210:213], v[12:15]
	s_setprio 0
	s_setprio 1
	v_mfma_f32_16x16x32_bf16 v[56:59], v[166:169], v[182:185], v[56:59]
	v_mfma_f32_16x16x32_bf16 v[60:63], v[174:177], v[182:185], v[60:63]
	v_mfma_f32_16x16x32_bf16 v[32:35], v[166:169], v[190:193], v[32:35]
	v_mfma_f32_16x16x32_bf16 v[36:39], v[174:177], v[190:193], v[36:39]
	v_mfma_f32_16x16x32_bf16 v[16:19], v[166:169], v[198:201], v[16:19]
	v_mfma_f32_16x16x32_bf16 v[20:23], v[174:177], v[198:201], v[20:23]
	v_mfma_f32_16x16x32_bf16 v[0:3], v[166:169], v[206:209], v[0:3]
	v_mfma_f32_16x16x32_bf16 v[4:7], v[174:177], v[206:209], v[4:7]
	v_mfma_f32_16x16x32_bf16 v[56:59], v[170:173], v[186:189], v[56:59]
	v_mfma_f32_16x16x32_bf16 v[60:63], v[178:181], v[186:189], v[60:63]
	v_mfma_f32_16x16x32_bf16 v[32:35], v[170:173], v[194:197], v[32:35]
	v_mfma_f32_16x16x32_bf16 v[36:39], v[178:181], v[194:197], v[36:39]
	v_mfma_f32_16x16x32_bf16 v[16:19], v[170:173], v[202:205], v[16:19]
	v_mfma_f32_16x16x32_bf16 v[20:23], v[178:181], v[202:205], v[20:23]
	v_mfma_f32_16x16x32_bf16 v[0:3], v[170:173], v[210:213], v[0:3]
	v_mfma_f32_16x16x32_bf16 v[4:7], v[178:181], v[210:213], v[4:7]
	s_barrier
	s_setprio 0
	s_add_i32 s88, s88, 2
	s_add_u32 s83, s83, 0x100
	s_addc_u32 s85, s85, 0
	s_add_u32 s76, s76, 0x100
	s_addc_u32 s77, s77, 0
	s_cmp_gt_u32 s88, 29
	s_cbranch_scc0 .LBB0_1953
	s_and_b64 vcc, exec, s[60:61]
	s_cbranch_vccz .LBB0_1956
	s_barrier

; template <class Epi, class Sched, bool ALIGN_EPI = false, bool SP2 = false, bool A_TILED = false>
; __device__ __forceinline__ void gemm_phase(PG8_LAS unsigned char* lds, const Gemm g, const Sched& S, const Epi& E, const int wave_s) {
;     ...
;         for (int t = PEEL ? 2 : 0; t < nt; t += 2) {
;             const bool last = (t == nt - 2);
;             const char* a1 = cA + (size_t)(t + 1) * kstepA;
;             const char* a2 = last ? nA : cA + (size_t)(t + 2) * kstepA; const char* b2 = last ? nB : cB + (size_t)(t + 2) * kstep;
;             const char* a3 = a2 + kstepA; const char* b3 = b2 + kstep;
.LBB0_2026:
	ds_read_b128 v[146:149], v140
	ds_read_b128 v[150:153], v140 offset:1024
	ds_read_b128 v[154:157], v140 offset:2048
	ds_read_b128 v[158:161], v140 offset:3072
	ds_read_b128 v[162:165], v141
	ds_read_b128 v[166:169], v141 offset:1024
	ds_read_b128 v[170:173], v141 offset:2048
	ds_read_b128 v[174:177], v141 offset:3072
	s_add_u32 s52, s60, s39
	s_addc_u32 s53, s61, s40
	s_add_u32 s54, s60, s37
	s_addc_u32 s55, s61, s38
	s_cmpk_eq_i32 s41, 0x7c
	s_cselect_b32 s72, s6, s52
	s_cselect_b32 s73, s7, s53
	s_cselect_b32 s70, s2, s54
	s_cselect_b32 s71, s3, s55
	s_add_u32 s68, s72, 0x8000
	s_addc_u32 s69, s73, 0
	s_mov_b32 m0, s42
	v_lshl_add_u64 v[210:211], s[60:61], 0, v[138:139]
	ds_read_b128 v[178:181], v142
	ds_read_b128 v[182:185], v142 offset:1024
	ds_read_b128 v[186:189], v142 offset:2048
	ds_read_b128 v[190:193], v142 offset:3072
	ds_read_b128 v[194:197], v142 offset:4096
	ds_read_b128 v[198:201], v142 offset:5120
	ds_read_b128 v[202:205], v142 offset:6144
	ds_read_b128 v[206:209], v142 offset:7168
	global_load_lds_dwordx4 v[210:211], off
	v_lshl_add_u64 v[210:211], s[60:61], 0, v[136:137]
	s_mov_b32 m0, s43
	s_nop 0
	global_load_lds_dwordx4 v[210:211], off
	s_waitcnt vmcnt(8) lgkmcnt(0)
	s_setprio 1
	s_barrier
	v_mfma_f32_16x16x32_bf16 v[8:11], v[146:149], v[178:181], v[8:11]
	v_mfma_f32_16x16x32_bf16 v[12:15], v[154:157], v[178:181], v[12:15]
	v_mfma_f32_16x16x32_bf16 v[60:63], v[146:149], v[186:189], v[60:63]
	v_mfma_f32_16x16x32_bf16 v[20:23], v[154:157], v[186:189], v[20:23]
	v_mfma_f32_16x16x32_bf16 v[76:79], v[146:149], v[194:197], v[76:79]
	v_mfma_f32_16x16x32_bf16 v[52:55], v[154:157], v[194:197], v[52:55]
	v_mfma_f32_16x16x32_bf16 v[128:131], v[146:149], v[202:205], v[128:131]
	v_mfma_f32_16x16x32_bf16 v[68:71], v[154:157], v[202:205], v[68:71]
	v_mfma_f32_16x16x32_bf16 v[8:11], v[150:153], v[182:185], v[8:11]
	v_mfma_f32_16x16x32_bf16 v[12:15], v[158:161], v[182:185], v[12:15]
	v_mfma_f32_16x16x32_bf16 v[60:63], v[150:153], v[190:193], v[60:63]
	v_mfma_f32_16x16x32_bf16 v[20:23], v[158:161], v[190:193], v[20:23]
	v_mfma_f32_16x16x32_bf16 v[76:79], v[150:153], v[198:201], v[76:79]
	v_mfma_f32_16x16x32_bf16 v[52:55], v[158:161], v[198:201], v[52:55]
	v_mfma_f32_16x16x32_bf16 v[128:131], v[150:153], v[206:209], v[128:131]
	v_mfma_f32_16x16x32_bf16 v[68:71], v[158:161], v[206:209], v[68:71]
	s_setprio 0
	s_setprio 1
	v_mfma_f32_16x16x32_bf16 v[28:31], v[162:165], v[178:181], v[28:31]
	v_mfma_f32_16x16x32_bf16 v[16:19], v[170:173], v[178:181], v[16:19]
	v_mfma_f32_16x16x32_bf16 v[56:59], v[162:165], v[186:189], v[56:59]
	v_mfma_f32_16x16x32_bf16 v[48:51], v[170:173], v[186:189], v[48:51]
	v_mfma_f32_16x16x32_bf16 v[72:75], v[162:165], v[194:197], v[72:75]
	v_mfma_f32_16x16x32_bf16 v[64:67], v[170:173], v[194:197], v[64:67]
	v_mfma_f32_16x16x32_bf16 v[108:111], v[162:165], v[202:205], v[108:111]
	v_mfma_f32_16x16x32_bf16 v[96:99], v[170:173], v[202:205], v[96:99]
	v_mfma_f32_16x16x32_bf16 v[28:31], v[166:169], v[182:185], v[28:31]
	v_mfma_f32_16x16x32_bf16 v[16:19], v[174:177], v[182:185], v[16:19]
	v_mfma_f32_16x16x32_bf16 v[56:59], v[166:169], v[190:193], v[56:59]
	v_mfma_f32_16x16x32_bf16 v[48:51], v[174:177], v[190:193], v[48:51]
	v_mfma_f32_16x16x32_bf16 v[72:75], v[166:169], v[198:201], v[72:75]
	v_mfma_f32_16x16x32_bf16 v[64:67], v[174:177], v[198:201], v[64:67]
	v_mfma_f32_16x16x32_bf16 v[108:111], v[166:169], v[206:209], v[108:111]
	v_mfma_f32_16x16x32_bf16 v[96:99], v[174:177], v[206:209], v[96:99]
	s_barrier
	s_setprio 0
	s_mov_b32 m0, s44
	v_lshl_add_u64 v[210:211], s[70:71], 0, v[34:35]
	s_add_u32 s52, s70, 0x200000
	ds_read_b128 v[178:181], v142 offset:16384
	ds_read_b128 v[182:185], v142 offset:17408
	ds_read_b128 v[186:189], v142 offset:18432
	ds_read_b128 v[190:193], v142 offset:19456
	ds_read_b128 v[194:197], v142 offset:20480
	ds_read_b128 v[198:201], v142 offset:21504
	ds_read_b128 v[202:205], v142 offset:22528
	ds_read_b128 v[206:209], v142 offset:23552
	global_load_lds_dwordx4 v[210:211], off
	v_lshl_add_u64 v[212:213], s[70:71], 0, v[134:135]
	s_mov_b32 m0, s45
	s_addc_u32 s53, s71, 0
	global_load_lds_dwordx4 v[212:213], off
	v_lshl_add_u64 v[214:215], s[52:53], 0, v[34:35]
	s_mov_b32 m0, s46
	s_nop 0
	global_load_lds_dwordx4 v[214:215], off
	v_lshl_add_u64 v[214:215], s[52:53], 0, v[134:135]
	s_mov_b32 m0, s47
	s_nop 0
	global_load_lds_dwordx4 v[214:215], off
	v_lshl_add_u64 v[214:215], s[72:73], 0, v[32:33]
	s_mov_b32 m0, s14
	s_nop 0
	global_load_lds_dwordx4 v[214:215], off
	v_lshl_add_u64 v[214:215], s[72:73], 0, v[132:133]
	s_mov_b32 m0, s15
	s_nop 0
	global_load_lds_dwordx4 v[214:215], off
	s_waitcnt vmcnt(8) lgkmcnt(0)
	s_setprio 1
	s_barrier
	v_mfma_f32_16x16x32_bf16 v[100:103], v[146:149], v[178:181], v[100:103]
	v_mfma_f32_16x16x32_bf16 v[104:107], v[154:157], v[178:181], v[104:107]
	v_mfma_f32_16x16x32_bf16 v[116:119], v[146:149], v[186:189], v[116:119]
	v_mfma_f32_16x16x32_bf16 v[120:123], v[154:157], v[186:189], v[120:123]
	v_mfma_f32_16x16x32_bf16 v[84:87], v[146:149], v[194:197], v[84:87]
	v_mfma_f32_16x16x32_bf16 v[80:83], v[154:157], v[194:197], v[80:83]
	v_mfma_f32_16x16x32_bf16 v[36:39], v[146:149], v[202:205], v[36:39]
	v_mfma_f32_16x16x32_bf16 v[24:27], v[154:157], v[202:205], v[24:27]
	v_mfma_f32_16x16x32_bf16 v[100:103], v[150:153], v[182:185], v[100:103]
	v_mfma_f32_16x16x32_bf16 v[104:107], v[158:161], v[182:185], v[104:107]
	v_mfma_f32_16x16x32_bf16 v[116:119], v[150:153], v[190:193], v[116:119]
	v_mfma_f32_16x16x32_bf16 v[120:123], v[158:161], v[190:193], v[120:123]
	v_mfma_f32_16x16x32_bf16 v[84:87], v[150:153], v[198:201], v[84:87]
	v_mfma_f32_16x16x32_bf16 v[80:83], v[158:161], v[198:201], v[80:83]
	v_mfma_f32_16x16x32_bf16 v[36:39], v[150:153], v[206:209], v[36:39]
	v_mfma_f32_16x16x32_bf16 v[24:27], v[158:161], v[206:209], v[24:27]
	s_setprio 0
	s_setprio 1
	v_mfma_f32_16x16x32_bf16 v[124:127], v[162:165], v[178:181], v[124:127]
	v_mfma_f32_16x16x32_bf16 v[112:115], v[170:173], v[178:181], v[112:115]
	v_mfma_f32_16x16x32_bf16 v[92:95], v[162:165], v[186:189], v[92:95]
	v_mfma_f32_16x16x32_bf16 v[88:91], v[170:173], v[186:189], v[88:91]
	v_mfma_f32_16x16x32_bf16 v[44:47], v[162:165], v[194:197], v[44:47]
	v_mfma_f32_16x16x32_bf16 v[40:43], v[170:173], v[194:197], v[40:43]
	v_mfma_f32_16x16x32_bf16 v[4:7], v[162:165], v[202:205], v[4:7]
	v_mfma_f32_16x16x32_bf16 v[0:3], v[170:173], v[202:205], v[0:3]
	v_mfma_f32_16x16x32_bf16 v[124:127], v[166:169], v[182:185], v[124:127]
	v_mfma_f32_16x16x32_bf16 v[112:115], v[174:177], v[182:185], v[112:115]
	v_mfma_f32_16x16x32_bf16 v[92:95], v[166:169], v[190:193], v[92:95]
	v_mfma_f32_16x16x32_bf16 v[88:91], v[174:177], v[190:193], v[88:91]
	v_mfma_f32_16x16x32_bf16 v[44:47], v[166:169], v[198:201], v[44:47]
	v_mfma_f32_16x16x32_bf16 v[40:43], v[174:177], v[198:201], v[40:43]
	v_mfma_f32_16x16x32_bf16 v[4:7], v[166:169], v[206:209], v[4:7]
	v_mfma_f32_16x16x32_bf16 v[0:3], v[174:177], v[206:209], v[0:3]
	s_barrier
	s_setprio 0
	ds_read_b128 v[146:149], v143
	ds_read_b128 v[150:153], v143 offset:1024
	ds_read_b128 v[154:157], v143 offset:2048
	ds_read_b128 v[158:161], v143 offset:3072
	ds_read_b128 v[162:165], v144
	ds_read_b128 v[166:169], v144 offset:1024
	ds_read_b128 v[170:173], v144 offset:2048
	ds_read_b128 v[174:177], v144 offset:3072
	s_add_u32 s52, s72, 0x4000
	s_addc_u32 s53, s73, 0
	s_mov_b32 m0, s21
	v_lshl_add_u64 v[214:215], s[52:53], 0, v[32:33]
	ds_read_b128 v[178:181], v142 offset:32768
	ds_read_b128 v[182:185], v142 offset:33792
	ds_read_b128 v[186:189], v142 offset:34816
	ds_read_b128 v[190:193], v142 offset:35840
	ds_read_b128 v[194:197], v142 offset:36864
	ds_read_b128 v[198:201], v142 offset:37888
	ds_read_b128 v[202:205], v142 offset:38912
	ds_read_b128 v[206:209], v142 offset:39936
	global_load_lds_dwordx4 v[214:215], off
	v_lshl_add_u64 v[214:215], s[52:53], 0, v[132:133]
	s_mov_b32 m0, s22
	s_nop 0
	global_load_lds_dwordx4 v[214:215], off
	s_waitcnt vmcnt(8) lgkmcnt(0)
	s_setprio 1
	s_barrier
	v_mfma_f32_16x16x32_bf16 v[8:11], v[146:149], v[178:181], v[8:11]
	v_mfma_f32_16x16x32_bf16 v[12:15], v[154:157], v[178:181], v[12:15]
	v_mfma_f32_16x16x32_bf16 v[60:63], v[146:149], v[186:189], v[60:63]
	v_mfma_f32_16x16x32_bf16 v[20:23], v[154:157], v[186:189], v[20:23]
	v_mfma_f32_16x16x32_bf16 v[76:79], v[146:149], v[194:197], v[76:79]
	v_mfma_f32_16x16x32_bf16 v[52:55], v[154:157], v[194:197], v[52:55]
	v_mfma_f32_16x16x32_bf16 v[128:131], v[146:149], v[202:205], v[128:131]
	v_mfma_f32_16x16x32_bf16 v[68:71], v[154:157], v[202:205], v[68:71]
	v_mfma_f32_16x16x32_bf16 v[8:11], v[150:153], v[182:185], v[8:11]
	v_mfma_f32_16x16x32_bf16 v[12:15], v[158:161], v[182:185], v[12:15]
	v_mfma_f32_16x16x32_bf16 v[60:63], v[150:153], v[190:193], v[60:63]
	v_mfma_f32_16x16x32_bf16 v[20:23], v[158:161], v[190:193], v[20:23]
	v_mfma_f32_16x16x32_bf16 v[76:79], v[150:153], v[198:201], v[76:79]
	v_mfma_f32_16x16x32_bf16 v[52:55], v[158:161], v[198:201], v[52:55]
	v_mfma_f32_16x16x32_bf16 v[128:131], v[150:153], v[206:209], v[128:131]
	v_mfma_f32_16x16x32_bf16 v[68:71], v[158:161], v[206:209], v[68:71]
	s_setprio 0
	s_setprio 1
	v_mfma_f32_16x16x32_bf16 v[28:31], v[162:165], v[178:181], v[28:31]
	v_mfma_f32_16x16x32_bf16 v[16:19], v[170:173], v[178:181], v[16:19]
	v_mfma_f32_16x16x32_bf16 v[56:59], v[162:165], v[186:189], v[56:59]
	v_mfma_f32_16x16x32_bf16 v[48:51], v[170:173], v[186:189], v[48:51]
	v_mfma_f32_16x16x32_bf16 v[72:75], v[162:165], v[194:197], v[72:75]
	v_mfma_f32_16x16x32_bf16 v[64:67], v[170:173], v[194:197], v[64:67]
	v_mfma_f32_16x16x32_bf16 v[108:111], v[162:165], v[202:205], v[108:111]
	v_mfma_f32_16x16x32_bf16 v[96:99], v[170:173], v[202:205], v[96:99]
	v_mfma_f32_16x16x32_bf16 v[28:31], v[166:169], v[182:185], v[28:31]
	v_mfma_f32_16x16x32_bf16 v[16:19], v[174:177], v[182:185], v[16:19]
	v_mfma_f32_16x16x32_bf16 v[56:59], v[166:169], v[190:193], v[56:59]
	v_mfma_f32_16x16x32_bf16 v[48:51], v[174:177], v[190:193], v[48:51]
	v_mfma_f32_16x16x32_bf16 v[72:75], v[166:169], v[198:201], v[72:75]
	v_mfma_f32_16x16x32_bf16 v[64:67], v[174:177], v[198:201], v[64:67]
	v_mfma_f32_16x16x32_bf16 v[108:111], v[166:169], v[206:209], v[108:111]
	v_mfma_f32_16x16x32_bf16 v[96:99], v[174:177], v[206:209], v[96:99]
	s_barrier
; #define PG8_WAIT_V(n) asm volatile("s_waitcnt vmcnt(" #n ")" ::: "memory")
; #define PG8_BAR __builtin_amdgcn_s_barrier()
; template <class Epi, class Sched, bool ALIGN_EPI = false, bool SP2 = false, bool A_TILED = false>
; __device__ __forceinline__ void gemm_phase(PG8_LAS unsigned char* lds, const Gemm g, const Sched& S, const Epi& E, const int wave_s) {
;     ...
;     PG8_WAIT_V(0);
;     if constexpr (!ALIGN_EPI) { if (wr == 0) PG8_BAR; }
	s_setprio 0
	s_mov_b32 m0, s48
	v_lshl_add_u64 v[210:211], v[210:211], 0, s[64:65]
	s_add_u32 s52, s70, 0x200080
	ds_read_b128 v[178:181], v142 offset:49152
	ds_read_b128 v[182:185], v142 offset:50176
	ds_read_b128 v[186:189], v142 offset:51200
	ds_read_b128 v[190:193], v142 offset:52224
	ds_read_b128 v[194:197], v142 offset:53248
	ds_read_b128 v[198:201], v142 offset:54272
	ds_read_b128 v[202:205], v142 offset:55296
	ds_read_b128 v[206:209], v142 offset:56320
	global_load_lds_dwordx4 v[210:211], off
	v_lshl_add_u64 v[210:211], v[212:213], 0, s[64:65]
	s_mov_b32 m0, s49
	s_addc_u32 s53, s71, 0
	global_load_lds_dwordx4 v[210:211], off
	v_lshl_add_u64 v[210:211], s[52:53], 0, v[34:35]
	s_mov_b32 m0, s50
	s_nop 0
	global_load_lds_dwordx4 v[210:211], off
	v_lshl_add_u64 v[210:211], s[52:53], 0, v[134:135]
	s_mov_b32 m0, s51
	s_nop 0
	global_load_lds_dwordx4 v[210:211], off
	v_lshl_add_u64 v[210:211], s[68:69], 0, v[32:33]
	s_mov_b32 m0, s23
	s_nop 0
	global_load_lds_dwordx4 v[210:211], off
	v_lshl_add_u64 v[210:211], s[68:69], 0, v[132:133]
	s_mov_b32 m0, s36
	s_nop 0
	global_load_lds_dwordx4 v[210:211], off
	s_waitcnt vmcnt(8) lgkmcnt(0)
	s_setprio 1
	s_barrier
	v_mfma_f32_16x16x32_bf16 v[100:103], v[146:149], v[178:181], v[100:103]
	v_mfma_f32_16x16x32_bf16 v[104:107], v[154:157], v[178:181], v[104:107]
	v_mfma_f32_16x16x32_bf16 v[116:119], v[146:149], v[186:189], v[116:119]
	v_mfma_f32_16x16x32_bf16 v[120:123], v[154:157], v[186:189], v[120:123]
	v_mfma_f32_16x16x32_bf16 v[84:87], v[146:149], v[194:197], v[84:87]
	v_mfma_f32_16x16x32_bf16 v[80:83], v[154:157], v[194:197], v[80:83]
	v_mfma_f32_16x16x32_bf16 v[36:39], v[146:149], v[202:205], v[36:39]
	v_mfma_f32_16x16x32_bf16 v[24:27], v[154:157], v[202:205], v[24:27]
	v_mfma_f32_16x16x32_bf16 v[100:103], v[150:153], v[182:185], v[100:103]
	v_mfma_f32_16x16x32_bf16 v[104:107], v[158:161], v[182:185], v[104:107]
	v_mfma_f32_16x16x32_bf16 v[116:119], v[150:153], v[190:193], v[116:119]
	v_mfma_f32_16x16x32_bf16 v[120:123], v[158:161], v[190:193], v[120:123]
	v_mfma_f32_16x16x32_bf16 v[84:87], v[150:153], v[198:201], v[84:87]
	v_mfma_f32_16x16x32_bf16 v[80:83], v[158:161], v[198:201], v[80:83]
	v_mfma_f32_16x16x32_bf16 v[36:39], v[150:153], v[206:209], v[36:39]
	v_mfma_f32_16x16x32_bf16 v[24:27], v[158:161], v[206:209], v[24:27]
	s_setprio 0
	s_setprio 1
	v_mfma_f32_16x16x32_bf16 v[124:127], v[162:165], v[178:181], v[124:127]
	v_mfma_f32_16x16x32_bf16 v[112:115], v[170:173], v[178:181], v[112:115]
	v_mfma_f32_16x16x32_bf16 v[92:95], v[162:165], v[186:189], v[92:95]
	v_mfma_f32_16x16x32_bf16 v[88:91], v[170:173], v[186:189], v[88:91]
	v_mfma_f32_16x16x32_bf16 v[44:47], v[162:165], v[194:197], v[44:47]
	v_mfma_f32_16x16x32_bf16 v[40:43], v[170:173], v[194:197], v[40:43]
	v_mfma_f32_16x16x32_bf16 v[4:7], v[162:165], v[202:205], v[4:7]
	v_mfma_f32_16x16x32_bf16 v[0:3], v[170:173], v[202:205], v[0:3]
	v_mfma_f32_16x16x32_bf16 v[124:127], v[166:169], v[182:185], v[124:127]
	v_mfma_f32_16x16x32_bf16 v[112:115], v[174:177], v[182:185], v[112:115]
	v_mfma_f32_16x16x32_bf16 v[92:95], v[166:169], v[190:193], v[92:95]
	v_mfma_f32_16x16x32_bf16 v[88:91], v[174:177], v[190:193], v[88:91]
	v_mfma_f32_16x16x32_bf16 v[44:47], v[166:169], v[198:201], v[44:47]
	v_mfma_f32_16x16x32_bf16 v[40:43], v[174:177], v[198:201], v[40:43]
	v_mfma_f32_16x16x32_bf16 v[4:7], v[166:169], v[206:209], v[4:7]
	v_mfma_f32_16x16x32_bf16 v[0:3], v[174:177], v[206:209], v[0:3]
	s_barrier
	s_setprio 0
	s_add_i32 s41, s41, 2
	s_add_u32 s37, s37, 0x100
	s_addc_u32 s38, s38, 0
	s_add_u32 s39, s39, 0x10000
	s_addc_u32 s40, s40, 0
	v_lshl_add_u64 v[136:137], v[136:137], 0, s[66:67]
	s_cmpk_gt_u32 s41, 0x7d
	v_lshl_add_u64 v[138:139], v[138:139], 0, s[66:67]
	s_cbranch_scc0 .LBB0_2026
	s_waitcnt vmcnt(0)
	s_cmpk_lt_u32 s0, 0x100
	s_cbranch_scc0 .LBB0_2029
	s_barrier

; template <class Epi, class Sched, bool ALIGN_EPI = false, bool SP2 = false, bool A_TILED = false>
; __device__ __forceinline__ void gemm_phase(PG8_LAS unsigned char* lds, const Gemm g, const Sched& S, const Epi& E, const int wave_s) {
;     ...
;         const bool has_next = Epi::AFTER_DRAIN ? false : S.next(ui + 1, nxt);
;         const char* nA = has_next ? (const char*)g.A + (size_t)nxt.pm * tstepA : cA; const char* nB = has_next ? (const char*)g.Bt + (size_t)nxt.pn * tstep : cB;
.LBB0_2416:
	s_ashr_i32 s73, s72, 31
	s_lshl_b64 s[50:51], s[72:73], 20
	s_add_u32 s74, s1, s50
	ds_read_b128 v[0:3], v141
	ds_read_b128 v[4:7], v141 offset:1024
	ds_read_b128 v[8:11], v141 offset:2048
	ds_read_b128 v[12:15], v141 offset:3072
	ds_read_b128 v[16:19], v142
	ds_read_b128 v[20:23], v142 offset:1024
	ds_read_b128 v[24:27], v142 offset:2048
	ds_read_b128 v[28:31], v142 offset:3072
	s_addc_u32 s75, s8, s51
	s_ashr_i32 s71, s70, 31
	s_lshl_b64 s[50:51], s[70:71], 20
	s_add_u32 s76, s9, s50
	s_addc_u32 s77, s14, s51
	s_and_b64 s[50:51], s[2:3], exec
	s_cselect_b32 s50, s75, s81
	s_cselect_b32 s51, s74, s80
	s_cselect_b32 s52, s77, s79
	s_cselect_b32 s53, s76, s78
	s_add_u32 s54, s80, 0x80080
	s_addc_u32 s55, s81, 0
	s_mov_b32 m0, s48
	v_lshl_add_u64 v[64:65], s[54:55], 0, v[128:129]
	ds_read_b128 v[32:35], v143
	ds_read_b128 v[36:39], v143 offset:1024
	ds_read_b128 v[40:43], v143 offset:2048
	ds_read_b128 v[44:47], v143 offset:3072
	ds_read_b128 v[48:51], v143 offset:4096
	ds_read_b128 v[52:55], v143 offset:5120
	ds_read_b128 v[56:59], v143 offset:6144
	ds_read_b128 v[60:63], v143 offset:7168
	global_load_lds_dwordx4 v[64:65], off
	v_lshl_add_u64 v[64:65], s[54:55], 0, v[130:131]
	s_mov_b32 m0, s49
	s_nop 0
	global_load_lds_dwordx4 v[64:65], off
	s_waitcnt vmcnt(8) lgkmcnt(0)
	s_setprio 1
	s_barrier
	v_mfma_f32_16x16x32_bf16 v[64:67], v[0:3], v[32:35], 0
	v_mfma_f32_16x16x32_bf16 v[68:71], v[8:11], v[32:35], 0
	v_mfma_f32_16x16x32_bf16 v[72:75], v[0:3], v[40:43], 0
	v_mfma_f32_16x16x32_bf16 v[76:79], v[8:11], v[40:43], 0
	v_mfma_f32_16x16x32_bf16 v[80:83], v[0:3], v[48:51], 0
	v_mfma_f32_16x16x32_bf16 v[84:87], v[8:11], v[48:51], 0
	v_mfma_f32_16x16x32_bf16 v[88:91], v[0:3], v[56:59], 0
	v_mfma_f32_16x16x32_bf16 v[92:95], v[8:11], v[56:59], 0
	v_mfma_f32_16x16x32_bf16 v[64:67], v[4:7], v[36:39], v[64:67]
	v_mfma_f32_16x16x32_bf16 v[68:71], v[12:15], v[36:39], v[68:71]
	v_mfma_f32_16x16x32_bf16 v[72:75], v[4:7], v[44:47], v[72:75]
	v_mfma_f32_16x16x32_bf16 v[76:79], v[12:15], v[44:47], v[76:79]
	v_mfma_f32_16x16x32_bf16 v[80:83], v[4:7], v[52:55], v[80:83]
	v_mfma_f32_16x16x32_bf16 v[84:87], v[12:15], v[52:55], v[84:87]
	v_mfma_f32_16x16x32_bf16 v[88:91], v[4:7], v[60:63], v[88:91]
	v_mfma_f32_16x16x32_bf16 v[92:95], v[12:15], v[60:63], v[92:95]
	s_setprio 0
	s_setprio 1
	v_mfma_f32_16x16x32_bf16 v[96:99], v[16:19], v[32:35], 0
	v_mfma_f32_16x16x32_bf16 v[32:35], v[24:27], v[32:35], 0
	v_mfma_f32_16x16x32_bf16 v[96:99], v[20:23], v[36:39], v[96:99]
	v_mfma_f32_16x16x32_bf16 v[32:35], v[28:31], v[36:39], v[32:35]
	v_mfma_f32_16x16x32_bf16 v[36:39], v[16:19], v[40:43], 0
	v_mfma_f32_16x16x32_bf16 v[40:43], v[24:27], v[40:43], 0
	v_mfma_f32_16x16x32_bf16 v[36:39], v[20:23], v[44:47], v[36:39]
	v_mfma_f32_16x16x32_bf16 v[40:43], v[28:31], v[44:47], v[40:43]
	v_mfma_f32_16x16x32_bf16 v[44:47], v[16:19], v[48:51], 0
	v_mfma_f32_16x16x32_bf16 v[48:51], v[24:27], v[48:51], 0
	v_mfma_f32_16x16x32_bf16 v[100:103], v[28:31], v[52:55], v[48:51]
	v_mfma_f32_16x16x32_bf16 v[48:51], v[16:19], v[56:59], 0
	v_mfma_f32_16x16x32_bf16 v[104:107], v[20:23], v[60:63], v[48:51]
	v_mfma_f32_16x16x32_bf16 v[48:51], v[24:27], v[56:59], 0
	v_mfma_f32_16x16x32_bf16 v[44:47], v[20:23], v[52:55], v[44:47]
	v_mfma_f32_16x16x32_bf16 v[108:111], v[28:31], v[60:63], v[48:51]
	s_barrier
	s_setprio 0
	s_add_i32 s54, s45, s15
	v_lshl_add_u64 v[250:251], s[78:79], 0, v[128:129]
	s_add_i32 s55, s54, 0x2000
	v_lshl_add_u64 v[144:145], v[250:251], 0, s[66:67]
	s_mov_b32 m0, s54
	v_lshl_add_u64 v[252:253], s[78:79], 0, v[130:131]
	s_add_u32 s58, s78, 0x80100
	ds_read_b128 v[48:51], v143 offset:16384
	ds_read_b128 v[52:55], v143 offset:17408
	ds_read_b128 v[56:59], v143 offset:18432
	ds_read_b128 v[60:63], v143 offset:19456
	ds_read_b128 v[112:115], v143 offset:20480
	ds_read_b128 v[116:119], v143 offset:21504
	ds_read_b128 v[120:123], v143 offset:22528
	ds_read_b128 v[124:127], v143 offset:23552
	global_load_lds_dwordx4 v[144:145], off
	v_lshl_add_u64 v[144:145], v[252:253], 0, s[66:67]
	s_mov_b32 m0, s55
	s_addc_u32 s59, s79, 0
	s_add_i32 s56, s46, s15
	global_load_lds_dwordx4 v[144:145], off
	v_lshl_add_u64 v[144:145], s[58:59], 0, v[128:129]
	s_mov_b32 m0, s56
	s_add_i32 s57, s56, 0x2000
	global_load_lds_dwordx4 v[144:145], off
	v_lshl_add_u64 v[144:145], s[58:59], 0, v[130:131]
	s_mov_b32 m0, s57
	v_lshl_add_u64 v[136:137], s[80:81], 0, v[128:129]
	global_load_lds_dwordx4 v[144:145], off
	v_lshl_add_u64 v[144:145], v[136:137], 0, s[66:67]
	s_mov_b32 m0, s22
	v_lshl_add_u64 v[138:139], s[80:81], 0, v[130:131]
	global_load_lds_dwordx4 v[144:145], off
	v_lshl_add_u64 v[144:145], v[138:139], 0, s[66:67]
	s_mov_b32 m0, s23
	s_nop 0
	global_load_lds_dwordx4 v[144:145], off
	s_waitcnt vmcnt(8) lgkmcnt(0)
	s_setprio 1
	s_barrier
	v_mfma_f32_16x16x32_bf16 v[144:147], v[0:3], v[48:51], 0
	v_mfma_f32_16x16x32_bf16 v[154:157], v[0:3], v[56:59], 0
	v_mfma_f32_16x16x32_bf16 v[162:165], v[0:3], v[112:115], 0
	v_mfma_f32_16x16x32_bf16 v[0:3], v[0:3], v[120:123], 0
	v_mfma_f32_16x16x32_bf16 v[150:153], v[8:11], v[48:51], 0
	v_mfma_f32_16x16x32_bf16 v[158:161], v[8:11], v[56:59], 0
	v_mfma_f32_16x16x32_bf16 v[166:169], v[8:11], v[112:115], 0
	v_mfma_f32_16x16x32_bf16 v[170:173], v[4:7], v[124:127], v[0:3]
	v_mfma_f32_16x16x32_bf16 v[0:3], v[8:11], v[120:123], 0
	v_mfma_f32_16x16x32_bf16 v[146:149], v[4:7], v[52:55], v[144:147]
	v_mfma_f32_16x16x32_bf16 v[150:153], v[12:15], v[52:55], v[150:153]
	v_mfma_f32_16x16x32_bf16 v[154:157], v[4:7], v[60:63], v[154:157]
	v_mfma_f32_16x16x32_bf16 v[158:161], v[12:15], v[60:63], v[158:161]
	v_mfma_f32_16x16x32_bf16 v[162:165], v[4:7], v[116:119], v[162:165]
	v_mfma_f32_16x16x32_bf16 v[166:169], v[12:15], v[116:119], v[166:169]
	v_mfma_f32_16x16x32_bf16 v[174:177], v[12:15], v[124:127], v[0:3]
	s_setprio 0
	s_setprio 1
	v_mfma_f32_16x16x32_bf16 v[0:3], v[16:19], v[48:51], 0
	v_mfma_f32_16x16x32_bf16 v[178:181], v[20:23], v[52:55], v[0:3]
	v_mfma_f32_16x16x32_bf16 v[0:3], v[24:27], v[48:51], 0
	v_mfma_f32_16x16x32_bf16 v[182:185], v[28:31], v[52:55], v[0:3]
	v_mfma_f32_16x16x32_bf16 v[0:3], v[16:19], v[56:59], 0
	v_mfma_f32_16x16x32_bf16 v[186:189], v[20:23], v[60:63], v[0:3]
	v_mfma_f32_16x16x32_bf16 v[0:3], v[24:27], v[56:59], 0
	v_mfma_f32_16x16x32_bf16 v[190:193], v[28:31], v[60:63], v[0:3]
	v_mfma_f32_16x16x32_bf16 v[0:3], v[16:19], v[112:115], 0
	v_mfma_f32_16x16x32_bf16 v[194:197], v[20:23], v[116:119], v[0:3]
	v_mfma_f32_16x16x32_bf16 v[0:3], v[24:27], v[112:115], 0
	v_mfma_f32_16x16x32_bf16 v[198:201], v[28:31], v[116:119], v[0:3]
	v_mfma_f32_16x16x32_bf16 v[0:3], v[16:19], v[120:123], 0
	v_mfma_f32_16x16x32_bf16 v[202:205], v[20:23], v[124:127], v[0:3]
	v_mfma_f32_16x16x32_bf16 v[0:3], v[24:27], v[120:123], 0
	v_mfma_f32_16x16x32_bf16 v[206:209], v[28:31], v[124:127], v[0:3]
	s_barrier
	s_setprio 0
	s_add_i32 s61, 0, 0x18000
	s_add_i32 s71, 0, 0x1c000
	v_add_u32_e32 v144, s61, v140
	v_add_u32_e32 v145, s71, v140
	ds_read_b128 v[112:115], v144
	ds_read_b128 v[116:119], v144 offset:1024
	ds_read_b128 v[120:123], v144 offset:2048
	ds_read_b128 v[124:127], v144 offset:3072
	ds_read_b128 v[210:213], v145
	ds_read_b128 v[214:217], v145 offset:1024
	ds_read_b128 v[218:221], v145 offset:2048
	ds_read_b128 v[222:225], v145 offset:3072
	s_add_u32 s58, s80, 0x80100
	s_addc_u32 s59, s81, 0
	s_mov_b32 m0, s36
	v_lshl_add_u64 v[0:1], s[58:59], 0, v[128:129]
	ds_read_b128 v[48:51], v143 offset:32768
	ds_read_b128 v[52:55], v143 offset:33792
	ds_read_b128 v[226:229], v143 offset:34816
	ds_read_b128 v[230:233], v143 offset:35840
	ds_read_b128 v[234:237], v143 offset:36864
	ds_read_b128 v[238:241], v143 offset:37888
	ds_read_b128 v[242:245], v143 offset:38912
	ds_read_b128 v[246:249], v143 offset:39936
	global_load_lds_dwordx4 v[0:1], off
	v_lshl_add_u64 v[0:1], s[58:59], 0, v[130:131]
	s_mov_b32 m0, s37
	s_nop 0
	global_load_lds_dwordx4 v[0:1], off
	s_waitcnt vmcnt(8) lgkmcnt(0)
	s_setprio 1
	s_barrier
	v_mfma_f32_16x16x32_bf16 v[0:3], v[112:115], v[48:51], v[64:67]
	v_mfma_f32_16x16x32_bf16 v[24:27], v[116:119], v[52:55], v[0:3]
	v_mfma_f32_16x16x32_bf16 v[0:3], v[120:123], v[48:51], v[68:71]
	v_mfma_f32_16x16x32_bf16 v[28:31], v[124:127], v[52:55], v[0:3]
	v_mfma_f32_16x16x32_bf16 v[0:3], v[112:115], v[226:229], v[72:75]
	v_mfma_f32_16x16x32_bf16 v[16:19], v[116:119], v[230:233], v[0:3]
	v_mfma_f32_16x16x32_bf16 v[0:3], v[120:123], v[226:229], v[76:79]
	v_mfma_f32_16x16x32_bf16 v[20:23], v[124:127], v[230:233], v[0:3]
	v_mfma_f32_16x16x32_bf16 v[0:3], v[112:115], v[234:237], v[80:83]
	v_mfma_f32_16x16x32_bf16 v[8:11], v[116:119], v[238:241], v[0:3]
	v_mfma_f32_16x16x32_bf16 v[0:3], v[120:123], v[234:237], v[84:87]
	v_mfma_f32_16x16x32_bf16 v[12:15], v[124:127], v[238:241], v[0:3]
	v_mfma_f32_16x16x32_bf16 v[0:3], v[112:115], v[242:245], v[88:91]
	v_mfma_f32_16x16x32_bf16 v[4:7], v[120:123], v[242:245], v[92:95]
	v_mfma_f32_16x16x32_bf16 v[0:3], v[116:119], v[246:249], v[0:3]
	v_mfma_f32_16x16x32_bf16 v[4:7], v[124:127], v[246:249], v[4:7]
	s_setprio 0
	s_setprio 1
	v_mfma_f32_16x16x32_bf16 v[32:35], v[218:221], v[48:51], v[32:35]
	v_mfma_f32_16x16x32_bf16 v[60:63], v[222:225], v[52:55], v[32:35]
	v_mfma_f32_16x16x32_bf16 v[32:35], v[210:213], v[226:229], v[36:39]
	v_mfma_f32_16x16x32_bf16 v[56:59], v[210:213], v[48:51], v[96:99]
	v_mfma_f32_16x16x32_bf16 v[48:51], v[214:217], v[230:233], v[32:35]
	v_mfma_f32_16x16x32_bf16 v[32:35], v[218:221], v[226:229], v[40:43]
	v_mfma_f32_16x16x32_bf16 v[56:59], v[214:217], v[52:55], v[56:59]
	v_mfma_f32_16x16x32_bf16 v[52:55], v[222:225], v[230:233], v[32:35]
	v_mfma_f32_16x16x32_bf16 v[32:35], v[210:213], v[234:237], v[44:47]
	v_mfma_f32_16x16x32_bf16 v[40:43], v[214:217], v[238:241], v[32:35]
	v_mfma_f32_16x16x32_bf16 v[32:35], v[218:221], v[234:237], v[100:103]
	v_mfma_f32_16x16x32_bf16 v[44:47], v[222:225], v[238:241], v[32:35]
	v_mfma_f32_16x16x32_bf16 v[32:35], v[210:213], v[242:245], v[104:107]
	v_mfma_f32_16x16x32_bf16 v[36:39], v[218:221], v[242:245], v[108:111]
	v_mfma_f32_16x16x32_bf16 v[32:35], v[214:217], v[246:249], v[32:35]
	v_mfma_f32_16x16x32_bf16 v[36:39], v[222:225], v[246:249], v[36:39]
	s_barrier
; template <class Epi, class Sched, bool ALIGN_EPI = false, bool SP2 = false, bool A_TILED = false>
; __device__ __forceinline__ void gemm_phase(PG8_LAS unsigned char* lds, const Gemm g, const Sched& S, const Epi& E, const int wave_s) {
;     ...
;         for (int t = PEEL ? 2 : 0; t < nt; t += 2) {
;             const bool last = (t == nt - 2);
;             const char* a1 = cA + (size_t)(t + 1) * kstepA;
;             const char* a2 = last ? nA : cA + (size_t)(t + 2) * kstepA; const char* b2 = last ? nB : cB + (size_t)(t + 2) * kstep;
;             const char* a3 = a2 + kstepA; const char* b3 = b2 + kstep;
	s_setprio 0
	s_add_i32 s58, s61, s15
	s_add_i32 s59, s58, 0x2000
	v_lshl_add_u64 v[64:65], v[250:251], 0, s[68:69]
	s_mov_b32 m0, s58
	s_add_u32 s82, s78, 0x80180
	ds_read_b128 v[96:99], v143 offset:49152
	ds_read_b128 v[100:103], v143 offset:50176
	ds_read_b128 v[104:107], v143 offset:51200
	ds_read_b128 v[108:111], v143 offset:52224
	ds_read_b128 v[226:229], v143 offset:53248
	ds_read_b128 v[230:233], v143 offset:54272
	ds_read_b128 v[234:237], v143 offset:55296
	ds_read_b128 v[238:241], v143 offset:56320
	global_load_lds_dwordx4 v[64:65], off
	v_lshl_add_u64 v[64:65], v[252:253], 0, s[68:69]
	s_mov_b32 m0, s59
	s_addc_u32 s83, s79, 0
	s_add_i32 s61, s71, s15
	global_load_lds_dwordx4 v[64:65], off
	v_lshl_add_u64 v[64:65], s[82:83], 0, v[128:129]
	s_mov_b32 m0, s61
	s_add_i32 s71, s61, 0x2000
	global_load_lds_dwordx4 v[64:65], off
	v_lshl_add_u64 v[64:65], s[82:83], 0, v[130:131]
	s_mov_b32 m0, s71
	s_nop 0
	global_load_lds_dwordx4 v[64:65], off
	v_lshl_add_u64 v[64:65], v[136:137], 0, s[68:69]
	s_mov_b32 m0, s42
	s_nop 0
	global_load_lds_dwordx4 v[64:65], off
	v_lshl_add_u64 v[64:65], v[138:139], 0, s[68:69]
	s_mov_b32 m0, s43
	s_nop 0
	global_load_lds_dwordx4 v[64:65], off
	s_waitcnt vmcnt(8) lgkmcnt(0)
	s_setprio 1
	s_barrier
	v_mfma_f32_16x16x32_bf16 v[64:67], v[112:115], v[96:99], v[146:149]
	v_mfma_f32_16x16x32_bf16 v[88:91], v[116:119], v[100:103], v[64:67]
	v_mfma_f32_16x16x32_bf16 v[64:67], v[120:123], v[96:99], v[150:153]
	v_mfma_f32_16x16x32_bf16 v[92:95], v[124:127], v[100:103], v[64:67]
	v_mfma_f32_16x16x32_bf16 v[64:67], v[112:115], v[104:107], v[154:157]
	v_mfma_f32_16x16x32_bf16 v[80:83], v[116:119], v[108:111], v[64:67]
	v_mfma_f32_16x16x32_bf16 v[64:67], v[120:123], v[104:107], v[158:161]
	v_mfma_f32_16x16x32_bf16 v[84:87], v[124:127], v[108:111], v[64:67]
	v_mfma_f32_16x16x32_bf16 v[64:67], v[112:115], v[226:229], v[162:165]
	v_mfma_f32_16x16x32_bf16 v[72:75], v[116:119], v[230:233], v[64:67]
	v_mfma_f32_16x16x32_bf16 v[64:67], v[120:123], v[226:229], v[166:169]
	v_mfma_f32_16x16x32_bf16 v[76:79], v[124:127], v[230:233], v[64:67]
	v_mfma_f32_16x16x32_bf16 v[64:67], v[112:115], v[234:237], v[170:173]
	v_mfma_f32_16x16x32_bf16 v[68:71], v[120:123], v[234:237], v[174:177]
	v_mfma_f32_16x16x32_bf16 v[64:67], v[116:119], v[238:241], v[64:67]
	v_mfma_f32_16x16x32_bf16 v[68:71], v[124:127], v[238:241], v[68:71]
	s_setprio 0
	s_setprio 1
	v_mfma_f32_16x16x32_bf16 v[112:115], v[210:213], v[96:99], v[178:181]
	v_mfma_f32_16x16x32_bf16 v[96:99], v[218:221], v[96:99], v[182:185]
	v_mfma_f32_16x16x32_bf16 v[124:127], v[222:225], v[100:103], v[96:99]
	v_mfma_f32_16x16x32_bf16 v[96:99], v[210:213], v[104:107], v[186:189]
	v_mfma_f32_16x16x32_bf16 v[120:123], v[214:217], v[100:103], v[112:115]
	v_mfma_f32_16x16x32_bf16 v[112:115], v[214:217], v[108:111], v[96:99]
	v_mfma_f32_16x16x32_bf16 v[96:99], v[218:221], v[104:107], v[190:193]
	v_mfma_f32_16x16x32_bf16 v[116:119], v[222:225], v[108:111], v[96:99]
	v_mfma_f32_16x16x32_bf16 v[96:99], v[210:213], v[226:229], v[194:197]
	v_mfma_f32_16x16x32_bf16 v[104:107], v[214:217], v[230:233], v[96:99]
	v_mfma_f32_16x16x32_bf16 v[96:99], v[218:221], v[226:229], v[198:201]
	v_mfma_f32_16x16x32_bf16 v[108:111], v[222:225], v[230:233], v[96:99]
	v_mfma_f32_16x16x32_bf16 v[96:99], v[210:213], v[234:237], v[202:205]
	v_mfma_f32_16x16x32_bf16 v[100:103], v[218:221], v[234:237], v[206:209]
	v_mfma_f32_16x16x32_bf16 v[96:99], v[214:217], v[238:241], v[96:99]
	v_mfma_f32_16x16x32_bf16 v[100:103], v[222:225], v[238:241], v[100:103]
	s_barrier
	s_setprio 0
	s_add_u32 s73, s78, 0x200
	s_addc_u32 s85, s79, 0
	s_add_u32 s78, s80, 0x80180
	s_addc_u32 s79, s81, 0
	s_mov_b32 s88, 0
.LBB0_2417:
	ds_read_b128 v[146:149], v141
	ds_read_b128 v[150:153], v141 offset:1024
	ds_read_b128 v[154:157], v141 offset:2048
	ds_read_b128 v[158:161], v141 offset:3072
	ds_read_b128 v[162:165], v142
	ds_read_b128 v[166:169], v142 offset:1024
	ds_read_b128 v[170:173], v142 offset:2048
	ds_read_b128 v[174:177], v142 offset:3072
	s_add_u32 s80, s78, 0xfff80080
	s_addc_u32 s81, s79, -1
	s_cmp_eq_u32 s88, 28
	s_cselect_b32 s83, s50, s81
	s_cselect_b32 s82, s51, s80
	s_cselect_b32 s81, s52, s85
	s_cselect_b32 s80, s53, s73
	s_mov_b32 m0, s48
	v_lshl_add_u64 v[136:137], s[78:79], 0, v[134:135]
	ds_read_b128 v[178:181], v143
	ds_read_b128 v[182:185], v143 offset:1024
	ds_read_b128 v[186:189], v143 offset:2048
	ds_read_b128 v[190:193], v143 offset:3072
	ds_read_b128 v[194:197], v143 offset:4096
	ds_read_b128 v[198:201], v143 offset:5120
	ds_read_b128 v[202:205], v143 offset:6144
	ds_read_b128 v[206:209], v143 offset:7168
	global_load_lds_dwordx4 v[136:137], off
	v_lshl_add_u64 v[136:137], s[78:79], 0, v[132:133]
	s_mov_b32 m0, s49
	s_nop 0
	global_load_lds_dwordx4 v[136:137], off
	s_waitcnt vmcnt(8) lgkmcnt(0)
	s_setprio 1
	s_barrier
	v_mfma_f32_16x16x32_bf16 v[24:27], v[146:149], v[178:181], v[24:27]
	v_mfma_f32_16x16x32_bf16 v[28:31], v[154:157], v[178:181], v[28:31]
	v_mfma_f32_16x16x32_bf16 v[16:19], v[146:149], v[186:189], v[16:19]
	v_mfma_f32_16x16x32_bf16 v[20:23], v[154:157], v[186:189], v[20:23]
	v_mfma_f32_16x16x32_bf16 v[8:11], v[146:149], v[194:197], v[8:11]
	v_mfma_f32_16x16x32_bf16 v[12:15], v[154:157], v[194:197], v[12:15]
	v_mfma_f32_16x16x32_bf16 v[0:3], v[146:149], v[202:205], v[0:3]
	v_mfma_f32_16x16x32_bf16 v[4:7], v[154:157], v[202:205], v[4:7]
	v_mfma_f32_16x16x32_bf16 v[24:27], v[150:153], v[182:185], v[24:27]
	v_mfma_f32_16x16x32_bf16 v[28:31], v[158:161], v[182:185], v[28:31]
	v_mfma_f32_16x16x32_bf16 v[16:19], v[150:153], v[190:193], v[16:19]
	v_mfma_f32_16x16x32_bf16 v[20:23], v[158:161], v[190:193], v[20:23]
	v_mfma_f32_16x16x32_bf16 v[8:11], v[150:153], v[198:201], v[8:11]
	v_mfma_f32_16x16x32_bf16 v[12:15], v[158:161], v[198:201], v[12:15]
	v_mfma_f32_16x16x32_bf16 v[0:3], v[150:153], v[206:209], v[0:3]
	v_mfma_f32_16x16x32_bf16 v[4:7], v[158:161], v[206:209], v[4:7]
	s_setprio 0
	s_setprio 1
	v_mfma_f32_16x16x32_bf16 v[56:59], v[162:165], v[178:181], v[56:59]
	v_mfma_f32_16x16x32_bf16 v[60:63], v[170:173], v[178:181], v[60:63]
	v_mfma_f32_16x16x32_bf16 v[48:51], v[162:165], v[186:189], v[48:51]
	v_mfma_f32_16x16x32_bf16 v[52:55], v[170:173], v[186:189], v[52:55]
	v_mfma_f32_16x16x32_bf16 v[40:43], v[162:165], v[194:197], v[40:43]
	v_mfma_f32_16x16x32_bf16 v[44:47], v[170:173], v[194:197], v[44:47]
	v_mfma_f32_16x16x32_bf16 v[32:35], v[162:165], v[202:205], v[32:35]
	v_mfma_f32_16x16x32_bf16 v[36:39], v[170:173], v[202:205], v[36:39]
	v_mfma_f32_16x16x32_bf16 v[56:59], v[166:169], v[182:185], v[56:59]
	v_mfma_f32_16x16x32_bf16 v[60:63], v[174:177], v[182:185], v[60:63]
	v_mfma_f32_16x16x32_bf16 v[48:51], v[166:169], v[190:193], v[48:51]
	v_mfma_f32_16x16x32_bf16 v[52:55], v[174:177], v[190:193], v[52:55]
	v_mfma_f32_16x16x32_bf16 v[40:43], v[166:169], v[198:201], v[40:43]
	v_mfma_f32_16x16x32_bf16 v[44:47], v[174:177], v[198:201], v[44:47]
	v_mfma_f32_16x16x32_bf16 v[32:35], v[166:169], v[206:209], v[32:35]
	v_mfma_f32_16x16x32_bf16 v[36:39], v[174:177], v[206:209], v[36:39]
	s_barrier
	s_setprio 0
	s_mov_b32 m0, s54
	v_lshl_add_u64 v[136:137], s[80:81], 0, v[128:129]
	s_add_u32 s90, s80, 0x80000
	ds_read_b128 v[178:181], v143 offset:16384
	ds_read_b128 v[182:185], v143 offset:17408
	ds_read_b128 v[186:189], v143 offset:18432
	ds_read_b128 v[190:193], v143 offset:19456
	ds_read_b128 v[194:197], v143 offset:20480
	ds_read_b128 v[198:201], v143 offset:21504
	ds_read_b128 v[202:205], v143 offset:22528
	ds_read_b128 v[206:209], v143 offset:23552
	global_load_lds_dwordx4 v[136:137], off
	v_lshl_add_u64 v[138:139], s[80:81], 0, v[130:131]
	s_mov_b32 m0, s55
	s_addc_u32 s91, s81, 0
	global_load_lds_dwordx4 v[138:139], off
	v_lshl_add_u64 v[210:211], s[90:91], 0, v[128:129]
	s_mov_b32 m0, s56
	v_lshl_add_u64 v[212:213], s[82:83], 0, v[130:131]
	global_load_lds_dwordx4 v[210:211], off
	v_lshl_add_u64 v[210:211], s[90:91], 0, v[130:131]
	s_mov_b32 m0, s57
	s_nop 0
	global_load_lds_dwordx4 v[210:211], off
	v_lshl_add_u64 v[210:211], s[82:83], 0, v[128:129]
	s_mov_b32 m0, s22
	s_nop 0
	global_load_lds_dwordx4 v[210:211], off
	s_mov_b32 m0, s23
	s_nop 0
	global_load_lds_dwordx4 v[212:213], off
	s_waitcnt vmcnt(8) lgkmcnt(0)
	s_setprio 1
	s_barrier
	v_mfma_f32_16x16x32_bf16 v[88:91], v[146:149], v[178:181], v[88:91]
	v_mfma_f32_16x16x32_bf16 v[92:95], v[154:157], v[178:181], v[92:95]
	v_mfma_f32_16x16x32_bf16 v[80:83], v[146:149], v[186:189], v[80:83]
	v_mfma_f32_16x16x32_bf16 v[84:87], v[154:157], v[186:189], v[84:87]
	v_mfma_f32_16x16x32_bf16 v[72:75], v[146:149], v[194:197], v[72:75]
	v_mfma_f32_16x16x32_bf16 v[76:79], v[154:157], v[194:197], v[76:79]
	v_mfma_f32_16x16x32_bf16 v[64:67], v[146:149], v[202:205], v[64:67]
	v_mfma_f32_16x16x32_bf16 v[68:71], v[154:157], v[202:205], v[68:71]
	v_mfma_f32_16x16x32_bf16 v[88:91], v[150:153], v[182:185], v[88:91]
	v_mfma_f32_16x16x32_bf16 v[92:95], v[158:161], v[182:185], v[92:95]
	v_mfma_f32_16x16x32_bf16 v[80:83], v[150:153], v[190:193], v[80:83]
	v_mfma_f32_16x16x32_bf16 v[84:87], v[158:161], v[190:193], v[84:87]
	v_mfma_f32_16x16x32_bf16 v[72:75], v[150:153], v[198:201], v[72:75]
	v_mfma_f32_16x16x32_bf16 v[76:79], v[158:161], v[198:201], v[76:79]
	v_mfma_f32_16x16x32_bf16 v[64:67], v[150:153], v[206:209], v[64:67]
	v_mfma_f32_16x16x32_bf16 v[68:71], v[158:161], v[206:209], v[68:71]
	s_setprio 0
	s_setprio 1
	v_mfma_f32_16x16x32_bf16 v[120:123], v[162:165], v[178:181], v[120:123]
	v_mfma_f32_16x16x32_bf16 v[124:127], v[170:173], v[178:181], v[124:127]
	v_mfma_f32_16x16x32_bf16 v[112:115], v[162:165], v[186:189], v[112:115]
	v_mfma_f32_16x16x32_bf16 v[116:119], v[170:173], v[186:189], v[116:119]
	v_mfma_f32_16x16x32_bf16 v[104:107], v[162:165], v[194:197], v[104:107]
	v_mfma_f32_16x16x32_bf16 v[108:111], v[170:173], v[194:197], v[108:111]
	v_mfma_f32_16x16x32_bf16 v[96:99], v[162:165], v[202:205], v[96:99]
	v_mfma_f32_16x16x32_bf16 v[100:103], v[170:173], v[202:205], v[100:103]
	v_mfma_f32_16x16x32_bf16 v[120:123], v[166:169], v[182:185], v[120:123]
	v_mfma_f32_16x16x32_bf16 v[124:127], v[174:177], v[182:185], v[124:127]
	v_mfma_f32_16x16x32_bf16 v[112:115], v[166:169], v[190:193], v[112:115]
	v_mfma_f32_16x16x32_bf16 v[116:119], v[174:177], v[190:193], v[116:119]
	v_mfma_f32_16x16x32_bf16 v[104:107], v[166:169], v[198:201], v[104:107]
	v_mfma_f32_16x16x32_bf16 v[108:111], v[174:177], v[198:201], v[108:111]
	v_mfma_f32_16x16x32_bf16 v[96:99], v[166:169], v[206:209], v[96:99]
	v_mfma_f32_16x16x32_bf16 v[100:103], v[174:177], v[206:209], v[100:103]
	s_barrier
	s_setprio 0
	ds_read_b128 v[146:149], v144
	ds_read_b128 v[150:153], v144 offset:1024
	ds_read_b128 v[154:157], v144 offset:2048
	ds_read_b128 v[158:161], v144 offset:3072
	ds_read_b128 v[162:165], v145
	ds_read_b128 v[166:169], v145 offset:1024
	ds_read_b128 v[170:173], v145 offset:2048
	ds_read_b128 v[174:177], v145 offset:3072
	s_add_u32 s82, s82, 0x80000
	s_addc_u32 s83, s83, 0
	s_mov_b32 m0, s36
	v_lshl_add_u64 v[214:215], s[82:83], 0, v[128:129]
	ds_read_b128 v[178:181], v143 offset:32768
	ds_read_b128 v[182:185], v143 offset:33792
	ds_read_b128 v[186:189], v143 offset:34816
	ds_read_b128 v[190:193], v143 offset:35840
	ds_read_b128 v[194:197], v143 offset:36864
	ds_read_b128 v[198:201], v143 offset:37888
	ds_read_b128 v[202:205], v143 offset:38912
	ds_read_b128 v[206:209], v143 offset:39936
	global_load_lds_dwordx4 v[214:215], off
	v_lshl_add_u64 v[214:215], s[82:83], 0, v[130:131]
	s_mov_b32 m0, s37
	s_nop 0
	global_load_lds_dwordx4 v[214:215], off
	s_waitcnt vmcnt(8) lgkmcnt(0)
	s_setprio 1
	s_barrier
	v_mfma_f32_16x16x32_bf16 v[24:27], v[146:149], v[178:181], v[24:27]
	v_mfma_f32_16x16x32_bf16 v[28:31], v[154:157], v[178:181], v[28:31]
	v_mfma_f32_16x16x32_bf16 v[16:19], v[146:149], v[186:189], v[16:19]
	v_mfma_f32_16x16x32_bf16 v[20:23], v[154:157], v[186:189], v[20:23]
	v_mfma_f32_16x16x32_bf16 v[8:11], v[146:149], v[194:197], v[8:11]
	v_mfma_f32_16x16x32_bf16 v[12:15], v[154:157], v[194:197], v[12:15]
	v_mfma_f32_16x16x32_bf16 v[0:3], v[146:149], v[202:205], v[0:3]
	v_mfma_f32_16x16x32_bf16 v[4:7], v[154:157], v[202:205], v[4:7]
	v_mfma_f32_16x16x32_bf16 v[24:27], v[150:153], v[182:185], v[24:27]
	v_mfma_f32_16x16x32_bf16 v[28:31], v[158:161], v[182:185], v[28:31]
	v_mfma_f32_16x16x32_bf16 v[16:19], v[150:153], v[190:193], v[16:19]
	v_mfma_f32_16x16x32_bf16 v[20:23], v[158:161], v[190:193], v[20:23]
	v_mfma_f32_16x16x32_bf16 v[8:11], v[150:153], v[198:201], v[8:11]
	v_mfma_f32_16x16x32_bf16 v[12:15], v[158:161], v[198:201], v[12:15]
	v_mfma_f32_16x16x32_bf16 v[0:3], v[150:153], v[206:209], v[0:3]
	v_mfma_f32_16x16x32_bf16 v[4:7], v[158:161], v[206:209], v[4:7]
	s_setprio 0
	s_setprio 1
	v_mfma_f32_16x16x32_bf16 v[56:59], v[162:165], v[178:181], v[56:59]
	v_mfma_f32_16x16x32_bf16 v[60:63], v[170:173], v[178:181], v[60:63]
	v_mfma_f32_16x16x32_bf16 v[48:51], v[162:165], v[186:189], v[48:51]
	v_mfma_f32_16x16x32_bf16 v[52:55], v[170:173], v[186:189], v[52:55]
	v_mfma_f32_16x16x32_bf16 v[40:43], v[162:165], v[194:197], v[40:43]
	v_mfma_f32_16x16x32_bf16 v[44:47], v[170:173], v[194:197], v[44:47]
	v_mfma_f32_16x16x32_bf16 v[32:35], v[162:165], v[202:205], v[32:35]
	v_mfma_f32_16x16x32_bf16 v[36:39], v[170:173], v[202:205], v[36:39]
	v_mfma_f32_16x16x32_bf16 v[56:59], v[166:169], v[182:185], v[56:59]
	v_mfma_f32_16x16x32_bf16 v[60:63], v[174:177], v[182:185], v[60:63]
	v_mfma_f32_16x16x32_bf16 v[48:51], v[166:169], v[190:193], v[48:51]
	v_mfma_f32_16x16x32_bf16 v[52:55], v[174:177], v[190:193], v[52:55]
	v_mfma_f32_16x16x32_bf16 v[40:43], v[166:169], v[198:201], v[40:43]
	v_mfma_f32_16x16x32_bf16 v[44:47], v[174:177], v[198:201], v[44:47]
	v_mfma_f32_16x16x32_bf16 v[32:35], v[166:169], v[206:209], v[32:35]
	v_mfma_f32_16x16x32_bf16 v[36:39], v[174:177], v[206:209], v[36:39]
	s_barrier
	s_setprio 0
	s_mov_b32 m0, s58
	v_lshl_add_u64 v[136:137], v[136:137], 0, s[62:63]
	s_add_u32 s80, s80, 0x80080
	ds_read_b128 v[178:181], v143 offset:49152
	ds_read_b128 v[182:185], v143 offset:50176
	ds_read_b128 v[186:189], v143 offset:51200
	ds_read_b128 v[190:193], v143 offset:52224
	ds_read_b128 v[194:197], v143 offset:53248
	ds_read_b128 v[198:201], v143 offset:54272
	ds_read_b128 v[202:205], v143 offset:55296
	ds_read_b128 v[206:209], v143 offset:56320
	global_load_lds_dwordx4 v[136:137], off
	v_lshl_add_u64 v[136:137], v[138:139], 0, s[62:63]
	s_mov_b32 m0, s59
	s_addc_u32 s81, s81, 0
	global_load_lds_dwordx4 v[136:137], off
	v_lshl_add_u64 v[136:137], s[80:81], 0, v[128:129]
	s_mov_b32 m0, s61
	s_nop 0
	global_load_lds_dwordx4 v[136:137], off
	v_lshl_add_u64 v[136:137], s[80:81], 0, v[130:131]
	s_mov_b32 m0, s71
	s_nop 0
	global_load_lds_dwordx4 v[136:137], off
	v_lshl_add_u64 v[136:137], v[210:211], 0, s[62:63]
	s_mov_b32 m0, s42
	s_nop 0
	global_load_lds_dwordx4 v[136:137], off
	v_lshl_add_u64 v[136:137], v[212:213], 0, s[62:63]
	s_mov_b32 m0, s43
	s_nop 0
	global_load_lds_dwordx4 v[136:137], off
	s_waitcnt vmcnt(8) lgkmcnt(0)
	s_setprio 1
	s_barrier
	v_mfma_f32_16x16x32_bf16 v[88:91], v[146:149], v[178:181], v[88:91]
	v_mfma_f32_16x16x32_bf16 v[92:95], v[154:157], v[178:181], v[92:95]
	v_mfma_f32_16x16x32_bf16 v[80:83], v[146:149], v[186:189], v[80:83]
	v_mfma_f32_16x16x32_bf16 v[84:87], v[154:157], v[186:189], v[84:87]
	v_mfma_f32_16x16x32_bf16 v[72:75], v[146:149], v[194:197], v[72:75]
	v_mfma_f32_16x16x32_bf16 v[76:79], v[154:157], v[194:197], v[76:79]
	v_mfma_f32_16x16x32_bf16 v[64:67], v[146:149], v[202:205], v[64:67]
	v_mfma_f32_16x16x32_bf16 v[68:71], v[154:157], v[202:205], v[68:71]
	v_mfma_f32_16x16x32_bf16 v[88:91], v[150:153], v[182:185], v[88:91]
	v_mfma_f32_16x16x32_bf16 v[92:95], v[158:161], v[182:185], v[92:95]
	v_mfma_f32_16x16x32_bf16 v[80:83], v[150:153], v[190:193], v[80:83]
	v_mfma_f32_16x16x32_bf16 v[84:87], v[158:161], v[190:193], v[84:87]
	v_mfma_f32_16x16x32_bf16 v[72:75], v[150:153], v[198:201], v[72:75]
	v_mfma_f32_16x16x32_bf16 v[76:79], v[158:161], v[198:201], v[76:79]
	v_mfma_f32_16x16x32_bf16 v[64:67], v[150:153], v[206:209], v[64:67]
	v_mfma_f32_16x16x32_bf16 v[68:71], v[158:161], v[206:209], v[68:71]
	s_setprio 0
	s_setprio 1
	v_mfma_f32_16x16x32_bf16 v[120:123], v[162:165], v[178:181], v[120:123]
	v_mfma_f32_16x16x32_bf16 v[124:127], v[170:173], v[178:181], v[124:127]
	v_mfma_f32_16x16x32_bf16 v[112:115], v[162:165], v[186:189], v[112:115]
	v_mfma_f32_16x16x32_bf16 v[116:119], v[170:173], v[186:189], v[116:119]
	v_mfma_f32_16x16x32_bf16 v[104:107], v[162:165], v[194:197], v[104:107]
	v_mfma_f32_16x16x32_bf16 v[108:111], v[170:173], v[194:197], v[108:111]
	v_mfma_f32_16x16x32_bf16 v[96:99], v[162:165], v[202:205], v[96:99]
	v_mfma_f32_16x16x32_bf16 v[100:103], v[170:173], v[202:205], v[100:103]
	v_mfma_f32_16x16x32_bf16 v[120:123], v[166:169], v[182:185], v[120:123]
	v_mfma_f32_16x16x32_bf16 v[124:127], v[174:177], v[182:185], v[124:127]
	v_mfma_f32_16x16x32_bf16 v[112:115], v[166:169], v[190:193], v[112:115]
	v_mfma_f32_16x16x32_bf16 v[116:119], v[174:177], v[190:193], v[116:119]
	v_mfma_f32_16x16x32_bf16 v[104:107], v[166:169], v[198:201], v[104:107]
	v_mfma_f32_16x16x32_bf16 v[108:111], v[174:177], v[198:201], v[108:111]
	v_mfma_f32_16x16x32_bf16 v[96:99], v[166:169], v[206:209], v[96:99]
	v_mfma_f32_16x16x32_bf16 v[100:103], v[174:177], v[206:209], v[100:103]
	s_barrier
	s_setprio 0
	s_add_i32 s88, s88, 2
	s_add_u32 s73, s73, 0x100
	s_addc_u32 s85, s85, 0
	s_add_u32 s78, s78, 0x100
	s_addc_u32 s79, s79, 0
	s_cmp_gt_u32 s88, 29
	s_cbranch_scc0 .LBB0_2417
	s_and_b64 vcc, exec, s[64:65]
	s_cbranch_vccz .LBB0_2420
	s_barrier

; template <class Epi, class Sched, bool ALIGN_EPI = false, bool SP2 = false, bool A_TILED = false>
; __device__ __forceinline__ void gemm_phase(PG8_LAS unsigned char* lds, const Gemm g, const Sched& S, const Epi& E, const int wave_s) {
;     ...
;         const bool has_next = Epi::AFTER_DRAIN ? false : S.next(ui + 1, nxt);
;         const char* nA = has_next ? (const char*)g.A + (size_t)nxt.pm * tstepA : cA; const char* nB = has_next ? (const char*)g.Bt + (size_t)nxt.pn * tstep : cB;
.LBB0_2545:
	s_ashr_i32 s73, s72, 31
	s_lshl_b64 s[58:59], s[72:73], 18
	s_add_u32 s74, s14, s58
	ds_read_b128 v[0:3], v149
	ds_read_b128 v[4:7], v149 offset:1024
	ds_read_b128 v[8:11], v149 offset:2048
	ds_read_b128 v[12:15], v149 offset:3072
	ds_read_b128 v[16:19], v150
	ds_read_b128 v[20:23], v150 offset:1024
	ds_read_b128 v[24:27], v150 offset:2048
	ds_read_b128 v[28:31], v150 offset:3072
	s_addc_u32 s75, s15, s59
	s_ashr_i32 s71, s70, 31
	s_lshl_b64 s[58:59], s[70:71], 18
	s_add_u32 s76, s23, s58
	s_addc_u32 s77, s36, s59
	s_and_b64 s[58:59], s[2:3], exec
	s_cselect_b32 s58, s75, s81
	s_cselect_b32 s59, s74, s80
	s_cselect_b32 s71, s77, s79
	s_cselect_b32 s73, s76, s78
	s_add_u32 s82, s80, 0x20080
	s_addc_u32 s83, s81, 0
	s_add_i32 s88, s38, 0xc000
	v_lshl_add_u64 v[64:65], s[82:83], 0, v[134:135]
	s_mov_b32 m0, s88
	s_add_i32 s89, s38, 0xe000
	ds_read_b128 v[32:35], v151
	ds_read_b128 v[36:39], v151 offset:1024
	ds_read_b128 v[40:43], v151 offset:2048
	ds_read_b128 v[44:47], v151 offset:3072
	ds_read_b128 v[48:51], v151 offset:4096
	ds_read_b128 v[52:55], v151 offset:5120
	ds_read_b128 v[56:59], v151 offset:6144
	ds_read_b128 v[60:63], v151 offset:7168
	global_load_lds_dwordx4 v[64:65], off
	v_lshl_add_u64 v[64:65], s[82:83], 0, v[132:133]
	s_mov_b32 m0, s89
	s_nop 0
	global_load_lds_dwordx4 v[64:65], off
	s_waitcnt vmcnt(8) lgkmcnt(0)
	s_setprio 1
	s_barrier
	v_mfma_f32_16x16x32_bf16 v[88:91], v[0:3], v[56:59], 0
	v_mfma_f32_16x16x32_bf16 v[64:67], v[0:3], v[32:35], 0
	v_mfma_f32_16x16x32_bf16 v[68:71], v[8:11], v[32:35], 0
	v_mfma_f32_16x16x32_bf16 v[72:75], v[0:3], v[40:43], 0
	v_mfma_f32_16x16x32_bf16 v[76:79], v[8:11], v[40:43], 0
	v_mfma_f32_16x16x32_bf16 v[80:83], v[0:3], v[48:51], 0
	v_mfma_f32_16x16x32_bf16 v[84:87], v[8:11], v[48:51], 0
	v_mfma_f32_16x16x32_bf16 v[96:99], v[4:7], v[60:63], v[88:91]
	v_mfma_f32_16x16x32_bf16 v[88:91], v[8:11], v[56:59], 0
	v_mfma_f32_16x16x32_bf16 v[64:67], v[4:7], v[36:39], v[64:67]
	v_mfma_f32_16x16x32_bf16 v[68:71], v[12:15], v[36:39], v[68:71]
	v_mfma_f32_16x16x32_bf16 v[72:75], v[4:7], v[44:47], v[72:75]
	v_mfma_f32_16x16x32_bf16 v[76:79], v[12:15], v[44:47], v[76:79]
	v_mfma_f32_16x16x32_bf16 v[80:83], v[4:7], v[52:55], v[80:83]
	v_mfma_f32_16x16x32_bf16 v[84:87], v[12:15], v[52:55], v[84:87]
	v_mfma_f32_16x16x32_bf16 v[100:103], v[12:15], v[60:63], v[88:91]
	s_setprio 0
	s_setprio 1
	v_mfma_f32_16x16x32_bf16 v[88:91], v[16:19], v[32:35], 0
	v_mfma_f32_16x16x32_bf16 v[32:35], v[24:27], v[32:35], 0
	v_mfma_f32_16x16x32_bf16 v[112:115], v[20:23], v[36:39], v[88:91]
	v_mfma_f32_16x16x32_bf16 v[32:35], v[28:31], v[36:39], v[32:35]
	v_mfma_f32_16x16x32_bf16 v[36:39], v[16:19], v[40:43], 0
	v_mfma_f32_16x16x32_bf16 v[40:43], v[24:27], v[40:43], 0
	v_mfma_f32_16x16x32_bf16 v[36:39], v[20:23], v[44:47], v[36:39]
	v_mfma_f32_16x16x32_bf16 v[40:43], v[28:31], v[44:47], v[40:43]
	v_mfma_f32_16x16x32_bf16 v[44:47], v[16:19], v[48:51], 0
	v_mfma_f32_16x16x32_bf16 v[48:51], v[24:27], v[48:51], 0
	v_mfma_f32_16x16x32_bf16 v[44:47], v[20:23], v[52:55], v[44:47]
	v_mfma_f32_16x16x32_bf16 v[48:51], v[28:31], v[52:55], v[48:51]
	v_mfma_f32_16x16x32_bf16 v[52:55], v[16:19], v[56:59], 0
	v_mfma_f32_16x16x32_bf16 v[56:59], v[24:27], v[56:59], 0
	v_mfma_f32_16x16x32_bf16 v[52:55], v[20:23], v[60:63], v[52:55]
	v_mfma_f32_16x16x32_bf16 v[56:59], v[28:31], v[60:63], v[56:59]
	s_barrier
	s_setprio 0
	s_add_i32 s90, s53, s37
	v_lshl_add_u64 v[250:251], s[78:79], 0, v[128:129]
	s_add_i32 s91, s90, 0x2000
	v_lshl_add_u64 v[144:145], v[250:251], 0, s[66:67]
	s_mov_b32 m0, s90
	v_lshl_add_u64 v[252:253], s[78:79], 0, v[130:131]
	s_add_u32 s82, s78, 0x20100
	ds_read_b128 v[60:63], v151 offset:16384
	ds_read_b128 v[88:91], v151 offset:17408
	ds_read_b128 v[92:95], v151 offset:18432
	ds_read_b128 v[104:107], v151 offset:19456
	ds_read_b128 v[108:111], v151 offset:20480
	ds_read_b128 v[116:119], v151 offset:21504
	ds_read_b128 v[120:123], v151 offset:22528
	ds_read_b128 v[124:127], v151 offset:23552
	global_load_lds_dwordx4 v[144:145], off
	v_lshl_add_u64 v[144:145], v[252:253], 0, s[66:67]
	s_mov_b32 m0, s91
	s_addc_u32 s83, s79, 0
	s_add_i32 s93, s54, s37
	global_load_lds_dwordx4 v[144:145], off
	v_lshl_add_u64 v[144:145], s[82:83], 0, v[128:129]
	s_mov_b32 m0, s93
	s_add_i32 s95, s93, 0x2000
	global_load_lds_dwordx4 v[144:145], off
	v_lshl_add_u64 v[144:145], s[82:83], 0, v[130:131]
	s_mov_b32 m0, s95
	v_lshl_add_u64 v[140:141], s[80:81], 0, v[134:135]
	global_load_lds_dwordx4 v[144:145], off
	v_lshl_add_u64 v[144:145], v[140:141], 0, s[66:67]
	s_mov_b32 m0, s38
	v_lshl_add_u64 v[142:143], s[80:81], 0, v[132:133]
	global_load_lds_dwordx4 v[144:145], off
	v_lshl_add_u64 v[144:145], v[142:143], 0, s[66:67]
	s_mov_b32 m0, s39
	s_nop 0
	global_load_lds_dwordx4 v[144:145], off
	s_waitcnt vmcnt(8) lgkmcnt(0)
	s_setprio 1
	s_barrier
	v_mfma_f32_16x16x32_bf16 v[144:147], v[0:3], v[60:63], 0
	v_mfma_f32_16x16x32_bf16 v[154:157], v[4:7], v[88:91], v[144:147]
	v_mfma_f32_16x16x32_bf16 v[144:147], v[8:11], v[60:63], 0
	v_mfma_f32_16x16x32_bf16 v[158:161], v[12:15], v[88:91], v[144:147]
	v_mfma_f32_16x16x32_bf16 v[144:147], v[0:3], v[92:95], 0
	v_mfma_f32_16x16x32_bf16 v[162:165], v[4:7], v[104:107], v[144:147]
	v_mfma_f32_16x16x32_bf16 v[144:147], v[8:11], v[92:95], 0
	v_mfma_f32_16x16x32_bf16 v[166:169], v[12:15], v[104:107], v[144:147]
	v_mfma_f32_16x16x32_bf16 v[144:147], v[0:3], v[108:111], 0
	v_mfma_f32_16x16x32_bf16 v[0:3], v[0:3], v[120:123], 0
	v_mfma_f32_16x16x32_bf16 v[170:173], v[4:7], v[116:119], v[144:147]
	v_mfma_f32_16x16x32_bf16 v[0:3], v[4:7], v[124:127], v[0:3]
	v_mfma_f32_16x16x32_bf16 v[4:7], v[8:11], v[120:123], 0
	v_mfma_f32_16x16x32_bf16 v[144:147], v[8:11], v[108:111], 0
	v_mfma_f32_16x16x32_bf16 v[4:7], v[12:15], v[124:127], v[4:7]
	v_mfma_f32_16x16x32_bf16 v[174:177], v[12:15], v[116:119], v[144:147]
	s_setprio 0
	s_setprio 1
	v_mfma_f32_16x16x32_bf16 v[8:11], v[16:19], v[60:63], 0
	v_mfma_f32_16x16x32_bf16 v[178:181], v[20:23], v[88:91], v[8:11]
	v_mfma_f32_16x16x32_bf16 v[8:11], v[24:27], v[60:63], 0
	v_mfma_f32_16x16x32_bf16 v[182:185], v[28:31], v[88:91], v[8:11]
	v_mfma_f32_16x16x32_bf16 v[8:11], v[16:19], v[92:95], 0
	v_mfma_f32_16x16x32_bf16 v[186:189], v[20:23], v[104:107], v[8:11]
	v_mfma_f32_16x16x32_bf16 v[8:11], v[24:27], v[92:95], 0
	v_mfma_f32_16x16x32_bf16 v[190:193], v[28:31], v[104:107], v[8:11]
	v_mfma_f32_16x16x32_bf16 v[8:11], v[16:19], v[108:111], 0
	v_mfma_f32_16x16x32_bf16 v[194:197], v[20:23], v[116:119], v[8:11]
	v_mfma_f32_16x16x32_bf16 v[8:11], v[24:27], v[108:111], 0
	v_mfma_f32_16x16x32_bf16 v[198:201], v[28:31], v[116:119], v[8:11]
	v_mfma_f32_16x16x32_bf16 v[8:11], v[16:19], v[120:123], 0
	v_mfma_f32_16x16x32_bf16 v[202:205], v[20:23], v[124:127], v[8:11]
	v_mfma_f32_16x16x32_bf16 v[8:11], v[24:27], v[120:123], 0
	v_mfma_f32_16x16x32_bf16 v[206:209], v[28:31], v[124:127], v[8:11]
	s_barrier
	s_setprio 0
	s_add_i32 s96, 0, 0x18000
	s_add_i32 vcc_lo, 0, 0x1c000
	v_add_u32_e32 v144, s96, v148
	v_add_u32_e32 v145, vcc_lo, v148
	s_nop 0
	ds_read_b128 v[8:11], v144
	ds_read_b128 v[12:15], v144 offset:1024
	ds_read_b128 v[16:19], v144 offset:2048
	ds_read_b128 v[20:23], v144 offset:3072
	ds_read_b128 v[210:213], v145
	ds_read_b128 v[214:217], v145 offset:1024
	ds_read_b128 v[218:221], v145 offset:2048
	ds_read_b128 v[222:225], v145 offset:3072
	s_add_u32 s82, s80, 0x20100
	s_addc_u32 s83, s81, 0
	s_mov_b32 m0, s40
	v_lshl_add_u64 v[88:89], s[82:83], 0, v[134:135]
	ds_read_b128 v[24:27], v151 offset:32768
	ds_read_b128 v[28:31], v151 offset:33792
	ds_read_b128 v[60:63], v151 offset:34816
	ds_read_b128 v[226:229], v151 offset:35840
	ds_read_b128 v[230:233], v151 offset:36864
	ds_read_b128 v[234:237], v151 offset:37888
	ds_read_b128 v[238:241], v151 offset:38912
	ds_read_b128 v[242:245], v151 offset:39936
	global_load_lds_dwordx4 v[88:89], off
	v_lshl_add_u64 v[88:89], s[82:83], 0, v[132:133]
	s_mov_b32 m0, s41
	s_nop 0
	global_load_lds_dwordx4 v[88:89], off
	s_waitcnt vmcnt(8) lgkmcnt(0)
	s_setprio 1
	s_barrier
	v_mfma_f32_16x16x32_bf16 v[64:67], v[8:11], v[24:27], v[64:67]
	v_mfma_f32_16x16x32_bf16 v[124:127], v[12:15], v[28:31], v[64:67]
	v_mfma_f32_16x16x32_bf16 v[64:67], v[16:19], v[24:27], v[68:71]
	v_mfma_f32_16x16x32_bf16 v[120:123], v[20:23], v[28:31], v[64:67]
	v_mfma_f32_16x16x32_bf16 v[64:67], v[8:11], v[60:63], v[72:75]
	v_mfma_f32_16x16x32_bf16 v[108:111], v[12:15], v[226:229], v[64:67]
	v_mfma_f32_16x16x32_bf16 v[64:67], v[16:19], v[60:63], v[76:79]
	v_mfma_f32_16x16x32_bf16 v[104:107], v[20:23], v[226:229], v[64:67]
	v_mfma_f32_16x16x32_bf16 v[64:67], v[8:11], v[230:233], v[80:83]
	v_mfma_f32_16x16x32_bf16 v[92:95], v[12:15], v[234:237], v[64:67]
	v_mfma_f32_16x16x32_bf16 v[64:67], v[16:19], v[230:233], v[84:87]
	v_mfma_f32_16x16x32_bf16 v[88:91], v[20:23], v[234:237], v[64:67]
	v_mfma_f32_16x16x32_bf16 v[64:67], v[8:11], v[238:241], v[96:99]
	v_mfma_f32_16x16x32_bf16 v[76:79], v[12:15], v[242:245], v[64:67]
	v_mfma_f32_16x16x32_bf16 v[64:67], v[16:19], v[238:241], v[100:103]
	v_mfma_f32_16x16x32_bf16 v[72:75], v[20:23], v[242:245], v[64:67]
	s_setprio 0
	s_setprio 1
	v_mfma_f32_16x16x32_bf16 v[64:67], v[210:213], v[24:27], v[112:115]
	v_mfma_f32_16x16x32_bf16 v[24:27], v[218:221], v[24:27], v[32:35]
	v_mfma_f32_16x16x32_bf16 v[112:115], v[222:225], v[28:31], v[24:27]
	v_mfma_f32_16x16x32_bf16 v[24:27], v[210:213], v[60:63], v[36:39]
	v_mfma_f32_16x16x32_bf16 v[100:103], v[214:217], v[226:229], v[24:27]
	v_mfma_f32_16x16x32_bf16 v[24:27], v[218:221], v[60:63], v[40:43]
	v_mfma_f32_16x16x32_bf16 v[96:99], v[222:225], v[226:229], v[24:27]
	v_mfma_f32_16x16x32_bf16 v[24:27], v[210:213], v[230:233], v[44:47]
	v_mfma_f32_16x16x32_bf16 v[84:87], v[214:217], v[234:237], v[24:27]
	v_mfma_f32_16x16x32_bf16 v[24:27], v[218:221], v[230:233], v[48:51]
	v_mfma_f32_16x16x32_bf16 v[80:83], v[222:225], v[234:237], v[24:27]
	v_mfma_f32_16x16x32_bf16 v[24:27], v[210:213], v[238:241], v[52:55]
	v_mfma_f32_16x16x32_bf16 v[68:71], v[214:217], v[242:245], v[24:27]
	v_mfma_f32_16x16x32_bf16 v[24:27], v[218:221], v[238:241], v[56:59]
	v_mfma_f32_16x16x32_bf16 v[116:119], v[214:217], v[28:31], v[64:67]
	v_mfma_f32_16x16x32_bf16 v[64:67], v[222:225], v[242:245], v[24:27]
	s_barrier
; template <class Epi, class Sched, bool ALIGN_EPI = false, bool SP2 = false, bool A_TILED = false>
; __device__ __forceinline__ void gemm_phase(PG8_LAS unsigned char* lds, const Gemm g, const Sched& S, const Epi& E, const int wave_s) {
;     ...
;         for (int t = PEEL ? 2 : 0; t < nt; t += 2) {
;             const bool last = (t == nt - 2);
;             const char* a1 = cA + (size_t)(t + 1) * kstepA;
;             const char* a2 = last ? nA : cA + (size_t)(t + 2) * kstepA; const char* b2 = last ? nB : cB + (size_t)(t + 2) * kstep;
;             const char* a3 = a2 + kstepA; const char* b3 = b2 + kstep;
	s_setprio 0
	s_add_i32 s96, s96, s37
	s_add_i32 s97, s96, 0x2000
	s_nop 1
	v_lshl_add_u64 v[24:25], v[250:251], 0, s[68:69]
	s_mov_b32 m0, s96
	s_add_u32 s82, s78, 0x20180
	ds_read_b128 v[32:35], v151 offset:49152
	ds_read_b128 v[36:39], v151 offset:50176
	ds_read_b128 v[226:229], v151 offset:51200
	ds_read_b128 v[230:233], v151 offset:52224
	ds_read_b128 v[234:237], v151 offset:53248
	ds_read_b128 v[238:241], v151 offset:54272
	ds_read_b128 v[242:245], v151 offset:55296
	ds_read_b128 v[246:249], v151 offset:56320
	global_load_lds_dwordx4 v[24:25], off
	v_lshl_add_u64 v[24:25], v[252:253], 0, s[68:69]
	s_mov_b32 m0, s97
	s_addc_u32 s83, s79, 0
	s_add_i32 vcc_lo, vcc_lo, s37
	global_load_lds_dwordx4 v[24:25], off
	v_lshl_add_u64 v[24:25], s[82:83], 0, v[128:129]
	s_mov_b32 m0, vcc_lo
	s_add_i32 vcc_hi, vcc_lo, 0x2000
	global_load_lds_dwordx4 v[24:25], off
	v_lshl_add_u64 v[24:25], s[82:83], 0, v[130:131]
	s_mov_b32 m0, vcc_hi
	s_nop 0
	global_load_lds_dwordx4 v[24:25], off
	v_lshl_add_u64 v[24:25], v[140:141], 0, s[68:69]
	s_mov_b32 m0, s51
	s_nop 0
	global_load_lds_dwordx4 v[24:25], off
	v_lshl_add_u64 v[24:25], v[142:143], 0, s[68:69]
	s_mov_b32 m0, s52
	s_nop 0
	global_load_lds_dwordx4 v[24:25], off
	s_waitcnt vmcnt(8) lgkmcnt(0)
	s_setprio 1
	s_barrier
	v_mfma_f32_16x16x32_bf16 v[24:27], v[8:11], v[32:35], v[154:157]
	v_mfma_f32_16x16x32_bf16 v[60:63], v[12:15], v[36:39], v[24:27]
	v_mfma_f32_16x16x32_bf16 v[24:27], v[16:19], v[32:35], v[158:161]
	v_mfma_f32_16x16x32_bf16 v[56:59], v[20:23], v[36:39], v[24:27]
	v_mfma_f32_16x16x32_bf16 v[24:27], v[8:11], v[226:229], v[162:165]
	v_mfma_f32_16x16x32_bf16 v[44:47], v[12:15], v[230:233], v[24:27]
	v_mfma_f32_16x16x32_bf16 v[24:27], v[16:19], v[226:229], v[166:169]
	v_mfma_f32_16x16x32_bf16 v[40:43], v[20:23], v[230:233], v[24:27]
	v_mfma_f32_16x16x32_bf16 v[24:27], v[8:11], v[234:237], v[170:173]
	v_mfma_f32_16x16x32_bf16 v[0:3], v[8:11], v[242:245], v[0:3]
	v_mfma_f32_16x16x32_bf16 v[28:31], v[12:15], v[238:241], v[24:27]
	v_mfma_f32_16x16x32_bf16 v[24:27], v[16:19], v[234:237], v[174:177]
	v_mfma_f32_16x16x32_bf16 v[12:15], v[12:15], v[246:249], v[0:3]
	v_mfma_f32_16x16x32_bf16 v[0:3], v[16:19], v[242:245], v[4:7]
	v_mfma_f32_16x16x32_bf16 v[24:27], v[20:23], v[238:241], v[24:27]
	v_mfma_f32_16x16x32_bf16 v[8:11], v[20:23], v[246:249], v[0:3]
	s_setprio 0
	s_setprio 1
	v_mfma_f32_16x16x32_bf16 v[0:3], v[210:213], v[32:35], v[178:181]
	v_mfma_f32_16x16x32_bf16 v[52:55], v[214:217], v[36:39], v[0:3]
	v_mfma_f32_16x16x32_bf16 v[0:3], v[218:221], v[32:35], v[182:185]
	v_mfma_f32_16x16x32_bf16 v[48:51], v[222:225], v[36:39], v[0:3]
	v_mfma_f32_16x16x32_bf16 v[0:3], v[210:213], v[226:229], v[186:189]
	v_mfma_f32_16x16x32_bf16 v[36:39], v[214:217], v[230:233], v[0:3]
	v_mfma_f32_16x16x32_bf16 v[0:3], v[218:221], v[226:229], v[190:193]
	v_mfma_f32_16x16x32_bf16 v[32:35], v[222:225], v[230:233], v[0:3]
	v_mfma_f32_16x16x32_bf16 v[0:3], v[210:213], v[234:237], v[194:197]
	v_mfma_f32_16x16x32_bf16 v[20:23], v[214:217], v[238:241], v[0:3]
	v_mfma_f32_16x16x32_bf16 v[0:3], v[218:221], v[234:237], v[198:201]
	v_mfma_f32_16x16x32_bf16 v[16:19], v[222:225], v[238:241], v[0:3]
	v_mfma_f32_16x16x32_bf16 v[0:3], v[210:213], v[242:245], v[202:205]
	v_mfma_f32_16x16x32_bf16 v[4:7], v[214:217], v[246:249], v[0:3]
	v_mfma_f32_16x16x32_bf16 v[0:3], v[218:221], v[242:245], v[206:209]
	v_mfma_f32_16x16x32_bf16 v[0:3], v[222:225], v[246:249], v[0:3]
	s_barrier
	s_setprio 0
	s_add_u32 s85, s78, 0x200
	s_addc_u32 s8, s79, 0
	s_add_u32 s78, s80, 0x20180
	s_addc_u32 s79, s81, 0
	s_mov_b32 s94, 0
.LBB0_2546:
	ds_read_b128 v[154:157], v149
	ds_read_b128 v[158:161], v149 offset:1024
	ds_read_b128 v[162:165], v149 offset:2048
	ds_read_b128 v[166:169], v149 offset:3072
	ds_read_b128 v[170:173], v150
	ds_read_b128 v[174:177], v150 offset:1024
	ds_read_b128 v[178:181], v150 offset:2048
	ds_read_b128 v[182:185], v150 offset:3072
	s_add_u32 s44, s78, 0xfffe0080
	s_addc_u32 s45, s79, -1
	s_cmp_eq_u32 s94, 4
	s_cselect_b32 s83, s58, s45
	s_cselect_b32 s82, s59, s44
	s_cselect_b32 s81, s71, s8
	s_cselect_b32 s80, s73, s85
	s_mov_b32 m0, s88
	v_lshl_add_u64 v[140:141], s[78:79], 0, v[138:139]
	ds_read_b128 v[186:189], v151
	ds_read_b128 v[190:193], v151 offset:1024
	ds_read_b128 v[194:197], v151 offset:2048
	ds_read_b128 v[198:201], v151 offset:3072
	ds_read_b128 v[202:205], v151 offset:4096
	ds_read_b128 v[206:209], v151 offset:5120
	ds_read_b128 v[210:213], v151 offset:6144
	ds_read_b128 v[214:217], v151 offset:7168
	global_load_lds_dwordx4 v[140:141], off
	v_lshl_add_u64 v[140:141], s[78:79], 0, v[136:137]
	s_mov_b32 m0, s89
	s_nop 0
	global_load_lds_dwordx4 v[140:141], off
	s_waitcnt vmcnt(8) lgkmcnt(0)
	s_setprio 1
	s_barrier
	v_mfma_f32_16x16x32_bf16 v[124:127], v[154:157], v[186:189], v[124:127]
	v_mfma_f32_16x16x32_bf16 v[120:123], v[162:165], v[186:189], v[120:123]
	v_mfma_f32_16x16x32_bf16 v[108:111], v[154:157], v[194:197], v[108:111]
	v_mfma_f32_16x16x32_bf16 v[104:107], v[162:165], v[194:197], v[104:107]
	v_mfma_f32_16x16x32_bf16 v[92:95], v[154:157], v[202:205], v[92:95]
	v_mfma_f32_16x16x32_bf16 v[88:91], v[162:165], v[202:205], v[88:91]
	v_mfma_f32_16x16x32_bf16 v[76:79], v[154:157], v[210:213], v[76:79]
	v_mfma_f32_16x16x32_bf16 v[72:75], v[162:165], v[210:213], v[72:75]
	v_mfma_f32_16x16x32_bf16 v[124:127], v[158:161], v[190:193], v[124:127]
	v_mfma_f32_16x16x32_bf16 v[120:123], v[166:169], v[190:193], v[120:123]
	v_mfma_f32_16x16x32_bf16 v[108:111], v[158:161], v[198:201], v[108:111]
	v_mfma_f32_16x16x32_bf16 v[104:107], v[166:169], v[198:201], v[104:107]
	v_mfma_f32_16x16x32_bf16 v[92:95], v[158:161], v[206:209], v[92:95]
	v_mfma_f32_16x16x32_bf16 v[88:91], v[166:169], v[206:209], v[88:91]
	v_mfma_f32_16x16x32_bf16 v[76:79], v[158:161], v[214:217], v[76:79]
	v_mfma_f32_16x16x32_bf16 v[72:75], v[166:169], v[214:217], v[72:75]
	s_setprio 0
	s_setprio 1
	v_mfma_f32_16x16x32_bf16 v[116:119], v[170:173], v[186:189], v[116:119]
	v_mfma_f32_16x16x32_bf16 v[112:115], v[178:181], v[186:189], v[112:115]
	v_mfma_f32_16x16x32_bf16 v[100:103], v[170:173], v[194:197], v[100:103]
	v_mfma_f32_16x16x32_bf16 v[96:99], v[178:181], v[194:197], v[96:99]
	v_mfma_f32_16x16x32_bf16 v[84:87], v[170:173], v[202:205], v[84:87]
	v_mfma_f32_16x16x32_bf16 v[80:83], v[178:181], v[202:205], v[80:83]
	v_mfma_f32_16x16x32_bf16 v[68:71], v[170:173], v[210:213], v[68:71]
	v_mfma_f32_16x16x32_bf16 v[64:67], v[178:181], v[210:213], v[64:67]
	v_mfma_f32_16x16x32_bf16 v[116:119], v[174:177], v[190:193], v[116:119]
	v_mfma_f32_16x16x32_bf16 v[112:115], v[182:185], v[190:193], v[112:115]
	v_mfma_f32_16x16x32_bf16 v[100:103], v[174:177], v[198:201], v[100:103]
	v_mfma_f32_16x16x32_bf16 v[96:99], v[182:185], v[198:201], v[96:99]
	v_mfma_f32_16x16x32_bf16 v[84:87], v[174:177], v[206:209], v[84:87]
	v_mfma_f32_16x16x32_bf16 v[80:83], v[182:185], v[206:209], v[80:83]
	v_mfma_f32_16x16x32_bf16 v[68:71], v[174:177], v[214:217], v[68:71]
	v_mfma_f32_16x16x32_bf16 v[64:67], v[182:185], v[214:217], v[64:67]
	s_barrier
	s_setprio 0
	s_mov_b32 m0, s90
	v_lshl_add_u64 v[140:141], s[80:81], 0, v[128:129]
	s_add_u32 s44, s80, 0x20000
	ds_read_b128 v[186:189], v151 offset:16384
	ds_read_b128 v[190:193], v151 offset:17408
	ds_read_b128 v[194:197], v151 offset:18432
	ds_read_b128 v[198:201], v151 offset:19456
	ds_read_b128 v[202:205], v151 offset:20480
	ds_read_b128 v[206:209], v151 offset:21504
	ds_read_b128 v[210:213], v151 offset:22528
	ds_read_b128 v[214:217], v151 offset:23552
	global_load_lds_dwordx4 v[140:141], off
	v_lshl_add_u64 v[142:143], s[80:81], 0, v[130:131]
	s_mov_b32 m0, s91
	s_addc_u32 s45, s81, 0
	global_load_lds_dwordx4 v[142:143], off
	v_lshl_add_u64 v[146:147], s[44:45], 0, v[128:129]
	s_mov_b32 m0, s93
	v_lshl_add_u64 v[218:219], s[82:83], 0, v[132:133]
	global_load_lds_dwordx4 v[146:147], off
	v_lshl_add_u64 v[146:147], s[44:45], 0, v[130:131]
	s_mov_b32 m0, s95
	s_nop 0
	global_load_lds_dwordx4 v[146:147], off
	v_lshl_add_u64 v[146:147], s[82:83], 0, v[134:135]
	s_mov_b32 m0, s38
	s_nop 0
	global_load_lds_dwordx4 v[146:147], off
	s_mov_b32 m0, s39
	s_nop 0
	global_load_lds_dwordx4 v[218:219], off
	s_waitcnt vmcnt(8) lgkmcnt(0)
	s_setprio 1
	s_barrier
	v_mfma_f32_16x16x32_bf16 v[60:63], v[154:157], v[186:189], v[60:63]
	v_mfma_f32_16x16x32_bf16 v[56:59], v[162:165], v[186:189], v[56:59]
	v_mfma_f32_16x16x32_bf16 v[44:47], v[154:157], v[194:197], v[44:47]
	v_mfma_f32_16x16x32_bf16 v[40:43], v[162:165], v[194:197], v[40:43]
	v_mfma_f32_16x16x32_bf16 v[28:31], v[154:157], v[202:205], v[28:31]
	v_mfma_f32_16x16x32_bf16 v[24:27], v[162:165], v[202:205], v[24:27]
	v_mfma_f32_16x16x32_bf16 v[12:15], v[154:157], v[210:213], v[12:15]
	v_mfma_f32_16x16x32_bf16 v[8:11], v[162:165], v[210:213], v[8:11]
	v_mfma_f32_16x16x32_bf16 v[60:63], v[158:161], v[190:193], v[60:63]
	v_mfma_f32_16x16x32_bf16 v[56:59], v[166:169], v[190:193], v[56:59]
	v_mfma_f32_16x16x32_bf16 v[44:47], v[158:161], v[198:201], v[44:47]
	v_mfma_f32_16x16x32_bf16 v[40:43], v[166:169], v[198:201], v[40:43]
	v_mfma_f32_16x16x32_bf16 v[28:31], v[158:161], v[206:209], v[28:31]
	v_mfma_f32_16x16x32_bf16 v[24:27], v[166:169], v[206:209], v[24:27]
	v_mfma_f32_16x16x32_bf16 v[12:15], v[158:161], v[214:217], v[12:15]
	v_mfma_f32_16x16x32_bf16 v[8:11], v[166:169], v[214:217], v[8:11]
	s_setprio 0
	s_setprio 1
	v_mfma_f32_16x16x32_bf16 v[52:55], v[170:173], v[186:189], v[52:55]
	v_mfma_f32_16x16x32_bf16 v[48:51], v[178:181], v[186:189], v[48:51]
	v_mfma_f32_16x16x32_bf16 v[36:39], v[170:173], v[194:197], v[36:39]
	v_mfma_f32_16x16x32_bf16 v[32:35], v[178:181], v[194:197], v[32:35]
	v_mfma_f32_16x16x32_bf16 v[20:23], v[170:173], v[202:205], v[20:23]
	v_mfma_f32_16x16x32_bf16 v[16:19], v[178:181], v[202:205], v[16:19]
	v_mfma_f32_16x16x32_bf16 v[4:7], v[170:173], v[210:213], v[4:7]
	v_mfma_f32_16x16x32_bf16 v[0:3], v[178:181], v[210:213], v[0:3]
	v_mfma_f32_16x16x32_bf16 v[52:55], v[174:177], v[190:193], v[52:55]
	v_mfma_f32_16x16x32_bf16 v[48:51], v[182:185], v[190:193], v[48:51]
	v_mfma_f32_16x16x32_bf16 v[36:39], v[174:177], v[198:201], v[36:39]
	v_mfma_f32_16x16x32_bf16 v[32:35], v[182:185], v[198:201], v[32:35]
	v_mfma_f32_16x16x32_bf16 v[20:23], v[174:177], v[206:209], v[20:23]
	v_mfma_f32_16x16x32_bf16 v[16:19], v[182:185], v[206:209], v[16:19]
	v_mfma_f32_16x16x32_bf16 v[4:7], v[174:177], v[214:217], v[4:7]
	v_mfma_f32_16x16x32_bf16 v[0:3], v[182:185], v[214:217], v[0:3]
	s_barrier
	s_setprio 0
	ds_read_b128 v[154:157], v144
	ds_read_b128 v[158:161], v144 offset:1024
	ds_read_b128 v[162:165], v144 offset:2048
	ds_read_b128 v[166:169], v144 offset:3072
	ds_read_b128 v[170:173], v145
	ds_read_b128 v[174:177], v145 offset:1024
	ds_read_b128 v[178:181], v145 offset:2048
	ds_read_b128 v[182:185], v145 offset:3072
	s_add_u32 s44, s82, 0x20000
	s_addc_u32 s45, s83, 0
	s_mov_b32 m0, s40
	v_lshl_add_u64 v[220:221], s[44:45], 0, v[134:135]
	ds_read_b128 v[186:189], v151 offset:32768
	ds_read_b128 v[190:193], v151 offset:33792
	ds_read_b128 v[194:197], v151 offset:34816
	ds_read_b128 v[198:201], v151 offset:35840
	ds_read_b128 v[202:205], v151 offset:36864
	ds_read_b128 v[206:209], v151 offset:37888
	ds_read_b128 v[210:213], v151 offset:38912
	ds_read_b128 v[214:217], v151 offset:39936
	global_load_lds_dwordx4 v[220:221], off
	v_lshl_add_u64 v[220:221], s[44:45], 0, v[132:133]
	s_mov_b32 m0, s41
	s_nop 0
	global_load_lds_dwordx4 v[220:221], off
	s_waitcnt vmcnt(8) lgkmcnt(0)
	s_setprio 1
	s_barrier
	v_mfma_f32_16x16x32_bf16 v[124:127], v[154:157], v[186:189], v[124:127]
	v_mfma_f32_16x16x32_bf16 v[120:123], v[162:165], v[186:189], v[120:123]
	v_mfma_f32_16x16x32_bf16 v[108:111], v[154:157], v[194:197], v[108:111]
	v_mfma_f32_16x16x32_bf16 v[104:107], v[162:165], v[194:197], v[104:107]
	v_mfma_f32_16x16x32_bf16 v[92:95], v[154:157], v[202:205], v[92:95]
	v_mfma_f32_16x16x32_bf16 v[88:91], v[162:165], v[202:205], v[88:91]
	v_mfma_f32_16x16x32_bf16 v[76:79], v[154:157], v[210:213], v[76:79]
	v_mfma_f32_16x16x32_bf16 v[72:75], v[162:165], v[210:213], v[72:75]
	v_mfma_f32_16x16x32_bf16 v[124:127], v[158:161], v[190:193], v[124:127]
	v_mfma_f32_16x16x32_bf16 v[120:123], v[166:169], v[190:193], v[120:123]
	v_mfma_f32_16x16x32_bf16 v[108:111], v[158:161], v[198:201], v[108:111]
	v_mfma_f32_16x16x32_bf16 v[104:107], v[166:169], v[198:201], v[104:107]
	v_mfma_f32_16x16x32_bf16 v[92:95], v[158:161], v[206:209], v[92:95]
	v_mfma_f32_16x16x32_bf16 v[88:91], v[166:169], v[206:209], v[88:91]
	v_mfma_f32_16x16x32_bf16 v[76:79], v[158:161], v[214:217], v[76:79]
	v_mfma_f32_16x16x32_bf16 v[72:75], v[166:169], v[214:217], v[72:75]
	s_setprio 0
	s_setprio 1
	v_mfma_f32_16x16x32_bf16 v[116:119], v[170:173], v[186:189], v[116:119]
	v_mfma_f32_16x16x32_bf16 v[112:115], v[178:181], v[186:189], v[112:115]
	v_mfma_f32_16x16x32_bf16 v[100:103], v[170:173], v[194:197], v[100:103]
	v_mfma_f32_16x16x32_bf16 v[96:99], v[178:181], v[194:197], v[96:99]
	v_mfma_f32_16x16x32_bf16 v[84:87], v[170:173], v[202:205], v[84:87]
	v_mfma_f32_16x16x32_bf16 v[80:83], v[178:181], v[202:205], v[80:83]
	v_mfma_f32_16x16x32_bf16 v[68:71], v[170:173], v[210:213], v[68:71]
	v_mfma_f32_16x16x32_bf16 v[64:67], v[178:181], v[210:213], v[64:67]
	v_mfma_f32_16x16x32_bf16 v[116:119], v[174:177], v[190:193], v[116:119]
	v_mfma_f32_16x16x32_bf16 v[112:115], v[182:185], v[190:193], v[112:115]
	v_mfma_f32_16x16x32_bf16 v[100:103], v[174:177], v[198:201], v[100:103]
	v_mfma_f32_16x16x32_bf16 v[96:99], v[182:185], v[198:201], v[96:99]
	v_mfma_f32_16x16x32_bf16 v[84:87], v[174:177], v[206:209], v[84:87]
	v_mfma_f32_16x16x32_bf16 v[80:83], v[182:185], v[206:209], v[80:83]
	v_mfma_f32_16x16x32_bf16 v[68:71], v[174:177], v[214:217], v[68:71]
	v_mfma_f32_16x16x32_bf16 v[64:67], v[182:185], v[214:217], v[64:67]
	s_barrier
	s_setprio 0
	s_mov_b32 m0, s96
	v_lshl_add_u64 v[140:141], v[140:141], 0, s[62:63]
	s_add_u32 s44, s80, 0x20080
	ds_read_b128 v[186:189], v151 offset:49152
	ds_read_b128 v[190:193], v151 offset:50176
	ds_read_b128 v[194:197], v151 offset:51200
	ds_read_b128 v[198:201], v151 offset:52224
	ds_read_b128 v[202:205], v151 offset:53248
	ds_read_b128 v[206:209], v151 offset:54272
	ds_read_b128 v[210:213], v151 offset:55296
	ds_read_b128 v[214:217], v151 offset:56320
	global_load_lds_dwordx4 v[140:141], off
	v_lshl_add_u64 v[140:141], v[142:143], 0, s[62:63]
	s_mov_b32 m0, s97
	s_addc_u32 s45, s81, 0
	global_load_lds_dwordx4 v[140:141], off
	v_lshl_add_u64 v[140:141], s[44:45], 0, v[128:129]
	s_mov_b32 m0, vcc_lo
	s_nop 0
	global_load_lds_dwordx4 v[140:141], off
	v_lshl_add_u64 v[140:141], s[44:45], 0, v[130:131]
	s_mov_b32 m0, vcc_hi
	s_nop 0
	global_load_lds_dwordx4 v[140:141], off
	v_lshl_add_u64 v[140:141], v[146:147], 0, s[62:63]
	s_mov_b32 m0, s51
	s_nop 0
	global_load_lds_dwordx4 v[140:141], off
	v_lshl_add_u64 v[140:141], v[218:219], 0, s[62:63]
	s_mov_b32 m0, s52
	s_nop 0
	global_load_lds_dwordx4 v[140:141], off
	s_waitcnt vmcnt(8) lgkmcnt(0)
	s_setprio 1
	s_barrier
	v_mfma_f32_16x16x32_bf16 v[60:63], v[154:157], v[186:189], v[60:63]
	v_mfma_f32_16x16x32_bf16 v[56:59], v[162:165], v[186:189], v[56:59]
	v_mfma_f32_16x16x32_bf16 v[44:47], v[154:157], v[194:197], v[44:47]
	v_mfma_f32_16x16x32_bf16 v[40:43], v[162:165], v[194:197], v[40:43]
	v_mfma_f32_16x16x32_bf16 v[28:31], v[154:157], v[202:205], v[28:31]
	v_mfma_f32_16x16x32_bf16 v[24:27], v[162:165], v[202:205], v[24:27]
	v_mfma_f32_16x16x32_bf16 v[12:15], v[154:157], v[210:213], v[12:15]
	v_mfma_f32_16x16x32_bf16 v[8:11], v[162:165], v[210:213], v[8:11]
	v_mfma_f32_16x16x32_bf16 v[60:63], v[158:161], v[190:193], v[60:63]
	v_mfma_f32_16x16x32_bf16 v[56:59], v[166:169], v[190:193], v[56:59]
	v_mfma_f32_16x16x32_bf16 v[44:47], v[158:161], v[198:201], v[44:47]
	v_mfma_f32_16x16x32_bf16 v[40:43], v[166:169], v[198:201], v[40:43]
	v_mfma_f32_16x16x32_bf16 v[28:31], v[158:161], v[206:209], v[28:31]
	v_mfma_f32_16x16x32_bf16 v[24:27], v[166:169], v[206:209], v[24:27]
	v_mfma_f32_16x16x32_bf16 v[12:15], v[158:161], v[214:217], v[12:15]
	v_mfma_f32_16x16x32_bf16 v[8:11], v[166:169], v[214:217], v[8:11]
	s_setprio 0
	s_setprio 1
	v_mfma_f32_16x16x32_bf16 v[52:55], v[170:173], v[186:189], v[52:55]
	v_mfma_f32_16x16x32_bf16 v[48:51], v[178:181], v[186:189], v[48:51]
	v_mfma_f32_16x16x32_bf16 v[36:39], v[170:173], v[194:197], v[36:39]
	v_mfma_f32_16x16x32_bf16 v[32:35], v[178:181], v[194:197], v[32:35]
	v_mfma_f32_16x16x32_bf16 v[20:23], v[170:173], v[202:205], v[20:23]
	v_mfma_f32_16x16x32_bf16 v[16:19], v[178:181], v[202:205], v[16:19]
	v_mfma_f32_16x16x32_bf16 v[4:7], v[170:173], v[210:213], v[4:7]
	v_mfma_f32_16x16x32_bf16 v[0:3], v[178:181], v[210:213], v[0:3]
	v_mfma_f32_16x16x32_bf16 v[52:55], v[174:177], v[190:193], v[52:55]
	v_mfma_f32_16x16x32_bf16 v[48:51], v[182:185], v[190:193], v[48:51]
	v_mfma_f32_16x16x32_bf16 v[36:39], v[174:177], v[198:201], v[36:39]
	v_mfma_f32_16x16x32_bf16 v[32:35], v[182:185], v[198:201], v[32:35]
	v_mfma_f32_16x16x32_bf16 v[20:23], v[174:177], v[206:209], v[20:23]
	v_mfma_f32_16x16x32_bf16 v[16:19], v[182:185], v[206:209], v[16:19]
	v_mfma_f32_16x16x32_bf16 v[4:7], v[174:177], v[214:217], v[4:7]
	v_mfma_f32_16x16x32_bf16 v[0:3], v[182:185], v[214:217], v[0:3]
	s_barrier
	s_setprio 0
	s_add_i32 s94, s94, 2
	s_add_u32 s85, s85, 0x100
	s_addc_u32 s8, s8, 0
	s_add_u32 s78, s78, 0x100
	s_addc_u32 s79, s79, 0
	s_cmp_gt_u32 s94, 5
	s_cbranch_scc0 .LBB0_2546
	s_and_b64 vcc, exec, s[64:65]
	s_cbranch_vccz .LBB0_2549
	s_barrier

; template <class Epi, class Sched, bool ALIGN_EPI = false, bool SP2 = false, bool A_TILED = false>
; __device__ __forceinline__ void gemm_phase(PG8_LAS unsigned char* lds, const Gemm g, const Sched& S, const Epi& E, const int wave_s) {
;     ...
;         const bool has_next = Epi::AFTER_DRAIN ? false : S.next(ui + 1, nxt);
;         const char* nA = has_next ? (const char*)g.A + (size_t)nxt.pm * tstepA : cA; const char* nB = has_next ? (const char*)g.Bt + (size_t)nxt.pn * tstep : cB;
.LBB0_2565:
	s_ashr_i32 s67, s66, 31
	ds_read_b128 v[0:3], v147
	ds_read_b128 v[4:7], v147 offset:1024
	ds_read_b128 v[8:11], v147 offset:2048
	ds_read_b128 v[12:15], v147 offset:3072
	ds_read_b128 v[16:19], v148
	ds_read_b128 v[20:23], v148 offset:1024
	ds_read_b128 v[24:27], v148 offset:2048
	ds_read_b128 v[28:31], v148 offset:3072
	s_lshl_b64 s[52:53], s[66:67], 18
	s_add_u32 s68, s8, s52
	s_addc_u32 s69, s14, s53
	s_and_b64 s[52:53], s[2:3], exec
	s_cselect_b32 s51, s69, s77
	s_cselect_b32 s52, s68, s76
	s_ashr_i32 s65, s64, 31
	s_lshl_b64 s[54:55], s[64:65], 18
	s_add_u32 s72, s15, s54
	s_addc_u32 s73, s23, s55
	s_and_b64 s[54:55], s[2:3], exec
	s_cselect_b32 s53, s73, s75
	s_cselect_b32 s54, s72, s74
	s_add_u32 s56, s76, 0x20080
	s_addc_u32 s57, s77, 0
	s_add_i32 s55, s0, 0xc000
	v_lshl_add_u64 v[64:65], s[56:57], 0, v[134:135]
	s_mov_b32 m0, s55
	ds_read_b128 v[32:35], v149
	ds_read_b128 v[36:39], v149 offset:1024
	ds_read_b128 v[40:43], v149 offset:2048
	ds_read_b128 v[44:47], v149 offset:3072
	ds_read_b128 v[48:51], v149 offset:4096
	ds_read_b128 v[52:55], v149 offset:5120
	ds_read_b128 v[56:59], v149 offset:6144
	ds_read_b128 v[60:63], v149 offset:7168
	global_load_lds_dwordx4 v[64:65], off
	v_lshl_add_u64 v[64:65], s[56:57], 0, v[132:133]
	s_add_i32 s56, s0, 0xe000
	s_mov_b32 m0, s56
	s_nop 0
	global_load_lds_dwordx4 v[64:65], off
	s_waitcnt vmcnt(8) lgkmcnt(0)
	s_setprio 1
	s_barrier
	v_mfma_f32_16x16x32_bf16 v[88:91], v[0:3], v[56:59], 0
	v_mfma_f32_16x16x32_bf16 v[64:67], v[0:3], v[32:35], 0
	v_mfma_f32_16x16x32_bf16 v[68:71], v[8:11], v[32:35], 0
	v_mfma_f32_16x16x32_bf16 v[72:75], v[0:3], v[40:43], 0
	v_mfma_f32_16x16x32_bf16 v[76:79], v[8:11], v[40:43], 0
	v_mfma_f32_16x16x32_bf16 v[80:83], v[0:3], v[48:51], 0
	v_mfma_f32_16x16x32_bf16 v[84:87], v[8:11], v[48:51], 0
	v_mfma_f32_16x16x32_bf16 v[92:95], v[4:7], v[60:63], v[88:91]
	v_mfma_f32_16x16x32_bf16 v[88:91], v[8:11], v[56:59], 0
	v_mfma_f32_16x16x32_bf16 v[64:67], v[4:7], v[36:39], v[64:67]
	v_mfma_f32_16x16x32_bf16 v[68:71], v[12:15], v[36:39], v[68:71]
	v_mfma_f32_16x16x32_bf16 v[72:75], v[4:7], v[44:47], v[72:75]
	v_mfma_f32_16x16x32_bf16 v[76:79], v[12:15], v[44:47], v[76:79]
	v_mfma_f32_16x16x32_bf16 v[80:83], v[4:7], v[52:55], v[80:83]
	v_mfma_f32_16x16x32_bf16 v[84:87], v[12:15], v[52:55], v[84:87]
	v_mfma_f32_16x16x32_bf16 v[100:103], v[12:15], v[60:63], v[88:91]
	s_setprio 0
	s_setprio 1
	v_mfma_f32_16x16x32_bf16 v[88:91], v[16:19], v[32:35], 0
	v_mfma_f32_16x16x32_bf16 v[32:35], v[24:27], v[32:35], 0
	v_mfma_f32_16x16x32_bf16 v[108:111], v[20:23], v[36:39], v[88:91]
	v_mfma_f32_16x16x32_bf16 v[32:35], v[28:31], v[36:39], v[32:35]
	v_mfma_f32_16x16x32_bf16 v[36:39], v[16:19], v[40:43], 0
	v_mfma_f32_16x16x32_bf16 v[40:43], v[24:27], v[40:43], 0
	v_mfma_f32_16x16x32_bf16 v[36:39], v[20:23], v[44:47], v[36:39]
	v_mfma_f32_16x16x32_bf16 v[40:43], v[28:31], v[44:47], v[40:43]
	v_mfma_f32_16x16x32_bf16 v[44:47], v[16:19], v[48:51], 0
	v_mfma_f32_16x16x32_bf16 v[48:51], v[24:27], v[48:51], 0
	v_mfma_f32_16x16x32_bf16 v[44:47], v[20:23], v[52:55], v[44:47]
	v_mfma_f32_16x16x32_bf16 v[52:55], v[28:31], v[52:55], v[48:51]
	v_mfma_f32_16x16x32_bf16 v[48:51], v[16:19], v[56:59], 0
	v_mfma_f32_16x16x32_bf16 v[150:153], v[20:23], v[60:63], v[48:51]
	v_mfma_f32_16x16x32_bf16 v[48:51], v[24:27], v[56:59], 0
	v_mfma_f32_16x16x32_bf16 v[154:157], v[28:31], v[60:63], v[48:51]
	s_barrier
	s_setprio 0
	s_add_i32 s57, s48, s36
	v_lshl_add_u64 v[250:251], s[74:75], 0, v[128:129]
	s_add_i32 s58, s57, 0x2000
	v_lshl_add_u64 v[120:121], v[250:251], 0, s[60:61]
	s_mov_b32 m0, s57
	v_lshl_add_u64 v[252:253], s[74:75], 0, v[130:131]
	s_add_u32 s78, s74, 0x20100
	ds_read_b128 v[48:51], v149 offset:16384
	ds_read_b128 v[56:59], v149 offset:17408
	ds_read_b128 v[60:63], v149 offset:18432
	ds_read_b128 v[88:91], v149 offset:19456
	ds_read_b128 v[96:99], v149 offset:20480
	ds_read_b128 v[104:107], v149 offset:21504
	ds_read_b128 v[112:115], v149 offset:22528
	ds_read_b128 v[116:119], v149 offset:23552
	global_load_lds_dwordx4 v[120:121], off
	v_lshl_add_u64 v[120:121], v[252:253], 0, s[60:61]
	s_mov_b32 m0, s58
	s_addc_u32 s79, s75, 0
	s_add_i32 s59, s49, s36
	global_load_lds_dwordx4 v[120:121], off
	v_lshl_add_u64 v[120:121], s[78:79], 0, v[128:129]
	s_mov_b32 m0, s59
	s_add_i32 s65, s59, 0x2000
	global_load_lds_dwordx4 v[120:121], off
	v_lshl_add_u64 v[120:121], s[78:79], 0, v[130:131]
	s_mov_b32 m0, s65
	v_lshl_add_u64 v[140:141], s[76:77], 0, v[134:135]
	global_load_lds_dwordx4 v[120:121], off
	v_lshl_add_u64 v[120:121], v[140:141], 0, s[60:61]
	s_mov_b32 m0, s0
	v_lshl_add_u64 v[142:143], s[76:77], 0, v[132:133]
	global_load_lds_dwordx4 v[120:121], off
	v_lshl_add_u64 v[120:121], v[142:143], 0, s[60:61]
	s_mov_b32 m0, s1
	s_nop 0
	global_load_lds_dwordx4 v[120:121], off
	s_waitcnt vmcnt(8) lgkmcnt(0)
	s_setprio 1
	s_barrier
	v_mfma_f32_16x16x32_bf16 v[120:123], v[0:3], v[48:51], 0
	v_mfma_f32_16x16x32_bf16 v[158:161], v[4:7], v[56:59], v[120:123]
	v_mfma_f32_16x16x32_bf16 v[120:123], v[8:11], v[48:51], 0
	v_mfma_f32_16x16x32_bf16 v[162:165], v[12:15], v[56:59], v[120:123]
	v_mfma_f32_16x16x32_bf16 v[120:123], v[0:3], v[60:63], 0
	v_mfma_f32_16x16x32_bf16 v[166:169], v[4:7], v[88:91], v[120:123]
	v_mfma_f32_16x16x32_bf16 v[120:123], v[8:11], v[60:63], 0
	v_mfma_f32_16x16x32_bf16 v[170:173], v[12:15], v[88:91], v[120:123]
	v_mfma_f32_16x16x32_bf16 v[120:123], v[0:3], v[96:99], 0
	v_mfma_f32_16x16x32_bf16 v[0:3], v[0:3], v[112:115], 0
	v_mfma_f32_16x16x32_bf16 v[174:177], v[4:7], v[104:107], v[120:123]
	v_mfma_f32_16x16x32_bf16 v[0:3], v[4:7], v[116:119], v[0:3]
	v_mfma_f32_16x16x32_bf16 v[4:7], v[8:11], v[112:115], 0
	v_mfma_f32_16x16x32_bf16 v[120:123], v[8:11], v[96:99], 0
	v_mfma_f32_16x16x32_bf16 v[4:7], v[12:15], v[116:119], v[4:7]
	v_mfma_f32_16x16x32_bf16 v[178:181], v[12:15], v[104:107], v[120:123]
	s_setprio 0
	s_setprio 1
	v_mfma_f32_16x16x32_bf16 v[8:11], v[16:19], v[48:51], 0
	v_mfma_f32_16x16x32_bf16 v[182:185], v[20:23], v[56:59], v[8:11]
	v_mfma_f32_16x16x32_bf16 v[8:11], v[24:27], v[48:51], 0
	v_mfma_f32_16x16x32_bf16 v[186:189], v[28:31], v[56:59], v[8:11]
	v_mfma_f32_16x16x32_bf16 v[8:11], v[16:19], v[60:63], 0
	v_mfma_f32_16x16x32_bf16 v[190:193], v[20:23], v[88:91], v[8:11]
	v_mfma_f32_16x16x32_bf16 v[8:11], v[24:27], v[60:63], 0
	v_mfma_f32_16x16x32_bf16 v[194:197], v[28:31], v[88:91], v[8:11]
	v_mfma_f32_16x16x32_bf16 v[8:11], v[16:19], v[96:99], 0
	v_mfma_f32_16x16x32_bf16 v[198:201], v[20:23], v[104:107], v[8:11]
	v_mfma_f32_16x16x32_bf16 v[8:11], v[24:27], v[96:99], 0
	v_mfma_f32_16x16x32_bf16 v[202:205], v[28:31], v[104:107], v[8:11]
	v_mfma_f32_16x16x32_bf16 v[8:11], v[16:19], v[112:115], 0
	v_mfma_f32_16x16x32_bf16 v[206:209], v[20:23], v[116:119], v[8:11]
	v_mfma_f32_16x16x32_bf16 v[8:11], v[24:27], v[112:115], 0
	v_mfma_f32_16x16x32_bf16 v[210:213], v[28:31], v[116:119], v[8:11]
	s_barrier
	s_setprio 0
	s_add_i32 s67, 0, 0x18000
	s_add_i32 s80, 0, 0x1c000
	v_add_u32_e32 v144, s67, v146
	v_add_u32_e32 v145, s80, v146
	s_nop 0
	ds_read_b128 v[8:11], v144
	ds_read_b128 v[12:15], v144 offset:1024
	ds_read_b128 v[16:19], v144 offset:2048
	ds_read_b128 v[20:23], v144 offset:3072
	ds_read_b128 v[214:217], v145
	ds_read_b128 v[218:221], v145 offset:1024
	ds_read_b128 v[222:225], v145 offset:2048
	ds_read_b128 v[226:229], v145 offset:3072
	s_add_u32 s78, s76, 0x20100
	s_addc_u32 s79, s77, 0
	s_mov_b32 m0, s37
	v_lshl_add_u64 v[48:49], s[78:79], 0, v[134:135]
	ds_read_b128 v[24:27], v149 offset:32768
	ds_read_b128 v[28:31], v149 offset:33792
	ds_read_b128 v[60:63], v149 offset:34816
	ds_read_b128 v[230:233], v149 offset:35840
	ds_read_b128 v[234:237], v149 offset:36864
	ds_read_b128 v[238:241], v149 offset:37888
	ds_read_b128 v[242:245], v149 offset:38912
	ds_read_b128 v[246:249], v149 offset:39936
	global_load_lds_dwordx4 v[48:49], off
	v_lshl_add_u64 v[48:49], s[78:79], 0, v[132:133]
	s_mov_b32 m0, s38
	s_nop 0
	global_load_lds_dwordx4 v[48:49], off
	s_waitcnt vmcnt(8) lgkmcnt(0)
	s_setprio 1
	s_barrier
	v_mfma_f32_16x16x32_bf16 v[48:51], v[8:11], v[24:27], v[64:67]
	v_mfma_f32_16x16x32_bf16 v[120:123], v[12:15], v[28:31], v[48:51]
	v_mfma_f32_16x16x32_bf16 v[48:51], v[16:19], v[24:27], v[68:71]
	v_mfma_f32_16x16x32_bf16 v[112:115], v[20:23], v[28:31], v[48:51]
	v_mfma_f32_16x16x32_bf16 v[48:51], v[8:11], v[60:63], v[72:75]
	v_mfma_f32_16x16x32_bf16 v[104:107], v[12:15], v[230:233], v[48:51]
	v_mfma_f32_16x16x32_bf16 v[48:51], v[16:19], v[60:63], v[76:79]
	v_mfma_f32_16x16x32_bf16 v[96:99], v[20:23], v[230:233], v[48:51]
	v_mfma_f32_16x16x32_bf16 v[48:51], v[8:11], v[234:237], v[80:83]
	v_mfma_f32_16x16x32_bf16 v[88:91], v[12:15], v[238:241], v[48:51]
	v_mfma_f32_16x16x32_bf16 v[48:51], v[16:19], v[234:237], v[84:87]
	v_mfma_f32_16x16x32_bf16 v[80:83], v[20:23], v[238:241], v[48:51]
	v_mfma_f32_16x16x32_bf16 v[48:51], v[8:11], v[242:245], v[92:95]
	v_mfma_f32_16x16x32_bf16 v[56:59], v[12:15], v[246:249], v[48:51]
	v_mfma_f32_16x16x32_bf16 v[48:51], v[16:19], v[242:245], v[100:103]
	v_mfma_f32_16x16x32_bf16 v[48:51], v[20:23], v[246:249], v[48:51]
	s_setprio 0
	s_setprio 1
	v_mfma_f32_16x16x32_bf16 v[64:67], v[214:217], v[24:27], v[108:111]
	v_mfma_f32_16x16x32_bf16 v[24:27], v[222:225], v[24:27], v[32:35]
	v_mfma_f32_16x16x32_bf16 v[116:119], v[226:229], v[28:31], v[24:27]
	v_mfma_f32_16x16x32_bf16 v[24:27], v[214:217], v[60:63], v[36:39]
	v_mfma_f32_16x16x32_bf16 v[108:111], v[218:221], v[230:233], v[24:27]
	v_mfma_f32_16x16x32_bf16 v[24:27], v[222:225], v[60:63], v[40:43]
	v_mfma_f32_16x16x32_bf16 v[100:103], v[226:229], v[230:233], v[24:27]
	v_mfma_f32_16x16x32_bf16 v[24:27], v[214:217], v[234:237], v[44:47]
	v_mfma_f32_16x16x32_bf16 v[92:95], v[218:221], v[238:241], v[24:27]
	v_mfma_f32_16x16x32_bf16 v[24:27], v[222:225], v[234:237], v[52:55]
	v_mfma_f32_16x16x32_bf16 v[84:87], v[226:229], v[238:241], v[24:27]
	v_mfma_f32_16x16x32_bf16 v[24:27], v[214:217], v[242:245], v[150:153]
	v_mfma_f32_16x16x32_bf16 v[60:63], v[218:221], v[246:249], v[24:27]
	v_mfma_f32_16x16x32_bf16 v[24:27], v[222:225], v[242:245], v[154:157]
	v_mfma_f32_16x16x32_bf16 v[124:127], v[218:221], v[28:31], v[64:67]
	v_mfma_f32_16x16x32_bf16 v[52:55], v[226:229], v[246:249], v[24:27]
	s_barrier
; template <class Epi, class Sched, bool ALIGN_EPI = false, bool SP2 = false, bool A_TILED = false>
; __device__ __forceinline__ void gemm_phase(PG8_LAS unsigned char* lds, const Gemm g, const Sched& S, const Epi& E, const int wave_s) {
;     ...
;         for (int t = PEEL ? 2 : 0; t < nt; t += 2) {
;             const bool last = (t == nt - 2);
;             const char* a1 = cA + (size_t)(t + 1) * kstepA;
;             const char* a2 = last ? nA : cA + (size_t)(t + 2) * kstepA; const char* b2 = last ? nB : cB + (size_t)(t + 2) * kstep;
;             const char* a3 = a2 + kstepA; const char* b3 = b2 + kstep;
	s_setprio 0
	s_add_i32 s67, s67, s36
	s_add_i32 s71, s67, 0x2000
	s_nop 1
	v_lshl_add_u64 v[24:25], v[250:251], 0, s[62:63]
	s_mov_b32 m0, s67
	s_add_u32 s78, s74, 0x20180
	ds_read_b128 v[32:35], v149 offset:49152
	ds_read_b128 v[36:39], v149 offset:50176
	ds_read_b128 v[150:153], v149 offset:51200
	ds_read_b128 v[154:157], v149 offset:52224
	ds_read_b128 v[230:233], v149 offset:53248
	ds_read_b128 v[234:237], v149 offset:54272
	ds_read_b128 v[238:241], v149 offset:55296
	ds_read_b128 v[242:245], v149 offset:56320
	global_load_lds_dwordx4 v[24:25], off
	v_lshl_add_u64 v[24:25], v[252:253], 0, s[62:63]
	s_mov_b32 m0, s71
	s_addc_u32 s79, s75, 0
	s_add_i32 s80, s80, s36
	global_load_lds_dwordx4 v[24:25], off
	v_lshl_add_u64 v[24:25], s[78:79], 0, v[128:129]
	s_mov_b32 m0, s80
	s_add_i32 s81, s80, 0x2000
	global_load_lds_dwordx4 v[24:25], off
	v_lshl_add_u64 v[24:25], s[78:79], 0, v[130:131]
	s_mov_b32 m0, s81
	s_nop 0
	global_load_lds_dwordx4 v[24:25], off
	v_lshl_add_u64 v[24:25], v[140:141], 0, s[62:63]
	s_mov_b32 m0, s42
	s_nop 0
	global_load_lds_dwordx4 v[24:25], off
	v_lshl_add_u64 v[24:25], v[142:143], 0, s[62:63]
	s_mov_b32 m0, s43
	s_nop 0
	global_load_lds_dwordx4 v[24:25], off
	s_waitcnt vmcnt(8) lgkmcnt(0)
	s_setprio 1
	s_barrier
	v_mfma_f32_16x16x32_bf16 v[24:27], v[8:11], v[32:35], v[158:161]
	v_mfma_f32_16x16x32_bf16 v[76:79], v[12:15], v[36:39], v[24:27]
	v_mfma_f32_16x16x32_bf16 v[24:27], v[16:19], v[32:35], v[162:165]
	v_mfma_f32_16x16x32_bf16 v[72:75], v[20:23], v[36:39], v[24:27]
	v_mfma_f32_16x16x32_bf16 v[24:27], v[8:11], v[150:153], v[166:169]
	v_mfma_f32_16x16x32_bf16 v[44:47], v[12:15], v[154:157], v[24:27]
	v_mfma_f32_16x16x32_bf16 v[24:27], v[16:19], v[150:153], v[170:173]
	v_mfma_f32_16x16x32_bf16 v[40:43], v[20:23], v[154:157], v[24:27]
	v_mfma_f32_16x16x32_bf16 v[24:27], v[8:11], v[230:233], v[174:177]
	v_mfma_f32_16x16x32_bf16 v[0:3], v[8:11], v[238:241], v[0:3]
	v_mfma_f32_16x16x32_bf16 v[28:31], v[12:15], v[234:237], v[24:27]
	v_mfma_f32_16x16x32_bf16 v[24:27], v[16:19], v[230:233], v[178:181]
	v_mfma_f32_16x16x32_bf16 v[12:15], v[12:15], v[242:245], v[0:3]
	v_mfma_f32_16x16x32_bf16 v[0:3], v[16:19], v[238:241], v[4:7]
	v_mfma_f32_16x16x32_bf16 v[24:27], v[20:23], v[234:237], v[24:27]
	v_mfma_f32_16x16x32_bf16 v[8:11], v[20:23], v[242:245], v[0:3]
	s_setprio 0
	s_setprio 1
	v_mfma_f32_16x16x32_bf16 v[0:3], v[214:217], v[32:35], v[182:185]
	v_mfma_f32_16x16x32_bf16 v[68:71], v[218:221], v[36:39], v[0:3]
	v_mfma_f32_16x16x32_bf16 v[0:3], v[222:225], v[32:35], v[186:189]
	v_mfma_f32_16x16x32_bf16 v[64:67], v[226:229], v[36:39], v[0:3]
	v_mfma_f32_16x16x32_bf16 v[0:3], v[214:217], v[150:153], v[190:193]
	v_mfma_f32_16x16x32_bf16 v[36:39], v[218:221], v[154:157], v[0:3]
	v_mfma_f32_16x16x32_bf16 v[0:3], v[222:225], v[150:153], v[194:197]
	v_mfma_f32_16x16x32_bf16 v[32:35], v[226:229], v[154:157], v[0:3]
	v_mfma_f32_16x16x32_bf16 v[0:3], v[214:217], v[230:233], v[198:201]
	v_mfma_f32_16x16x32_bf16 v[20:23], v[218:221], v[234:237], v[0:3]
	v_mfma_f32_16x16x32_bf16 v[0:3], v[222:225], v[230:233], v[202:205]
	v_mfma_f32_16x16x32_bf16 v[16:19], v[226:229], v[234:237], v[0:3]
	v_mfma_f32_16x16x32_bf16 v[0:3], v[214:217], v[238:241], v[206:209]
	v_mfma_f32_16x16x32_bf16 v[4:7], v[218:221], v[242:245], v[0:3]
	v_mfma_f32_16x16x32_bf16 v[0:3], v[222:225], v[238:241], v[210:213]
	v_mfma_f32_16x16x32_bf16 v[0:3], v[226:229], v[242:245], v[0:3]
	s_barrier
	s_setprio 0
	s_add_u32 s82, s74, 0x200
	s_addc_u32 s83, s75, 0
	s_add_u32 s74, s76, 0x20180
	s_addc_u32 s75, s77, 0
	s_mov_b32 s85, 0
.LBB0_2566:
	ds_read_b128 v[150:153], v147
	ds_read_b128 v[154:157], v147 offset:1024
	ds_read_b128 v[158:161], v147 offset:2048
	ds_read_b128 v[162:165], v147 offset:3072
	ds_read_b128 v[166:169], v148
	ds_read_b128 v[170:173], v148 offset:1024
	ds_read_b128 v[174:177], v148 offset:2048
	ds_read_b128 v[178:181], v148 offset:3072
	s_add_u32 s76, s74, 0xfffe0080
	s_addc_u32 s77, s75, -1
	s_cmp_eq_u32 s85, 4
	s_cselect_b32 s79, s51, s77
	s_cselect_b32 s78, s52, s76
	s_cselect_b32 s77, s53, s83
	s_cselect_b32 s76, s54, s82
	s_mov_b32 m0, s55
	v_lshl_add_u64 v[140:141], s[74:75], 0, v[138:139]
	ds_read_b128 v[182:185], v149
	ds_read_b128 v[186:189], v149 offset:1024
	ds_read_b128 v[190:193], v149 offset:2048
	ds_read_b128 v[194:197], v149 offset:3072
	ds_read_b128 v[198:201], v149 offset:4096
	ds_read_b128 v[202:205], v149 offset:5120
	ds_read_b128 v[206:209], v149 offset:6144
	ds_read_b128 v[210:213], v149 offset:7168
	global_load_lds_dwordx4 v[140:141], off
	v_lshl_add_u64 v[140:141], s[74:75], 0, v[136:137]
	s_mov_b32 m0, s56
	s_nop 0
	global_load_lds_dwordx4 v[140:141], off
	s_waitcnt vmcnt(8) lgkmcnt(0)
	s_setprio 1
	s_barrier
	v_mfma_f32_16x16x32_bf16 v[120:123], v[150:153], v[182:185], v[120:123]
	v_mfma_f32_16x16x32_bf16 v[112:115], v[158:161], v[182:185], v[112:115]
	v_mfma_f32_16x16x32_bf16 v[104:107], v[150:153], v[190:193], v[104:107]
	v_mfma_f32_16x16x32_bf16 v[96:99], v[158:161], v[190:193], v[96:99]
	v_mfma_f32_16x16x32_bf16 v[88:91], v[150:153], v[198:201], v[88:91]
	v_mfma_f32_16x16x32_bf16 v[80:83], v[158:161], v[198:201], v[80:83]
	v_mfma_f32_16x16x32_bf16 v[56:59], v[150:153], v[206:209], v[56:59]
	v_mfma_f32_16x16x32_bf16 v[48:51], v[158:161], v[206:209], v[48:51]
	v_mfma_f32_16x16x32_bf16 v[120:123], v[154:157], v[186:189], v[120:123]
	v_mfma_f32_16x16x32_bf16 v[112:115], v[162:165], v[186:189], v[112:115]
	v_mfma_f32_16x16x32_bf16 v[104:107], v[154:157], v[194:197], v[104:107]
	v_mfma_f32_16x16x32_bf16 v[96:99], v[162:165], v[194:197], v[96:99]
	v_mfma_f32_16x16x32_bf16 v[88:91], v[154:157], v[202:205], v[88:91]
	v_mfma_f32_16x16x32_bf16 v[80:83], v[162:165], v[202:205], v[80:83]
	v_mfma_f32_16x16x32_bf16 v[56:59], v[154:157], v[210:213], v[56:59]
	v_mfma_f32_16x16x32_bf16 v[48:51], v[162:165], v[210:213], v[48:51]
	s_setprio 0
	s_setprio 1
	v_mfma_f32_16x16x32_bf16 v[124:127], v[166:169], v[182:185], v[124:127]
	v_mfma_f32_16x16x32_bf16 v[116:119], v[174:177], v[182:185], v[116:119]
	v_mfma_f32_16x16x32_bf16 v[108:111], v[166:169], v[190:193], v[108:111]
	v_mfma_f32_16x16x32_bf16 v[100:103], v[174:177], v[190:193], v[100:103]
	v_mfma_f32_16x16x32_bf16 v[92:95], v[166:169], v[198:201], v[92:95]
	v_mfma_f32_16x16x32_bf16 v[84:87], v[174:177], v[198:201], v[84:87]
	v_mfma_f32_16x16x32_bf16 v[60:63], v[166:169], v[206:209], v[60:63]
	v_mfma_f32_16x16x32_bf16 v[52:55], v[174:177], v[206:209], v[52:55]
	v_mfma_f32_16x16x32_bf16 v[124:127], v[170:173], v[186:189], v[124:127]
	v_mfma_f32_16x16x32_bf16 v[116:119], v[178:181], v[186:189], v[116:119]
	v_mfma_f32_16x16x32_bf16 v[108:111], v[170:173], v[194:197], v[108:111]
	v_mfma_f32_16x16x32_bf16 v[100:103], v[178:181], v[194:197], v[100:103]
	v_mfma_f32_16x16x32_bf16 v[92:95], v[170:173], v[202:205], v[92:95]
	v_mfma_f32_16x16x32_bf16 v[84:87], v[178:181], v[202:205], v[84:87]
	v_mfma_f32_16x16x32_bf16 v[60:63], v[170:173], v[210:213], v[60:63]
	v_mfma_f32_16x16x32_bf16 v[52:55], v[178:181], v[210:213], v[52:55]
	s_barrier
	s_setprio 0
	s_mov_b32 m0, s57
	v_lshl_add_u64 v[140:141], s[76:77], 0, v[128:129]
	s_add_u32 s88, s76, 0x20000
	ds_read_b128 v[182:185], v149 offset:16384
	ds_read_b128 v[186:189], v149 offset:17408
	ds_read_b128 v[190:193], v149 offset:18432
	ds_read_b128 v[194:197], v149 offset:19456
	ds_read_b128 v[198:201], v149 offset:20480
	ds_read_b128 v[202:205], v149 offset:21504
	ds_read_b128 v[206:209], v149 offset:22528
	ds_read_b128 v[210:213], v149 offset:23552
	global_load_lds_dwordx4 v[140:141], off
	v_lshl_add_u64 v[142:143], s[76:77], 0, v[130:131]
	s_mov_b32 m0, s58
	s_addc_u32 s89, s77, 0
	global_load_lds_dwordx4 v[142:143], off
	v_lshl_add_u64 v[214:215], s[88:89], 0, v[128:129]
	s_mov_b32 m0, s59
	v_lshl_add_u64 v[216:217], s[78:79], 0, v[132:133]
	global_load_lds_dwordx4 v[214:215], off
	v_lshl_add_u64 v[214:215], s[88:89], 0, v[130:131]
	s_mov_b32 m0, s65
	s_nop 0
	global_load_lds_dwordx4 v[214:215], off
	v_lshl_add_u64 v[214:215], s[78:79], 0, v[134:135]
	s_mov_b32 m0, s0
	s_nop 0
	global_load_lds_dwordx4 v[214:215], off
	s_mov_b32 m0, s1
	s_nop 0
	global_load_lds_dwordx4 v[216:217], off
	s_waitcnt vmcnt(8) lgkmcnt(0)
	s_setprio 1
	s_barrier
	v_mfma_f32_16x16x32_bf16 v[76:79], v[150:153], v[182:185], v[76:79]
	v_mfma_f32_16x16x32_bf16 v[72:75], v[158:161], v[182:185], v[72:75]
	v_mfma_f32_16x16x32_bf16 v[44:47], v[150:153], v[190:193], v[44:47]
	v_mfma_f32_16x16x32_bf16 v[40:43], v[158:161], v[190:193], v[40:43]
	v_mfma_f32_16x16x32_bf16 v[28:31], v[150:153], v[198:201], v[28:31]
	v_mfma_f32_16x16x32_bf16 v[24:27], v[158:161], v[198:201], v[24:27]
	v_mfma_f32_16x16x32_bf16 v[12:15], v[150:153], v[206:209], v[12:15]
	v_mfma_f32_16x16x32_bf16 v[8:11], v[158:161], v[206:209], v[8:11]
	v_mfma_f32_16x16x32_bf16 v[76:79], v[154:157], v[186:189], v[76:79]
	v_mfma_f32_16x16x32_bf16 v[72:75], v[162:165], v[186:189], v[72:75]
	v_mfma_f32_16x16x32_bf16 v[44:47], v[154:157], v[194:197], v[44:47]
	v_mfma_f32_16x16x32_bf16 v[40:43], v[162:165], v[194:197], v[40:43]
	v_mfma_f32_16x16x32_bf16 v[28:31], v[154:157], v[202:205], v[28:31]
	v_mfma_f32_16x16x32_bf16 v[24:27], v[162:165], v[202:205], v[24:27]
	v_mfma_f32_16x16x32_bf16 v[12:15], v[154:157], v[210:213], v[12:15]
	v_mfma_f32_16x16x32_bf16 v[8:11], v[162:165], v[210:213], v[8:11]
	s_setprio 0
	s_setprio 1
	v_mfma_f32_16x16x32_bf16 v[68:71], v[166:169], v[182:185], v[68:71]
	v_mfma_f32_16x16x32_bf16 v[64:67], v[174:177], v[182:185], v[64:67]
	v_mfma_f32_16x16x32_bf16 v[36:39], v[166:169], v[190:193], v[36:39]
	v_mfma_f32_16x16x32_bf16 v[32:35], v[174:177], v[190:193], v[32:35]
	v_mfma_f32_16x16x32_bf16 v[20:23], v[166:169], v[198:201], v[20:23]
	v_mfma_f32_16x16x32_bf16 v[16:19], v[174:177], v[198:201], v[16:19]
	v_mfma_f32_16x16x32_bf16 v[4:7], v[166:169], v[206:209], v[4:7]
	v_mfma_f32_16x16x32_bf16 v[0:3], v[174:177], v[206:209], v[0:3]
	v_mfma_f32_16x16x32_bf16 v[68:71], v[170:173], v[186:189], v[68:71]
	v_mfma_f32_16x16x32_bf16 v[64:67], v[178:181], v[186:189], v[64:67]
	v_mfma_f32_16x16x32_bf16 v[36:39], v[170:173], v[194:197], v[36:39]
	v_mfma_f32_16x16x32_bf16 v[32:35], v[178:181], v[194:197], v[32:35]
	v_mfma_f32_16x16x32_bf16 v[20:23], v[170:173], v[202:205], v[20:23]
	v_mfma_f32_16x16x32_bf16 v[16:19], v[178:181], v[202:205], v[16:19]
	v_mfma_f32_16x16x32_bf16 v[4:7], v[170:173], v[210:213], v[4:7]
	v_mfma_f32_16x16x32_bf16 v[0:3], v[178:181], v[210:213], v[0:3]
	s_barrier
; template <class Epi, class Sched, bool ALIGN_EPI = false, bool SP2 = false, bool A_TILED = false>
; __device__ __forceinline__ void gemm_phase(PG8_LAS unsigned char* lds, const Gemm g, const Sched& S, const Epi& E, const int wave_s) {
;     ...
;         for (int t = PEEL ? 2 : 0; t < nt; t += 2) {
;             const bool last = (t == nt - 2);
;             const char* a1 = cA + (size_t)(t + 1) * kstepA;
;             const char* a2 = last ? nA : cA + (size_t)(t + 2) * kstepA; const char* b2 = last ? nB : cB + (size_t)(t + 2) * kstep;
;             const char* a3 = a2 + kstepA; const char* b3 = b2 + kstep;
;             if (last && has_next) S.a_ready(nxt);
	s_setprio 0
	ds_read_b128 v[150:153], v144
	ds_read_b128 v[154:157], v144 offset:1024
	ds_read_b128 v[158:161], v144 offset:2048
	ds_read_b128 v[162:165], v144 offset:3072
	ds_read_b128 v[166:169], v145
	ds_read_b128 v[170:173], v145 offset:1024
	ds_read_b128 v[174:177], v145 offset:2048
	ds_read_b128 v[178:181], v145 offset:3072
	s_add_u32 s78, s78, 0x20000
	s_addc_u32 s79, s79, 0
	s_mov_b32 m0, s37
	v_lshl_add_u64 v[218:219], s[78:79], 0, v[134:135]
	ds_read_b128 v[182:185], v149 offset:32768
	ds_read_b128 v[186:189], v149 offset:33792
	ds_read_b128 v[190:193], v149 offset:34816
	ds_read_b128 v[194:197], v149 offset:35840
	ds_read_b128 v[198:201], v149 offset:36864
	ds_read_b128 v[202:205], v149 offset:37888
	ds_read_b128 v[206:209], v149 offset:38912
	ds_read_b128 v[210:213], v149 offset:39936
	global_load_lds_dwordx4 v[218:219], off
	v_lshl_add_u64 v[218:219], s[78:79], 0, v[132:133]
	s_mov_b32 m0, s38
	s_nop 0
	global_load_lds_dwordx4 v[218:219], off
	s_waitcnt vmcnt(8) lgkmcnt(0)
	s_setprio 1
	s_barrier
	v_mfma_f32_16x16x32_bf16 v[120:123], v[150:153], v[182:185], v[120:123]
	v_mfma_f32_16x16x32_bf16 v[112:115], v[158:161], v[182:185], v[112:115]
	v_mfma_f32_16x16x32_bf16 v[104:107], v[150:153], v[190:193], v[104:107]
	v_mfma_f32_16x16x32_bf16 v[96:99], v[158:161], v[190:193], v[96:99]
	v_mfma_f32_16x16x32_bf16 v[88:91], v[150:153], v[198:201], v[88:91]
	v_mfma_f32_16x16x32_bf16 v[80:83], v[158:161], v[198:201], v[80:83]
	v_mfma_f32_16x16x32_bf16 v[56:59], v[150:153], v[206:209], v[56:59]
	v_mfma_f32_16x16x32_bf16 v[48:51], v[158:161], v[206:209], v[48:51]
	v_mfma_f32_16x16x32_bf16 v[120:123], v[154:157], v[186:189], v[120:123]
	v_mfma_f32_16x16x32_bf16 v[112:115], v[162:165], v[186:189], v[112:115]
	v_mfma_f32_16x16x32_bf16 v[104:107], v[154:157], v[194:197], v[104:107]
	v_mfma_f32_16x16x32_bf16 v[96:99], v[162:165], v[194:197], v[96:99]
	v_mfma_f32_16x16x32_bf16 v[88:91], v[154:157], v[202:205], v[88:91]
	v_mfma_f32_16x16x32_bf16 v[80:83], v[162:165], v[202:205], v[80:83]
	v_mfma_f32_16x16x32_bf16 v[56:59], v[154:157], v[210:213], v[56:59]
	v_mfma_f32_16x16x32_bf16 v[48:51], v[162:165], v[210:213], v[48:51]
	s_setprio 0
	s_setprio 1
	v_mfma_f32_16x16x32_bf16 v[124:127], v[166:169], v[182:185], v[124:127]
	v_mfma_f32_16x16x32_bf16 v[116:119], v[174:177], v[182:185], v[116:119]
	v_mfma_f32_16x16x32_bf16 v[108:111], v[166:169], v[190:193], v[108:111]
	v_mfma_f32_16x16x32_bf16 v[100:103], v[174:177], v[190:193], v[100:103]
	v_mfma_f32_16x16x32_bf16 v[92:95], v[166:169], v[198:201], v[92:95]
	v_mfma_f32_16x16x32_bf16 v[84:87], v[174:177], v[198:201], v[84:87]
	v_mfma_f32_16x16x32_bf16 v[60:63], v[166:169], v[206:209], v[60:63]
	v_mfma_f32_16x16x32_bf16 v[52:55], v[174:177], v[206:209], v[52:55]
	v_mfma_f32_16x16x32_bf16 v[124:127], v[170:173], v[186:189], v[124:127]
	v_mfma_f32_16x16x32_bf16 v[116:119], v[178:181], v[186:189], v[116:119]
	v_mfma_f32_16x16x32_bf16 v[108:111], v[170:173], v[194:197], v[108:111]
	v_mfma_f32_16x16x32_bf16 v[100:103], v[178:181], v[194:197], v[100:103]
	v_mfma_f32_16x16x32_bf16 v[92:95], v[170:173], v[202:205], v[92:95]
	v_mfma_f32_16x16x32_bf16 v[84:87], v[178:181], v[202:205], v[84:87]
	v_mfma_f32_16x16x32_bf16 v[60:63], v[170:173], v[210:213], v[60:63]
	v_mfma_f32_16x16x32_bf16 v[52:55], v[178:181], v[210:213], v[52:55]
	s_barrier
	s_setprio 0
	s_mov_b32 m0, s67
	v_lshl_add_u64 v[140:141], v[140:141], 0, s[44:45]
	s_add_u32 s76, s76, 0x20080
	ds_read_b128 v[182:185], v149 offset:49152
	ds_read_b128 v[186:189], v149 offset:50176
	ds_read_b128 v[190:193], v149 offset:51200
	ds_read_b128 v[194:197], v149 offset:52224
	ds_read_b128 v[198:201], v149 offset:53248
	ds_read_b128 v[202:205], v149 offset:54272
	ds_read_b128 v[206:209], v149 offset:55296
	ds_read_b128 v[210:213], v149 offset:56320
	global_load_lds_dwordx4 v[140:141], off
	v_lshl_add_u64 v[140:141], v[142:143], 0, s[44:45]
	s_mov_b32 m0, s71
	s_addc_u32 s77, s77, 0
	global_load_lds_dwordx4 v[140:141], off
	v_lshl_add_u64 v[140:141], s[76:77], 0, v[128:129]
	s_mov_b32 m0, s80
	s_nop 0
	global_load_lds_dwordx4 v[140:141], off
	v_lshl_add_u64 v[140:141], s[76:77], 0, v[130:131]
	s_mov_b32 m0, s81
	s_nop 0
	global_load_lds_dwordx4 v[140:141], off
	v_lshl_add_u64 v[140:141], v[214:215], 0, s[44:45]
	s_mov_b32 m0, s42
	s_nop 0
	global_load_lds_dwordx4 v[140:141], off
	v_lshl_add_u64 v[140:141], v[216:217], 0, s[44:45]
	s_mov_b32 m0, s43
	s_nop 0
	global_load_lds_dwordx4 v[140:141], off
	s_waitcnt vmcnt(8) lgkmcnt(0)
	s_setprio 1
	s_barrier
	v_mfma_f32_16x16x32_bf16 v[76:79], v[150:153], v[182:185], v[76:79]
	v_mfma_f32_16x16x32_bf16 v[72:75], v[158:161], v[182:185], v[72:75]
	v_mfma_f32_16x16x32_bf16 v[44:47], v[150:153], v[190:193], v[44:47]
	v_mfma_f32_16x16x32_bf16 v[40:43], v[158:161], v[190:193], v[40:43]
	v_mfma_f32_16x16x32_bf16 v[28:31], v[150:153], v[198:201], v[28:31]
	v_mfma_f32_16x16x32_bf16 v[24:27], v[158:161], v[198:201], v[24:27]
	v_mfma_f32_16x16x32_bf16 v[12:15], v[150:153], v[206:209], v[12:15]
	v_mfma_f32_16x16x32_bf16 v[8:11], v[158:161], v[206:209], v[8:11]
	v_mfma_f32_16x16x32_bf16 v[76:79], v[154:157], v[186:189], v[76:79]
	v_mfma_f32_16x16x32_bf16 v[72:75], v[162:165], v[186:189], v[72:75]
	v_mfma_f32_16x16x32_bf16 v[44:47], v[154:157], v[194:197], v[44:47]
	v_mfma_f32_16x16x32_bf16 v[40:43], v[162:165], v[194:197], v[40:43]
	v_mfma_f32_16x16x32_bf16 v[28:31], v[154:157], v[202:205], v[28:31]
	v_mfma_f32_16x16x32_bf16 v[24:27], v[162:165], v[202:205], v[24:27]
	v_mfma_f32_16x16x32_bf16 v[12:15], v[154:157], v[210:213], v[12:15]
	v_mfma_f32_16x16x32_bf16 v[8:11], v[162:165], v[210:213], v[8:11]
	s_setprio 0
	s_setprio 1
	v_mfma_f32_16x16x32_bf16 v[68:71], v[166:169], v[182:185], v[68:71]
	v_mfma_f32_16x16x32_bf16 v[64:67], v[174:177], v[182:185], v[64:67]
	v_mfma_f32_16x16x32_bf16 v[36:39], v[166:169], v[190:193], v[36:39]
	v_mfma_f32_16x16x32_bf16 v[32:35], v[174:177], v[190:193], v[32:35]
	v_mfma_f32_16x16x32_bf16 v[20:23], v[166:169], v[198:201], v[20:23]
	v_mfma_f32_16x16x32_bf16 v[16:19], v[174:177], v[198:201], v[16:19]
	v_mfma_f32_16x16x32_bf16 v[4:7], v[166:169], v[206:209], v[4:7]
	v_mfma_f32_16x16x32_bf16 v[0:3], v[174:177], v[206:209], v[0:3]
	v_mfma_f32_16x16x32_bf16 v[68:71], v[170:173], v[186:189], v[68:71]
	v_mfma_f32_16x16x32_bf16 v[64:67], v[178:181], v[186:189], v[64:67]
	v_mfma_f32_16x16x32_bf16 v[36:39], v[170:173], v[194:197], v[36:39]
	v_mfma_f32_16x16x32_bf16 v[32:35], v[178:181], v[194:197], v[32:35]
	v_mfma_f32_16x16x32_bf16 v[20:23], v[170:173], v[202:205], v[20:23]
	v_mfma_f32_16x16x32_bf16 v[16:19], v[178:181], v[202:205], v[16:19]
	v_mfma_f32_16x16x32_bf16 v[4:7], v[170:173], v[210:213], v[4:7]
	v_mfma_f32_16x16x32_bf16 v[0:3], v[178:181], v[210:213], v[0:3]
	s_barrier
	s_setprio 0
	s_add_i32 s85, s85, 2
	s_add_u32 s82, s82, 0x100
	s_addc_u32 s83, s83, 0
	s_add_u32 s74, s74, 0x100
	s_addc_u32 s75, s75, 0
	s_cmp_gt_u32 s85, 5
	s_cbranch_scc0 .LBB0_2566
	s_and_b64 vcc, exec, s[46:47]
	s_cbranch_vccz .LBB0_2569
	s_barrier

.LBB0_2729:
	ds_read_b128 v[146:149], v140
	ds_read_b128 v[150:153], v140 offset:1024
	ds_read_b128 v[154:157], v140 offset:2048
	ds_read_b128 v[158:161], v140 offset:3072
	ds_read_b128 v[162:165], v141
	ds_read_b128 v[166:169], v141 offset:1024
	ds_read_b128 v[170:173], v141 offset:2048
	ds_read_b128 v[174:177], v141 offset:3072
	s_add_u32 s55, s44, s39
	s_addc_u32 s56, s45, s40
	s_add_u32 s57, s44, s37
	s_addc_u32 s58, s45, s38
	s_cmp_eq_u32 s41, 28
	s_cselect_b32 s67, s7, s56
	s_cselect_b32 s66, s6, s55
	s_cselect_b32 s65, s3, s58
	s_cselect_b32 s64, s2, s57
	s_mov_b32 m0, s42
	v_lshl_add_u64 v[210:211], s[44:45], 0, v[138:139]
	ds_read_b128 v[178:181], v142
	ds_read_b128 v[182:185], v142 offset:1024
	ds_read_b128 v[186:189], v142 offset:2048
	ds_read_b128 v[190:193], v142 offset:3072
	ds_read_b128 v[194:197], v142 offset:4096
	ds_read_b128 v[198:201], v142 offset:5120
	ds_read_b128 v[202:205], v142 offset:6144
	ds_read_b128 v[206:209], v142 offset:7168
	global_load_lds_dwordx4 v[210:211], off
	v_lshl_add_u64 v[210:211], s[44:45], 0, v[136:137]
	s_mov_b32 m0, s43
	s_nop 0
	global_load_lds_dwordx4 v[210:211], off
	s_waitcnt vmcnt(8) lgkmcnt(0)
	s_setprio 1
	s_barrier
	v_mfma_f32_16x16x32_bf16 v[8:11], v[146:149], v[178:181], v[8:11]
	v_mfma_f32_16x16x32_bf16 v[12:15], v[154:157], v[178:181], v[12:15]
	v_mfma_f32_16x16x32_bf16 v[60:63], v[146:149], v[186:189], v[60:63]
	v_mfma_f32_16x16x32_bf16 v[20:23], v[154:157], v[186:189], v[20:23]
	v_mfma_f32_16x16x32_bf16 v[76:79], v[146:149], v[194:197], v[76:79]
	v_mfma_f32_16x16x32_bf16 v[52:55], v[154:157], v[194:197], v[52:55]
	v_mfma_f32_16x16x32_bf16 v[128:131], v[146:149], v[202:205], v[128:131]
	v_mfma_f32_16x16x32_bf16 v[68:71], v[154:157], v[202:205], v[68:71]
	v_mfma_f32_16x16x32_bf16 v[8:11], v[150:153], v[182:185], v[8:11]
	v_mfma_f32_16x16x32_bf16 v[12:15], v[158:161], v[182:185], v[12:15]
	v_mfma_f32_16x16x32_bf16 v[60:63], v[150:153], v[190:193], v[60:63]
	v_mfma_f32_16x16x32_bf16 v[20:23], v[158:161], v[190:193], v[20:23]
	v_mfma_f32_16x16x32_bf16 v[76:79], v[150:153], v[198:201], v[76:79]
	v_mfma_f32_16x16x32_bf16 v[52:55], v[158:161], v[198:201], v[52:55]
	v_mfma_f32_16x16x32_bf16 v[128:131], v[150:153], v[206:209], v[128:131]
	v_mfma_f32_16x16x32_bf16 v[68:71], v[158:161], v[206:209], v[68:71]
	s_setprio 0
	s_setprio 1
	v_mfma_f32_16x16x32_bf16 v[24:27], v[162:165], v[178:181], v[24:27]
	v_mfma_f32_16x16x32_bf16 v[16:19], v[170:173], v[178:181], v[16:19]
	v_mfma_f32_16x16x32_bf16 v[56:59], v[162:165], v[186:189], v[56:59]
	v_mfma_f32_16x16x32_bf16 v[48:51], v[170:173], v[186:189], v[48:51]
	v_mfma_f32_16x16x32_bf16 v[72:75], v[162:165], v[194:197], v[72:75]
	v_mfma_f32_16x16x32_bf16 v[64:67], v[170:173], v[194:197], v[64:67]
	v_mfma_f32_16x16x32_bf16 v[108:111], v[162:165], v[202:205], v[108:111]
	v_mfma_f32_16x16x32_bf16 v[96:99], v[170:173], v[202:205], v[96:99]
	v_mfma_f32_16x16x32_bf16 v[24:27], v[166:169], v[182:185], v[24:27]
	v_mfma_f32_16x16x32_bf16 v[16:19], v[174:177], v[182:185], v[16:19]
	v_mfma_f32_16x16x32_bf16 v[56:59], v[166:169], v[190:193], v[56:59]
	v_mfma_f32_16x16x32_bf16 v[48:51], v[174:177], v[190:193], v[48:51]
	v_mfma_f32_16x16x32_bf16 v[72:75], v[166:169], v[198:201], v[72:75]
	v_mfma_f32_16x16x32_bf16 v[64:67], v[174:177], v[198:201], v[64:67]
	v_mfma_f32_16x16x32_bf16 v[108:111], v[166:169], v[206:209], v[108:111]
	v_mfma_f32_16x16x32_bf16 v[96:99], v[174:177], v[206:209], v[96:99]
	s_barrier
	s_setprio 0
	s_mov_b32 m0, s47
	v_lshl_add_u64 v[210:211], s[64:65], 0, v[34:35]
	s_add_u32 s56, s64, 0x80000
	ds_read_b128 v[178:181], v142 offset:16384
	ds_read_b128 v[182:185], v142 offset:17408
	ds_read_b128 v[186:189], v142 offset:18432
	ds_read_b128 v[190:193], v142 offset:19456
	ds_read_b128 v[194:197], v142 offset:20480
	ds_read_b128 v[198:201], v142 offset:21504
	ds_read_b128 v[202:205], v142 offset:22528
	ds_read_b128 v[206:209], v142 offset:23552
	global_load_lds_dwordx4 v[210:211], off
	v_lshl_add_u64 v[212:213], s[64:65], 0, v[134:135]
	s_mov_b32 m0, s48
	s_addc_u32 s57, s65, 0
	global_load_lds_dwordx4 v[212:213], off
	v_lshl_add_u64 v[214:215], s[56:57], 0, v[34:35]
	s_mov_b32 m0, s49
	v_lshl_add_u64 v[216:217], s[66:67], 0, v[132:133]
	global_load_lds_dwordx4 v[214:215], off
	v_lshl_add_u64 v[214:215], s[56:57], 0, v[134:135]
	s_mov_b32 m0, s50
	s_nop 0
	global_load_lds_dwordx4 v[214:215], off
	v_lshl_add_u64 v[214:215], s[66:67], 0, v[32:33]
	s_mov_b32 m0, s14
	s_nop 0
	global_load_lds_dwordx4 v[214:215], off
	s_mov_b32 m0, s15
	s_nop 0
	global_load_lds_dwordx4 v[216:217], off
	s_waitcnt vmcnt(8) lgkmcnt(0)
	s_setprio 1
	s_barrier
	v_mfma_f32_16x16x32_bf16 v[100:103], v[146:149], v[178:181], v[100:103]
	v_mfma_f32_16x16x32_bf16 v[104:107], v[154:157], v[178:181], v[104:107]
	v_mfma_f32_16x16x32_bf16 v[116:119], v[146:149], v[186:189], v[116:119]
	v_mfma_f32_16x16x32_bf16 v[120:123], v[154:157], v[186:189], v[120:123]
	v_mfma_f32_16x16x32_bf16 v[84:87], v[146:149], v[194:197], v[84:87]
	v_mfma_f32_16x16x32_bf16 v[80:83], v[154:157], v[194:197], v[80:83]
	v_mfma_f32_16x16x32_bf16 v[36:39], v[146:149], v[202:205], v[36:39]
	v_mfma_f32_16x16x32_bf16 v[28:31], v[154:157], v[202:205], v[28:31]
	v_mfma_f32_16x16x32_bf16 v[100:103], v[150:153], v[182:185], v[100:103]
	v_mfma_f32_16x16x32_bf16 v[104:107], v[158:161], v[182:185], v[104:107]
	v_mfma_f32_16x16x32_bf16 v[116:119], v[150:153], v[190:193], v[116:119]
	v_mfma_f32_16x16x32_bf16 v[120:123], v[158:161], v[190:193], v[120:123]
	v_mfma_f32_16x16x32_bf16 v[84:87], v[150:153], v[198:201], v[84:87]
	v_mfma_f32_16x16x32_bf16 v[80:83], v[158:161], v[198:201], v[80:83]
	v_mfma_f32_16x16x32_bf16 v[36:39], v[150:153], v[206:209], v[36:39]
	v_mfma_f32_16x16x32_bf16 v[28:31], v[158:161], v[206:209], v[28:31]
	s_setprio 0
	s_setprio 1
	v_mfma_f32_16x16x32_bf16 v[124:127], v[162:165], v[178:181], v[124:127]
	v_mfma_f32_16x16x32_bf16 v[112:115], v[170:173], v[178:181], v[112:115]
	v_mfma_f32_16x16x32_bf16 v[92:95], v[162:165], v[186:189], v[92:95]
	v_mfma_f32_16x16x32_bf16 v[88:91], v[170:173], v[186:189], v[88:91]
	v_mfma_f32_16x16x32_bf16 v[44:47], v[162:165], v[194:197], v[44:47]
	v_mfma_f32_16x16x32_bf16 v[40:43], v[170:173], v[194:197], v[40:43]
	v_mfma_f32_16x16x32_bf16 v[4:7], v[162:165], v[202:205], v[4:7]
	v_mfma_f32_16x16x32_bf16 v[0:3], v[170:173], v[202:205], v[0:3]
	v_mfma_f32_16x16x32_bf16 v[124:127], v[166:169], v[182:185], v[124:127]
	v_mfma_f32_16x16x32_bf16 v[112:115], v[174:177], v[182:185], v[112:115]
	v_mfma_f32_16x16x32_bf16 v[92:95], v[166:169], v[190:193], v[92:95]
	v_mfma_f32_16x16x32_bf16 v[88:91], v[174:177], v[190:193], v[88:91]
	v_mfma_f32_16x16x32_bf16 v[44:47], v[166:169], v[198:201], v[44:47]
	v_mfma_f32_16x16x32_bf16 v[40:43], v[174:177], v[198:201], v[40:43]
	v_mfma_f32_16x16x32_bf16 v[4:7], v[166:169], v[206:209], v[4:7]
	v_mfma_f32_16x16x32_bf16 v[0:3], v[174:177], v[206:209], v[0:3]
	s_barrier
	s_setprio 0
	ds_read_b128 v[146:149], v143
	ds_read_b128 v[150:153], v143 offset:1024
	ds_read_b128 v[154:157], v143 offset:2048
	ds_read_b128 v[158:161], v143 offset:3072
	ds_read_b128 v[162:165], v144
	ds_read_b128 v[166:169], v144 offset:1024
	ds_read_b128 v[170:173], v144 offset:2048
	ds_read_b128 v[174:177], v144 offset:3072
	s_add_u32 s56, s66, 0x80000
	s_addc_u32 s57, s67, 0
	s_mov_b32 m0, s21
	v_lshl_add_u64 v[218:219], s[56:57], 0, v[32:33]
	ds_read_b128 v[178:181], v142 offset:32768
	ds_read_b128 v[182:185], v142 offset:33792
	ds_read_b128 v[186:189], v142 offset:34816
	ds_read_b128 v[190:193], v142 offset:35840
	ds_read_b128 v[194:197], v142 offset:36864
	ds_read_b128 v[198:201], v142 offset:37888
	ds_read_b128 v[202:205], v142 offset:38912
	ds_read_b128 v[206:209], v142 offset:39936
	global_load_lds_dwordx4 v[218:219], off
	v_lshl_add_u64 v[218:219], s[56:57], 0, v[132:133]
	s_mov_b32 m0, s22
	s_nop 0
	global_load_lds_dwordx4 v[218:219], off
	s_waitcnt vmcnt(8) lgkmcnt(0)
	s_setprio 1
	s_barrier
	v_mfma_f32_16x16x32_bf16 v[8:11], v[146:149], v[178:181], v[8:11]
	v_mfma_f32_16x16x32_bf16 v[12:15], v[154:157], v[178:181], v[12:15]
	v_mfma_f32_16x16x32_bf16 v[60:63], v[146:149], v[186:189], v[60:63]
	v_mfma_f32_16x16x32_bf16 v[20:23], v[154:157], v[186:189], v[20:23]
	v_mfma_f32_16x16x32_bf16 v[76:79], v[146:149], v[194:197], v[76:79]
	v_mfma_f32_16x16x32_bf16 v[52:55], v[154:157], v[194:197], v[52:55]
	v_mfma_f32_16x16x32_bf16 v[128:131], v[146:149], v[202:205], v[128:131]
	v_mfma_f32_16x16x32_bf16 v[68:71], v[154:157], v[202:205], v[68:71]
	v_mfma_f32_16x16x32_bf16 v[8:11], v[150:153], v[182:185], v[8:11]
	v_mfma_f32_16x16x32_bf16 v[12:15], v[158:161], v[182:185], v[12:15]
	v_mfma_f32_16x16x32_bf16 v[60:63], v[150:153], v[190:193], v[60:63]
	v_mfma_f32_16x16x32_bf16 v[20:23], v[158:161], v[190:193], v[20:23]
	v_mfma_f32_16x16x32_bf16 v[76:79], v[150:153], v[198:201], v[76:79]
	v_mfma_f32_16x16x32_bf16 v[52:55], v[158:161], v[198:201], v[52:55]
	v_mfma_f32_16x16x32_bf16 v[128:131], v[150:153], v[206:209], v[128:131]
	v_mfma_f32_16x16x32_bf16 v[68:71], v[158:161], v[206:209], v[68:71]
	s_setprio 0
	s_setprio 1
	v_mfma_f32_16x16x32_bf16 v[24:27], v[162:165], v[178:181], v[24:27]
	v_mfma_f32_16x16x32_bf16 v[16:19], v[170:173], v[178:181], v[16:19]
	v_mfma_f32_16x16x32_bf16 v[56:59], v[162:165], v[186:189], v[56:59]
	v_mfma_f32_16x16x32_bf16 v[48:51], v[170:173], v[186:189], v[48:51]
	v_mfma_f32_16x16x32_bf16 v[72:75], v[162:165], v[194:197], v[72:75]
	v_mfma_f32_16x16x32_bf16 v[64:67], v[170:173], v[194:197], v[64:67]
	v_mfma_f32_16x16x32_bf16 v[108:111], v[162:165], v[202:205], v[108:111]
	v_mfma_f32_16x16x32_bf16 v[96:99], v[170:173], v[202:205], v[96:99]
	v_mfma_f32_16x16x32_bf16 v[24:27], v[166:169], v[182:185], v[24:27]
	v_mfma_f32_16x16x32_bf16 v[16:19], v[174:177], v[182:185], v[16:19]
	v_mfma_f32_16x16x32_bf16 v[56:59], v[166:169], v[190:193], v[56:59]
	v_mfma_f32_16x16x32_bf16 v[48:51], v[174:177], v[190:193], v[48:51]
	v_mfma_f32_16x16x32_bf16 v[72:75], v[166:169], v[198:201], v[72:75]
	v_mfma_f32_16x16x32_bf16 v[64:67], v[174:177], v[198:201], v[64:67]
	v_mfma_f32_16x16x32_bf16 v[108:111], v[166:169], v[206:209], v[108:111]
	v_mfma_f32_16x16x32_bf16 v[96:99], v[174:177], v[206:209], v[96:99]
	s_barrier
; #define PG8_WAIT_V(n) asm volatile("s_waitcnt vmcnt(" #n ")" ::: "memory")
; #define PG8_BAR __builtin_amdgcn_s_barrier()
; template <class Epi, class Sched, bool ALIGN_EPI = false, bool SP2 = false, bool A_TILED = false>
; __device__ __forceinline__ void gemm_phase(PG8_LAS unsigned char* lds, const Gemm g, const Sched& S, const Epi& E, const int wave_s) {
;     ...
;     PG8_WAIT_V(0);
;     if constexpr (!ALIGN_EPI) { if (wr == 0) PG8_BAR; }
	s_setprio 0
	s_mov_b32 m0, s51
	v_lshl_add_u64 v[210:211], v[210:211], 0, s[60:61]
	s_add_u32 s56, s64, 0x80080
	ds_read_b128 v[178:181], v142 offset:49152
	ds_read_b128 v[182:185], v142 offset:50176
	ds_read_b128 v[186:189], v142 offset:51200
	ds_read_b128 v[190:193], v142 offset:52224
	ds_read_b128 v[194:197], v142 offset:53248
	ds_read_b128 v[198:201], v142 offset:54272
	ds_read_b128 v[202:205], v142 offset:55296
	ds_read_b128 v[206:209], v142 offset:56320
	global_load_lds_dwordx4 v[210:211], off
	v_lshl_add_u64 v[210:211], v[212:213], 0, s[60:61]
	s_mov_b32 m0, s52
	s_addc_u32 s57, s65, 0
	global_load_lds_dwordx4 v[210:211], off
	v_lshl_add_u64 v[210:211], s[56:57], 0, v[34:35]
	s_mov_b32 m0, s53
	s_nop 0
	global_load_lds_dwordx4 v[210:211], off
	v_lshl_add_u64 v[210:211], s[56:57], 0, v[134:135]
	s_mov_b32 m0, s54
	s_nop 0
	global_load_lds_dwordx4 v[210:211], off
	v_lshl_add_u64 v[210:211], v[214:215], 0, s[60:61]
	s_mov_b32 m0, s23
	s_nop 0
	global_load_lds_dwordx4 v[210:211], off
	v_lshl_add_u64 v[210:211], v[216:217], 0, s[60:61]
	s_mov_b32 m0, s36
	s_nop 0
	global_load_lds_dwordx4 v[210:211], off
	s_waitcnt vmcnt(8) lgkmcnt(0)
	s_setprio 1
	s_barrier
	v_mfma_f32_16x16x32_bf16 v[100:103], v[146:149], v[178:181], v[100:103]
	v_mfma_f32_16x16x32_bf16 v[104:107], v[154:157], v[178:181], v[104:107]
	v_mfma_f32_16x16x32_bf16 v[116:119], v[146:149], v[186:189], v[116:119]
	v_mfma_f32_16x16x32_bf16 v[120:123], v[154:157], v[186:189], v[120:123]
	v_mfma_f32_16x16x32_bf16 v[84:87], v[146:149], v[194:197], v[84:87]
	v_mfma_f32_16x16x32_bf16 v[80:83], v[154:157], v[194:197], v[80:83]
	v_mfma_f32_16x16x32_bf16 v[36:39], v[146:149], v[202:205], v[36:39]
	v_mfma_f32_16x16x32_bf16 v[28:31], v[154:157], v[202:205], v[28:31]
	v_mfma_f32_16x16x32_bf16 v[100:103], v[150:153], v[182:185], v[100:103]
	v_mfma_f32_16x16x32_bf16 v[104:107], v[158:161], v[182:185], v[104:107]
	v_mfma_f32_16x16x32_bf16 v[116:119], v[150:153], v[190:193], v[116:119]
	v_mfma_f32_16x16x32_bf16 v[120:123], v[158:161], v[190:193], v[120:123]
	v_mfma_f32_16x16x32_bf16 v[84:87], v[150:153], v[198:201], v[84:87]
	v_mfma_f32_16x16x32_bf16 v[80:83], v[158:161], v[198:201], v[80:83]
	v_mfma_f32_16x16x32_bf16 v[36:39], v[150:153], v[206:209], v[36:39]
	v_mfma_f32_16x16x32_bf16 v[28:31], v[158:161], v[206:209], v[28:31]
	s_setprio 0
	s_setprio 1
	v_mfma_f32_16x16x32_bf16 v[124:127], v[162:165], v[178:181], v[124:127]
	v_mfma_f32_16x16x32_bf16 v[112:115], v[170:173], v[178:181], v[112:115]
	v_mfma_f32_16x16x32_bf16 v[92:95], v[162:165], v[186:189], v[92:95]
	v_mfma_f32_16x16x32_bf16 v[88:91], v[170:173], v[186:189], v[88:91]
	v_mfma_f32_16x16x32_bf16 v[44:47], v[162:165], v[194:197], v[44:47]
	v_mfma_f32_16x16x32_bf16 v[40:43], v[170:173], v[194:197], v[40:43]
	v_mfma_f32_16x16x32_bf16 v[4:7], v[162:165], v[202:205], v[4:7]
	v_mfma_f32_16x16x32_bf16 v[0:3], v[170:173], v[202:205], v[0:3]
	v_mfma_f32_16x16x32_bf16 v[124:127], v[166:169], v[182:185], v[124:127]
	v_mfma_f32_16x16x32_bf16 v[112:115], v[174:177], v[182:185], v[112:115]
	v_mfma_f32_16x16x32_bf16 v[92:95], v[166:169], v[190:193], v[92:95]
	v_mfma_f32_16x16x32_bf16 v[88:91], v[174:177], v[190:193], v[88:91]
	v_mfma_f32_16x16x32_bf16 v[44:47], v[166:169], v[198:201], v[44:47]
	v_mfma_f32_16x16x32_bf16 v[40:43], v[174:177], v[198:201], v[40:43]
	v_mfma_f32_16x16x32_bf16 v[4:7], v[166:169], v[206:209], v[4:7]
	v_mfma_f32_16x16x32_bf16 v[0:3], v[174:177], v[206:209], v[0:3]
	s_barrier
	s_setprio 0
	s_add_i32 s41, s41, 2
	s_add_u32 s37, s37, 0x100
	s_addc_u32 s38, s38, 0
	s_add_u32 s39, s39, 0x100
	s_addc_u32 s40, s40, 0
	v_lshl_add_u64 v[136:137], v[136:137], 0, s[62:63]
	s_cmp_gt_u32 s41, 29
	v_lshl_add_u64 v[138:139], v[138:139], 0, s[62:63]
	s_cbranch_scc0 .LBB0_2729
	s_waitcnt vmcnt(0)
	s_cmpk_lt_u32 s0, 0x100
	s_cbranch_scc0 .LBB0_2732
	s_barrier

; template <class Epi, class Sched, bool ALIGN_EPI = false, bool SP2 = false, bool A_TILED = false>
; __device__ __forceinline__ void gemm_phase(PG8_LAS unsigned char* lds, const Gemm g, const Sched& S, const Epi& E, const int wave_s) {
;     ...
;         const char* nA = has_next ? (const char*)g.A + (size_t)nxt.pm * tstepA : cA; const char* nB = has_next ? (const char*)g.Bt + (size_t)nxt.pn * tstep : cB;
;         constexpr bool PEEL = SP2 && !Epi::AFTER_DRAIN;
;         if constexpr (PEEL) {
;             const char* a1 = cA + kstepA; const char* a2 = cA + 2 * kstepA; const char* b2 = cB + 2 * kstep; const char* a3 = a2 + kstepA; const char* b3 = b2 + kstep;
;             PG8_ITER(PG8_MMAZ)
.LBB0_2840:
	s_ashr_i32 s65, s64, 31
	s_lshl_b64 s[54:55], s[64:65], 20
	s_add_u32 s66, s1, s54
	ds_read_b128 v[0:3], v145
	ds_read_b128 v[4:7], v145 offset:1024
	ds_read_b128 v[8:11], v145 offset:2048
	ds_read_b128 v[12:15], v145 offset:3072
	ds_read_b128 v[16:19], v146
	ds_read_b128 v[20:23], v146 offset:1024
	ds_read_b128 v[24:27], v146 offset:2048
	ds_read_b128 v[28:31], v146 offset:3072
	s_addc_u32 s67, s8, s55
	s_ashr_i32 s63, s62, 31
	s_lshl_b64 s[54:55], s[62:63], 20
	s_add_u32 s68, s9, s54
	s_addc_u32 s69, s14, s55
	s_and_b64 s[54:55], s[2:3], exec
	s_cselect_b32 s54, s67, s75
	s_cselect_b32 s55, s66, s74
	s_cselect_b32 s56, s69, s73
	s_cselect_b32 s57, s68, s72
	s_add_u32 s76, s74, 0x80080
	s_addc_u32 s77, s75, 0
	s_add_i32 s58, s22, 0xc000
	v_lshl_add_u64 v[64:65], s[76:77], 0, v[134:135]
	s_mov_b32 m0, s58
	s_add_i32 s59, s22, 0xe000
	ds_read_b128 v[32:35], v147
	ds_read_b128 v[36:39], v147 offset:1024
	ds_read_b128 v[40:43], v147 offset:2048
	ds_read_b128 v[44:47], v147 offset:3072
	ds_read_b128 v[48:51], v147 offset:4096
	ds_read_b128 v[52:55], v147 offset:5120
	ds_read_b128 v[56:59], v147 offset:6144
	ds_read_b128 v[60:63], v147 offset:7168
	global_load_lds_dwordx4 v[64:65], off
	v_lshl_add_u64 v[64:65], s[76:77], 0, v[132:133]
	s_mov_b32 m0, s59
	s_nop 0
	global_load_lds_dwordx4 v[64:65], off
	s_waitcnt vmcnt(8) lgkmcnt(0)
	s_setprio 1
	s_barrier
	v_mfma_f32_16x16x32_bf16 v[88:91], v[0:3], v[56:59], 0
	v_mfma_f32_16x16x32_bf16 v[64:67], v[0:3], v[32:35], 0
	v_mfma_f32_16x16x32_bf16 v[68:71], v[8:11], v[32:35], 0
	v_mfma_f32_16x16x32_bf16 v[72:75], v[0:3], v[40:43], 0
	v_mfma_f32_16x16x32_bf16 v[76:79], v[8:11], v[40:43], 0
	v_mfma_f32_16x16x32_bf16 v[80:83], v[0:3], v[48:51], 0
	v_mfma_f32_16x16x32_bf16 v[84:87], v[8:11], v[48:51], 0
	v_mfma_f32_16x16x32_bf16 v[96:99], v[4:7], v[60:63], v[88:91]
	v_mfma_f32_16x16x32_bf16 v[88:91], v[8:11], v[56:59], 0
	v_mfma_f32_16x16x32_bf16 v[64:67], v[4:7], v[36:39], v[64:67]
	v_mfma_f32_16x16x32_bf16 v[68:71], v[12:15], v[36:39], v[68:71]
	v_mfma_f32_16x16x32_bf16 v[72:75], v[4:7], v[44:47], v[72:75]
	v_mfma_f32_16x16x32_bf16 v[76:79], v[12:15], v[44:47], v[76:79]
	v_mfma_f32_16x16x32_bf16 v[80:83], v[4:7], v[52:55], v[80:83]
	v_mfma_f32_16x16x32_bf16 v[84:87], v[12:15], v[52:55], v[84:87]
	v_mfma_f32_16x16x32_bf16 v[100:103], v[12:15], v[60:63], v[88:91]
	s_setprio 0
	s_setprio 1
	v_mfma_f32_16x16x32_bf16 v[88:91], v[16:19], v[32:35], 0
	v_mfma_f32_16x16x32_bf16 v[32:35], v[24:27], v[32:35], 0
	v_mfma_f32_16x16x32_bf16 v[112:115], v[20:23], v[36:39], v[88:91]
	v_mfma_f32_16x16x32_bf16 v[32:35], v[28:31], v[36:39], v[32:35]
	v_mfma_f32_16x16x32_bf16 v[36:39], v[16:19], v[40:43], 0
	v_mfma_f32_16x16x32_bf16 v[40:43], v[24:27], v[40:43], 0
	v_mfma_f32_16x16x32_bf16 v[36:39], v[20:23], v[44:47], v[36:39]
	v_mfma_f32_16x16x32_bf16 v[40:43], v[28:31], v[44:47], v[40:43]
	v_mfma_f32_16x16x32_bf16 v[44:47], v[16:19], v[48:51], 0
	v_mfma_f32_16x16x32_bf16 v[48:51], v[24:27], v[48:51], 0
	v_mfma_f32_16x16x32_bf16 v[44:47], v[20:23], v[52:55], v[44:47]
	v_mfma_f32_16x16x32_bf16 v[48:51], v[28:31], v[52:55], v[48:51]
	v_mfma_f32_16x16x32_bf16 v[52:55], v[16:19], v[56:59], 0
	v_mfma_f32_16x16x32_bf16 v[56:59], v[24:27], v[56:59], 0
	v_mfma_f32_16x16x32_bf16 v[52:55], v[20:23], v[60:63], v[52:55]
	v_mfma_f32_16x16x32_bf16 v[56:59], v[28:31], v[60:63], v[56:59]
	s_barrier
	s_setprio 0
	s_add_i32 s63, s51, s15
	v_lshl_add_u64 v[242:243], s[72:73], 0, v[128:129]
	s_add_i32 s65, s63, 0x2000
	v_lshl_add_u64 v[148:149], v[242:243], 0, s[46:47]
	s_mov_b32 m0, s63
	v_lshl_add_u64 v[244:245], s[72:73], 0, v[130:131]
	s_add_u32 s76, s72, 0x80100
	ds_read_b128 v[60:63], v147 offset:16384
	ds_read_b128 v[88:91], v147 offset:17408
	ds_read_b128 v[92:95], v147 offset:18432
	ds_read_b128 v[104:107], v147 offset:19456
	ds_read_b128 v[108:111], v147 offset:20480
	ds_read_b128 v[116:119], v147 offset:21504
	ds_read_b128 v[120:123], v147 offset:22528
	ds_read_b128 v[124:127], v147 offset:23552
	global_load_lds_dwordx4 v[148:149], off
	v_lshl_add_u64 v[148:149], v[244:245], 0, s[46:47]
	s_mov_b32 m0, s65
	s_addc_u32 s77, s73, 0
	s_add_i32 s71, s52, s15
	global_load_lds_dwordx4 v[148:149], off
	v_lshl_add_u64 v[148:149], s[76:77], 0, v[128:129]
	s_mov_b32 m0, s71
	s_add_i32 s78, s71, 0x2000
	global_load_lds_dwordx4 v[148:149], off
	v_lshl_add_u64 v[148:149], s[76:77], 0, v[130:131]
	s_mov_b32 m0, s78
	v_lshl_add_u64 v[246:247], s[74:75], 0, v[134:135]
	global_load_lds_dwordx4 v[148:149], off
	v_lshl_add_u64 v[148:149], v[246:247], 0, s[46:47]
	s_mov_b32 m0, s22
	v_lshl_add_u64 v[248:249], s[74:75], 0, v[132:133]
	global_load_lds_dwordx4 v[148:149], off
	v_lshl_add_u64 v[148:149], v[248:249], 0, s[46:47]
	s_mov_b32 m0, s23
	s_nop 0
	global_load_lds_dwordx4 v[148:149], off
	s_waitcnt vmcnt(8) lgkmcnt(0)
	s_setprio 1
	s_barrier
	v_mfma_f32_16x16x32_bf16 v[148:151], v[0:3], v[60:63], 0
	v_mfma_f32_16x16x32_bf16 v[158:161], v[0:3], v[92:95], 0
	v_mfma_f32_16x16x32_bf16 v[166:169], v[0:3], v[108:111], 0
	v_mfma_f32_16x16x32_bf16 v[0:3], v[0:3], v[120:123], 0
	v_mfma_f32_16x16x32_bf16 v[150:153], v[4:7], v[88:91], v[148:151]
	v_mfma_f32_16x16x32_bf16 v[158:161], v[4:7], v[104:107], v[158:161]
	v_mfma_f32_16x16x32_bf16 v[166:169], v[4:7], v[116:119], v[166:169]
	v_mfma_f32_16x16x32_bf16 v[0:3], v[4:7], v[124:127], v[0:3]
	v_mfma_f32_16x16x32_bf16 v[4:7], v[8:11], v[120:123], 0
	v_mfma_f32_16x16x32_bf16 v[154:157], v[8:11], v[60:63], 0
	v_mfma_f32_16x16x32_bf16 v[162:165], v[8:11], v[92:95], 0
	v_mfma_f32_16x16x32_bf16 v[170:173], v[8:11], v[108:111], 0
	v_mfma_f32_16x16x32_bf16 v[4:7], v[12:15], v[124:127], v[4:7]
	v_mfma_f32_16x16x32_bf16 v[154:157], v[12:15], v[88:91], v[154:157]
	v_mfma_f32_16x16x32_bf16 v[162:165], v[12:15], v[104:107], v[162:165]
	v_mfma_f32_16x16x32_bf16 v[170:173], v[12:15], v[116:119], v[170:173]
	s_setprio 0
	s_setprio 1
	v_mfma_f32_16x16x32_bf16 v[8:11], v[16:19], v[60:63], 0
	v_mfma_f32_16x16x32_bf16 v[174:177], v[20:23], v[88:91], v[8:11]
	v_mfma_f32_16x16x32_bf16 v[8:11], v[24:27], v[60:63], 0
	v_mfma_f32_16x16x32_bf16 v[60:63], v[28:31], v[88:91], v[8:11]
	v_mfma_f32_16x16x32_bf16 v[8:11], v[16:19], v[92:95], 0
	v_mfma_f32_16x16x32_bf16 v[178:181], v[20:23], v[104:107], v[8:11]
	v_mfma_f32_16x16x32_bf16 v[8:11], v[24:27], v[92:95], 0
	v_mfma_f32_16x16x32_bf16 v[182:185], v[28:31], v[104:107], v[8:11]
	v_mfma_f32_16x16x32_bf16 v[8:11], v[16:19], v[108:111], 0
	v_mfma_f32_16x16x32_bf16 v[186:189], v[20:23], v[116:119], v[8:11]
	v_mfma_f32_16x16x32_bf16 v[8:11], v[24:27], v[108:111], 0
	v_mfma_f32_16x16x32_bf16 v[190:193], v[28:31], v[116:119], v[8:11]
	v_mfma_f32_16x16x32_bf16 v[8:11], v[16:19], v[120:123], 0
	v_mfma_f32_16x16x32_bf16 v[194:197], v[20:23], v[124:127], v[8:11]
	v_mfma_f32_16x16x32_bf16 v[8:11], v[24:27], v[120:123], 0
	v_mfma_f32_16x16x32_bf16 v[198:201], v[28:31], v[124:127], v[8:11]
	s_barrier
	s_setprio 0
	s_add_i32 s79, 0, 0x18000
	s_add_i32 s81, 0, 0x1c000
	v_add_u32_e32 v148, s79, v144
	v_add_u32_e32 v149, s81, v144
	s_nop 0
	ds_read_b128 v[8:11], v148
	ds_read_b128 v[12:15], v148 offset:1024
	ds_read_b128 v[16:19], v148 offset:2048
	ds_read_b128 v[20:23], v148 offset:3072
	ds_read_b128 v[202:205], v149
	ds_read_b128 v[206:209], v149 offset:1024
	ds_read_b128 v[210:213], v149 offset:2048
	ds_read_b128 v[214:217], v149 offset:3072
	s_add_u32 s76, s74, 0x80100
	s_addc_u32 s77, s75, 0
	s_mov_b32 m0, s36
	v_lshl_add_u64 v[88:89], s[76:77], 0, v[134:135]
	ds_read_b128 v[24:27], v147 offset:32768
	ds_read_b128 v[28:31], v147 offset:33792
	ds_read_b128 v[218:221], v147 offset:34816
	ds_read_b128 v[222:225], v147 offset:35840
	ds_read_b128 v[226:229], v147 offset:36864
	ds_read_b128 v[230:233], v147 offset:37888
	ds_read_b128 v[234:237], v147 offset:38912
	ds_read_b128 v[238:241], v147 offset:39936
	global_load_lds_dwordx4 v[88:89], off
	v_lshl_add_u64 v[88:89], s[76:77], 0, v[132:133]
	s_mov_b32 m0, s37
	s_nop 0
	global_load_lds_dwordx4 v[88:89], off
	s_waitcnt vmcnt(8) lgkmcnt(0)
	s_setprio 1
	s_barrier
	v_mfma_f32_16x16x32_bf16 v[64:67], v[8:11], v[24:27], v[64:67]
	v_mfma_f32_16x16x32_bf16 v[120:123], v[12:15], v[28:31], v[64:67]
	v_mfma_f32_16x16x32_bf16 v[64:67], v[16:19], v[24:27], v[68:71]
	v_mfma_f32_16x16x32_bf16 v[124:127], v[20:23], v[28:31], v[64:67]
	v_mfma_f32_16x16x32_bf16 v[64:67], v[8:11], v[218:221], v[72:75]
	v_mfma_f32_16x16x32_bf16 v[104:107], v[12:15], v[222:225], v[64:67]
	v_mfma_f32_16x16x32_bf16 v[64:67], v[16:19], v[218:221], v[76:79]
	v_mfma_f32_16x16x32_bf16 v[108:111], v[20:23], v[222:225], v[64:67]
	v_mfma_f32_16x16x32_bf16 v[64:67], v[8:11], v[226:229], v[80:83]
	v_mfma_f32_16x16x32_bf16 v[88:91], v[12:15], v[230:233], v[64:67]
	v_mfma_f32_16x16x32_bf16 v[64:67], v[16:19], v[226:229], v[84:87]
	v_mfma_f32_16x16x32_bf16 v[92:95], v[20:23], v[230:233], v[64:67]
	v_mfma_f32_16x16x32_bf16 v[64:67], v[8:11], v[234:237], v[96:99]
	v_mfma_f32_16x16x32_bf16 v[68:71], v[16:19], v[234:237], v[100:103]
	v_mfma_f32_16x16x32_bf16 v[64:67], v[12:15], v[238:241], v[64:67]
	v_mfma_f32_16x16x32_bf16 v[68:71], v[20:23], v[238:241], v[68:71]
	s_setprio 0
	s_setprio 1
	v_mfma_f32_16x16x32_bf16 v[72:75], v[202:205], v[24:27], v[112:115]
	v_mfma_f32_16x16x32_bf16 v[24:27], v[210:213], v[24:27], v[32:35]
	v_mfma_f32_16x16x32_bf16 v[116:119], v[214:217], v[28:31], v[24:27]
	v_mfma_f32_16x16x32_bf16 v[24:27], v[202:205], v[218:221], v[36:39]
	v_mfma_f32_16x16x32_bf16 v[96:99], v[206:209], v[222:225], v[24:27]
	v_mfma_f32_16x16x32_bf16 v[24:27], v[210:213], v[218:221], v[40:43]
	v_mfma_f32_16x16x32_bf16 v[100:103], v[214:217], v[222:225], v[24:27]
	v_mfma_f32_16x16x32_bf16 v[24:27], v[202:205], v[226:229], v[44:47]
	v_mfma_f32_16x16x32_bf16 v[80:83], v[206:209], v[230:233], v[24:27]
	v_mfma_f32_16x16x32_bf16 v[24:27], v[210:213], v[226:229], v[48:51]
	v_mfma_f32_16x16x32_bf16 v[84:87], v[214:217], v[230:233], v[24:27]
	v_mfma_f32_16x16x32_bf16 v[24:27], v[202:205], v[234:237], v[52:55]
	v_mfma_f32_16x16x32_bf16 v[48:51], v[206:209], v[238:241], v[24:27]
	v_mfma_f32_16x16x32_bf16 v[24:27], v[210:213], v[234:237], v[56:59]
	v_mfma_f32_16x16x32_bf16 v[112:115], v[206:209], v[28:31], v[72:75]
	v_mfma_f32_16x16x32_bf16 v[52:55], v[214:217], v[238:241], v[24:27]
	s_barrier
; template <class Epi, class Sched, bool ALIGN_EPI = false, bool SP2 = false, bool A_TILED = false>
; __device__ __forceinline__ void gemm_phase(PG8_LAS unsigned char* lds, const Gemm g, const Sched& S, const Epi& E, const int wave_s) {
;     ...
;         for (int t = PEEL ? 2 : 0; t < nt; t += 2) {
;             const bool last = (t == nt - 2);
;             const char* a1 = cA + (size_t)(t + 1) * kstepA;
;             const char* a2 = last ? nA : cA + (size_t)(t + 2) * kstepA; const char* b2 = last ? nB : cB + (size_t)(t + 2) * kstep;
;             const char* a3 = a2 + kstepA; const char* b3 = b2 + kstep;
;             if (last && has_next) S.a_ready(nxt);
	s_setprio 0
	s_add_i32 s79, s79, s15
	s_add_i32 s80, s79, 0x2000
	s_nop 1
	v_lshl_add_u64 v[24:25], v[242:243], 0, s[60:61]
	s_mov_b32 m0, s79
	s_add_u32 s76, s72, 0x80180
	ds_read_b128 v[32:35], v147 offset:49152
	ds_read_b128 v[36:39], v147 offset:50176
	ds_read_b128 v[218:221], v147 offset:51200
	ds_read_b128 v[222:225], v147 offset:52224
	ds_read_b128 v[226:229], v147 offset:53248
	ds_read_b128 v[230:233], v147 offset:54272
	ds_read_b128 v[234:237], v147 offset:55296
	ds_read_b128 v[238:241], v147 offset:56320
	global_load_lds_dwordx4 v[24:25], off
	v_lshl_add_u64 v[24:25], v[244:245], 0, s[60:61]
	s_mov_b32 m0, s80
	s_addc_u32 s77, s73, 0
	s_add_i32 s81, s81, s15
	global_load_lds_dwordx4 v[24:25], off
	v_lshl_add_u64 v[24:25], s[76:77], 0, v[128:129]
	s_mov_b32 m0, s81
	s_add_i32 s82, s81, 0x2000
	global_load_lds_dwordx4 v[24:25], off
	v_lshl_add_u64 v[24:25], s[76:77], 0, v[130:131]
	s_mov_b32 m0, s82
	s_nop 0
	global_load_lds_dwordx4 v[24:25], off
	v_lshl_add_u64 v[24:25], v[246:247], 0, s[60:61]
	s_mov_b32 m0, s43
	s_nop 0
	global_load_lds_dwordx4 v[24:25], off
	v_lshl_add_u64 v[24:25], v[248:249], 0, s[60:61]
	s_mov_b32 m0, s48
	s_nop 0
	global_load_lds_dwordx4 v[24:25], off
	s_waitcnt vmcnt(8) lgkmcnt(0)
	s_setprio 1
	s_barrier
	v_mfma_f32_16x16x32_bf16 v[24:27], v[8:11], v[32:35], v[150:153]
	v_mfma_f32_16x16x32_bf16 v[72:75], v[12:15], v[36:39], v[24:27]
	v_mfma_f32_16x16x32_bf16 v[24:27], v[16:19], v[32:35], v[154:157]
	v_mfma_f32_16x16x32_bf16 v[76:79], v[20:23], v[36:39], v[24:27]
	v_mfma_f32_16x16x32_bf16 v[24:27], v[8:11], v[218:221], v[158:161]
	v_mfma_f32_16x16x32_bf16 v[40:43], v[12:15], v[222:225], v[24:27]
	v_mfma_f32_16x16x32_bf16 v[24:27], v[16:19], v[218:221], v[162:165]
	v_mfma_f32_16x16x32_bf16 v[0:3], v[8:11], v[234:237], v[0:3]
	v_mfma_f32_16x16x32_bf16 v[44:47], v[20:23], v[222:225], v[24:27]
	v_mfma_f32_16x16x32_bf16 v[24:27], v[8:11], v[226:229], v[166:169]
	v_mfma_f32_16x16x32_bf16 v[28:31], v[16:19], v[226:229], v[170:173]
	v_mfma_f32_16x16x32_bf16 v[8:11], v[12:15], v[238:241], v[0:3]
	v_mfma_f32_16x16x32_bf16 v[0:3], v[16:19], v[234:237], v[4:7]
	v_mfma_f32_16x16x32_bf16 v[24:27], v[12:15], v[230:233], v[24:27]
	v_mfma_f32_16x16x32_bf16 v[28:31], v[20:23], v[230:233], v[28:31]
	v_mfma_f32_16x16x32_bf16 v[12:15], v[20:23], v[238:241], v[0:3]
	s_setprio 0
	s_setprio 1
	v_mfma_f32_16x16x32_bf16 v[0:3], v[202:205], v[32:35], v[174:177]
	v_mfma_f32_16x16x32_bf16 v[56:59], v[206:209], v[36:39], v[0:3]
	v_mfma_f32_16x16x32_bf16 v[0:3], v[210:213], v[32:35], v[60:63]
	v_mfma_f32_16x16x32_bf16 v[60:63], v[214:217], v[36:39], v[0:3]
	v_mfma_f32_16x16x32_bf16 v[0:3], v[202:205], v[218:221], v[178:181]
	v_mfma_f32_16x16x32_bf16 v[32:35], v[206:209], v[222:225], v[0:3]
	v_mfma_f32_16x16x32_bf16 v[0:3], v[210:213], v[218:221], v[182:185]
	v_mfma_f32_16x16x32_bf16 v[36:39], v[214:217], v[222:225], v[0:3]
	v_mfma_f32_16x16x32_bf16 v[0:3], v[202:205], v[226:229], v[186:189]
	v_mfma_f32_16x16x32_bf16 v[16:19], v[206:209], v[230:233], v[0:3]
	v_mfma_f32_16x16x32_bf16 v[0:3], v[210:213], v[226:229], v[190:193]
	v_mfma_f32_16x16x32_bf16 v[20:23], v[214:217], v[230:233], v[0:3]
	v_mfma_f32_16x16x32_bf16 v[0:3], v[202:205], v[234:237], v[194:197]
	v_mfma_f32_16x16x32_bf16 v[4:7], v[210:213], v[234:237], v[198:201]
	v_mfma_f32_16x16x32_bf16 v[0:3], v[206:209], v[238:241], v[0:3]
	v_mfma_f32_16x16x32_bf16 v[4:7], v[214:217], v[238:241], v[4:7]
	s_barrier
	s_setprio 0
	s_add_u32 s83, s72, 0x200
	s_addc_u32 s85, s73, 0
	s_add_u32 s72, s74, 0x80180
	s_addc_u32 s73, s75, 0
	s_mov_b32 s88, 0
.LBB0_2841:
	ds_read_b128 v[150:153], v145
	ds_read_b128 v[154:157], v145 offset:1024
	ds_read_b128 v[158:161], v145 offset:2048
	ds_read_b128 v[162:165], v145 offset:3072
	ds_read_b128 v[166:169], v146
	ds_read_b128 v[170:173], v146 offset:1024
	ds_read_b128 v[174:177], v146 offset:2048
	ds_read_b128 v[178:181], v146 offset:3072
	s_add_u32 s74, s72, 0xfff80080
	s_addc_u32 s75, s73, -1
	s_cmp_eq_u32 s88, 28
	s_cselect_b32 s77, s54, s75
	s_cselect_b32 s76, s55, s74
	s_cselect_b32 s75, s56, s85
	s_cselect_b32 s74, s57, s83
	s_mov_b32 m0, s58
	v_lshl_add_u64 v[214:215], s[72:73], 0, v[138:139]
	ds_read_b128 v[182:185], v147
	ds_read_b128 v[186:189], v147 offset:1024
	ds_read_b128 v[190:193], v147 offset:2048
	ds_read_b128 v[194:197], v147 offset:3072
	ds_read_b128 v[198:201], v147 offset:4096
	ds_read_b128 v[202:205], v147 offset:5120
	ds_read_b128 v[206:209], v147 offset:6144
	ds_read_b128 v[210:213], v147 offset:7168
	global_load_lds_dwordx4 v[214:215], off
	v_lshl_add_u64 v[214:215], s[72:73], 0, v[136:137]
	s_mov_b32 m0, s59
	s_nop 0
	global_load_lds_dwordx4 v[214:215], off
	s_waitcnt vmcnt(8) lgkmcnt(0)
	s_setprio 1
	s_barrier
	v_mfma_f32_16x16x32_bf16 v[120:123], v[150:153], v[182:185], v[120:123]
	v_mfma_f32_16x16x32_bf16 v[124:127], v[158:161], v[182:185], v[124:127]
	v_mfma_f32_16x16x32_bf16 v[104:107], v[150:153], v[190:193], v[104:107]
	v_mfma_f32_16x16x32_bf16 v[108:111], v[158:161], v[190:193], v[108:111]
	v_mfma_f32_16x16x32_bf16 v[88:91], v[150:153], v[198:201], v[88:91]
	v_mfma_f32_16x16x32_bf16 v[92:95], v[158:161], v[198:201], v[92:95]
	v_mfma_f32_16x16x32_bf16 v[64:67], v[150:153], v[206:209], v[64:67]
	v_mfma_f32_16x16x32_bf16 v[68:71], v[158:161], v[206:209], v[68:71]
	v_mfma_f32_16x16x32_bf16 v[120:123], v[154:157], v[186:189], v[120:123]
	v_mfma_f32_16x16x32_bf16 v[124:127], v[162:165], v[186:189], v[124:127]
	v_mfma_f32_16x16x32_bf16 v[104:107], v[154:157], v[194:197], v[104:107]
	v_mfma_f32_16x16x32_bf16 v[108:111], v[162:165], v[194:197], v[108:111]
	v_mfma_f32_16x16x32_bf16 v[88:91], v[154:157], v[202:205], v[88:91]
	v_mfma_f32_16x16x32_bf16 v[92:95], v[162:165], v[202:205], v[92:95]
	v_mfma_f32_16x16x32_bf16 v[64:67], v[154:157], v[210:213], v[64:67]
	v_mfma_f32_16x16x32_bf16 v[68:71], v[162:165], v[210:213], v[68:71]
	s_setprio 0
	s_setprio 1
	v_mfma_f32_16x16x32_bf16 v[112:115], v[166:169], v[182:185], v[112:115]
	v_mfma_f32_16x16x32_bf16 v[116:119], v[174:177], v[182:185], v[116:119]
	v_mfma_f32_16x16x32_bf16 v[96:99], v[166:169], v[190:193], v[96:99]
	v_mfma_f32_16x16x32_bf16 v[100:103], v[174:177], v[190:193], v[100:103]
	v_mfma_f32_16x16x32_bf16 v[80:83], v[166:169], v[198:201], v[80:83]
	v_mfma_f32_16x16x32_bf16 v[84:87], v[174:177], v[198:201], v[84:87]
	v_mfma_f32_16x16x32_bf16 v[48:51], v[166:169], v[206:209], v[48:51]
	v_mfma_f32_16x16x32_bf16 v[52:55], v[174:177], v[206:209], v[52:55]
	v_mfma_f32_16x16x32_bf16 v[112:115], v[170:173], v[186:189], v[112:115]
	v_mfma_f32_16x16x32_bf16 v[116:119], v[178:181], v[186:189], v[116:119]
	v_mfma_f32_16x16x32_bf16 v[96:99], v[170:173], v[194:197], v[96:99]
	v_mfma_f32_16x16x32_bf16 v[100:103], v[178:181], v[194:197], v[100:103]
	v_mfma_f32_16x16x32_bf16 v[80:83], v[170:173], v[202:205], v[80:83]
	v_mfma_f32_16x16x32_bf16 v[84:87], v[178:181], v[202:205], v[84:87]
	v_mfma_f32_16x16x32_bf16 v[48:51], v[170:173], v[210:213], v[48:51]
	v_mfma_f32_16x16x32_bf16 v[52:55], v[178:181], v[210:213], v[52:55]
	s_barrier
	s_setprio 0
	s_mov_b32 m0, s63
	v_lshl_add_u64 v[214:215], s[74:75], 0, v[128:129]
	s_add_u32 s90, s74, 0x80000
	ds_read_b128 v[182:185], v147 offset:16384
	ds_read_b128 v[186:189], v147 offset:17408
	ds_read_b128 v[190:193], v147 offset:18432
	ds_read_b128 v[194:197], v147 offset:19456
	ds_read_b128 v[198:201], v147 offset:20480
	ds_read_b128 v[202:205], v147 offset:21504
	ds_read_b128 v[206:209], v147 offset:22528
	ds_read_b128 v[210:213], v147 offset:23552
	global_load_lds_dwordx4 v[214:215], off
	v_lshl_add_u64 v[216:217], s[74:75], 0, v[130:131]
	s_mov_b32 m0, s65
	s_addc_u32 s91, s75, 0
	global_load_lds_dwordx4 v[216:217], off
	v_lshl_add_u64 v[218:219], s[90:91], 0, v[128:129]
	s_mov_b32 m0, s71
	v_lshl_add_u64 v[220:221], s[76:77], 0, v[132:133]
	global_load_lds_dwordx4 v[218:219], off
	v_lshl_add_u64 v[218:219], s[90:91], 0, v[130:131]
	s_mov_b32 m0, s78
	s_nop 0
	global_load_lds_dwordx4 v[218:219], off
	v_lshl_add_u64 v[218:219], s[76:77], 0, v[134:135]
	s_mov_b32 m0, s22
	s_nop 0
	global_load_lds_dwordx4 v[218:219], off
	s_mov_b32 m0, s23
	s_nop 0
	global_load_lds_dwordx4 v[220:221], off
	s_waitcnt vmcnt(8) lgkmcnt(0)
	s_setprio 1
	s_barrier
	v_mfma_f32_16x16x32_bf16 v[72:75], v[150:153], v[182:185], v[72:75]
	v_mfma_f32_16x16x32_bf16 v[76:79], v[158:161], v[182:185], v[76:79]
	v_mfma_f32_16x16x32_bf16 v[40:43], v[150:153], v[190:193], v[40:43]
	v_mfma_f32_16x16x32_bf16 v[44:47], v[158:161], v[190:193], v[44:47]
	v_mfma_f32_16x16x32_bf16 v[24:27], v[150:153], v[198:201], v[24:27]
	v_mfma_f32_16x16x32_bf16 v[28:31], v[158:161], v[198:201], v[28:31]
	v_mfma_f32_16x16x32_bf16 v[8:11], v[150:153], v[206:209], v[8:11]
	v_mfma_f32_16x16x32_bf16 v[12:15], v[158:161], v[206:209], v[12:15]
	v_mfma_f32_16x16x32_bf16 v[72:75], v[154:157], v[186:189], v[72:75]
	v_mfma_f32_16x16x32_bf16 v[76:79], v[162:165], v[186:189], v[76:79]
	v_mfma_f32_16x16x32_bf16 v[40:43], v[154:157], v[194:197], v[40:43]
	v_mfma_f32_16x16x32_bf16 v[44:47], v[162:165], v[194:197], v[44:47]
	v_mfma_f32_16x16x32_bf16 v[24:27], v[154:157], v[202:205], v[24:27]
	v_mfma_f32_16x16x32_bf16 v[28:31], v[162:165], v[202:205], v[28:31]
	v_mfma_f32_16x16x32_bf16 v[8:11], v[154:157], v[210:213], v[8:11]
	v_mfma_f32_16x16x32_bf16 v[12:15], v[162:165], v[210:213], v[12:15]
	s_setprio 0
	s_setprio 1
	v_mfma_f32_16x16x32_bf16 v[56:59], v[166:169], v[182:185], v[56:59]
	v_mfma_f32_16x16x32_bf16 v[60:63], v[174:177], v[182:185], v[60:63]
	v_mfma_f32_16x16x32_bf16 v[32:35], v[166:169], v[190:193], v[32:35]
	v_mfma_f32_16x16x32_bf16 v[36:39], v[174:177], v[190:193], v[36:39]
	v_mfma_f32_16x16x32_bf16 v[16:19], v[166:169], v[198:201], v[16:19]
	v_mfma_f32_16x16x32_bf16 v[20:23], v[174:177], v[198:201], v[20:23]
	v_mfma_f32_16x16x32_bf16 v[0:3], v[166:169], v[206:209], v[0:3]
	v_mfma_f32_16x16x32_bf16 v[4:7], v[174:177], v[206:209], v[4:7]
	v_mfma_f32_16x16x32_bf16 v[56:59], v[170:173], v[186:189], v[56:59]
	v_mfma_f32_16x16x32_bf16 v[60:63], v[178:181], v[186:189], v[60:63]
	v_mfma_f32_16x16x32_bf16 v[32:35], v[170:173], v[194:197], v[32:35]
	v_mfma_f32_16x16x32_bf16 v[36:39], v[178:181], v[194:197], v[36:39]
	v_mfma_f32_16x16x32_bf16 v[16:19], v[170:173], v[202:205], v[16:19]
	v_mfma_f32_16x16x32_bf16 v[20:23], v[178:181], v[202:205], v[20:23]
	v_mfma_f32_16x16x32_bf16 v[0:3], v[170:173], v[210:213], v[0:3]
	v_mfma_f32_16x16x32_bf16 v[4:7], v[178:181], v[210:213], v[4:7]
	s_barrier
	s_setprio 0
	ds_read_b128 v[150:153], v148
	ds_read_b128 v[154:157], v148 offset:1024
	ds_read_b128 v[158:161], v148 offset:2048
	ds_read_b128 v[162:165], v148 offset:3072
	ds_read_b128 v[166:169], v149
	ds_read_b128 v[170:173], v149 offset:1024
	ds_read_b128 v[174:177], v149 offset:2048
	ds_read_b128 v[178:181], v149 offset:3072
	s_add_u32 s76, s76, 0x80000
	s_addc_u32 s77, s77, 0
	s_mov_b32 m0, s36
	v_lshl_add_u64 v[222:223], s[76:77], 0, v[134:135]
	ds_read_b128 v[182:185], v147 offset:32768
	ds_read_b128 v[186:189], v147 offset:33792
	ds_read_b128 v[190:193], v147 offset:34816
	ds_read_b128 v[194:197], v147 offset:35840
	ds_read_b128 v[198:201], v147 offset:36864
	ds_read_b128 v[202:205], v147 offset:37888
	ds_read_b128 v[206:209], v147 offset:38912
	ds_read_b128 v[210:213], v147 offset:39936
	global_load_lds_dwordx4 v[222:223], off
	v_lshl_add_u64 v[222:223], s[76:77], 0, v[132:133]
	s_mov_b32 m0, s37
	s_nop 0
	global_load_lds_dwordx4 v[222:223], off
	s_waitcnt vmcnt(8) lgkmcnt(0)
	s_setprio 1
	s_barrier
	v_mfma_f32_16x16x32_bf16 v[120:123], v[150:153], v[182:185], v[120:123]
	v_mfma_f32_16x16x32_bf16 v[124:127], v[158:161], v[182:185], v[124:127]
	v_mfma_f32_16x16x32_bf16 v[104:107], v[150:153], v[190:193], v[104:107]
	v_mfma_f32_16x16x32_bf16 v[108:111], v[158:161], v[190:193], v[108:111]
	v_mfma_f32_16x16x32_bf16 v[88:91], v[150:153], v[198:201], v[88:91]
	v_mfma_f32_16x16x32_bf16 v[92:95], v[158:161], v[198:201], v[92:95]
	v_mfma_f32_16x16x32_bf16 v[64:67], v[150:153], v[206:209], v[64:67]
	v_mfma_f32_16x16x32_bf16 v[68:71], v[158:161], v[206:209], v[68:71]
	v_mfma_f32_16x16x32_bf16 v[120:123], v[154:157], v[186:189], v[120:123]
	v_mfma_f32_16x16x32_bf16 v[124:127], v[162:165], v[186:189], v[124:127]
	v_mfma_f32_16x16x32_bf16 v[104:107], v[154:157], v[194:197], v[104:107]
	v_mfma_f32_16x16x32_bf16 v[108:111], v[162:165], v[194:197], v[108:111]
	v_mfma_f32_16x16x32_bf16 v[88:91], v[154:157], v[202:205], v[88:91]
	v_mfma_f32_16x16x32_bf16 v[92:95], v[162:165], v[202:205], v[92:95]
	v_mfma_f32_16x16x32_bf16 v[64:67], v[154:157], v[210:213], v[64:67]
	v_mfma_f32_16x16x32_bf16 v[68:71], v[162:165], v[210:213], v[68:71]
	s_setprio 0
	s_setprio 1
	v_mfma_f32_16x16x32_bf16 v[112:115], v[166:169], v[182:185], v[112:115]
	v_mfma_f32_16x16x32_bf16 v[116:119], v[174:177], v[182:185], v[116:119]
	v_mfma_f32_16x16x32_bf16 v[96:99], v[166:169], v[190:193], v[96:99]
	v_mfma_f32_16x16x32_bf16 v[100:103], v[174:177], v[190:193], v[100:103]
	v_mfma_f32_16x16x32_bf16 v[80:83], v[166:169], v[198:201], v[80:83]
	v_mfma_f32_16x16x32_bf16 v[84:87], v[174:177], v[198:201], v[84:87]
	v_mfma_f32_16x16x32_bf16 v[48:51], v[166:169], v[206:209], v[48:51]
	v_mfma_f32_16x16x32_bf16 v[52:55], v[174:177], v[206:209], v[52:55]
	v_mfma_f32_16x16x32_bf16 v[112:115], v[170:173], v[186:189], v[112:115]
	v_mfma_f32_16x16x32_bf16 v[116:119], v[178:181], v[186:189], v[116:119]
	v_mfma_f32_16x16x32_bf16 v[96:99], v[170:173], v[194:197], v[96:99]
	v_mfma_f32_16x16x32_bf16 v[100:103], v[178:181], v[194:197], v[100:103]
	v_mfma_f32_16x16x32_bf16 v[80:83], v[170:173], v[202:205], v[80:83]
	v_mfma_f32_16x16x32_bf16 v[84:87], v[178:181], v[202:205], v[84:87]
	v_mfma_f32_16x16x32_bf16 v[48:51], v[170:173], v[210:213], v[48:51]
	v_mfma_f32_16x16x32_bf16 v[52:55], v[178:181], v[210:213], v[52:55]
	s_barrier
	s_setprio 0
	s_mov_b32 m0, s79
	v_lshl_add_u64 v[214:215], v[214:215], 0, s[12:13]
	s_add_u32 s74, s74, 0x80080
	ds_read_b128 v[182:185], v147 offset:49152
	ds_read_b128 v[186:189], v147 offset:50176
	ds_read_b128 v[190:193], v147 offset:51200
	ds_read_b128 v[194:197], v147 offset:52224
	ds_read_b128 v[198:201], v147 offset:53248
	ds_read_b128 v[202:205], v147 offset:54272
	ds_read_b128 v[206:209], v147 offset:55296
	ds_read_b128 v[210:213], v147 offset:56320
	global_load_lds_dwordx4 v[214:215], off
	v_lshl_add_u64 v[214:215], v[216:217], 0, s[12:13]
	s_mov_b32 m0, s80
	s_addc_u32 s75, s75, 0
	global_load_lds_dwordx4 v[214:215], off
	v_lshl_add_u64 v[214:215], s[74:75], 0, v[128:129]
	s_mov_b32 m0, s81
	s_nop 0
	global_load_lds_dwordx4 v[214:215], off
	v_lshl_add_u64 v[214:215], s[74:75], 0, v[130:131]
	s_mov_b32 m0, s82
	s_nop 0
	global_load_lds_dwordx4 v[214:215], off
	v_lshl_add_u64 v[214:215], v[218:219], 0, s[12:13]
	s_mov_b32 m0, s43
	s_nop 0
	global_load_lds_dwordx4 v[214:215], off
	v_lshl_add_u64 v[214:215], v[220:221], 0, s[12:13]
	s_mov_b32 m0, s48
	s_nop 0
	global_load_lds_dwordx4 v[214:215], off
	s_waitcnt vmcnt(8) lgkmcnt(0)
	s_setprio 1
	s_barrier
	v_mfma_f32_16x16x32_bf16 v[72:75], v[150:153], v[182:185], v[72:75]
	v_mfma_f32_16x16x32_bf16 v[76:79], v[158:161], v[182:185], v[76:79]
	v_mfma_f32_16x16x32_bf16 v[40:43], v[150:153], v[190:193], v[40:43]
	v_mfma_f32_16x16x32_bf16 v[44:47], v[158:161], v[190:193], v[44:47]
	v_mfma_f32_16x16x32_bf16 v[24:27], v[150:153], v[198:201], v[24:27]
	v_mfma_f32_16x16x32_bf16 v[28:31], v[158:161], v[198:201], v[28:31]
	v_mfma_f32_16x16x32_bf16 v[8:11], v[150:153], v[206:209], v[8:11]
	v_mfma_f32_16x16x32_bf16 v[12:15], v[158:161], v[206:209], v[12:15]
	v_mfma_f32_16x16x32_bf16 v[72:75], v[154:157], v[186:189], v[72:75]
	v_mfma_f32_16x16x32_bf16 v[76:79], v[162:165], v[186:189], v[76:79]
	v_mfma_f32_16x16x32_bf16 v[40:43], v[154:157], v[194:197], v[40:43]
	v_mfma_f32_16x16x32_bf16 v[44:47], v[162:165], v[194:197], v[44:47]
	v_mfma_f32_16x16x32_bf16 v[24:27], v[154:157], v[202:205], v[24:27]
	v_mfma_f32_16x16x32_bf16 v[28:31], v[162:165], v[202:205], v[28:31]
	v_mfma_f32_16x16x32_bf16 v[8:11], v[154:157], v[210:213], v[8:11]
	v_mfma_f32_16x16x32_bf16 v[12:15], v[162:165], v[210:213], v[12:15]
	s_setprio 0
	s_setprio 1
	v_mfma_f32_16x16x32_bf16 v[56:59], v[166:169], v[182:185], v[56:59]
	v_mfma_f32_16x16x32_bf16 v[60:63], v[174:177], v[182:185], v[60:63]
	v_mfma_f32_16x16x32_bf16 v[32:35], v[166:169], v[190:193], v[32:35]
	v_mfma_f32_16x16x32_bf16 v[36:39], v[174:177], v[190:193], v[36:39]
	v_mfma_f32_16x16x32_bf16 v[16:19], v[166:169], v[198:201], v[16:19]
	v_mfma_f32_16x16x32_bf16 v[20:23], v[174:177], v[198:201], v[20:23]
	v_mfma_f32_16x16x32_bf16 v[0:3], v[166:169], v[206:209], v[0:3]
	v_mfma_f32_16x16x32_bf16 v[4:7], v[174:177], v[206:209], v[4:7]
	v_mfma_f32_16x16x32_bf16 v[56:59], v[170:173], v[186:189], v[56:59]
	v_mfma_f32_16x16x32_bf16 v[60:63], v[178:181], v[186:189], v[60:63]
	v_mfma_f32_16x16x32_bf16 v[32:35], v[170:173], v[194:197], v[32:35]
	v_mfma_f32_16x16x32_bf16 v[36:39], v[178:181], v[194:197], v[36:39]
	v_mfma_f32_16x16x32_bf16 v[16:19], v[170:173], v[202:205], v[16:19]
	v_mfma_f32_16x16x32_bf16 v[20:23], v[178:181], v[202:205], v[20:23]
	v_mfma_f32_16x16x32_bf16 v[0:3], v[170:173], v[210:213], v[0:3]
	v_mfma_f32_16x16x32_bf16 v[4:7], v[178:181], v[210:213], v[4:7]
	s_barrier
	s_setprio 0
	s_add_i32 s88, s88, 2
	s_add_u32 s83, s83, 0x100
	s_addc_u32 s85, s85, 0
	s_add_u32 s72, s72, 0x100
	s_addc_u32 s73, s73, 0
	s_cmp_gt_u32 s88, 29
	s_cbranch_scc0 .LBB0_2841
	s_and_b64 vcc, exec, s[44:45]
	s_cbranch_vccz .LBB0_2844
	s_barrier

.LBB0_2914:
	ds_read_b128 v[146:149], v140
	ds_read_b128 v[150:153], v140 offset:1024
	ds_read_b128 v[154:157], v140 offset:2048
	ds_read_b128 v[158:161], v140 offset:3072
	ds_read_b128 v[162:165], v141
	ds_read_b128 v[166:169], v141 offset:1024
	ds_read_b128 v[170:173], v141 offset:2048
	ds_read_b128 v[174:177], v141 offset:3072
	s_add_u32 s55, s44, s39
	s_addc_u32 s56, s45, s40
	s_add_u32 s57, s44, s37
	s_addc_u32 s58, s45, s38
	s_cmpk_eq_i32 s41, 0x7c
	s_cselect_b32 s68, s6, s55
	s_cselect_b32 s69, s7, s56
	s_cselect_b32 s66, s2, s57
	s_cselect_b32 s67, s3, s58
	s_add_u32 s64, s68, 0x8000
	s_addc_u32 s65, s69, 0
	s_mov_b32 m0, s42
	v_lshl_add_u64 v[210:211], s[44:45], 0, v[138:139]
	ds_read_b128 v[178:181], v142
	ds_read_b128 v[182:185], v142 offset:1024
	ds_read_b128 v[186:189], v142 offset:2048
	ds_read_b128 v[190:193], v142 offset:3072
	ds_read_b128 v[194:197], v142 offset:4096
	ds_read_b128 v[198:201], v142 offset:5120
	ds_read_b128 v[202:205], v142 offset:6144
	ds_read_b128 v[206:209], v142 offset:7168
	global_load_lds_dwordx4 v[210:211], off
	v_lshl_add_u64 v[210:211], s[44:45], 0, v[136:137]
	s_mov_b32 m0, s43
	s_nop 0
	global_load_lds_dwordx4 v[210:211], off
	s_waitcnt vmcnt(8) lgkmcnt(0)
	s_setprio 1
	s_barrier
	v_mfma_f32_16x16x32_bf16 v[8:11], v[146:149], v[178:181], v[8:11]
	v_mfma_f32_16x16x32_bf16 v[12:15], v[154:157], v[178:181], v[12:15]
	v_mfma_f32_16x16x32_bf16 v[60:63], v[146:149], v[186:189], v[60:63]
	v_mfma_f32_16x16x32_bf16 v[20:23], v[154:157], v[186:189], v[20:23]
	v_mfma_f32_16x16x32_bf16 v[76:79], v[146:149], v[194:197], v[76:79]
	v_mfma_f32_16x16x32_bf16 v[52:55], v[154:157], v[194:197], v[52:55]
	v_mfma_f32_16x16x32_bf16 v[128:131], v[146:149], v[202:205], v[128:131]
	v_mfma_f32_16x16x32_bf16 v[68:71], v[154:157], v[202:205], v[68:71]
	v_mfma_f32_16x16x32_bf16 v[8:11], v[150:153], v[182:185], v[8:11]
	v_mfma_f32_16x16x32_bf16 v[12:15], v[158:161], v[182:185], v[12:15]
	v_mfma_f32_16x16x32_bf16 v[60:63], v[150:153], v[190:193], v[60:63]
	v_mfma_f32_16x16x32_bf16 v[20:23], v[158:161], v[190:193], v[20:23]
	v_mfma_f32_16x16x32_bf16 v[76:79], v[150:153], v[198:201], v[76:79]
	v_mfma_f32_16x16x32_bf16 v[52:55], v[158:161], v[198:201], v[52:55]
	v_mfma_f32_16x16x32_bf16 v[128:131], v[150:153], v[206:209], v[128:131]
	v_mfma_f32_16x16x32_bf16 v[68:71], v[158:161], v[206:209], v[68:71]
	s_setprio 0
	s_setprio 1
	v_mfma_f32_16x16x32_bf16 v[28:31], v[162:165], v[178:181], v[28:31]
	v_mfma_f32_16x16x32_bf16 v[16:19], v[170:173], v[178:181], v[16:19]
	v_mfma_f32_16x16x32_bf16 v[56:59], v[162:165], v[186:189], v[56:59]
	v_mfma_f32_16x16x32_bf16 v[48:51], v[170:173], v[186:189], v[48:51]
	v_mfma_f32_16x16x32_bf16 v[72:75], v[162:165], v[194:197], v[72:75]
	v_mfma_f32_16x16x32_bf16 v[64:67], v[170:173], v[194:197], v[64:67]
	v_mfma_f32_16x16x32_bf16 v[108:111], v[162:165], v[202:205], v[108:111]
	v_mfma_f32_16x16x32_bf16 v[96:99], v[170:173], v[202:205], v[96:99]
	v_mfma_f32_16x16x32_bf16 v[28:31], v[166:169], v[182:185], v[28:31]
	v_mfma_f32_16x16x32_bf16 v[16:19], v[174:177], v[182:185], v[16:19]
	v_mfma_f32_16x16x32_bf16 v[56:59], v[166:169], v[190:193], v[56:59]
	v_mfma_f32_16x16x32_bf16 v[48:51], v[174:177], v[190:193], v[48:51]
	v_mfma_f32_16x16x32_bf16 v[72:75], v[166:169], v[198:201], v[72:75]
	v_mfma_f32_16x16x32_bf16 v[64:67], v[174:177], v[198:201], v[64:67]
	v_mfma_f32_16x16x32_bf16 v[108:111], v[166:169], v[206:209], v[108:111]
	v_mfma_f32_16x16x32_bf16 v[96:99], v[174:177], v[206:209], v[96:99]
	s_barrier
	s_setprio 0
	s_mov_b32 m0, s47
	v_lshl_add_u64 v[210:211], s[66:67], 0, v[34:35]
	s_add_u32 s56, s66, 0x200000
	ds_read_b128 v[178:181], v142 offset:16384
	ds_read_b128 v[182:185], v142 offset:17408
	ds_read_b128 v[186:189], v142 offset:18432
	ds_read_b128 v[190:193], v142 offset:19456
	ds_read_b128 v[194:197], v142 offset:20480
	ds_read_b128 v[198:201], v142 offset:21504
	ds_read_b128 v[202:205], v142 offset:22528
	ds_read_b128 v[206:209], v142 offset:23552
	global_load_lds_dwordx4 v[210:211], off
	v_lshl_add_u64 v[212:213], s[66:67], 0, v[134:135]
	s_mov_b32 m0, s48
	s_addc_u32 s57, s67, 0
	global_load_lds_dwordx4 v[212:213], off
	v_lshl_add_u64 v[214:215], s[56:57], 0, v[34:35]
	s_mov_b32 m0, s49
	s_nop 0
	global_load_lds_dwordx4 v[214:215], off
	v_lshl_add_u64 v[214:215], s[56:57], 0, v[134:135]
	s_mov_b32 m0, s50
	s_nop 0
	global_load_lds_dwordx4 v[214:215], off
	v_lshl_add_u64 v[214:215], s[68:69], 0, v[32:33]
	s_mov_b32 m0, s14
	s_nop 0
	global_load_lds_dwordx4 v[214:215], off
	v_lshl_add_u64 v[214:215], s[68:69], 0, v[132:133]
	s_mov_b32 m0, s15
	s_nop 0
	global_load_lds_dwordx4 v[214:215], off
	s_waitcnt vmcnt(8) lgkmcnt(0)
	s_setprio 1
	s_barrier
	v_mfma_f32_16x16x32_bf16 v[100:103], v[146:149], v[178:181], v[100:103]
	v_mfma_f32_16x16x32_bf16 v[104:107], v[154:157], v[178:181], v[104:107]
	v_mfma_f32_16x16x32_bf16 v[116:119], v[146:149], v[186:189], v[116:119]
	v_mfma_f32_16x16x32_bf16 v[120:123], v[154:157], v[186:189], v[120:123]
	v_mfma_f32_16x16x32_bf16 v[84:87], v[146:149], v[194:197], v[84:87]
	v_mfma_f32_16x16x32_bf16 v[80:83], v[154:157], v[194:197], v[80:83]
	v_mfma_f32_16x16x32_bf16 v[36:39], v[146:149], v[202:205], v[36:39]
	v_mfma_f32_16x16x32_bf16 v[24:27], v[154:157], v[202:205], v[24:27]
	v_mfma_f32_16x16x32_bf16 v[100:103], v[150:153], v[182:185], v[100:103]
	v_mfma_f32_16x16x32_bf16 v[104:107], v[158:161], v[182:185], v[104:107]
	v_mfma_f32_16x16x32_bf16 v[116:119], v[150:153], v[190:193], v[116:119]
	v_mfma_f32_16x16x32_bf16 v[120:123], v[158:161], v[190:193], v[120:123]
	v_mfma_f32_16x16x32_bf16 v[84:87], v[150:153], v[198:201], v[84:87]
	v_mfma_f32_16x16x32_bf16 v[80:83], v[158:161], v[198:201], v[80:83]
	v_mfma_f32_16x16x32_bf16 v[36:39], v[150:153], v[206:209], v[36:39]
	v_mfma_f32_16x16x32_bf16 v[24:27], v[158:161], v[206:209], v[24:27]
	s_setprio 0
	s_setprio 1
	v_mfma_f32_16x16x32_bf16 v[124:127], v[162:165], v[178:181], v[124:127]
	v_mfma_f32_16x16x32_bf16 v[112:115], v[170:173], v[178:181], v[112:115]
	v_mfma_f32_16x16x32_bf16 v[92:95], v[162:165], v[186:189], v[92:95]
	v_mfma_f32_16x16x32_bf16 v[88:91], v[170:173], v[186:189], v[88:91]
	v_mfma_f32_16x16x32_bf16 v[44:47], v[162:165], v[194:197], v[44:47]
	v_mfma_f32_16x16x32_bf16 v[40:43], v[170:173], v[194:197], v[40:43]
	v_mfma_f32_16x16x32_bf16 v[4:7], v[162:165], v[202:205], v[4:7]
	v_mfma_f32_16x16x32_bf16 v[0:3], v[170:173], v[202:205], v[0:3]
	v_mfma_f32_16x16x32_bf16 v[124:127], v[166:169], v[182:185], v[124:127]
	v_mfma_f32_16x16x32_bf16 v[112:115], v[174:177], v[182:185], v[112:115]
	v_mfma_f32_16x16x32_bf16 v[92:95], v[166:169], v[190:193], v[92:95]
	v_mfma_f32_16x16x32_bf16 v[88:91], v[174:177], v[190:193], v[88:91]
	v_mfma_f32_16x16x32_bf16 v[44:47], v[166:169], v[198:201], v[44:47]
	v_mfma_f32_16x16x32_bf16 v[40:43], v[174:177], v[198:201], v[40:43]
	v_mfma_f32_16x16x32_bf16 v[4:7], v[166:169], v[206:209], v[4:7]
	v_mfma_f32_16x16x32_bf16 v[0:3], v[174:177], v[206:209], v[0:3]
	s_barrier
	s_setprio 0
	ds_read_b128 v[146:149], v143
	ds_read_b128 v[150:153], v143 offset:1024
	ds_read_b128 v[154:157], v143 offset:2048
	ds_read_b128 v[158:161], v143 offset:3072
	ds_read_b128 v[162:165], v144
	ds_read_b128 v[166:169], v144 offset:1024
	ds_read_b128 v[170:173], v144 offset:2048
	ds_read_b128 v[174:177], v144 offset:3072
	s_add_u32 s56, s68, 0x4000
	s_addc_u32 s57, s69, 0
	s_mov_b32 m0, s21
	v_lshl_add_u64 v[214:215], s[56:57], 0, v[32:33]
	ds_read_b128 v[178:181], v142 offset:32768
	ds_read_b128 v[182:185], v142 offset:33792
	ds_read_b128 v[186:189], v142 offset:34816
	ds_read_b128 v[190:193], v142 offset:35840
	ds_read_b128 v[194:197], v142 offset:36864
	ds_read_b128 v[198:201], v142 offset:37888
	ds_read_b128 v[202:205], v142 offset:38912
	ds_read_b128 v[206:209], v142 offset:39936
	global_load_lds_dwordx4 v[214:215], off
	v_lshl_add_u64 v[214:215], s[56:57], 0, v[132:133]
	s_mov_b32 m0, s22
	s_nop 0
	global_load_lds_dwordx4 v[214:215], off
	s_waitcnt vmcnt(8) lgkmcnt(0)
	s_setprio 1
	s_barrier
	v_mfma_f32_16x16x32_bf16 v[8:11], v[146:149], v[178:181], v[8:11]
	v_mfma_f32_16x16x32_bf16 v[12:15], v[154:157], v[178:181], v[12:15]
	v_mfma_f32_16x16x32_bf16 v[60:63], v[146:149], v[186:189], v[60:63]
	v_mfma_f32_16x16x32_bf16 v[20:23], v[154:157], v[186:189], v[20:23]
	v_mfma_f32_16x16x32_bf16 v[76:79], v[146:149], v[194:197], v[76:79]
	v_mfma_f32_16x16x32_bf16 v[52:55], v[154:157], v[194:197], v[52:55]
	v_mfma_f32_16x16x32_bf16 v[128:131], v[146:149], v[202:205], v[128:131]
	v_mfma_f32_16x16x32_bf16 v[68:71], v[154:157], v[202:205], v[68:71]
	v_mfma_f32_16x16x32_bf16 v[8:11], v[150:153], v[182:185], v[8:11]
	v_mfma_f32_16x16x32_bf16 v[12:15], v[158:161], v[182:185], v[12:15]
	v_mfma_f32_16x16x32_bf16 v[60:63], v[150:153], v[190:193], v[60:63]
	v_mfma_f32_16x16x32_bf16 v[20:23], v[158:161], v[190:193], v[20:23]
	v_mfma_f32_16x16x32_bf16 v[76:79], v[150:153], v[198:201], v[76:79]
	v_mfma_f32_16x16x32_bf16 v[52:55], v[158:161], v[198:201], v[52:55]
	v_mfma_f32_16x16x32_bf16 v[128:131], v[150:153], v[206:209], v[128:131]
	v_mfma_f32_16x16x32_bf16 v[68:71], v[158:161], v[206:209], v[68:71]
	s_setprio 0
	s_setprio 1
	v_mfma_f32_16x16x32_bf16 v[28:31], v[162:165], v[178:181], v[28:31]
	v_mfma_f32_16x16x32_bf16 v[16:19], v[170:173], v[178:181], v[16:19]
	v_mfma_f32_16x16x32_bf16 v[56:59], v[162:165], v[186:189], v[56:59]
	v_mfma_f32_16x16x32_bf16 v[48:51], v[170:173], v[186:189], v[48:51]
	v_mfma_f32_16x16x32_bf16 v[72:75], v[162:165], v[194:197], v[72:75]
	v_mfma_f32_16x16x32_bf16 v[64:67], v[170:173], v[194:197], v[64:67]
	v_mfma_f32_16x16x32_bf16 v[108:111], v[162:165], v[202:205], v[108:111]
	v_mfma_f32_16x16x32_bf16 v[96:99], v[170:173], v[202:205], v[96:99]
	v_mfma_f32_16x16x32_bf16 v[28:31], v[166:169], v[182:185], v[28:31]
	v_mfma_f32_16x16x32_bf16 v[16:19], v[174:177], v[182:185], v[16:19]
	v_mfma_f32_16x16x32_bf16 v[56:59], v[166:169], v[190:193], v[56:59]
	v_mfma_f32_16x16x32_bf16 v[48:51], v[174:177], v[190:193], v[48:51]
	v_mfma_f32_16x16x32_bf16 v[72:75], v[166:169], v[198:201], v[72:75]
	v_mfma_f32_16x16x32_bf16 v[64:67], v[174:177], v[198:201], v[64:67]
	v_mfma_f32_16x16x32_bf16 v[108:111], v[166:169], v[206:209], v[108:111]
	v_mfma_f32_16x16x32_bf16 v[96:99], v[174:177], v[206:209], v[96:99]
	s_barrier
; #define PG8_WAIT_V(n) asm volatile("s_waitcnt vmcnt(" #n ")" ::: "memory")
; #define PG8_BAR __builtin_amdgcn_s_barrier()
; template <class Epi, class Sched, bool ALIGN_EPI = false, bool SP2 = false, bool A_TILED = false>
; __device__ __forceinline__ void gemm_phase(PG8_LAS unsigned char* lds, const Gemm g, const Sched& S, const Epi& E, const int wave_s) {
;     ...
;     PG8_WAIT_V(0);
;     if constexpr (!ALIGN_EPI) { if (wr == 0) PG8_BAR; }
	s_setprio 0
	s_mov_b32 m0, s51
	v_lshl_add_u64 v[210:211], v[210:211], 0, s[60:61]
	s_add_u32 s56, s66, 0x200080
	ds_read_b128 v[178:181], v142 offset:49152
	ds_read_b128 v[182:185], v142 offset:50176
	ds_read_b128 v[186:189], v142 offset:51200
	ds_read_b128 v[190:193], v142 offset:52224
	ds_read_b128 v[194:197], v142 offset:53248
	ds_read_b128 v[198:201], v142 offset:54272
	ds_read_b128 v[202:205], v142 offset:55296
	ds_read_b128 v[206:209], v142 offset:56320
	global_load_lds_dwordx4 v[210:211], off
	v_lshl_add_u64 v[210:211], v[212:213], 0, s[60:61]
	s_mov_b32 m0, s52
	s_addc_u32 s57, s67, 0
	global_load_lds_dwordx4 v[210:211], off
	v_lshl_add_u64 v[210:211], s[56:57], 0, v[34:35]
	s_mov_b32 m0, s53
	s_nop 0
	global_load_lds_dwordx4 v[210:211], off
	v_lshl_add_u64 v[210:211], s[56:57], 0, v[134:135]
	s_mov_b32 m0, s54
	s_nop 0
	global_load_lds_dwordx4 v[210:211], off
	v_lshl_add_u64 v[210:211], s[64:65], 0, v[32:33]
	s_mov_b32 m0, s23
	s_nop 0
	global_load_lds_dwordx4 v[210:211], off
	v_lshl_add_u64 v[210:211], s[64:65], 0, v[132:133]
	s_mov_b32 m0, s36
	s_nop 0
	global_load_lds_dwordx4 v[210:211], off
	s_waitcnt vmcnt(8) lgkmcnt(0)
	s_setprio 1
	s_barrier
	v_mfma_f32_16x16x32_bf16 v[100:103], v[146:149], v[178:181], v[100:103]
	v_mfma_f32_16x16x32_bf16 v[104:107], v[154:157], v[178:181], v[104:107]
	v_mfma_f32_16x16x32_bf16 v[116:119], v[146:149], v[186:189], v[116:119]
	v_mfma_f32_16x16x32_bf16 v[120:123], v[154:157], v[186:189], v[120:123]
	v_mfma_f32_16x16x32_bf16 v[84:87], v[146:149], v[194:197], v[84:87]
	v_mfma_f32_16x16x32_bf16 v[80:83], v[154:157], v[194:197], v[80:83]
	v_mfma_f32_16x16x32_bf16 v[36:39], v[146:149], v[202:205], v[36:39]
	v_mfma_f32_16x16x32_bf16 v[24:27], v[154:157], v[202:205], v[24:27]
	v_mfma_f32_16x16x32_bf16 v[100:103], v[150:153], v[182:185], v[100:103]
	v_mfma_f32_16x16x32_bf16 v[104:107], v[158:161], v[182:185], v[104:107]
	v_mfma_f32_16x16x32_bf16 v[116:119], v[150:153], v[190:193], v[116:119]
	v_mfma_f32_16x16x32_bf16 v[120:123], v[158:161], v[190:193], v[120:123]
	v_mfma_f32_16x16x32_bf16 v[84:87], v[150:153], v[198:201], v[84:87]
	v_mfma_f32_16x16x32_bf16 v[80:83], v[158:161], v[198:201], v[80:83]
	v_mfma_f32_16x16x32_bf16 v[36:39], v[150:153], v[206:209], v[36:39]
	v_mfma_f32_16x16x32_bf16 v[24:27], v[158:161], v[206:209], v[24:27]
	s_setprio 0
	s_setprio 1
	v_mfma_f32_16x16x32_bf16 v[124:127], v[162:165], v[178:181], v[124:127]
	v_mfma_f32_16x16x32_bf16 v[112:115], v[170:173], v[178:181], v[112:115]
	v_mfma_f32_16x16x32_bf16 v[92:95], v[162:165], v[186:189], v[92:95]
	v_mfma_f32_16x16x32_bf16 v[88:91], v[170:173], v[186:189], v[88:91]
	v_mfma_f32_16x16x32_bf16 v[44:47], v[162:165], v[194:197], v[44:47]
	v_mfma_f32_16x16x32_bf16 v[40:43], v[170:173], v[194:197], v[40:43]
	v_mfma_f32_16x16x32_bf16 v[4:7], v[162:165], v[202:205], v[4:7]
	v_mfma_f32_16x16x32_bf16 v[0:3], v[170:173], v[202:205], v[0:3]
	v_mfma_f32_16x16x32_bf16 v[124:127], v[166:169], v[182:185], v[124:127]
	v_mfma_f32_16x16x32_bf16 v[112:115], v[174:177], v[182:185], v[112:115]
	v_mfma_f32_16x16x32_bf16 v[92:95], v[166:169], v[190:193], v[92:95]
	v_mfma_f32_16x16x32_bf16 v[88:91], v[174:177], v[190:193], v[88:91]
	v_mfma_f32_16x16x32_bf16 v[44:47], v[166:169], v[198:201], v[44:47]
	v_mfma_f32_16x16x32_bf16 v[40:43], v[174:177], v[198:201], v[40:43]
	v_mfma_f32_16x16x32_bf16 v[4:7], v[166:169], v[206:209], v[4:7]
	v_mfma_f32_16x16x32_bf16 v[0:3], v[174:177], v[206:209], v[0:3]
	s_barrier
	s_setprio 0
	s_add_i32 s41, s41, 2
	s_add_u32 s37, s37, 0x100
	s_addc_u32 s38, s38, 0
	s_add_u32 s39, s39, 0x10000
	s_addc_u32 s40, s40, 0
	v_lshl_add_u64 v[136:137], v[136:137], 0, s[62:63]
	s_cmpk_gt_u32 s41, 0x7d
	v_lshl_add_u64 v[138:139], v[138:139], 0, s[62:63]
	s_cbranch_scc0 .LBB0_2914
	s_waitcnt vmcnt(0)
	s_cmpk_lt_u32 s0, 0x100
	s_cbranch_scc0 .LBB0_2917
	s_barrier

; template <class Epi, class Sched, bool ALIGN_EPI = false, bool SP2 = false, bool A_TILED = false>
; __device__ __forceinline__ void gemm_phase(PG8_LAS unsigned char* lds, const Gemm g, const Sched& S, const Epi& E, const int wave_s) {
;     ...
;         const char* nA = has_next ? (const char*)g.A + (size_t)nxt.pm * tstepA : cA; const char* nB = has_next ? (const char*)g.Bt + (size_t)nxt.pn * tstep : cB;
;         constexpr bool PEEL = SP2 && !Epi::AFTER_DRAIN;
;         if constexpr (PEEL) {
;             const char* a1 = cA + kstepA; const char* a2 = cA + 2 * kstepA; const char* b2 = cB + 2 * kstep; const char* a3 = a2 + kstepA; const char* b3 = b2 + kstep;
;             PG8_ITER(PG8_MMAZ)
.LBB0_3341:
	s_ashr_i32 s25, s24, 31
	ds_read_b128 v[0:3], v149
	ds_read_b128 v[4:7], v149 offset:1024
	ds_read_b128 v[8:11], v149 offset:2048
	ds_read_b128 v[12:15], v149 offset:3072
	ds_read_b128 v[16:19], v150
	ds_read_b128 v[20:23], v150 offset:1024
	ds_read_b128 v[24:27], v150 offset:2048
	ds_read_b128 v[28:31], v150 offset:3072
	s_lshl_b64 s[26:27], s[24:25], 20
	s_add_u32 s26, s9, s26
	s_addc_u32 s27, s36, s27
	s_and_b64 s[38:39], s[0:1], exec
	s_cselect_b32 s25, s27, s45
	s_cselect_b32 s67, s26, s44
	s_ashr_i32 s23, s22, 31
	s_lshl_b64 s[38:39], s[22:23], 20
	s_add_u32 s38, s37, s38
	s_addc_u32 s39, s48, s39
	s_and_b64 s[46:47], s[0:1], exec
	s_cselect_b32 s23, s39, s43
	s_cselect_b32 s68, s38, s42
	s_add_u32 s46, s44, 0x80080
	s_addc_u32 s47, s45, 0
	s_mov_b32 m0, s64
	v_lshl_add_u64 v[64:65], s[46:47], 0, v[134:135]
	ds_read_b128 v[32:35], v151
	ds_read_b128 v[36:39], v151 offset:1024
	ds_read_b128 v[40:43], v151 offset:2048
	ds_read_b128 v[44:47], v151 offset:3072
	ds_read_b128 v[48:51], v151 offset:4096
	ds_read_b128 v[52:55], v151 offset:5120
	ds_read_b128 v[56:59], v151 offset:6144
	ds_read_b128 v[60:63], v151 offset:7168
	global_load_lds_dwordx4 v[64:65], off
	v_lshl_add_u64 v[64:65], s[46:47], 0, v[132:133]
	s_mov_b32 m0, s65
	s_nop 0
	global_load_lds_dwordx4 v[64:65], off
	s_waitcnt vmcnt(8) lgkmcnt(0)
	s_setprio 1
	s_barrier
	v_mfma_f32_16x16x32_bf16 v[88:91], v[0:3], v[56:59], 0
	v_mfma_f32_16x16x32_bf16 v[64:67], v[0:3], v[32:35], 0
	v_mfma_f32_16x16x32_bf16 v[68:71], v[8:11], v[32:35], 0
	v_mfma_f32_16x16x32_bf16 v[72:75], v[0:3], v[40:43], 0
	v_mfma_f32_16x16x32_bf16 v[76:79], v[8:11], v[40:43], 0
	v_mfma_f32_16x16x32_bf16 v[80:83], v[0:3], v[48:51], 0
	v_mfma_f32_16x16x32_bf16 v[84:87], v[8:11], v[48:51], 0
	v_mfma_f32_16x16x32_bf16 v[92:95], v[4:7], v[60:63], v[88:91]
	v_mfma_f32_16x16x32_bf16 v[88:91], v[8:11], v[56:59], 0
	v_mfma_f32_16x16x32_bf16 v[64:67], v[4:7], v[36:39], v[64:67]
	v_mfma_f32_16x16x32_bf16 v[68:71], v[12:15], v[36:39], v[68:71]
	v_mfma_f32_16x16x32_bf16 v[72:75], v[4:7], v[44:47], v[72:75]
	v_mfma_f32_16x16x32_bf16 v[76:79], v[12:15], v[44:47], v[76:79]
	v_mfma_f32_16x16x32_bf16 v[80:83], v[4:7], v[52:55], v[80:83]
	v_mfma_f32_16x16x32_bf16 v[84:87], v[12:15], v[52:55], v[84:87]
	v_mfma_f32_16x16x32_bf16 v[100:103], v[12:15], v[60:63], v[88:91]
	s_setprio 0
	s_setprio 1
	v_mfma_f32_16x16x32_bf16 v[88:91], v[16:19], v[32:35], 0
	v_mfma_f32_16x16x32_bf16 v[32:35], v[24:27], v[32:35], 0
	v_mfma_f32_16x16x32_bf16 v[108:111], v[20:23], v[36:39], v[88:91]
	v_mfma_f32_16x16x32_bf16 v[32:35], v[28:31], v[36:39], v[32:35]
	v_mfma_f32_16x16x32_bf16 v[36:39], v[16:19], v[40:43], 0
	v_mfma_f32_16x16x32_bf16 v[40:43], v[24:27], v[40:43], 0
	v_mfma_f32_16x16x32_bf16 v[36:39], v[20:23], v[44:47], v[36:39]
	v_mfma_f32_16x16x32_bf16 v[40:43], v[28:31], v[44:47], v[40:43]
	v_mfma_f32_16x16x32_bf16 v[44:47], v[16:19], v[48:51], 0
	v_mfma_f32_16x16x32_bf16 v[48:51], v[24:27], v[48:51], 0
	v_mfma_f32_16x16x32_bf16 v[44:47], v[20:23], v[52:55], v[44:47]
	v_mfma_f32_16x16x32_bf16 v[52:55], v[28:31], v[52:55], v[48:51]
	v_mfma_f32_16x16x32_bf16 v[48:51], v[16:19], v[56:59], 0
	v_mfma_f32_16x16x32_bf16 v[152:155], v[20:23], v[60:63], v[48:51]
	v_mfma_f32_16x16x32_bf16 v[48:51], v[24:27], v[56:59], 0
	v_mfma_f32_16x16x32_bf16 v[156:159], v[28:31], v[60:63], v[48:51]
	s_barrier
	s_setprio 0
	s_add_i32 s69, s61, s49
	v_lshl_add_u64 v[146:147], s[42:43], 0, v[128:129]
	s_add_i32 s70, s69, 0x2000
	v_lshl_add_u64 v[120:121], v[146:147], 0, s[20:21]
	s_mov_b32 m0, s69
	v_lshl_add_u64 v[252:253], s[42:43], 0, v[130:131]
	s_add_u32 s46, s42, 0x80100
	ds_read_b128 v[48:51], v151 offset:16384
	ds_read_b128 v[56:59], v151 offset:17408
	ds_read_b128 v[60:63], v151 offset:18432
	ds_read_b128 v[88:91], v151 offset:19456
	ds_read_b128 v[96:99], v151 offset:20480
	ds_read_b128 v[104:107], v151 offset:21504
	ds_read_b128 v[112:115], v151 offset:22528
	ds_read_b128 v[116:119], v151 offset:23552
	global_load_lds_dwordx4 v[120:121], off
	v_lshl_add_u64 v[120:121], v[252:253], 0, s[20:21]
	s_mov_b32 m0, s70
	s_addc_u32 s47, s43, 0
	s_add_i32 s71, s62, s49
	global_load_lds_dwordx4 v[120:121], off
	v_lshl_add_u64 v[120:121], s[46:47], 0, v[128:129]
	s_mov_b32 m0, s71
	s_add_i32 s72, s71, 0x2000
	global_load_lds_dwordx4 v[120:121], off
	v_lshl_add_u64 v[120:121], s[46:47], 0, v[130:131]
	s_mov_b32 m0, s72
	v_lshl_add_u64 v[140:141], s[44:45], 0, v[134:135]
	global_load_lds_dwordx4 v[120:121], off
	v_lshl_add_u64 v[120:121], v[140:141], 0, s[20:21]
	s_mov_b32 m0, s41
	v_lshl_add_u64 v[142:143], s[44:45], 0, v[132:133]
	global_load_lds_dwordx4 v[120:121], off
	v_lshl_add_u64 v[120:121], v[142:143], 0, s[20:21]
	s_mov_b32 m0, s52
	s_nop 0
	global_load_lds_dwordx4 v[120:121], off
	s_waitcnt vmcnt(8) lgkmcnt(0)
	s_setprio 1
	s_barrier
	v_mfma_f32_16x16x32_bf16 v[120:123], v[0:3], v[48:51], 0
	v_mfma_f32_16x16x32_bf16 v[160:163], v[4:7], v[56:59], v[120:123]
	v_mfma_f32_16x16x32_bf16 v[120:123], v[8:11], v[48:51], 0
	v_mfma_f32_16x16x32_bf16 v[164:167], v[12:15], v[56:59], v[120:123]
	v_mfma_f32_16x16x32_bf16 v[120:123], v[0:3], v[60:63], 0
	v_mfma_f32_16x16x32_bf16 v[168:171], v[4:7], v[88:91], v[120:123]
	v_mfma_f32_16x16x32_bf16 v[120:123], v[8:11], v[60:63], 0
	v_mfma_f32_16x16x32_bf16 v[172:175], v[12:15], v[88:91], v[120:123]
	v_mfma_f32_16x16x32_bf16 v[120:123], v[0:3], v[96:99], 0
	v_mfma_f32_16x16x32_bf16 v[0:3], v[0:3], v[112:115], 0
	v_mfma_f32_16x16x32_bf16 v[176:179], v[4:7], v[104:107], v[120:123]
	v_mfma_f32_16x16x32_bf16 v[0:3], v[4:7], v[116:119], v[0:3]
	v_mfma_f32_16x16x32_bf16 v[4:7], v[8:11], v[112:115], 0
	v_mfma_f32_16x16x32_bf16 v[120:123], v[8:11], v[96:99], 0
	v_mfma_f32_16x16x32_bf16 v[4:7], v[12:15], v[116:119], v[4:7]
	v_mfma_f32_16x16x32_bf16 v[180:183], v[12:15], v[104:107], v[120:123]
	s_setprio 0
	s_setprio 1
	v_mfma_f32_16x16x32_bf16 v[8:11], v[16:19], v[48:51], 0
	v_mfma_f32_16x16x32_bf16 v[12:15], v[20:23], v[56:59], v[8:11]
	v_mfma_f32_16x16x32_bf16 v[8:11], v[24:27], v[48:51], 0
	v_mfma_f32_16x16x32_bf16 v[184:187], v[28:31], v[56:59], v[8:11]
	v_mfma_f32_16x16x32_bf16 v[8:11], v[16:19], v[60:63], 0
	v_mfma_f32_16x16x32_bf16 v[188:191], v[20:23], v[88:91], v[8:11]
	v_mfma_f32_16x16x32_bf16 v[8:11], v[24:27], v[60:63], 0
	v_mfma_f32_16x16x32_bf16 v[192:195], v[28:31], v[88:91], v[8:11]
	v_mfma_f32_16x16x32_bf16 v[8:11], v[16:19], v[96:99], 0
	v_mfma_f32_16x16x32_bf16 v[196:199], v[20:23], v[104:107], v[8:11]
	v_mfma_f32_16x16x32_bf16 v[8:11], v[24:27], v[96:99], 0
	v_mfma_f32_16x16x32_bf16 v[200:203], v[28:31], v[104:107], v[8:11]
	v_mfma_f32_16x16x32_bf16 v[8:11], v[16:19], v[112:115], 0
	v_mfma_f32_16x16x32_bf16 v[204:207], v[20:23], v[116:119], v[8:11]
	v_mfma_f32_16x16x32_bf16 v[8:11], v[24:27], v[112:115], 0
	v_mfma_f32_16x16x32_bf16 v[208:211], v[28:31], v[116:119], v[8:11]
	s_barrier
	s_setprio 0
	s_add_i32 s73, 0, 0x18000
	s_add_i32 s75, 0, 0x1c000
	v_add_u32_e32 v144, s73, v148
	v_add_u32_e32 v145, s75, v148
	s_nop 0
	ds_read_b128 v[8:11], v144
	ds_read_b128 v[20:23], v144 offset:1024
	ds_read_b128 v[28:31], v144 offset:2048
	ds_read_b128 v[212:215], v144 offset:3072
	ds_read_b128 v[216:219], v145
	ds_read_b128 v[220:223], v145 offset:1024
	ds_read_b128 v[224:227], v145 offset:2048
	ds_read_b128 v[228:231], v145 offset:3072
	s_add_u32 s46, s44, 0x80100
	s_addc_u32 s47, s45, 0
	s_mov_b32 m0, s53
	v_lshl_add_u64 v[48:49], s[46:47], 0, v[134:135]
	ds_read_b128 v[16:19], v151 offset:32768
	ds_read_b128 v[24:27], v151 offset:33792
	ds_read_b128 v[60:63], v151 offset:34816
	ds_read_b128 v[232:235], v151 offset:35840
	ds_read_b128 v[236:239], v151 offset:36864
	ds_read_b128 v[240:243], v151 offset:37888
	ds_read_b128 v[244:247], v151 offset:38912
	ds_read_b128 v[248:251], v151 offset:39936
	global_load_lds_dwordx4 v[48:49], off
	v_lshl_add_u64 v[48:49], s[46:47], 0, v[132:133]
	s_mov_b32 m0, s54
	s_nop 0
	global_load_lds_dwordx4 v[48:49], off
	s_waitcnt vmcnt(8) lgkmcnt(0)
	s_setprio 1
	s_barrier
	v_mfma_f32_16x16x32_bf16 v[48:51], v[8:11], v[16:19], v[64:67]
	v_mfma_f32_16x16x32_bf16 v[120:123], v[20:23], v[24:27], v[48:51]
	v_mfma_f32_16x16x32_bf16 v[48:51], v[28:31], v[16:19], v[68:71]
	v_mfma_f32_16x16x32_bf16 v[112:115], v[212:215], v[24:27], v[48:51]
	v_mfma_f32_16x16x32_bf16 v[48:51], v[8:11], v[60:63], v[72:75]
	v_mfma_f32_16x16x32_bf16 v[104:107], v[20:23], v[232:235], v[48:51]
	v_mfma_f32_16x16x32_bf16 v[48:51], v[28:31], v[60:63], v[76:79]
	v_mfma_f32_16x16x32_bf16 v[96:99], v[212:215], v[232:235], v[48:51]
	v_mfma_f32_16x16x32_bf16 v[48:51], v[8:11], v[236:239], v[80:83]
	v_mfma_f32_16x16x32_bf16 v[88:91], v[20:23], v[240:243], v[48:51]
	v_mfma_f32_16x16x32_bf16 v[48:51], v[28:31], v[236:239], v[84:87]
	v_mfma_f32_16x16x32_bf16 v[80:83], v[212:215], v[240:243], v[48:51]
	v_mfma_f32_16x16x32_bf16 v[48:51], v[8:11], v[244:247], v[92:95]
	v_mfma_f32_16x16x32_bf16 v[56:59], v[20:23], v[248:251], v[48:51]
	v_mfma_f32_16x16x32_bf16 v[48:51], v[28:31], v[244:247], v[100:103]
	v_mfma_f32_16x16x32_bf16 v[48:51], v[212:215], v[248:251], v[48:51]
	s_setprio 0
	s_setprio 1
	v_mfma_f32_16x16x32_bf16 v[64:67], v[216:219], v[16:19], v[108:111]
	v_mfma_f32_16x16x32_bf16 v[16:19], v[224:227], v[16:19], v[32:35]
	v_mfma_f32_16x16x32_bf16 v[116:119], v[228:231], v[24:27], v[16:19]
	v_mfma_f32_16x16x32_bf16 v[16:19], v[216:219], v[60:63], v[36:39]
	v_mfma_f32_16x16x32_bf16 v[108:111], v[220:223], v[232:235], v[16:19]
	v_mfma_f32_16x16x32_bf16 v[16:19], v[224:227], v[60:63], v[40:43]
	v_mfma_f32_16x16x32_bf16 v[100:103], v[228:231], v[232:235], v[16:19]
	v_mfma_f32_16x16x32_bf16 v[16:19], v[216:219], v[236:239], v[44:47]
	v_mfma_f32_16x16x32_bf16 v[92:95], v[220:223], v[240:243], v[16:19]
	v_mfma_f32_16x16x32_bf16 v[16:19], v[224:227], v[236:239], v[52:55]
	v_mfma_f32_16x16x32_bf16 v[84:87], v[228:231], v[240:243], v[16:19]
	v_mfma_f32_16x16x32_bf16 v[16:19], v[216:219], v[244:247], v[152:155]
	v_mfma_f32_16x16x32_bf16 v[60:63], v[220:223], v[248:251], v[16:19]
	v_mfma_f32_16x16x32_bf16 v[16:19], v[224:227], v[244:247], v[156:159]
	v_mfma_f32_16x16x32_bf16 v[124:127], v[220:223], v[24:27], v[64:67]
	v_mfma_f32_16x16x32_bf16 v[52:55], v[228:231], v[248:251], v[16:19]
	s_barrier
; template <class Epi, class Sched, bool ALIGN_EPI = false, bool SP2 = false, bool A_TILED = false>
; __device__ __forceinline__ void gemm_phase(PG8_LAS unsigned char* lds, const Gemm g, const Sched& S, const Epi& E, const int wave_s) {
;     ...
;         for (int t = PEEL ? 2 : 0; t < nt; t += 2) {
;             const bool last = (t == nt - 2);
;             const char* a1 = cA + (size_t)(t + 1) * kstepA;
;             const char* a2 = last ? nA : cA + (size_t)(t + 2) * kstepA; const char* b2 = last ? nB : cB + (size_t)(t + 2) * kstep;
;             const char* a3 = a2 + kstepA; const char* b3 = b2 + kstep;
;             if (last && has_next) S.a_ready(nxt);
	s_setprio 0
	s_add_i32 s73, s73, s49
	s_add_i32 s74, s73, 0x2000
	s_nop 1
	v_lshl_add_u64 v[16:17], v[146:147], 0, s[16:17]
	s_mov_b32 m0, s73
	s_add_u32 s46, s42, 0x80180
	ds_read_b128 v[36:39], v151 offset:49152
	ds_read_b128 v[44:47], v151 offset:50176
	ds_read_b128 v[152:155], v151 offset:51200
	ds_read_b128 v[156:159], v151 offset:52224
	ds_read_b128 v[232:235], v151 offset:53248
	ds_read_b128 v[236:239], v151 offset:54272
	ds_read_b128 v[240:243], v151 offset:55296
	ds_read_b128 v[244:247], v151 offset:56320
	global_load_lds_dwordx4 v[16:17], off
	v_lshl_add_u64 v[16:17], v[252:253], 0, s[16:17]
	s_mov_b32 m0, s74
	s_addc_u32 s47, s43, 0
	s_add_i32 s75, s75, s49
	global_load_lds_dwordx4 v[16:17], off
	v_lshl_add_u64 v[16:17], s[46:47], 0, v[128:129]
	s_mov_b32 m0, s75
	s_add_i32 s76, s75, 0x2000
	global_load_lds_dwordx4 v[16:17], off
	v_lshl_add_u64 v[16:17], s[46:47], 0, v[130:131]
	s_mov_b32 m0, s76
	s_nop 0
	global_load_lds_dwordx4 v[16:17], off
	v_lshl_add_u64 v[16:17], v[140:141], 0, s[16:17]
	s_mov_b32 m0, s59
	s_nop 0
	global_load_lds_dwordx4 v[16:17], off
	v_lshl_add_u64 v[16:17], v[142:143], 0, s[16:17]
	s_mov_b32 m0, s60
	s_nop 0
	global_load_lds_dwordx4 v[16:17], off
	s_waitcnt vmcnt(8) lgkmcnt(0)
	s_setprio 1
	s_barrier
	v_mfma_f32_16x16x32_bf16 v[16:19], v[8:11], v[36:39], v[160:163]
	v_mfma_f32_16x16x32_bf16 v[72:75], v[20:23], v[44:47], v[16:19]
	v_mfma_f32_16x16x32_bf16 v[16:19], v[28:31], v[36:39], v[164:167]
	v_mfma_f32_16x16x32_bf16 v[64:67], v[212:215], v[44:47], v[16:19]
	v_mfma_f32_16x16x32_bf16 v[16:19], v[8:11], v[152:155], v[168:171]
	v_mfma_f32_16x16x32_bf16 v[40:43], v[20:23], v[156:159], v[16:19]
	v_mfma_f32_16x16x32_bf16 v[16:19], v[28:31], v[152:155], v[172:175]
	v_mfma_f32_16x16x32_bf16 v[32:35], v[212:215], v[156:159], v[16:19]
	v_mfma_f32_16x16x32_bf16 v[16:19], v[8:11], v[232:235], v[176:179]
	v_mfma_f32_16x16x32_bf16 v[0:3], v[8:11], v[240:243], v[0:3]
	v_mfma_f32_16x16x32_bf16 v[24:27], v[20:23], v[236:239], v[16:19]
	v_mfma_f32_16x16x32_bf16 v[16:19], v[28:31], v[232:235], v[180:183]
	v_mfma_f32_16x16x32_bf16 v[8:11], v[20:23], v[244:247], v[0:3]
	v_mfma_f32_16x16x32_bf16 v[0:3], v[28:31], v[240:243], v[4:7]
	v_mfma_f32_16x16x32_bf16 v[16:19], v[212:215], v[236:239], v[16:19]
	v_mfma_f32_16x16x32_bf16 v[0:3], v[212:215], v[244:247], v[0:3]
	s_setprio 0
	s_setprio 1
	v_mfma_f32_16x16x32_bf16 v[4:7], v[216:219], v[36:39], v[12:15]
	v_mfma_f32_16x16x32_bf16 v[76:79], v[220:223], v[44:47], v[4:7]
	v_mfma_f32_16x16x32_bf16 v[4:7], v[224:227], v[36:39], v[184:187]
	v_mfma_f32_16x16x32_bf16 v[68:71], v[228:231], v[44:47], v[4:7]
	v_mfma_f32_16x16x32_bf16 v[4:7], v[216:219], v[152:155], v[188:191]
	v_mfma_f32_16x16x32_bf16 v[44:47], v[220:223], v[156:159], v[4:7]
	v_mfma_f32_16x16x32_bf16 v[4:7], v[224:227], v[152:155], v[192:195]
	v_mfma_f32_16x16x32_bf16 v[36:39], v[228:231], v[156:159], v[4:7]
	v_mfma_f32_16x16x32_bf16 v[4:7], v[216:219], v[232:235], v[196:199]
	v_mfma_f32_16x16x32_bf16 v[28:31], v[220:223], v[236:239], v[4:7]
	v_mfma_f32_16x16x32_bf16 v[4:7], v[224:227], v[232:235], v[200:203]
	v_mfma_f32_16x16x32_bf16 v[20:23], v[228:231], v[236:239], v[4:7]
	v_mfma_f32_16x16x32_bf16 v[4:7], v[216:219], v[240:243], v[204:207]
	v_mfma_f32_16x16x32_bf16 v[12:15], v[220:223], v[244:247], v[4:7]
	v_mfma_f32_16x16x32_bf16 v[4:7], v[224:227], v[240:243], v[208:211]
	v_mfma_f32_16x16x32_bf16 v[4:7], v[228:231], v[244:247], v[4:7]
	s_barrier
	s_setprio 0
	s_add_u32 s77, s42, 0x200
	s_addc_u32 s78, s43, 0
	s_add_u32 s42, s44, 0x80180
	s_addc_u32 s43, s45, 0
	s_mov_b32 s79, 0
.LBB0_3342:
	ds_read_b128 v[152:155], v149
	ds_read_b128 v[156:159], v149 offset:1024
	ds_read_b128 v[160:163], v149 offset:2048
	ds_read_b128 v[164:167], v149 offset:3072
	ds_read_b128 v[168:171], v150
	ds_read_b128 v[172:175], v150 offset:1024
	ds_read_b128 v[176:179], v150 offset:2048
	ds_read_b128 v[180:183], v150 offset:3072
	s_add_u32 s44, s42, 0xfff80080
	s_addc_u32 s45, s43, -1
	s_cmp_eq_u32 s79, 28
	s_cselect_b32 s47, s25, s45
	s_cselect_b32 s46, s67, s44
	s_cselect_b32 s45, s23, s78
	s_cselect_b32 s44, s68, s77
	s_mov_b32 m0, s64
	v_lshl_add_u64 v[140:141], s[42:43], 0, v[138:139]
	ds_read_b128 v[184:187], v151
	ds_read_b128 v[188:191], v151 offset:1024
	ds_read_b128 v[192:195], v151 offset:2048
	ds_read_b128 v[196:199], v151 offset:3072
	ds_read_b128 v[200:203], v151 offset:4096
	ds_read_b128 v[204:207], v151 offset:5120
	ds_read_b128 v[208:211], v151 offset:6144
	ds_read_b128 v[212:215], v151 offset:7168
	global_load_lds_dwordx4 v[140:141], off
	v_lshl_add_u64 v[140:141], s[42:43], 0, v[136:137]
	s_mov_b32 m0, s65
	s_nop 0
	global_load_lds_dwordx4 v[140:141], off
	s_waitcnt vmcnt(8) lgkmcnt(0)
	s_setprio 1
	s_barrier
	v_mfma_f32_16x16x32_bf16 v[120:123], v[152:155], v[184:187], v[120:123]
	v_mfma_f32_16x16x32_bf16 v[112:115], v[160:163], v[184:187], v[112:115]
	v_mfma_f32_16x16x32_bf16 v[104:107], v[152:155], v[192:195], v[104:107]
	v_mfma_f32_16x16x32_bf16 v[96:99], v[160:163], v[192:195], v[96:99]
	v_mfma_f32_16x16x32_bf16 v[88:91], v[152:155], v[200:203], v[88:91]
	v_mfma_f32_16x16x32_bf16 v[80:83], v[160:163], v[200:203], v[80:83]
	v_mfma_f32_16x16x32_bf16 v[56:59], v[152:155], v[208:211], v[56:59]
	v_mfma_f32_16x16x32_bf16 v[48:51], v[160:163], v[208:211], v[48:51]
	v_mfma_f32_16x16x32_bf16 v[120:123], v[156:159], v[188:191], v[120:123]
	v_mfma_f32_16x16x32_bf16 v[112:115], v[164:167], v[188:191], v[112:115]
	v_mfma_f32_16x16x32_bf16 v[104:107], v[156:159], v[196:199], v[104:107]
	v_mfma_f32_16x16x32_bf16 v[96:99], v[164:167], v[196:199], v[96:99]
	v_mfma_f32_16x16x32_bf16 v[88:91], v[156:159], v[204:207], v[88:91]
	v_mfma_f32_16x16x32_bf16 v[80:83], v[164:167], v[204:207], v[80:83]
	v_mfma_f32_16x16x32_bf16 v[56:59], v[156:159], v[212:215], v[56:59]
	v_mfma_f32_16x16x32_bf16 v[48:51], v[164:167], v[212:215], v[48:51]
	s_setprio 0
	s_setprio 1
	v_mfma_f32_16x16x32_bf16 v[124:127], v[168:171], v[184:187], v[124:127]
	v_mfma_f32_16x16x32_bf16 v[116:119], v[176:179], v[184:187], v[116:119]
	v_mfma_f32_16x16x32_bf16 v[108:111], v[168:171], v[192:195], v[108:111]
	v_mfma_f32_16x16x32_bf16 v[100:103], v[176:179], v[192:195], v[100:103]
	v_mfma_f32_16x16x32_bf16 v[92:95], v[168:171], v[200:203], v[92:95]
	v_mfma_f32_16x16x32_bf16 v[84:87], v[176:179], v[200:203], v[84:87]
	v_mfma_f32_16x16x32_bf16 v[60:63], v[168:171], v[208:211], v[60:63]
	v_mfma_f32_16x16x32_bf16 v[52:55], v[176:179], v[208:211], v[52:55]
	v_mfma_f32_16x16x32_bf16 v[124:127], v[172:175], v[188:191], v[124:127]
	v_mfma_f32_16x16x32_bf16 v[116:119], v[180:183], v[188:191], v[116:119]
	v_mfma_f32_16x16x32_bf16 v[108:111], v[172:175], v[196:199], v[108:111]
	v_mfma_f32_16x16x32_bf16 v[100:103], v[180:183], v[196:199], v[100:103]
	v_mfma_f32_16x16x32_bf16 v[92:95], v[172:175], v[204:207], v[92:95]
	v_mfma_f32_16x16x32_bf16 v[84:87], v[180:183], v[204:207], v[84:87]
	v_mfma_f32_16x16x32_bf16 v[60:63], v[172:175], v[212:215], v[60:63]
	v_mfma_f32_16x16x32_bf16 v[52:55], v[180:183], v[212:215], v[52:55]
	s_barrier
	s_setprio 0
	s_mov_b32 m0, s69
	v_lshl_add_u64 v[140:141], s[44:45], 0, v[128:129]
	s_add_u32 s80, s44, 0x80000
	ds_read_b128 v[184:187], v151 offset:16384
	ds_read_b128 v[188:191], v151 offset:17408
	ds_read_b128 v[192:195], v151 offset:18432
	ds_read_b128 v[196:199], v151 offset:19456
	ds_read_b128 v[200:203], v151 offset:20480
	ds_read_b128 v[204:207], v151 offset:21504
	ds_read_b128 v[208:211], v151 offset:22528
	ds_read_b128 v[212:215], v151 offset:23552
	global_load_lds_dwordx4 v[140:141], off
	v_lshl_add_u64 v[142:143], s[44:45], 0, v[130:131]
	s_mov_b32 m0, s70
	s_addc_u32 s81, s45, 0
	global_load_lds_dwordx4 v[142:143], off
	v_lshl_add_u64 v[146:147], s[80:81], 0, v[128:129]
	s_mov_b32 m0, s71
	v_lshl_add_u64 v[216:217], s[46:47], 0, v[132:133]
	global_load_lds_dwordx4 v[146:147], off
	v_lshl_add_u64 v[146:147], s[80:81], 0, v[130:131]
	s_mov_b32 m0, s72
	s_nop 0
	global_load_lds_dwordx4 v[146:147], off
	v_lshl_add_u64 v[146:147], s[46:47], 0, v[134:135]
	s_mov_b32 m0, s41
	s_nop 0
	global_load_lds_dwordx4 v[146:147], off
	s_mov_b32 m0, s52
	s_nop 0
	global_load_lds_dwordx4 v[216:217], off
	s_waitcnt vmcnt(8) lgkmcnt(0)
	s_setprio 1
	s_barrier
	v_mfma_f32_16x16x32_bf16 v[72:75], v[152:155], v[184:187], v[72:75]
	v_mfma_f32_16x16x32_bf16 v[64:67], v[160:163], v[184:187], v[64:67]
	v_mfma_f32_16x16x32_bf16 v[40:43], v[152:155], v[192:195], v[40:43]
	v_mfma_f32_16x16x32_bf16 v[32:35], v[160:163], v[192:195], v[32:35]
	v_mfma_f32_16x16x32_bf16 v[24:27], v[152:155], v[200:203], v[24:27]
	v_mfma_f32_16x16x32_bf16 v[16:19], v[160:163], v[200:203], v[16:19]
	v_mfma_f32_16x16x32_bf16 v[8:11], v[152:155], v[208:211], v[8:11]
	v_mfma_f32_16x16x32_bf16 v[0:3], v[160:163], v[208:211], v[0:3]
	v_mfma_f32_16x16x32_bf16 v[72:75], v[156:159], v[188:191], v[72:75]
	v_mfma_f32_16x16x32_bf16 v[64:67], v[164:167], v[188:191], v[64:67]
	v_mfma_f32_16x16x32_bf16 v[40:43], v[156:159], v[196:199], v[40:43]
	v_mfma_f32_16x16x32_bf16 v[32:35], v[164:167], v[196:199], v[32:35]
	v_mfma_f32_16x16x32_bf16 v[24:27], v[156:159], v[204:207], v[24:27]
	v_mfma_f32_16x16x32_bf16 v[16:19], v[164:167], v[204:207], v[16:19]
	v_mfma_f32_16x16x32_bf16 v[8:11], v[156:159], v[212:215], v[8:11]
	v_mfma_f32_16x16x32_bf16 v[0:3], v[164:167], v[212:215], v[0:3]
	s_setprio 0
	s_setprio 1
	v_mfma_f32_16x16x32_bf16 v[76:79], v[168:171], v[184:187], v[76:79]
	v_mfma_f32_16x16x32_bf16 v[68:71], v[176:179], v[184:187], v[68:71]
	v_mfma_f32_16x16x32_bf16 v[44:47], v[168:171], v[192:195], v[44:47]
	v_mfma_f32_16x16x32_bf16 v[36:39], v[176:179], v[192:195], v[36:39]
	v_mfma_f32_16x16x32_bf16 v[28:31], v[168:171], v[200:203], v[28:31]
	v_mfma_f32_16x16x32_bf16 v[20:23], v[176:179], v[200:203], v[20:23]
	v_mfma_f32_16x16x32_bf16 v[12:15], v[168:171], v[208:211], v[12:15]
	v_mfma_f32_16x16x32_bf16 v[4:7], v[176:179], v[208:211], v[4:7]
	v_mfma_f32_16x16x32_bf16 v[76:79], v[172:175], v[188:191], v[76:79]
	v_mfma_f32_16x16x32_bf16 v[68:71], v[180:183], v[188:191], v[68:71]
	v_mfma_f32_16x16x32_bf16 v[44:47], v[172:175], v[196:199], v[44:47]
	v_mfma_f32_16x16x32_bf16 v[36:39], v[180:183], v[196:199], v[36:39]
	v_mfma_f32_16x16x32_bf16 v[28:31], v[172:175], v[204:207], v[28:31]
	v_mfma_f32_16x16x32_bf16 v[20:23], v[180:183], v[204:207], v[20:23]
	v_mfma_f32_16x16x32_bf16 v[12:15], v[172:175], v[212:215], v[12:15]
	v_mfma_f32_16x16x32_bf16 v[4:7], v[180:183], v[212:215], v[4:7]
	s_barrier
	s_setprio 0
	ds_read_b128 v[152:155], v144
	ds_read_b128 v[156:159], v144 offset:1024
	ds_read_b128 v[160:163], v144 offset:2048
	ds_read_b128 v[164:167], v144 offset:3072
	ds_read_b128 v[168:171], v145
	ds_read_b128 v[172:175], v145 offset:1024
	ds_read_b128 v[176:179], v145 offset:2048
	ds_read_b128 v[180:183], v145 offset:3072
	s_add_u32 s46, s46, 0x80000
	s_addc_u32 s47, s47, 0
	s_mov_b32 m0, s53
	v_lshl_add_u64 v[218:219], s[46:47], 0, v[134:135]
	ds_read_b128 v[184:187], v151 offset:32768
	ds_read_b128 v[188:191], v151 offset:33792
	ds_read_b128 v[192:195], v151 offset:34816
	ds_read_b128 v[196:199], v151 offset:35840
	ds_read_b128 v[200:203], v151 offset:36864
	ds_read_b128 v[204:207], v151 offset:37888
	ds_read_b128 v[208:211], v151 offset:38912
	ds_read_b128 v[212:215], v151 offset:39936
	global_load_lds_dwordx4 v[218:219], off
	v_lshl_add_u64 v[218:219], s[46:47], 0, v[132:133]
	s_mov_b32 m0, s54
	s_nop 0
	global_load_lds_dwordx4 v[218:219], off
	s_waitcnt vmcnt(8) lgkmcnt(0)
	s_setprio 1
	s_barrier
	v_mfma_f32_16x16x32_bf16 v[120:123], v[152:155], v[184:187], v[120:123]
	v_mfma_f32_16x16x32_bf16 v[112:115], v[160:163], v[184:187], v[112:115]
	v_mfma_f32_16x16x32_bf16 v[104:107], v[152:155], v[192:195], v[104:107]
	v_mfma_f32_16x16x32_bf16 v[96:99], v[160:163], v[192:195], v[96:99]
	v_mfma_f32_16x16x32_bf16 v[88:91], v[152:155], v[200:203], v[88:91]
	v_mfma_f32_16x16x32_bf16 v[80:83], v[160:163], v[200:203], v[80:83]
	v_mfma_f32_16x16x32_bf16 v[56:59], v[152:155], v[208:211], v[56:59]
	v_mfma_f32_16x16x32_bf16 v[48:51], v[160:163], v[208:211], v[48:51]
	v_mfma_f32_16x16x32_bf16 v[120:123], v[156:159], v[188:191], v[120:123]
	v_mfma_f32_16x16x32_bf16 v[112:115], v[164:167], v[188:191], v[112:115]
	v_mfma_f32_16x16x32_bf16 v[104:107], v[156:159], v[196:199], v[104:107]
	v_mfma_f32_16x16x32_bf16 v[96:99], v[164:167], v[196:199], v[96:99]
	v_mfma_f32_16x16x32_bf16 v[88:91], v[156:159], v[204:207], v[88:91]
	v_mfma_f32_16x16x32_bf16 v[80:83], v[164:167], v[204:207], v[80:83]
	v_mfma_f32_16x16x32_bf16 v[56:59], v[156:159], v[212:215], v[56:59]
	v_mfma_f32_16x16x32_bf16 v[48:51], v[164:167], v[212:215], v[48:51]
	s_setprio 0
	s_setprio 1
	v_mfma_f32_16x16x32_bf16 v[124:127], v[168:171], v[184:187], v[124:127]
	v_mfma_f32_16x16x32_bf16 v[116:119], v[176:179], v[184:187], v[116:119]
	v_mfma_f32_16x16x32_bf16 v[108:111], v[168:171], v[192:195], v[108:111]
	v_mfma_f32_16x16x32_bf16 v[100:103], v[176:179], v[192:195], v[100:103]
	v_mfma_f32_16x16x32_bf16 v[92:95], v[168:171], v[200:203], v[92:95]
	v_mfma_f32_16x16x32_bf16 v[84:87], v[176:179], v[200:203], v[84:87]
	v_mfma_f32_16x16x32_bf16 v[60:63], v[168:171], v[208:211], v[60:63]
	v_mfma_f32_16x16x32_bf16 v[52:55], v[176:179], v[208:211], v[52:55]
	v_mfma_f32_16x16x32_bf16 v[124:127], v[172:175], v[188:191], v[124:127]
	v_mfma_f32_16x16x32_bf16 v[116:119], v[180:183], v[188:191], v[116:119]
	v_mfma_f32_16x16x32_bf16 v[108:111], v[172:175], v[196:199], v[108:111]
	v_mfma_f32_16x16x32_bf16 v[100:103], v[180:183], v[196:199], v[100:103]
	v_mfma_f32_16x16x32_bf16 v[92:95], v[172:175], v[204:207], v[92:95]
	v_mfma_f32_16x16x32_bf16 v[84:87], v[180:183], v[204:207], v[84:87]
	v_mfma_f32_16x16x32_bf16 v[60:63], v[172:175], v[212:215], v[60:63]
	v_mfma_f32_16x16x32_bf16 v[52:55], v[180:183], v[212:215], v[52:55]
	s_barrier
	s_setprio 0
	s_mov_b32 m0, s73
	v_lshl_add_u64 v[140:141], v[140:141], 0, s[12:13]
	s_add_u32 s44, s44, 0x80080
	ds_read_b128 v[184:187], v151 offset:49152
	ds_read_b128 v[188:191], v151 offset:50176
	ds_read_b128 v[192:195], v151 offset:51200
	ds_read_b128 v[196:199], v151 offset:52224
	ds_read_b128 v[200:203], v151 offset:53248
	ds_read_b128 v[204:207], v151 offset:54272
	ds_read_b128 v[208:211], v151 offset:55296
	ds_read_b128 v[212:215], v151 offset:56320
	global_load_lds_dwordx4 v[140:141], off
	v_lshl_add_u64 v[140:141], v[142:143], 0, s[12:13]
	s_mov_b32 m0, s74
	s_addc_u32 s45, s45, 0
	global_load_lds_dwordx4 v[140:141], off
	v_lshl_add_u64 v[140:141], s[44:45], 0, v[128:129]
	s_mov_b32 m0, s75
	s_nop 0
	global_load_lds_dwordx4 v[140:141], off
	v_lshl_add_u64 v[140:141], s[44:45], 0, v[130:131]
	s_mov_b32 m0, s76
	s_nop 0
	global_load_lds_dwordx4 v[140:141], off
	v_lshl_add_u64 v[140:141], v[146:147], 0, s[12:13]
	s_mov_b32 m0, s59
	s_nop 0
	global_load_lds_dwordx4 v[140:141], off
	v_lshl_add_u64 v[140:141], v[216:217], 0, s[12:13]
	s_mov_b32 m0, s60
	s_nop 0
	global_load_lds_dwordx4 v[140:141], off
	s_waitcnt vmcnt(8) lgkmcnt(0)
	s_setprio 1
	s_barrier
	v_mfma_f32_16x16x32_bf16 v[72:75], v[152:155], v[184:187], v[72:75]
	v_mfma_f32_16x16x32_bf16 v[64:67], v[160:163], v[184:187], v[64:67]
	v_mfma_f32_16x16x32_bf16 v[40:43], v[152:155], v[192:195], v[40:43]
	v_mfma_f32_16x16x32_bf16 v[32:35], v[160:163], v[192:195], v[32:35]
	v_mfma_f32_16x16x32_bf16 v[24:27], v[152:155], v[200:203], v[24:27]
	v_mfma_f32_16x16x32_bf16 v[16:19], v[160:163], v[200:203], v[16:19]
	v_mfma_f32_16x16x32_bf16 v[8:11], v[152:155], v[208:211], v[8:11]
	v_mfma_f32_16x16x32_bf16 v[0:3], v[160:163], v[208:211], v[0:3]
	v_mfma_f32_16x16x32_bf16 v[72:75], v[156:159], v[188:191], v[72:75]
	v_mfma_f32_16x16x32_bf16 v[64:67], v[164:167], v[188:191], v[64:67]
	v_mfma_f32_16x16x32_bf16 v[40:43], v[156:159], v[196:199], v[40:43]
	v_mfma_f32_16x16x32_bf16 v[32:35], v[164:167], v[196:199], v[32:35]
	v_mfma_f32_16x16x32_bf16 v[24:27], v[156:159], v[204:207], v[24:27]
	v_mfma_f32_16x16x32_bf16 v[16:19], v[164:167], v[204:207], v[16:19]
	v_mfma_f32_16x16x32_bf16 v[8:11], v[156:159], v[212:215], v[8:11]
	v_mfma_f32_16x16x32_bf16 v[0:3], v[164:167], v[212:215], v[0:3]
	s_setprio 0
	s_setprio 1
	v_mfma_f32_16x16x32_bf16 v[76:79], v[168:171], v[184:187], v[76:79]
	v_mfma_f32_16x16x32_bf16 v[68:71], v[176:179], v[184:187], v[68:71]
	v_mfma_f32_16x16x32_bf16 v[44:47], v[168:171], v[192:195], v[44:47]
	v_mfma_f32_16x16x32_bf16 v[36:39], v[176:179], v[192:195], v[36:39]
	v_mfma_f32_16x16x32_bf16 v[28:31], v[168:171], v[200:203], v[28:31]
	v_mfma_f32_16x16x32_bf16 v[20:23], v[176:179], v[200:203], v[20:23]
	v_mfma_f32_16x16x32_bf16 v[12:15], v[168:171], v[208:211], v[12:15]
	v_mfma_f32_16x16x32_bf16 v[4:7], v[176:179], v[208:211], v[4:7]
	v_mfma_f32_16x16x32_bf16 v[76:79], v[172:175], v[188:191], v[76:79]
	v_mfma_f32_16x16x32_bf16 v[68:71], v[180:183], v[188:191], v[68:71]
	v_mfma_f32_16x16x32_bf16 v[44:47], v[172:175], v[196:199], v[44:47]
	v_mfma_f32_16x16x32_bf16 v[36:39], v[180:183], v[196:199], v[36:39]
	v_mfma_f32_16x16x32_bf16 v[28:31], v[172:175], v[204:207], v[28:31]
	v_mfma_f32_16x16x32_bf16 v[20:23], v[180:183], v[204:207], v[20:23]
	v_mfma_f32_16x16x32_bf16 v[12:15], v[172:175], v[212:215], v[12:15]
	v_mfma_f32_16x16x32_bf16 v[4:7], v[180:183], v[212:215], v[4:7]
	s_barrier
	s_setprio 0
	s_add_i32 s79, s79, 2
	s_add_u32 s77, s77, 0x100
	s_addc_u32 s78, s78, 0
	s_add_u32 s42, s42, 0x100
	s_addc_u32 s43, s43, 0
	s_cmp_gt_u32 s79, 29
	s_cbranch_scc0 .LBB0_3342
	s_and_b64 vcc, exec, s[14:15]
	s_cbranch_vccz .LBB0_3345
	s_barrier

.LBB0_3608:
	ds_read_b128 v[146:149], v140
	ds_read_b128 v[150:153], v140 offset:1024
	ds_read_b128 v[154:157], v140 offset:2048
	ds_read_b128 v[158:161], v140 offset:3072
	ds_read_b128 v[162:165], v141
	ds_read_b128 v[166:169], v141 offset:1024
	ds_read_b128 v[170:173], v141 offset:2048
	ds_read_b128 v[174:177], v141 offset:3072
	s_add_u32 s20, s8, s43
	s_addc_u32 s21, s9, s44
	s_add_u32 s56, s8, s41
	s_addc_u32 s57, s9, s42
	s_cmp_eq_u32 s45, 28
	s_cselect_b32 s23, s5, s21
	s_cselect_b32 s22, s4, s20
	s_cselect_b32 s21, s1, s57
	s_cselect_b32 s20, s0, s56
	s_mov_b32 m0, s46
	v_lshl_add_u64 v[210:211], s[8:9], 0, v[138:139]
	ds_read_b128 v[178:181], v142
	ds_read_b128 v[182:185], v142 offset:1024
	ds_read_b128 v[186:189], v142 offset:2048
	ds_read_b128 v[190:193], v142 offset:3072
	ds_read_b128 v[194:197], v142 offset:4096
	ds_read_b128 v[198:201], v142 offset:5120
	ds_read_b128 v[202:205], v142 offset:6144
	ds_read_b128 v[206:209], v142 offset:7168
	global_load_lds_dwordx4 v[210:211], off
	v_lshl_add_u64 v[210:211], s[8:9], 0, v[136:137]
	s_mov_b32 m0, s47
	s_nop 0
	global_load_lds_dwordx4 v[210:211], off
	s_waitcnt vmcnt(8) lgkmcnt(0)
	s_setprio 1
	s_barrier
	v_mfma_f32_16x16x32_bf16 v[8:11], v[146:149], v[178:181], v[8:11]
	v_mfma_f32_16x16x32_bf16 v[12:15], v[154:157], v[178:181], v[12:15]
	v_mfma_f32_16x16x32_bf16 v[60:63], v[146:149], v[186:189], v[60:63]
	v_mfma_f32_16x16x32_bf16 v[20:23], v[154:157], v[186:189], v[20:23]
	v_mfma_f32_16x16x32_bf16 v[76:79], v[146:149], v[194:197], v[76:79]
	v_mfma_f32_16x16x32_bf16 v[52:55], v[154:157], v[194:197], v[52:55]
	v_mfma_f32_16x16x32_bf16 v[128:131], v[146:149], v[202:205], v[128:131]
	v_mfma_f32_16x16x32_bf16 v[68:71], v[154:157], v[202:205], v[68:71]
	v_mfma_f32_16x16x32_bf16 v[8:11], v[150:153], v[182:185], v[8:11]
	v_mfma_f32_16x16x32_bf16 v[12:15], v[158:161], v[182:185], v[12:15]
	v_mfma_f32_16x16x32_bf16 v[60:63], v[150:153], v[190:193], v[60:63]
	v_mfma_f32_16x16x32_bf16 v[20:23], v[158:161], v[190:193], v[20:23]
	v_mfma_f32_16x16x32_bf16 v[76:79], v[150:153], v[198:201], v[76:79]
	v_mfma_f32_16x16x32_bf16 v[52:55], v[158:161], v[198:201], v[52:55]
	v_mfma_f32_16x16x32_bf16 v[128:131], v[150:153], v[206:209], v[128:131]
	v_mfma_f32_16x16x32_bf16 v[68:71], v[158:161], v[206:209], v[68:71]
	s_setprio 0
	s_setprio 1
	v_mfma_f32_16x16x32_bf16 v[24:27], v[162:165], v[178:181], v[24:27]
	v_mfma_f32_16x16x32_bf16 v[16:19], v[170:173], v[178:181], v[16:19]
	v_mfma_f32_16x16x32_bf16 v[56:59], v[162:165], v[186:189], v[56:59]
	v_mfma_f32_16x16x32_bf16 v[48:51], v[170:173], v[186:189], v[48:51]
	v_mfma_f32_16x16x32_bf16 v[72:75], v[162:165], v[194:197], v[72:75]
	v_mfma_f32_16x16x32_bf16 v[64:67], v[170:173], v[194:197], v[64:67]
	v_mfma_f32_16x16x32_bf16 v[108:111], v[162:165], v[202:205], v[108:111]
	v_mfma_f32_16x16x32_bf16 v[96:99], v[170:173], v[202:205], v[96:99]
	v_mfma_f32_16x16x32_bf16 v[24:27], v[166:169], v[182:185], v[24:27]
	v_mfma_f32_16x16x32_bf16 v[16:19], v[174:177], v[182:185], v[16:19]
	v_mfma_f32_16x16x32_bf16 v[56:59], v[166:169], v[190:193], v[56:59]
	v_mfma_f32_16x16x32_bf16 v[48:51], v[174:177], v[190:193], v[48:51]
	v_mfma_f32_16x16x32_bf16 v[72:75], v[166:169], v[198:201], v[72:75]
	v_mfma_f32_16x16x32_bf16 v[64:67], v[174:177], v[198:201], v[64:67]
	v_mfma_f32_16x16x32_bf16 v[108:111], v[166:169], v[206:209], v[108:111]
	v_mfma_f32_16x16x32_bf16 v[96:99], v[174:177], v[206:209], v[96:99]
	s_barrier
	s_setprio 0
	s_mov_b32 m0, s48
	v_lshl_add_u64 v[210:211], s[20:21], 0, v[34:35]
	s_add_u32 s56, s20, 0x80000
	ds_read_b128 v[178:181], v142 offset:16384
	ds_read_b128 v[182:185], v142 offset:17408
	ds_read_b128 v[186:189], v142 offset:18432
	ds_read_b128 v[190:193], v142 offset:19456
	ds_read_b128 v[194:197], v142 offset:20480
	ds_read_b128 v[198:201], v142 offset:21504
	ds_read_b128 v[202:205], v142 offset:22528
	ds_read_b128 v[206:209], v142 offset:23552
	global_load_lds_dwordx4 v[210:211], off
	v_lshl_add_u64 v[212:213], s[20:21], 0, v[134:135]
	s_mov_b32 m0, s49
	s_addc_u32 s57, s21, 0
	global_load_lds_dwordx4 v[212:213], off
	v_lshl_add_u64 v[214:215], s[56:57], 0, v[34:35]
	s_mov_b32 m0, s50
	v_lshl_add_u64 v[216:217], s[22:23], 0, v[132:133]
	global_load_lds_dwordx4 v[214:215], off
	v_lshl_add_u64 v[214:215], s[56:57], 0, v[134:135]
	s_mov_b32 m0, s51
	s_nop 0
	global_load_lds_dwordx4 v[214:215], off
	v_lshl_add_u64 v[214:215], s[22:23], 0, v[32:33]
	s_mov_b32 m0, s27
	s_nop 0
	global_load_lds_dwordx4 v[214:215], off
	s_mov_b32 m0, s36
	s_nop 0
	global_load_lds_dwordx4 v[216:217], off
	s_waitcnt vmcnt(8) lgkmcnt(0)
	s_setprio 1
	s_barrier
	v_mfma_f32_16x16x32_bf16 v[100:103], v[146:149], v[178:181], v[100:103]
	v_mfma_f32_16x16x32_bf16 v[104:107], v[154:157], v[178:181], v[104:107]
	v_mfma_f32_16x16x32_bf16 v[116:119], v[146:149], v[186:189], v[116:119]
	v_mfma_f32_16x16x32_bf16 v[120:123], v[154:157], v[186:189], v[120:123]
	v_mfma_f32_16x16x32_bf16 v[84:87], v[146:149], v[194:197], v[84:87]
	v_mfma_f32_16x16x32_bf16 v[80:83], v[154:157], v[194:197], v[80:83]
	v_mfma_f32_16x16x32_bf16 v[36:39], v[146:149], v[202:205], v[36:39]
	v_mfma_f32_16x16x32_bf16 v[28:31], v[154:157], v[202:205], v[28:31]
	v_mfma_f32_16x16x32_bf16 v[100:103], v[150:153], v[182:185], v[100:103]
	v_mfma_f32_16x16x32_bf16 v[104:107], v[158:161], v[182:185], v[104:107]
	v_mfma_f32_16x16x32_bf16 v[116:119], v[150:153], v[190:193], v[116:119]
	v_mfma_f32_16x16x32_bf16 v[120:123], v[158:161], v[190:193], v[120:123]
	v_mfma_f32_16x16x32_bf16 v[84:87], v[150:153], v[198:201], v[84:87]
	v_mfma_f32_16x16x32_bf16 v[80:83], v[158:161], v[198:201], v[80:83]
	v_mfma_f32_16x16x32_bf16 v[36:39], v[150:153], v[206:209], v[36:39]
	v_mfma_f32_16x16x32_bf16 v[28:31], v[158:161], v[206:209], v[28:31]
	s_setprio 0
	s_setprio 1
	v_mfma_f32_16x16x32_bf16 v[124:127], v[162:165], v[178:181], v[124:127]
	v_mfma_f32_16x16x32_bf16 v[112:115], v[170:173], v[178:181], v[112:115]
	v_mfma_f32_16x16x32_bf16 v[92:95], v[162:165], v[186:189], v[92:95]
	v_mfma_f32_16x16x32_bf16 v[88:91], v[170:173], v[186:189], v[88:91]
	v_mfma_f32_16x16x32_bf16 v[44:47], v[162:165], v[194:197], v[44:47]
	v_mfma_f32_16x16x32_bf16 v[40:43], v[170:173], v[194:197], v[40:43]
	v_mfma_f32_16x16x32_bf16 v[4:7], v[162:165], v[202:205], v[4:7]
	v_mfma_f32_16x16x32_bf16 v[0:3], v[170:173], v[202:205], v[0:3]
	v_mfma_f32_16x16x32_bf16 v[124:127], v[166:169], v[182:185], v[124:127]
	v_mfma_f32_16x16x32_bf16 v[112:115], v[174:177], v[182:185], v[112:115]
	v_mfma_f32_16x16x32_bf16 v[92:95], v[166:169], v[190:193], v[92:95]
	v_mfma_f32_16x16x32_bf16 v[88:91], v[174:177], v[190:193], v[88:91]
	v_mfma_f32_16x16x32_bf16 v[44:47], v[166:169], v[198:201], v[44:47]
	v_mfma_f32_16x16x32_bf16 v[40:43], v[174:177], v[198:201], v[40:43]
	v_mfma_f32_16x16x32_bf16 v[4:7], v[166:169], v[206:209], v[4:7]
	v_mfma_f32_16x16x32_bf16 v[0:3], v[174:177], v[206:209], v[0:3]
	s_barrier
	s_setprio 0
	ds_read_b128 v[146:149], v143
	ds_read_b128 v[150:153], v143 offset:1024
	ds_read_b128 v[154:157], v143 offset:2048
	ds_read_b128 v[158:161], v143 offset:3072
	ds_read_b128 v[162:165], v144
	ds_read_b128 v[166:169], v144 offset:1024
	ds_read_b128 v[170:173], v144 offset:2048
	ds_read_b128 v[174:177], v144 offset:3072
	s_add_u32 s22, s22, 0x80000
	s_addc_u32 s23, s23, 0
	s_mov_b32 m0, s37
	v_lshl_add_u64 v[218:219], s[22:23], 0, v[32:33]
	ds_read_b128 v[178:181], v142 offset:32768
	ds_read_b128 v[182:185], v142 offset:33792
	ds_read_b128 v[186:189], v142 offset:34816
	ds_read_b128 v[190:193], v142 offset:35840
	ds_read_b128 v[194:197], v142 offset:36864
	ds_read_b128 v[198:201], v142 offset:37888
	ds_read_b128 v[202:205], v142 offset:38912
	ds_read_b128 v[206:209], v142 offset:39936
	global_load_lds_dwordx4 v[218:219], off
	v_lshl_add_u64 v[218:219], s[22:23], 0, v[132:133]
	s_mov_b32 m0, s38
	s_nop 0
	global_load_lds_dwordx4 v[218:219], off
	s_waitcnt vmcnt(8) lgkmcnt(0)
	s_setprio 1
	s_barrier
	v_mfma_f32_16x16x32_bf16 v[8:11], v[146:149], v[178:181], v[8:11]
	v_mfma_f32_16x16x32_bf16 v[12:15], v[154:157], v[178:181], v[12:15]
	v_mfma_f32_16x16x32_bf16 v[60:63], v[146:149], v[186:189], v[60:63]
	v_mfma_f32_16x16x32_bf16 v[20:23], v[154:157], v[186:189], v[20:23]
	v_mfma_f32_16x16x32_bf16 v[76:79], v[146:149], v[194:197], v[76:79]
	v_mfma_f32_16x16x32_bf16 v[52:55], v[154:157], v[194:197], v[52:55]
	v_mfma_f32_16x16x32_bf16 v[128:131], v[146:149], v[202:205], v[128:131]
	v_mfma_f32_16x16x32_bf16 v[68:71], v[154:157], v[202:205], v[68:71]
	v_mfma_f32_16x16x32_bf16 v[8:11], v[150:153], v[182:185], v[8:11]
	v_mfma_f32_16x16x32_bf16 v[12:15], v[158:161], v[182:185], v[12:15]
	v_mfma_f32_16x16x32_bf16 v[60:63], v[150:153], v[190:193], v[60:63]
	v_mfma_f32_16x16x32_bf16 v[20:23], v[158:161], v[190:193], v[20:23]
	v_mfma_f32_16x16x32_bf16 v[76:79], v[150:153], v[198:201], v[76:79]
	v_mfma_f32_16x16x32_bf16 v[52:55], v[158:161], v[198:201], v[52:55]
	v_mfma_f32_16x16x32_bf16 v[128:131], v[150:153], v[206:209], v[128:131]
	v_mfma_f32_16x16x32_bf16 v[68:71], v[158:161], v[206:209], v[68:71]
	s_setprio 0
	s_setprio 1
	v_mfma_f32_16x16x32_bf16 v[24:27], v[162:165], v[178:181], v[24:27]
	v_mfma_f32_16x16x32_bf16 v[16:19], v[170:173], v[178:181], v[16:19]
	v_mfma_f32_16x16x32_bf16 v[56:59], v[162:165], v[186:189], v[56:59]
	v_mfma_f32_16x16x32_bf16 v[48:51], v[170:173], v[186:189], v[48:51]
	v_mfma_f32_16x16x32_bf16 v[72:75], v[162:165], v[194:197], v[72:75]
	v_mfma_f32_16x16x32_bf16 v[64:67], v[170:173], v[194:197], v[64:67]
	v_mfma_f32_16x16x32_bf16 v[108:111], v[162:165], v[202:205], v[108:111]
	v_mfma_f32_16x16x32_bf16 v[96:99], v[170:173], v[202:205], v[96:99]
	v_mfma_f32_16x16x32_bf16 v[24:27], v[166:169], v[182:185], v[24:27]
	v_mfma_f32_16x16x32_bf16 v[16:19], v[174:177], v[182:185], v[16:19]
	v_mfma_f32_16x16x32_bf16 v[56:59], v[166:169], v[190:193], v[56:59]
	v_mfma_f32_16x16x32_bf16 v[48:51], v[174:177], v[190:193], v[48:51]
	v_mfma_f32_16x16x32_bf16 v[72:75], v[166:169], v[198:201], v[72:75]
	v_mfma_f32_16x16x32_bf16 v[64:67], v[174:177], v[198:201], v[64:67]
	v_mfma_f32_16x16x32_bf16 v[108:111], v[166:169], v[206:209], v[108:111]
	v_mfma_f32_16x16x32_bf16 v[96:99], v[174:177], v[206:209], v[96:99]
	s_barrier
; #define PG8_WAIT_V(n) asm volatile("s_waitcnt vmcnt(" #n ")" ::: "memory")
; #define PG8_BAR __builtin_amdgcn_s_barrier()
; template <class Epi, class Sched, bool ALIGN_EPI = false, bool SP2 = false, bool A_TILED = false>
; __device__ __forceinline__ void gemm_phase(PG8_LAS unsigned char* lds, const Gemm g, const Sched& S, const Epi& E, const int wave_s) {
;     ...
;     PG8_WAIT_V(0);
;     if constexpr (!ALIGN_EPI) { if (wr == 0) PG8_BAR; }
	s_setprio 0
	s_mov_b32 m0, s52
	v_lshl_add_u64 v[210:211], v[210:211], 0, s[14:15]
	s_add_u32 s20, s20, 0x80080
	ds_read_b128 v[178:181], v142 offset:49152
	ds_read_b128 v[182:185], v142 offset:50176
	ds_read_b128 v[186:189], v142 offset:51200
	ds_read_b128 v[190:193], v142 offset:52224
	ds_read_b128 v[194:197], v142 offset:53248
	ds_read_b128 v[198:201], v142 offset:54272
	ds_read_b128 v[202:205], v142 offset:55296
	ds_read_b128 v[206:209], v142 offset:56320
	global_load_lds_dwordx4 v[210:211], off
	v_lshl_add_u64 v[210:211], v[212:213], 0, s[14:15]
	s_mov_b32 m0, s53
	s_addc_u32 s21, s21, 0
	global_load_lds_dwordx4 v[210:211], off
	v_lshl_add_u64 v[210:211], s[20:21], 0, v[34:35]
	s_mov_b32 m0, s54
	s_nop 0
	global_load_lds_dwordx4 v[210:211], off
	v_lshl_add_u64 v[210:211], s[20:21], 0, v[134:135]
	s_mov_b32 m0, s55
	s_nop 0
	global_load_lds_dwordx4 v[210:211], off
	v_lshl_add_u64 v[210:211], v[214:215], 0, s[14:15]
	s_mov_b32 m0, s39
	s_nop 0
	global_load_lds_dwordx4 v[210:211], off
	v_lshl_add_u64 v[210:211], v[216:217], 0, s[14:15]
	s_mov_b32 m0, s40
	s_nop 0
	global_load_lds_dwordx4 v[210:211], off
	s_waitcnt vmcnt(8) lgkmcnt(0)
	s_setprio 1
	s_barrier
	v_mfma_f32_16x16x32_bf16 v[100:103], v[146:149], v[178:181], v[100:103]
	v_mfma_f32_16x16x32_bf16 v[104:107], v[154:157], v[178:181], v[104:107]
	v_mfma_f32_16x16x32_bf16 v[116:119], v[146:149], v[186:189], v[116:119]
	v_mfma_f32_16x16x32_bf16 v[120:123], v[154:157], v[186:189], v[120:123]
	v_mfma_f32_16x16x32_bf16 v[84:87], v[146:149], v[194:197], v[84:87]
	v_mfma_f32_16x16x32_bf16 v[80:83], v[154:157], v[194:197], v[80:83]
	v_mfma_f32_16x16x32_bf16 v[36:39], v[146:149], v[202:205], v[36:39]
	v_mfma_f32_16x16x32_bf16 v[28:31], v[154:157], v[202:205], v[28:31]
	v_mfma_f32_16x16x32_bf16 v[100:103], v[150:153], v[182:185], v[100:103]
	v_mfma_f32_16x16x32_bf16 v[104:107], v[158:161], v[182:185], v[104:107]
	v_mfma_f32_16x16x32_bf16 v[116:119], v[150:153], v[190:193], v[116:119]
	v_mfma_f32_16x16x32_bf16 v[120:123], v[158:161], v[190:193], v[120:123]
	v_mfma_f32_16x16x32_bf16 v[84:87], v[150:153], v[198:201], v[84:87]
	v_mfma_f32_16x16x32_bf16 v[80:83], v[158:161], v[198:201], v[80:83]
	v_mfma_f32_16x16x32_bf16 v[36:39], v[150:153], v[206:209], v[36:39]
	v_mfma_f32_16x16x32_bf16 v[28:31], v[158:161], v[206:209], v[28:31]
	s_setprio 0
	s_setprio 1
	v_mfma_f32_16x16x32_bf16 v[124:127], v[162:165], v[178:181], v[124:127]
	v_mfma_f32_16x16x32_bf16 v[112:115], v[170:173], v[178:181], v[112:115]
	v_mfma_f32_16x16x32_bf16 v[92:95], v[162:165], v[186:189], v[92:95]
	v_mfma_f32_16x16x32_bf16 v[88:91], v[170:173], v[186:189], v[88:91]
	v_mfma_f32_16x16x32_bf16 v[44:47], v[162:165], v[194:197], v[44:47]
	v_mfma_f32_16x16x32_bf16 v[40:43], v[170:173], v[194:197], v[40:43]
	v_mfma_f32_16x16x32_bf16 v[4:7], v[162:165], v[202:205], v[4:7]
	v_mfma_f32_16x16x32_bf16 v[0:3], v[170:173], v[202:205], v[0:3]
	v_mfma_f32_16x16x32_bf16 v[124:127], v[166:169], v[182:185], v[124:127]
	v_mfma_f32_16x16x32_bf16 v[112:115], v[174:177], v[182:185], v[112:115]
	v_mfma_f32_16x16x32_bf16 v[92:95], v[166:169], v[190:193], v[92:95]
	v_mfma_f32_16x16x32_bf16 v[88:91], v[174:177], v[190:193], v[88:91]
	v_mfma_f32_16x16x32_bf16 v[44:47], v[166:169], v[198:201], v[44:47]
	v_mfma_f32_16x16x32_bf16 v[40:43], v[174:177], v[198:201], v[40:43]
	v_mfma_f32_16x16x32_bf16 v[4:7], v[166:169], v[206:209], v[4:7]
	v_mfma_f32_16x16x32_bf16 v[0:3], v[174:177], v[206:209], v[0:3]
	s_barrier
	s_setprio 0
	s_add_i32 s45, s45, 2
	s_add_u32 s41, s41, 0x100
	s_addc_u32 s42, s42, 0
	s_add_u32 s43, s43, 0x100
	s_addc_u32 s44, s44, 0
	v_lshl_add_u64 v[136:137], v[136:137], 0, s[16:17]
	s_cmp_gt_u32 s45, 29
	v_lshl_add_u64 v[138:139], v[138:139], 0, s[16:17]
	s_cbranch_scc0 .LBB0_3608
	s_waitcnt vmcnt(0)
	s_cmpk_lt_u32 s24, 0x100
	s_cbranch_scc0 .LBB0_3611
	s_barrier

; template <class Epi, class Sched, bool ALIGN_EPI = false, bool SP2 = false, bool A_TILED = false>
; __device__ __forceinline__ void gemm_phase(PG8_LAS unsigned char* lds, const Gemm g, const Sched& S, const Epi& E, const int wave_s) {
;     ...
;         const char* nA = has_next ? (const char*)g.A + (size_t)nxt.pm * tstepA : cA; const char* nB = has_next ? (const char*)g.Bt + (size_t)nxt.pn * tstep : cB;
;         constexpr bool PEEL = SP2 && !Epi::AFTER_DRAIN;
;         if constexpr (PEEL) {
;             const char* a1 = cA + kstepA; const char* a2 = cA + 2 * kstepA; const char* b2 = cB + 2 * kstep; const char* a3 = a2 + kstepA; const char* b3 = b2 + kstep;
;             PG8_ITER(PG8_MMAZ)
.LBB0_3719:
	s_ashr_i32 s19, s18, 31
	s_lshl_b64 s[20:21], s[18:19], 20
	s_add_u32 s20, s41, s20
	ds_read_b128 v[0:3], v145
	ds_read_b128 v[4:7], v145 offset:1024
	ds_read_b128 v[8:11], v145 offset:2048
	ds_read_b128 v[12:15], v145 offset:3072
	ds_read_b128 v[16:19], v146
	ds_read_b128 v[20:23], v146 offset:1024
	ds_read_b128 v[24:27], v146 offset:2048
	ds_read_b128 v[28:31], v146 offset:3072
	s_addc_u32 s21, s42, s21
	s_ashr_i32 s17, s16, 31
	s_lshl_b64 s[22:23], s[16:17], 20
	s_add_u32 s22, s43, s22
	s_addc_u32 s23, s44, s23
	s_and_b64 s[38:39], s[0:1], exec
	s_cselect_b32 s17, s21, s37
	s_cselect_b32 s19, s20, s36
	s_cselect_b32 s62, s23, s27
	s_cselect_b32 s63, s22, s26
	s_add_u32 s38, s36, 0x80080
	s_addc_u32 s39, s37, 0
	s_add_i32 s64, s47, 0xc000
	v_lshl_add_u64 v[64:65], s[38:39], 0, v[134:135]
	s_mov_b32 m0, s64
	s_add_i32 s65, s47, 0xe000
	ds_read_b128 v[32:35], v147
	ds_read_b128 v[36:39], v147 offset:1024
	ds_read_b128 v[40:43], v147 offset:2048
	ds_read_b128 v[44:47], v147 offset:3072
	ds_read_b128 v[48:51], v147 offset:4096
	ds_read_b128 v[52:55], v147 offset:5120
	ds_read_b128 v[56:59], v147 offset:6144
	ds_read_b128 v[60:63], v147 offset:7168
	global_load_lds_dwordx4 v[64:65], off
	v_lshl_add_u64 v[64:65], s[38:39], 0, v[132:133]
	s_mov_b32 m0, s65
	s_nop 0
	global_load_lds_dwordx4 v[64:65], off
	s_waitcnt vmcnt(8) lgkmcnt(0)
	s_setprio 1
	s_barrier
	v_mfma_f32_16x16x32_bf16 v[88:91], v[0:3], v[56:59], 0
	v_mfma_f32_16x16x32_bf16 v[64:67], v[0:3], v[32:35], 0
	v_mfma_f32_16x16x32_bf16 v[68:71], v[8:11], v[32:35], 0
	v_mfma_f32_16x16x32_bf16 v[72:75], v[0:3], v[40:43], 0
	v_mfma_f32_16x16x32_bf16 v[76:79], v[8:11], v[40:43], 0
	v_mfma_f32_16x16x32_bf16 v[80:83], v[0:3], v[48:51], 0
	v_mfma_f32_16x16x32_bf16 v[84:87], v[8:11], v[48:51], 0
	v_mfma_f32_16x16x32_bf16 v[96:99], v[4:7], v[60:63], v[88:91]
	v_mfma_f32_16x16x32_bf16 v[88:91], v[8:11], v[56:59], 0
	v_mfma_f32_16x16x32_bf16 v[64:67], v[4:7], v[36:39], v[64:67]
	v_mfma_f32_16x16x32_bf16 v[68:71], v[12:15], v[36:39], v[68:71]
	v_mfma_f32_16x16x32_bf16 v[72:75], v[4:7], v[44:47], v[72:75]
	v_mfma_f32_16x16x32_bf16 v[76:79], v[12:15], v[44:47], v[76:79]
	v_mfma_f32_16x16x32_bf16 v[80:83], v[4:7], v[52:55], v[80:83]
	v_mfma_f32_16x16x32_bf16 v[84:87], v[12:15], v[52:55], v[84:87]
	v_mfma_f32_16x16x32_bf16 v[100:103], v[12:15], v[60:63], v[88:91]
	s_setprio 0
	s_setprio 1
	v_mfma_f32_16x16x32_bf16 v[88:91], v[16:19], v[32:35], 0
	v_mfma_f32_16x16x32_bf16 v[32:35], v[24:27], v[32:35], 0
	v_mfma_f32_16x16x32_bf16 v[112:115], v[20:23], v[36:39], v[88:91]
	v_mfma_f32_16x16x32_bf16 v[32:35], v[28:31], v[36:39], v[32:35]
	v_mfma_f32_16x16x32_bf16 v[36:39], v[16:19], v[40:43], 0
	v_mfma_f32_16x16x32_bf16 v[40:43], v[24:27], v[40:43], 0
	v_mfma_f32_16x16x32_bf16 v[36:39], v[20:23], v[44:47], v[36:39]
	v_mfma_f32_16x16x32_bf16 v[40:43], v[28:31], v[44:47], v[40:43]
	v_mfma_f32_16x16x32_bf16 v[44:47], v[16:19], v[48:51], 0
	v_mfma_f32_16x16x32_bf16 v[48:51], v[24:27], v[48:51], 0
	v_mfma_f32_16x16x32_bf16 v[44:47], v[20:23], v[52:55], v[44:47]
	v_mfma_f32_16x16x32_bf16 v[48:51], v[28:31], v[52:55], v[48:51]
	v_mfma_f32_16x16x32_bf16 v[52:55], v[16:19], v[56:59], 0
	v_mfma_f32_16x16x32_bf16 v[56:59], v[24:27], v[56:59], 0
	v_mfma_f32_16x16x32_bf16 v[52:55], v[20:23], v[60:63], v[52:55]
	v_mfma_f32_16x16x32_bf16 v[56:59], v[28:31], v[60:63], v[56:59]
	s_barrier
	s_setprio 0
	s_add_i32 s66, s60, s45
	v_lshl_add_u64 v[242:243], s[26:27], 0, v[128:129]
	s_add_i32 s67, s66, 0x2000
	v_lshl_add_u64 v[148:149], v[242:243], 0, s[12:13]
	s_mov_b32 m0, s66
	v_lshl_add_u64 v[244:245], s[26:27], 0, v[130:131]
	s_add_u32 s38, s26, 0x80100
	ds_read_b128 v[60:63], v147 offset:16384
	ds_read_b128 v[88:91], v147 offset:17408
	ds_read_b128 v[92:95], v147 offset:18432
	ds_read_b128 v[104:107], v147 offset:19456
	ds_read_b128 v[108:111], v147 offset:20480
	ds_read_b128 v[116:119], v147 offset:21504
	ds_read_b128 v[120:123], v147 offset:22528
	ds_read_b128 v[124:127], v147 offset:23552
	global_load_lds_dwordx4 v[148:149], off
	v_lshl_add_u64 v[148:149], v[244:245], 0, s[12:13]
	s_mov_b32 m0, s67
	s_addc_u32 s39, s27, 0
	s_add_i32 s68, s61, s45
	global_load_lds_dwordx4 v[148:149], off
	v_lshl_add_u64 v[148:149], s[38:39], 0, v[128:129]
	s_mov_b32 m0, s68
	s_add_i32 s69, s68, 0x2000
	global_load_lds_dwordx4 v[148:149], off
	v_lshl_add_u64 v[148:149], s[38:39], 0, v[130:131]
	s_mov_b32 m0, s69
	v_lshl_add_u64 v[246:247], s[36:37], 0, v[134:135]
	global_load_lds_dwordx4 v[148:149], off
	v_lshl_add_u64 v[148:149], v[246:247], 0, s[12:13]
	s_mov_b32 m0, s47
	v_lshl_add_u64 v[248:249], s[36:37], 0, v[132:133]
	global_load_lds_dwordx4 v[148:149], off
	v_lshl_add_u64 v[148:149], v[248:249], 0, s[12:13]
	s_mov_b32 m0, s48
	s_nop 0
	global_load_lds_dwordx4 v[148:149], off
	s_waitcnt vmcnt(8) lgkmcnt(0)
	s_setprio 1
	s_barrier
	v_mfma_f32_16x16x32_bf16 v[148:151], v[0:3], v[60:63], 0
	v_mfma_f32_16x16x32_bf16 v[158:161], v[0:3], v[92:95], 0
	v_mfma_f32_16x16x32_bf16 v[166:169], v[0:3], v[108:111], 0
	v_mfma_f32_16x16x32_bf16 v[0:3], v[0:3], v[120:123], 0
	v_mfma_f32_16x16x32_bf16 v[150:153], v[4:7], v[88:91], v[148:151]
	v_mfma_f32_16x16x32_bf16 v[158:161], v[4:7], v[104:107], v[158:161]
	v_mfma_f32_16x16x32_bf16 v[166:169], v[4:7], v[116:119], v[166:169]
	v_mfma_f32_16x16x32_bf16 v[0:3], v[4:7], v[124:127], v[0:3]
	v_mfma_f32_16x16x32_bf16 v[4:7], v[8:11], v[120:123], 0
	v_mfma_f32_16x16x32_bf16 v[154:157], v[8:11], v[60:63], 0
	v_mfma_f32_16x16x32_bf16 v[162:165], v[8:11], v[92:95], 0
	v_mfma_f32_16x16x32_bf16 v[170:173], v[8:11], v[108:111], 0
	v_mfma_f32_16x16x32_bf16 v[4:7], v[12:15], v[124:127], v[4:7]
	v_mfma_f32_16x16x32_bf16 v[154:157], v[12:15], v[88:91], v[154:157]
	v_mfma_f32_16x16x32_bf16 v[162:165], v[12:15], v[104:107], v[162:165]
	v_mfma_f32_16x16x32_bf16 v[170:173], v[12:15], v[116:119], v[170:173]
	s_setprio 0
	s_setprio 1
	v_mfma_f32_16x16x32_bf16 v[8:11], v[16:19], v[60:63], 0
	v_mfma_f32_16x16x32_bf16 v[174:177], v[20:23], v[88:91], v[8:11]
	v_mfma_f32_16x16x32_bf16 v[8:11], v[24:27], v[60:63], 0
	v_mfma_f32_16x16x32_bf16 v[60:63], v[28:31], v[88:91], v[8:11]
	v_mfma_f32_16x16x32_bf16 v[8:11], v[16:19], v[92:95], 0
	v_mfma_f32_16x16x32_bf16 v[178:181], v[20:23], v[104:107], v[8:11]
	v_mfma_f32_16x16x32_bf16 v[8:11], v[24:27], v[92:95], 0
	v_mfma_f32_16x16x32_bf16 v[182:185], v[28:31], v[104:107], v[8:11]
	v_mfma_f32_16x16x32_bf16 v[8:11], v[16:19], v[108:111], 0
	v_mfma_f32_16x16x32_bf16 v[186:189], v[20:23], v[116:119], v[8:11]
	v_mfma_f32_16x16x32_bf16 v[8:11], v[24:27], v[108:111], 0
	v_mfma_f32_16x16x32_bf16 v[190:193], v[28:31], v[116:119], v[8:11]
	v_mfma_f32_16x16x32_bf16 v[8:11], v[16:19], v[120:123], 0
	v_mfma_f32_16x16x32_bf16 v[194:197], v[20:23], v[124:127], v[8:11]
	v_mfma_f32_16x16x32_bf16 v[8:11], v[24:27], v[120:123], 0
	v_mfma_f32_16x16x32_bf16 v[198:201], v[28:31], v[124:127], v[8:11]
	s_barrier
	s_setprio 0
	s_add_i32 s70, 0, 0x18000
	s_add_i32 s72, 0, 0x1c000
	v_add_u32_e32 v148, s70, v144
	v_add_u32_e32 v149, s72, v144
	s_nop 0
	ds_read_b128 v[8:11], v148
	ds_read_b128 v[12:15], v148 offset:1024
	ds_read_b128 v[16:19], v148 offset:2048
	ds_read_b128 v[20:23], v148 offset:3072
	ds_read_b128 v[202:205], v149
	ds_read_b128 v[206:209], v149 offset:1024
	ds_read_b128 v[210:213], v149 offset:2048
	ds_read_b128 v[214:217], v149 offset:3072
	s_add_u32 s38, s36, 0x80100
	s_addc_u32 s39, s37, 0
	s_mov_b32 m0, s49
	v_lshl_add_u64 v[88:89], s[38:39], 0, v[134:135]
	ds_read_b128 v[24:27], v147 offset:32768
	ds_read_b128 v[28:31], v147 offset:33792
	ds_read_b128 v[218:221], v147 offset:34816
	ds_read_b128 v[222:225], v147 offset:35840
	ds_read_b128 v[226:229], v147 offset:36864
	ds_read_b128 v[230:233], v147 offset:37888
	ds_read_b128 v[234:237], v147 offset:38912
	ds_read_b128 v[238:241], v147 offset:39936
	global_load_lds_dwordx4 v[88:89], off
	v_lshl_add_u64 v[88:89], s[38:39], 0, v[132:133]
	s_mov_b32 m0, s50
	s_nop 0
	global_load_lds_dwordx4 v[88:89], off
	s_waitcnt vmcnt(8) lgkmcnt(0)
	s_setprio 1
	s_barrier
	v_mfma_f32_16x16x32_bf16 v[64:67], v[8:11], v[24:27], v[64:67]
	v_mfma_f32_16x16x32_bf16 v[120:123], v[12:15], v[28:31], v[64:67]
	v_mfma_f32_16x16x32_bf16 v[64:67], v[16:19], v[24:27], v[68:71]
	v_mfma_f32_16x16x32_bf16 v[124:127], v[20:23], v[28:31], v[64:67]
	v_mfma_f32_16x16x32_bf16 v[64:67], v[8:11], v[218:221], v[72:75]
	v_mfma_f32_16x16x32_bf16 v[104:107], v[12:15], v[222:225], v[64:67]
	v_mfma_f32_16x16x32_bf16 v[64:67], v[16:19], v[218:221], v[76:79]
	v_mfma_f32_16x16x32_bf16 v[108:111], v[20:23], v[222:225], v[64:67]
	v_mfma_f32_16x16x32_bf16 v[64:67], v[8:11], v[226:229], v[80:83]
	v_mfma_f32_16x16x32_bf16 v[88:91], v[12:15], v[230:233], v[64:67]
	v_mfma_f32_16x16x32_bf16 v[64:67], v[16:19], v[226:229], v[84:87]
	v_mfma_f32_16x16x32_bf16 v[92:95], v[20:23], v[230:233], v[64:67]
	v_mfma_f32_16x16x32_bf16 v[64:67], v[8:11], v[234:237], v[96:99]
	v_mfma_f32_16x16x32_bf16 v[68:71], v[16:19], v[234:237], v[100:103]
	v_mfma_f32_16x16x32_bf16 v[64:67], v[12:15], v[238:241], v[64:67]
	v_mfma_f32_16x16x32_bf16 v[68:71], v[20:23], v[238:241], v[68:71]
	s_setprio 0
	s_setprio 1
	v_mfma_f32_16x16x32_bf16 v[72:75], v[202:205], v[24:27], v[112:115]
	v_mfma_f32_16x16x32_bf16 v[24:27], v[210:213], v[24:27], v[32:35]
	v_mfma_f32_16x16x32_bf16 v[116:119], v[214:217], v[28:31], v[24:27]
	v_mfma_f32_16x16x32_bf16 v[24:27], v[202:205], v[218:221], v[36:39]
	v_mfma_f32_16x16x32_bf16 v[96:99], v[206:209], v[222:225], v[24:27]
	v_mfma_f32_16x16x32_bf16 v[24:27], v[210:213], v[218:221], v[40:43]
	v_mfma_f32_16x16x32_bf16 v[100:103], v[214:217], v[222:225], v[24:27]
	v_mfma_f32_16x16x32_bf16 v[24:27], v[202:205], v[226:229], v[44:47]
	v_mfma_f32_16x16x32_bf16 v[80:83], v[206:209], v[230:233], v[24:27]
	v_mfma_f32_16x16x32_bf16 v[24:27], v[210:213], v[226:229], v[48:51]
	v_mfma_f32_16x16x32_bf16 v[84:87], v[214:217], v[230:233], v[24:27]
	v_mfma_f32_16x16x32_bf16 v[24:27], v[202:205], v[234:237], v[52:55]
	v_mfma_f32_16x16x32_bf16 v[48:51], v[206:209], v[238:241], v[24:27]
	v_mfma_f32_16x16x32_bf16 v[24:27], v[210:213], v[234:237], v[56:59]
	v_mfma_f32_16x16x32_bf16 v[112:115], v[206:209], v[28:31], v[72:75]
	v_mfma_f32_16x16x32_bf16 v[52:55], v[214:217], v[238:241], v[24:27]
	s_barrier
; template <class Epi, class Sched, bool ALIGN_EPI = false, bool SP2 = false, bool A_TILED = false>
; __device__ __forceinline__ void gemm_phase(PG8_LAS unsigned char* lds, const Gemm g, const Sched& S, const Epi& E, const int wave_s) {
;     ...
;         for (int t = PEEL ? 2 : 0; t < nt; t += 2) {
;             const bool last = (t == nt - 2);
;             const char* a1 = cA + (size_t)(t + 1) * kstepA;
;             const char* a2 = last ? nA : cA + (size_t)(t + 2) * kstepA; const char* b2 = last ? nB : cB + (size_t)(t + 2) * kstep;
;             const char* a3 = a2 + kstepA; const char* b3 = b2 + kstep;
	s_setprio 0
	s_add_i32 s70, s70, s45
	s_add_i32 s71, s70, 0x2000
	s_nop 1
	v_lshl_add_u64 v[24:25], v[242:243], 0, s[14:15]
	s_mov_b32 m0, s70
	s_add_u32 s38, s26, 0x80180
	ds_read_b128 v[32:35], v147 offset:49152
	ds_read_b128 v[36:39], v147 offset:50176
	ds_read_b128 v[218:221], v147 offset:51200
	ds_read_b128 v[222:225], v147 offset:52224
	ds_read_b128 v[226:229], v147 offset:53248
	ds_read_b128 v[230:233], v147 offset:54272
	ds_read_b128 v[234:237], v147 offset:55296
	ds_read_b128 v[238:241], v147 offset:56320
	global_load_lds_dwordx4 v[24:25], off
	v_lshl_add_u64 v[24:25], v[244:245], 0, s[14:15]
	s_mov_b32 m0, s71
	s_addc_u32 s39, s27, 0
	s_add_i32 s72, s72, s45
	global_load_lds_dwordx4 v[24:25], off
	v_lshl_add_u64 v[24:25], s[38:39], 0, v[128:129]
	s_mov_b32 m0, s72
	s_add_i32 s73, s72, 0x2000
	global_load_lds_dwordx4 v[24:25], off
	v_lshl_add_u64 v[24:25], s[38:39], 0, v[130:131]
	s_mov_b32 m0, s73
	s_nop 0
	global_load_lds_dwordx4 v[24:25], off
	v_lshl_add_u64 v[24:25], v[246:247], 0, s[14:15]
	s_mov_b32 m0, s56
	s_nop 0
	global_load_lds_dwordx4 v[24:25], off
	v_lshl_add_u64 v[24:25], v[248:249], 0, s[14:15]
	s_mov_b32 m0, s57
	s_nop 0
	global_load_lds_dwordx4 v[24:25], off
	s_waitcnt vmcnt(8) lgkmcnt(0)
	s_setprio 1
	s_barrier
	v_mfma_f32_16x16x32_bf16 v[24:27], v[8:11], v[32:35], v[150:153]
	v_mfma_f32_16x16x32_bf16 v[72:75], v[12:15], v[36:39], v[24:27]
	v_mfma_f32_16x16x32_bf16 v[24:27], v[16:19], v[32:35], v[154:157]
	v_mfma_f32_16x16x32_bf16 v[76:79], v[20:23], v[36:39], v[24:27]
	v_mfma_f32_16x16x32_bf16 v[24:27], v[8:11], v[218:221], v[158:161]
	v_mfma_f32_16x16x32_bf16 v[40:43], v[12:15], v[222:225], v[24:27]
	v_mfma_f32_16x16x32_bf16 v[24:27], v[16:19], v[218:221], v[162:165]
	v_mfma_f32_16x16x32_bf16 v[0:3], v[8:11], v[234:237], v[0:3]
	v_mfma_f32_16x16x32_bf16 v[44:47], v[20:23], v[222:225], v[24:27]
	v_mfma_f32_16x16x32_bf16 v[24:27], v[8:11], v[226:229], v[166:169]
	v_mfma_f32_16x16x32_bf16 v[28:31], v[16:19], v[226:229], v[170:173]
	v_mfma_f32_16x16x32_bf16 v[8:11], v[12:15], v[238:241], v[0:3]
	v_mfma_f32_16x16x32_bf16 v[0:3], v[16:19], v[234:237], v[4:7]
	v_mfma_f32_16x16x32_bf16 v[24:27], v[12:15], v[230:233], v[24:27]
	v_mfma_f32_16x16x32_bf16 v[28:31], v[20:23], v[230:233], v[28:31]
	v_mfma_f32_16x16x32_bf16 v[12:15], v[20:23], v[238:241], v[0:3]
	s_setprio 0
	s_setprio 1
	v_mfma_f32_16x16x32_bf16 v[0:3], v[202:205], v[32:35], v[174:177]
	v_mfma_f32_16x16x32_bf16 v[56:59], v[206:209], v[36:39], v[0:3]
	v_mfma_f32_16x16x32_bf16 v[0:3], v[210:213], v[32:35], v[60:63]
	v_mfma_f32_16x16x32_bf16 v[60:63], v[214:217], v[36:39], v[0:3]
	v_mfma_f32_16x16x32_bf16 v[0:3], v[202:205], v[218:221], v[178:181]
	v_mfma_f32_16x16x32_bf16 v[32:35], v[206:209], v[222:225], v[0:3]
	v_mfma_f32_16x16x32_bf16 v[0:3], v[210:213], v[218:221], v[182:185]
	v_mfma_f32_16x16x32_bf16 v[36:39], v[214:217], v[222:225], v[0:3]
	v_mfma_f32_16x16x32_bf16 v[0:3], v[202:205], v[226:229], v[186:189]
	v_mfma_f32_16x16x32_bf16 v[16:19], v[206:209], v[230:233], v[0:3]
	v_mfma_f32_16x16x32_bf16 v[0:3], v[210:213], v[226:229], v[190:193]
	v_mfma_f32_16x16x32_bf16 v[20:23], v[214:217], v[230:233], v[0:3]
	v_mfma_f32_16x16x32_bf16 v[0:3], v[202:205], v[234:237], v[194:197]
	v_mfma_f32_16x16x32_bf16 v[4:7], v[210:213], v[234:237], v[198:201]
	v_mfma_f32_16x16x32_bf16 v[0:3], v[206:209], v[238:241], v[0:3]
	v_mfma_f32_16x16x32_bf16 v[4:7], v[214:217], v[238:241], v[4:7]
	s_barrier
	s_setprio 0
	s_add_u32 s74, s26, 0x200
	s_addc_u32 s75, s27, 0
	s_add_u32 s26, s36, 0x80180
	s_addc_u32 s27, s37, 0
	s_mov_b32 s76, 0
.LBB0_3720:
	ds_read_b128 v[150:153], v145
	ds_read_b128 v[154:157], v145 offset:1024
	ds_read_b128 v[158:161], v145 offset:2048
	ds_read_b128 v[162:165], v145 offset:3072
	ds_read_b128 v[166:169], v146
	ds_read_b128 v[170:173], v146 offset:1024
	ds_read_b128 v[174:177], v146 offset:2048
	ds_read_b128 v[178:181], v146 offset:3072
	s_add_u32 s36, s26, 0xfff80080
	s_addc_u32 s37, s27, -1
	s_cmp_eq_u32 s76, 28
	s_cselect_b32 s39, s17, s37
	s_cselect_b32 s38, s19, s36
	s_cselect_b32 s37, s62, s75
	s_cselect_b32 s36, s63, s74
	s_mov_b32 m0, s64
	v_lshl_add_u64 v[214:215], s[26:27], 0, v[138:139]
	ds_read_b128 v[182:185], v147
	ds_read_b128 v[186:189], v147 offset:1024
	ds_read_b128 v[190:193], v147 offset:2048
	ds_read_b128 v[194:197], v147 offset:3072
	ds_read_b128 v[198:201], v147 offset:4096
	ds_read_b128 v[202:205], v147 offset:5120
	ds_read_b128 v[206:209], v147 offset:6144
	ds_read_b128 v[210:213], v147 offset:7168
	global_load_lds_dwordx4 v[214:215], off
	v_lshl_add_u64 v[214:215], s[26:27], 0, v[136:137]
	s_mov_b32 m0, s65
	s_nop 0
	global_load_lds_dwordx4 v[214:215], off
	s_waitcnt vmcnt(8) lgkmcnt(0)
	s_setprio 1
	s_barrier
	v_mfma_f32_16x16x32_bf16 v[120:123], v[150:153], v[182:185], v[120:123]
	v_mfma_f32_16x16x32_bf16 v[124:127], v[158:161], v[182:185], v[124:127]
	v_mfma_f32_16x16x32_bf16 v[104:107], v[150:153], v[190:193], v[104:107]
	v_mfma_f32_16x16x32_bf16 v[108:111], v[158:161], v[190:193], v[108:111]
	v_mfma_f32_16x16x32_bf16 v[88:91], v[150:153], v[198:201], v[88:91]
	v_mfma_f32_16x16x32_bf16 v[92:95], v[158:161], v[198:201], v[92:95]
	v_mfma_f32_16x16x32_bf16 v[64:67], v[150:153], v[206:209], v[64:67]
	v_mfma_f32_16x16x32_bf16 v[68:71], v[158:161], v[206:209], v[68:71]
	v_mfma_f32_16x16x32_bf16 v[120:123], v[154:157], v[186:189], v[120:123]
	v_mfma_f32_16x16x32_bf16 v[124:127], v[162:165], v[186:189], v[124:127]
	v_mfma_f32_16x16x32_bf16 v[104:107], v[154:157], v[194:197], v[104:107]
	v_mfma_f32_16x16x32_bf16 v[108:111], v[162:165], v[194:197], v[108:111]
	v_mfma_f32_16x16x32_bf16 v[88:91], v[154:157], v[202:205], v[88:91]
	v_mfma_f32_16x16x32_bf16 v[92:95], v[162:165], v[202:205], v[92:95]
	v_mfma_f32_16x16x32_bf16 v[64:67], v[154:157], v[210:213], v[64:67]
	v_mfma_f32_16x16x32_bf16 v[68:71], v[162:165], v[210:213], v[68:71]
	s_setprio 0
	s_setprio 1
	v_mfma_f32_16x16x32_bf16 v[112:115], v[166:169], v[182:185], v[112:115]
	v_mfma_f32_16x16x32_bf16 v[116:119], v[174:177], v[182:185], v[116:119]
	v_mfma_f32_16x16x32_bf16 v[96:99], v[166:169], v[190:193], v[96:99]
	v_mfma_f32_16x16x32_bf16 v[100:103], v[174:177], v[190:193], v[100:103]
	v_mfma_f32_16x16x32_bf16 v[80:83], v[166:169], v[198:201], v[80:83]
	v_mfma_f32_16x16x32_bf16 v[84:87], v[174:177], v[198:201], v[84:87]
	v_mfma_f32_16x16x32_bf16 v[48:51], v[166:169], v[206:209], v[48:51]
	v_mfma_f32_16x16x32_bf16 v[52:55], v[174:177], v[206:209], v[52:55]
	v_mfma_f32_16x16x32_bf16 v[112:115], v[170:173], v[186:189], v[112:115]
	v_mfma_f32_16x16x32_bf16 v[116:119], v[178:181], v[186:189], v[116:119]
	v_mfma_f32_16x16x32_bf16 v[96:99], v[170:173], v[194:197], v[96:99]
	v_mfma_f32_16x16x32_bf16 v[100:103], v[178:181], v[194:197], v[100:103]
	v_mfma_f32_16x16x32_bf16 v[80:83], v[170:173], v[202:205], v[80:83]
	v_mfma_f32_16x16x32_bf16 v[84:87], v[178:181], v[202:205], v[84:87]
	v_mfma_f32_16x16x32_bf16 v[48:51], v[170:173], v[210:213], v[48:51]
	v_mfma_f32_16x16x32_bf16 v[52:55], v[178:181], v[210:213], v[52:55]
	s_barrier
	s_setprio 0
	s_mov_b32 m0, s66
	v_lshl_add_u64 v[214:215], s[36:37], 0, v[128:129]
	s_add_u32 s78, s36, 0x80000
	ds_read_b128 v[182:185], v147 offset:16384
	ds_read_b128 v[186:189], v147 offset:17408
	ds_read_b128 v[190:193], v147 offset:18432
	ds_read_b128 v[194:197], v147 offset:19456
	ds_read_b128 v[198:201], v147 offset:20480
	ds_read_b128 v[202:205], v147 offset:21504
	ds_read_b128 v[206:209], v147 offset:22528
	ds_read_b128 v[210:213], v147 offset:23552
	global_load_lds_dwordx4 v[214:215], off
	v_lshl_add_u64 v[216:217], s[36:37], 0, v[130:131]
	s_mov_b32 m0, s67
	s_addc_u32 s79, s37, 0
	global_load_lds_dwordx4 v[216:217], off
	v_lshl_add_u64 v[218:219], s[78:79], 0, v[128:129]
	s_mov_b32 m0, s68
	v_lshl_add_u64 v[220:221], s[38:39], 0, v[132:133]
	global_load_lds_dwordx4 v[218:219], off
	v_lshl_add_u64 v[218:219], s[78:79], 0, v[130:131]
	s_mov_b32 m0, s69
	s_nop 0
	global_load_lds_dwordx4 v[218:219], off
	v_lshl_add_u64 v[218:219], s[38:39], 0, v[134:135]
	s_mov_b32 m0, s47
	s_nop 0
	global_load_lds_dwordx4 v[218:219], off
	s_mov_b32 m0, s48
	s_nop 0
	global_load_lds_dwordx4 v[220:221], off
	s_waitcnt vmcnt(8) lgkmcnt(0)
	s_setprio 1
	s_barrier
	v_mfma_f32_16x16x32_bf16 v[72:75], v[150:153], v[182:185], v[72:75]
	v_mfma_f32_16x16x32_bf16 v[76:79], v[158:161], v[182:185], v[76:79]
	v_mfma_f32_16x16x32_bf16 v[40:43], v[150:153], v[190:193], v[40:43]
	v_mfma_f32_16x16x32_bf16 v[44:47], v[158:161], v[190:193], v[44:47]
	v_mfma_f32_16x16x32_bf16 v[24:27], v[150:153], v[198:201], v[24:27]
	v_mfma_f32_16x16x32_bf16 v[28:31], v[158:161], v[198:201], v[28:31]
	v_mfma_f32_16x16x32_bf16 v[8:11], v[150:153], v[206:209], v[8:11]
	v_mfma_f32_16x16x32_bf16 v[12:15], v[158:161], v[206:209], v[12:15]
	v_mfma_f32_16x16x32_bf16 v[72:75], v[154:157], v[186:189], v[72:75]
	v_mfma_f32_16x16x32_bf16 v[76:79], v[162:165], v[186:189], v[76:79]
	v_mfma_f32_16x16x32_bf16 v[40:43], v[154:157], v[194:197], v[40:43]
	v_mfma_f32_16x16x32_bf16 v[44:47], v[162:165], v[194:197], v[44:47]
	v_mfma_f32_16x16x32_bf16 v[24:27], v[154:157], v[202:205], v[24:27]
	v_mfma_f32_16x16x32_bf16 v[28:31], v[162:165], v[202:205], v[28:31]
	v_mfma_f32_16x16x32_bf16 v[8:11], v[154:157], v[210:213], v[8:11]
	v_mfma_f32_16x16x32_bf16 v[12:15], v[162:165], v[210:213], v[12:15]
	s_setprio 0
	s_setprio 1
	v_mfma_f32_16x16x32_bf16 v[56:59], v[166:169], v[182:185], v[56:59]
	v_mfma_f32_16x16x32_bf16 v[60:63], v[174:177], v[182:185], v[60:63]
	v_mfma_f32_16x16x32_bf16 v[32:35], v[166:169], v[190:193], v[32:35]
	v_mfma_f32_16x16x32_bf16 v[36:39], v[174:177], v[190:193], v[36:39]
	v_mfma_f32_16x16x32_bf16 v[16:19], v[166:169], v[198:201], v[16:19]
	v_mfma_f32_16x16x32_bf16 v[20:23], v[174:177], v[198:201], v[20:23]
	v_mfma_f32_16x16x32_bf16 v[0:3], v[166:169], v[206:209], v[0:3]
	v_mfma_f32_16x16x32_bf16 v[4:7], v[174:177], v[206:209], v[4:7]
	v_mfma_f32_16x16x32_bf16 v[56:59], v[170:173], v[186:189], v[56:59]
	v_mfma_f32_16x16x32_bf16 v[60:63], v[178:181], v[186:189], v[60:63]
	v_mfma_f32_16x16x32_bf16 v[32:35], v[170:173], v[194:197], v[32:35]
	v_mfma_f32_16x16x32_bf16 v[36:39], v[178:181], v[194:197], v[36:39]
	v_mfma_f32_16x16x32_bf16 v[16:19], v[170:173], v[202:205], v[16:19]
	v_mfma_f32_16x16x32_bf16 v[20:23], v[178:181], v[202:205], v[20:23]
	v_mfma_f32_16x16x32_bf16 v[0:3], v[170:173], v[210:213], v[0:3]
	v_mfma_f32_16x16x32_bf16 v[4:7], v[178:181], v[210:213], v[4:7]
	s_barrier
; #define PG8_BAR __builtin_amdgcn_s_barrier()
; template <class Epi, class Sched, bool ALIGN_EPI = false, bool SP2 = false, bool A_TILED = false>
; __device__ __forceinline__ void gemm_phase(PG8_LAS unsigned char* lds, const Gemm g, const Sched& S, const Epi& E, const int wave_s) {
;     ...
;         if constexpr (ALIGN_EPI) { if (wr == 0) PG8_BAR; }
	s_setprio 0
	ds_read_b128 v[150:153], v148
	ds_read_b128 v[154:157], v148 offset:1024
	ds_read_b128 v[158:161], v148 offset:2048
	ds_read_b128 v[162:165], v148 offset:3072
	ds_read_b128 v[166:169], v149
	ds_read_b128 v[170:173], v149 offset:1024
	ds_read_b128 v[174:177], v149 offset:2048
	ds_read_b128 v[178:181], v149 offset:3072
	s_add_u32 s38, s38, 0x80000
	s_addc_u32 s39, s39, 0
	s_mov_b32 m0, s49
	v_lshl_add_u64 v[222:223], s[38:39], 0, v[134:135]
	ds_read_b128 v[182:185], v147 offset:32768
	ds_read_b128 v[186:189], v147 offset:33792
	ds_read_b128 v[190:193], v147 offset:34816
	ds_read_b128 v[194:197], v147 offset:35840
	ds_read_b128 v[198:201], v147 offset:36864
	ds_read_b128 v[202:205], v147 offset:37888
	ds_read_b128 v[206:209], v147 offset:38912
	ds_read_b128 v[210:213], v147 offset:39936
	global_load_lds_dwordx4 v[222:223], off
	v_lshl_add_u64 v[222:223], s[38:39], 0, v[132:133]
	s_mov_b32 m0, s50
	s_nop 0
	global_load_lds_dwordx4 v[222:223], off
	s_waitcnt vmcnt(8) lgkmcnt(0)
	s_setprio 1
	s_barrier
	v_mfma_f32_16x16x32_bf16 v[120:123], v[150:153], v[182:185], v[120:123]
	v_mfma_f32_16x16x32_bf16 v[124:127], v[158:161], v[182:185], v[124:127]
	v_mfma_f32_16x16x32_bf16 v[104:107], v[150:153], v[190:193], v[104:107]
	v_mfma_f32_16x16x32_bf16 v[108:111], v[158:161], v[190:193], v[108:111]
	v_mfma_f32_16x16x32_bf16 v[88:91], v[150:153], v[198:201], v[88:91]
	v_mfma_f32_16x16x32_bf16 v[92:95], v[158:161], v[198:201], v[92:95]
	v_mfma_f32_16x16x32_bf16 v[64:67], v[150:153], v[206:209], v[64:67]
	v_mfma_f32_16x16x32_bf16 v[68:71], v[158:161], v[206:209], v[68:71]
	v_mfma_f32_16x16x32_bf16 v[120:123], v[154:157], v[186:189], v[120:123]
	v_mfma_f32_16x16x32_bf16 v[124:127], v[162:165], v[186:189], v[124:127]
	v_mfma_f32_16x16x32_bf16 v[104:107], v[154:157], v[194:197], v[104:107]
	v_mfma_f32_16x16x32_bf16 v[108:111], v[162:165], v[194:197], v[108:111]
	v_mfma_f32_16x16x32_bf16 v[88:91], v[154:157], v[202:205], v[88:91]
	v_mfma_f32_16x16x32_bf16 v[92:95], v[162:165], v[202:205], v[92:95]
	v_mfma_f32_16x16x32_bf16 v[64:67], v[154:157], v[210:213], v[64:67]
	v_mfma_f32_16x16x32_bf16 v[68:71], v[162:165], v[210:213], v[68:71]
	s_setprio 0
	s_setprio 1
	v_mfma_f32_16x16x32_bf16 v[112:115], v[166:169], v[182:185], v[112:115]
	v_mfma_f32_16x16x32_bf16 v[116:119], v[174:177], v[182:185], v[116:119]
	v_mfma_f32_16x16x32_bf16 v[96:99], v[166:169], v[190:193], v[96:99]
	v_mfma_f32_16x16x32_bf16 v[100:103], v[174:177], v[190:193], v[100:103]
	v_mfma_f32_16x16x32_bf16 v[80:83], v[166:169], v[198:201], v[80:83]
	v_mfma_f32_16x16x32_bf16 v[84:87], v[174:177], v[198:201], v[84:87]
	v_mfma_f32_16x16x32_bf16 v[48:51], v[166:169], v[206:209], v[48:51]
	v_mfma_f32_16x16x32_bf16 v[52:55], v[174:177], v[206:209], v[52:55]
	v_mfma_f32_16x16x32_bf16 v[112:115], v[170:173], v[186:189], v[112:115]
	v_mfma_f32_16x16x32_bf16 v[116:119], v[178:181], v[186:189], v[116:119]
	v_mfma_f32_16x16x32_bf16 v[96:99], v[170:173], v[194:197], v[96:99]
	v_mfma_f32_16x16x32_bf16 v[100:103], v[178:181], v[194:197], v[100:103]
	v_mfma_f32_16x16x32_bf16 v[80:83], v[170:173], v[202:205], v[80:83]
	v_mfma_f32_16x16x32_bf16 v[84:87], v[178:181], v[202:205], v[84:87]
	v_mfma_f32_16x16x32_bf16 v[48:51], v[170:173], v[210:213], v[48:51]
	v_mfma_f32_16x16x32_bf16 v[52:55], v[178:181], v[210:213], v[52:55]
	s_barrier
	s_setprio 0
	s_mov_b32 m0, s70
	v_lshl_add_u64 v[214:215], v[214:215], 0, s[6:7]
	s_add_u32 s36, s36, 0x80080
	ds_read_b128 v[182:185], v147 offset:49152
	ds_read_b128 v[186:189], v147 offset:50176
	ds_read_b128 v[190:193], v147 offset:51200
	ds_read_b128 v[194:197], v147 offset:52224
	ds_read_b128 v[198:201], v147 offset:53248
	ds_read_b128 v[202:205], v147 offset:54272
	ds_read_b128 v[206:209], v147 offset:55296
	ds_read_b128 v[210:213], v147 offset:56320
	global_load_lds_dwordx4 v[214:215], off
	v_lshl_add_u64 v[214:215], v[216:217], 0, s[6:7]
	s_mov_b32 m0, s71
	s_addc_u32 s37, s37, 0
	global_load_lds_dwordx4 v[214:215], off
	v_lshl_add_u64 v[214:215], s[36:37], 0, v[128:129]
	s_mov_b32 m0, s72
	s_nop 0
	global_load_lds_dwordx4 v[214:215], off
	v_lshl_add_u64 v[214:215], s[36:37], 0, v[130:131]
	s_mov_b32 m0, s73
	s_nop 0
	global_load_lds_dwordx4 v[214:215], off
	v_lshl_add_u64 v[214:215], v[218:219], 0, s[6:7]
	s_mov_b32 m0, s56
	s_nop 0
	global_load_lds_dwordx4 v[214:215], off
	v_lshl_add_u64 v[214:215], v[220:221], 0, s[6:7]
	s_mov_b32 m0, s57
	s_nop 0
	global_load_lds_dwordx4 v[214:215], off
	s_waitcnt vmcnt(8) lgkmcnt(0)
	s_setprio 1
	s_barrier
	v_mfma_f32_16x16x32_bf16 v[72:75], v[150:153], v[182:185], v[72:75]
	v_mfma_f32_16x16x32_bf16 v[76:79], v[158:161], v[182:185], v[76:79]
	v_mfma_f32_16x16x32_bf16 v[40:43], v[150:153], v[190:193], v[40:43]
	v_mfma_f32_16x16x32_bf16 v[44:47], v[158:161], v[190:193], v[44:47]
	v_mfma_f32_16x16x32_bf16 v[24:27], v[150:153], v[198:201], v[24:27]
	v_mfma_f32_16x16x32_bf16 v[28:31], v[158:161], v[198:201], v[28:31]
	v_mfma_f32_16x16x32_bf16 v[8:11], v[150:153], v[206:209], v[8:11]
	v_mfma_f32_16x16x32_bf16 v[12:15], v[158:161], v[206:209], v[12:15]
	v_mfma_f32_16x16x32_bf16 v[72:75], v[154:157], v[186:189], v[72:75]
	v_mfma_f32_16x16x32_bf16 v[76:79], v[162:165], v[186:189], v[76:79]
	v_mfma_f32_16x16x32_bf16 v[40:43], v[154:157], v[194:197], v[40:43]
	v_mfma_f32_16x16x32_bf16 v[44:47], v[162:165], v[194:197], v[44:47]
	v_mfma_f32_16x16x32_bf16 v[24:27], v[154:157], v[202:205], v[24:27]
	v_mfma_f32_16x16x32_bf16 v[28:31], v[162:165], v[202:205], v[28:31]
	v_mfma_f32_16x16x32_bf16 v[8:11], v[154:157], v[210:213], v[8:11]
	v_mfma_f32_16x16x32_bf16 v[12:15], v[162:165], v[210:213], v[12:15]
	s_setprio 0
	s_setprio 1
	v_mfma_f32_16x16x32_bf16 v[56:59], v[166:169], v[182:185], v[56:59]
	v_mfma_f32_16x16x32_bf16 v[60:63], v[174:177], v[182:185], v[60:63]
	v_mfma_f32_16x16x32_bf16 v[32:35], v[166:169], v[190:193], v[32:35]
	v_mfma_f32_16x16x32_bf16 v[36:39], v[174:177], v[190:193], v[36:39]
	v_mfma_f32_16x16x32_bf16 v[16:19], v[166:169], v[198:201], v[16:19]
	v_mfma_f32_16x16x32_bf16 v[20:23], v[174:177], v[198:201], v[20:23]
	v_mfma_f32_16x16x32_bf16 v[0:3], v[166:169], v[206:209], v[0:3]
	v_mfma_f32_16x16x32_bf16 v[4:7], v[174:177], v[206:209], v[4:7]
	v_mfma_f32_16x16x32_bf16 v[56:59], v[170:173], v[186:189], v[56:59]
	v_mfma_f32_16x16x32_bf16 v[60:63], v[178:181], v[186:189], v[60:63]
	v_mfma_f32_16x16x32_bf16 v[32:35], v[170:173], v[194:197], v[32:35]
	v_mfma_f32_16x16x32_bf16 v[36:39], v[178:181], v[194:197], v[36:39]
	v_mfma_f32_16x16x32_bf16 v[16:19], v[170:173], v[202:205], v[16:19]
	v_mfma_f32_16x16x32_bf16 v[20:23], v[178:181], v[202:205], v[20:23]
	v_mfma_f32_16x16x32_bf16 v[0:3], v[170:173], v[210:213], v[0:3]
	v_mfma_f32_16x16x32_bf16 v[4:7], v[178:181], v[210:213], v[4:7]
	s_barrier
	s_setprio 0
	s_add_i32 s76, s76, 2
	s_add_u32 s74, s74, 0x100
	s_addc_u32 s75, s75, 0
	s_add_u32 s26, s26, 0x100
	s_addc_u32 s27, s27, 0
	s_cmp_gt_u32 s76, 29
	s_cbranch_scc0 .LBB0_3720
	s_and_b64 vcc, exec, s[8:9]
	s_cbranch_vccz .LBB0_3723
	s_barrier

; template <class Epi, class Sched, bool ALIGN_EPI = false, bool SP2 = false, bool A_TILED = false>
; __device__ __forceinline__ void gemm_phase(PG8_LAS unsigned char* lds, const Gemm g, const Sched& S, const Epi& E, const int wave_s) {
;     ...
;             const bool last = (t == nt - 2);
;             const char* a1 = cA + (size_t)(t + 1) * kstepA;
;             const char* a2 = last ? nA : cA + (size_t)(t + 2) * kstepA; const char* b2 = last ? nB : cB + (size_t)(t + 2) * kstep;
;             const char* a3 = a2 + kstepA; const char* b3 = b2 + kstep;
.LBB0_3793:
	ds_read_b128 v[146:149], v140
	ds_read_b128 v[150:153], v140 offset:1024
	ds_read_b128 v[154:157], v140 offset:2048
	ds_read_b128 v[158:161], v140 offset:3072
	ds_read_b128 v[162:165], v141
	ds_read_b128 v[166:169], v141 offset:1024
	ds_read_b128 v[170:173], v141 offset:2048
	ds_read_b128 v[174:177], v141 offset:3072
	s_add_u32 s16, s58, s40
	s_addc_u32 s17, s59, s41
	s_add_u32 s18, s58, s38
	s_addc_u32 s19, s59, s39
	s_cmpk_eq_i32 s42, 0x7c
	s_cselect_b32 s20, s4, s16
	s_cselect_b32 s21, s5, s17
	s_cselect_b32 s18, s0, s18
	s_cselect_b32 s19, s1, s19
	s_add_u32 s16, s20, 0x8000
	s_addc_u32 s17, s21, 0
	s_mov_b32 m0, s43
	v_lshl_add_u64 v[210:211], s[58:59], 0, v[138:139]
	ds_read_b128 v[178:181], v142
	ds_read_b128 v[182:185], v142 offset:1024
	ds_read_b128 v[186:189], v142 offset:2048
	ds_read_b128 v[190:193], v142 offset:3072
	ds_read_b128 v[194:197], v142 offset:4096
	ds_read_b128 v[198:201], v142 offset:5120
	ds_read_b128 v[202:205], v142 offset:6144
	ds_read_b128 v[206:209], v142 offset:7168
	global_load_lds_dwordx4 v[210:211], off
	v_lshl_add_u64 v[210:211], s[58:59], 0, v[136:137]
	s_mov_b32 m0, s44
	s_nop 0
	global_load_lds_dwordx4 v[210:211], off
	s_waitcnt vmcnt(8) lgkmcnt(0)
	s_setprio 1
	s_barrier
	v_mfma_f32_16x16x32_bf16 v[32:35], v[146:149], v[178:181], v[32:35]
	v_mfma_f32_16x16x32_bf16 v[36:39], v[154:157], v[178:181], v[36:39]
	v_mfma_f32_16x16x32_bf16 v[76:79], v[146:149], v[186:189], v[76:79]
	v_mfma_f32_16x16x32_bf16 v[80:83], v[154:157], v[186:189], v[80:83]
	v_mfma_f32_16x16x32_bf16 v[92:95], v[146:149], v[194:197], v[92:95]
	v_mfma_f32_16x16x32_bf16 v[84:87], v[154:157], v[194:197], v[84:87]
	v_mfma_f32_16x16x32_bf16 v[108:111], v[146:149], v[202:205], v[108:111]
	v_mfma_f32_16x16x32_bf16 v[104:107], v[154:157], v[202:205], v[104:107]
	v_mfma_f32_16x16x32_bf16 v[32:35], v[150:153], v[182:185], v[32:35]
	v_mfma_f32_16x16x32_bf16 v[36:39], v[158:161], v[182:185], v[36:39]
	v_mfma_f32_16x16x32_bf16 v[76:79], v[150:153], v[190:193], v[76:79]
	v_mfma_f32_16x16x32_bf16 v[80:83], v[158:161], v[190:193], v[80:83]
	v_mfma_f32_16x16x32_bf16 v[92:95], v[150:153], v[198:201], v[92:95]
	v_mfma_f32_16x16x32_bf16 v[84:87], v[158:161], v[198:201], v[84:87]
	v_mfma_f32_16x16x32_bf16 v[108:111], v[150:153], v[206:209], v[108:111]
	v_mfma_f32_16x16x32_bf16 v[104:107], v[158:161], v[206:209], v[104:107]
	s_setprio 0
	s_setprio 1
	v_mfma_f32_16x16x32_bf16 v[40:43], v[162:165], v[178:181], v[40:43]
	v_mfma_f32_16x16x32_bf16 v[44:47], v[170:173], v[178:181], v[44:47]
	v_mfma_f32_16x16x32_bf16 v[68:71], v[162:165], v[186:189], v[68:71]
	v_mfma_f32_16x16x32_bf16 v[64:67], v[170:173], v[186:189], v[64:67]
	v_mfma_f32_16x16x32_bf16 v[60:63], v[162:165], v[194:197], v[60:63]
	v_mfma_f32_16x16x32_bf16 v[56:59], v[170:173], v[194:197], v[56:59]
	v_mfma_f32_16x16x32_bf16 v[100:103], v[162:165], v[202:205], v[100:103]
	v_mfma_f32_16x16x32_bf16 v[96:99], v[170:173], v[202:205], v[96:99]
	v_mfma_f32_16x16x32_bf16 v[40:43], v[166:169], v[182:185], v[40:43]
	v_mfma_f32_16x16x32_bf16 v[44:47], v[174:177], v[182:185], v[44:47]
	v_mfma_f32_16x16x32_bf16 v[68:71], v[166:169], v[190:193], v[68:71]
	v_mfma_f32_16x16x32_bf16 v[64:67], v[174:177], v[190:193], v[64:67]
	v_mfma_f32_16x16x32_bf16 v[60:63], v[166:169], v[198:201], v[60:63]
	v_mfma_f32_16x16x32_bf16 v[56:59], v[174:177], v[198:201], v[56:59]
	v_mfma_f32_16x16x32_bf16 v[100:103], v[166:169], v[206:209], v[100:103]
	v_mfma_f32_16x16x32_bf16 v[96:99], v[174:177], v[206:209], v[96:99]
	s_barrier
	s_setprio 0
	s_mov_b32 m0, s45
	v_lshl_add_u64 v[210:211], s[18:19], 0, v[130:131]
	s_add_u32 s54, s18, 0x200000
	ds_read_b128 v[178:181], v142 offset:16384
	ds_read_b128 v[182:185], v142 offset:17408
	ds_read_b128 v[186:189], v142 offset:18432
	ds_read_b128 v[190:193], v142 offset:19456
	ds_read_b128 v[194:197], v142 offset:20480
	ds_read_b128 v[198:201], v142 offset:21504
	ds_read_b128 v[202:205], v142 offset:22528
	ds_read_b128 v[206:209], v142 offset:23552
	global_load_lds_dwordx4 v[210:211], off
	v_lshl_add_u64 v[212:213], s[18:19], 0, v[134:135]
	s_mov_b32 m0, s46
	s_addc_u32 s55, s19, 0
	global_load_lds_dwordx4 v[212:213], off
	v_lshl_add_u64 v[214:215], s[54:55], 0, v[130:131]
	s_mov_b32 m0, s47
	s_nop 0
	global_load_lds_dwordx4 v[214:215], off
	v_lshl_add_u64 v[214:215], s[54:55], 0, v[134:135]
	s_mov_b32 m0, s48
	s_nop 0
	global_load_lds_dwordx4 v[214:215], off
	v_lshl_add_u64 v[214:215], s[20:21], 0, v[128:129]
	s_mov_b32 m0, s25
	s_nop 0
	global_load_lds_dwordx4 v[214:215], off
	v_lshl_add_u64 v[214:215], s[20:21], 0, v[132:133]
	s_mov_b32 m0, s26
	s_nop 0
	global_load_lds_dwordx4 v[214:215], off
	s_waitcnt vmcnt(8) lgkmcnt(0)
	s_setprio 1
	s_barrier
	v_mfma_f32_16x16x32_bf16 v[124:127], v[146:149], v[178:181], v[124:127]
	v_mfma_f32_16x16x32_bf16 v[120:123], v[154:157], v[178:181], v[120:123]
	v_mfma_f32_16x16x32_bf16 v[88:91], v[146:149], v[186:189], v[88:91]
	v_mfma_f32_16x16x32_bf16 v[72:75], v[154:157], v[186:189], v[72:75]
	v_mfma_f32_16x16x32_bf16 v[28:31], v[146:149], v[194:197], v[28:31]
	v_mfma_f32_16x16x32_bf16 v[24:27], v[154:157], v[194:197], v[24:27]
	v_mfma_f32_16x16x32_bf16 v[12:15], v[146:149], v[202:205], v[12:15]
	v_mfma_f32_16x16x32_bf16 v[8:11], v[154:157], v[202:205], v[8:11]
	v_mfma_f32_16x16x32_bf16 v[124:127], v[150:153], v[182:185], v[124:127]
	v_mfma_f32_16x16x32_bf16 v[120:123], v[158:161], v[182:185], v[120:123]
	v_mfma_f32_16x16x32_bf16 v[88:91], v[150:153], v[190:193], v[88:91]
	v_mfma_f32_16x16x32_bf16 v[72:75], v[158:161], v[190:193], v[72:75]
	v_mfma_f32_16x16x32_bf16 v[28:31], v[150:153], v[198:201], v[28:31]
	v_mfma_f32_16x16x32_bf16 v[24:27], v[158:161], v[198:201], v[24:27]
	v_mfma_f32_16x16x32_bf16 v[12:15], v[150:153], v[206:209], v[12:15]
	v_mfma_f32_16x16x32_bf16 v[8:11], v[158:161], v[206:209], v[8:11]
	s_setprio 0
	s_setprio 1
	v_mfma_f32_16x16x32_bf16 v[116:119], v[162:165], v[178:181], v[116:119]
	v_mfma_f32_16x16x32_bf16 v[112:115], v[170:173], v[178:181], v[112:115]
	v_mfma_f32_16x16x32_bf16 v[52:55], v[162:165], v[186:189], v[52:55]
	v_mfma_f32_16x16x32_bf16 v[48:51], v[170:173], v[186:189], v[48:51]
	v_mfma_f32_16x16x32_bf16 v[20:23], v[162:165], v[194:197], v[20:23]
	v_mfma_f32_16x16x32_bf16 v[16:19], v[170:173], v[194:197], v[16:19]
	v_mfma_f32_16x16x32_bf16 v[4:7], v[162:165], v[202:205], v[4:7]
	v_mfma_f32_16x16x32_bf16 v[0:3], v[170:173], v[202:205], v[0:3]
	v_mfma_f32_16x16x32_bf16 v[116:119], v[166:169], v[182:185], v[116:119]
	v_mfma_f32_16x16x32_bf16 v[112:115], v[174:177], v[182:185], v[112:115]
	v_mfma_f32_16x16x32_bf16 v[52:55], v[166:169], v[190:193], v[52:55]
	v_mfma_f32_16x16x32_bf16 v[48:51], v[174:177], v[190:193], v[48:51]
	v_mfma_f32_16x16x32_bf16 v[20:23], v[166:169], v[198:201], v[20:23]
	v_mfma_f32_16x16x32_bf16 v[16:19], v[174:177], v[198:201], v[16:19]
	v_mfma_f32_16x16x32_bf16 v[4:7], v[166:169], v[206:209], v[4:7]
	v_mfma_f32_16x16x32_bf16 v[0:3], v[174:177], v[206:209], v[0:3]
	s_barrier
	s_setprio 0
	ds_read_b128 v[146:149], v143
	ds_read_b128 v[150:153], v143 offset:1024
	ds_read_b128 v[154:157], v143 offset:2048
	ds_read_b128 v[158:161], v143 offset:3072
	ds_read_b128 v[162:165], v144
	ds_read_b128 v[166:169], v144 offset:1024
	ds_read_b128 v[170:173], v144 offset:2048
	ds_read_b128 v[174:177], v144 offset:3072
	s_add_u32 s20, s20, 0x4000
	s_addc_u32 s21, s21, 0
	s_mov_b32 m0, s27
	v_lshl_add_u64 v[214:215], s[20:21], 0, v[128:129]
	ds_read_b128 v[178:181], v142 offset:32768
	ds_read_b128 v[182:185], v142 offset:33792
	ds_read_b128 v[186:189], v142 offset:34816
	ds_read_b128 v[190:193], v142 offset:35840
	ds_read_b128 v[194:197], v142 offset:36864
	ds_read_b128 v[198:201], v142 offset:37888
	ds_read_b128 v[202:205], v142 offset:38912
	ds_read_b128 v[206:209], v142 offset:39936
	global_load_lds_dwordx4 v[214:215], off
	v_lshl_add_u64 v[214:215], s[20:21], 0, v[132:133]
	s_mov_b32 m0, s34
	s_nop 0
	global_load_lds_dwordx4 v[214:215], off
	s_waitcnt vmcnt(8) lgkmcnt(0)
	s_setprio 1
	s_barrier
	v_mfma_f32_16x16x32_bf16 v[32:35], v[146:149], v[178:181], v[32:35]
	v_mfma_f32_16x16x32_bf16 v[36:39], v[154:157], v[178:181], v[36:39]
	v_mfma_f32_16x16x32_bf16 v[76:79], v[146:149], v[186:189], v[76:79]
	v_mfma_f32_16x16x32_bf16 v[80:83], v[154:157], v[186:189], v[80:83]
	v_mfma_f32_16x16x32_bf16 v[92:95], v[146:149], v[194:197], v[92:95]
	v_mfma_f32_16x16x32_bf16 v[84:87], v[154:157], v[194:197], v[84:87]
	v_mfma_f32_16x16x32_bf16 v[108:111], v[146:149], v[202:205], v[108:111]
	v_mfma_f32_16x16x32_bf16 v[104:107], v[154:157], v[202:205], v[104:107]
	v_mfma_f32_16x16x32_bf16 v[32:35], v[150:153], v[182:185], v[32:35]
	v_mfma_f32_16x16x32_bf16 v[36:39], v[158:161], v[182:185], v[36:39]
	v_mfma_f32_16x16x32_bf16 v[76:79], v[150:153], v[190:193], v[76:79]
	v_mfma_f32_16x16x32_bf16 v[80:83], v[158:161], v[190:193], v[80:83]
	v_mfma_f32_16x16x32_bf16 v[92:95], v[150:153], v[198:201], v[92:95]
	v_mfma_f32_16x16x32_bf16 v[84:87], v[158:161], v[198:201], v[84:87]
	v_mfma_f32_16x16x32_bf16 v[108:111], v[150:153], v[206:209], v[108:111]
	v_mfma_f32_16x16x32_bf16 v[104:107], v[158:161], v[206:209], v[104:107]
	s_setprio 0
	s_setprio 1
	v_mfma_f32_16x16x32_bf16 v[40:43], v[162:165], v[178:181], v[40:43]
	v_mfma_f32_16x16x32_bf16 v[44:47], v[170:173], v[178:181], v[44:47]
	v_mfma_f32_16x16x32_bf16 v[68:71], v[162:165], v[186:189], v[68:71]
	v_mfma_f32_16x16x32_bf16 v[64:67], v[170:173], v[186:189], v[64:67]
	v_mfma_f32_16x16x32_bf16 v[60:63], v[162:165], v[194:197], v[60:63]
	v_mfma_f32_16x16x32_bf16 v[56:59], v[170:173], v[194:197], v[56:59]
	v_mfma_f32_16x16x32_bf16 v[100:103], v[162:165], v[202:205], v[100:103]
	v_mfma_f32_16x16x32_bf16 v[96:99], v[170:173], v[202:205], v[96:99]
	v_mfma_f32_16x16x32_bf16 v[40:43], v[166:169], v[182:185], v[40:43]
	v_mfma_f32_16x16x32_bf16 v[44:47], v[174:177], v[182:185], v[44:47]
	v_mfma_f32_16x16x32_bf16 v[68:71], v[166:169], v[190:193], v[68:71]
	v_mfma_f32_16x16x32_bf16 v[64:67], v[174:177], v[190:193], v[64:67]
	v_mfma_f32_16x16x32_bf16 v[60:63], v[166:169], v[198:201], v[60:63]
	v_mfma_f32_16x16x32_bf16 v[56:59], v[174:177], v[198:201], v[56:59]
	v_mfma_f32_16x16x32_bf16 v[100:103], v[166:169], v[206:209], v[100:103]
	v_mfma_f32_16x16x32_bf16 v[96:99], v[174:177], v[206:209], v[96:99]
	s_barrier
; #define PG8_WAIT_V(n) asm volatile("s_waitcnt vmcnt(" #n ")" ::: "memory")
; #define PG8_BAR __builtin_amdgcn_s_barrier()
; template <class Epi, class Sched, bool ALIGN_EPI = false, bool SP2 = false, bool A_TILED = false>
; __device__ __forceinline__ void gemm_phase(PG8_LAS unsigned char* lds, const Gemm g, const Sched& S, const Epi& E, const int wave_s) {
;     ...
;     PG8_WAIT_V(0);
;     if constexpr (!ALIGN_EPI) { if (wr == 0) PG8_BAR; }
	s_setprio 0
	s_mov_b32 m0, s49
	v_lshl_add_u64 v[210:211], v[210:211], 0, s[12:13]
	s_add_u32 s18, s18, 0x200080
	ds_read_b128 v[178:181], v142 offset:49152
	ds_read_b128 v[182:185], v142 offset:50176
	ds_read_b128 v[186:189], v142 offset:51200
	ds_read_b128 v[190:193], v142 offset:52224
	ds_read_b128 v[194:197], v142 offset:53248
	ds_read_b128 v[198:201], v142 offset:54272
	ds_read_b128 v[202:205], v142 offset:55296
	ds_read_b128 v[206:209], v142 offset:56320
	global_load_lds_dwordx4 v[210:211], off
	v_lshl_add_u64 v[210:211], v[212:213], 0, s[12:13]
	s_mov_b32 m0, s50
	s_addc_u32 s19, s19, 0
	global_load_lds_dwordx4 v[210:211], off
	v_lshl_add_u64 v[210:211], s[18:19], 0, v[130:131]
	s_mov_b32 m0, s51
	s_nop 0
	global_load_lds_dwordx4 v[210:211], off
	v_lshl_add_u64 v[210:211], s[18:19], 0, v[134:135]
	s_mov_b32 m0, s52
	s_nop 0
	global_load_lds_dwordx4 v[210:211], off
	v_lshl_add_u64 v[210:211], s[16:17], 0, v[128:129]
	s_mov_b32 m0, s36
	s_nop 0
	global_load_lds_dwordx4 v[210:211], off
	v_lshl_add_u64 v[210:211], s[16:17], 0, v[132:133]
	s_mov_b32 m0, s37
	s_nop 0
	global_load_lds_dwordx4 v[210:211], off
	s_waitcnt vmcnt(8) lgkmcnt(0)
	s_setprio 1
	s_barrier
	v_mfma_f32_16x16x32_bf16 v[124:127], v[146:149], v[178:181], v[124:127]
	v_mfma_f32_16x16x32_bf16 v[120:123], v[154:157], v[178:181], v[120:123]
	v_mfma_f32_16x16x32_bf16 v[88:91], v[146:149], v[186:189], v[88:91]
	v_mfma_f32_16x16x32_bf16 v[72:75], v[154:157], v[186:189], v[72:75]
	v_mfma_f32_16x16x32_bf16 v[28:31], v[146:149], v[194:197], v[28:31]
	v_mfma_f32_16x16x32_bf16 v[24:27], v[154:157], v[194:197], v[24:27]
	v_mfma_f32_16x16x32_bf16 v[12:15], v[146:149], v[202:205], v[12:15]
	v_mfma_f32_16x16x32_bf16 v[8:11], v[154:157], v[202:205], v[8:11]
	v_mfma_f32_16x16x32_bf16 v[124:127], v[150:153], v[182:185], v[124:127]
	v_mfma_f32_16x16x32_bf16 v[120:123], v[158:161], v[182:185], v[120:123]
	v_mfma_f32_16x16x32_bf16 v[88:91], v[150:153], v[190:193], v[88:91]
	v_mfma_f32_16x16x32_bf16 v[72:75], v[158:161], v[190:193], v[72:75]
	v_mfma_f32_16x16x32_bf16 v[28:31], v[150:153], v[198:201], v[28:31]
	v_mfma_f32_16x16x32_bf16 v[24:27], v[158:161], v[198:201], v[24:27]
	v_mfma_f32_16x16x32_bf16 v[12:15], v[150:153], v[206:209], v[12:15]
	v_mfma_f32_16x16x32_bf16 v[8:11], v[158:161], v[206:209], v[8:11]
	s_setprio 0
	s_setprio 1
	v_mfma_f32_16x16x32_bf16 v[116:119], v[162:165], v[178:181], v[116:119]
	v_mfma_f32_16x16x32_bf16 v[112:115], v[170:173], v[178:181], v[112:115]
	v_mfma_f32_16x16x32_bf16 v[52:55], v[162:165], v[186:189], v[52:55]
	v_mfma_f32_16x16x32_bf16 v[48:51], v[170:173], v[186:189], v[48:51]
	v_mfma_f32_16x16x32_bf16 v[20:23], v[162:165], v[194:197], v[20:23]
	v_mfma_f32_16x16x32_bf16 v[16:19], v[170:173], v[194:197], v[16:19]
	v_mfma_f32_16x16x32_bf16 v[4:7], v[162:165], v[202:205], v[4:7]
	v_mfma_f32_16x16x32_bf16 v[0:3], v[170:173], v[202:205], v[0:3]
	v_mfma_f32_16x16x32_bf16 v[116:119], v[166:169], v[182:185], v[116:119]
	v_mfma_f32_16x16x32_bf16 v[112:115], v[174:177], v[182:185], v[112:115]
	v_mfma_f32_16x16x32_bf16 v[52:55], v[166:169], v[190:193], v[52:55]
	v_mfma_f32_16x16x32_bf16 v[48:51], v[174:177], v[190:193], v[48:51]
	v_mfma_f32_16x16x32_bf16 v[20:23], v[166:169], v[198:201], v[20:23]
	v_mfma_f32_16x16x32_bf16 v[16:19], v[174:177], v[198:201], v[16:19]
	v_mfma_f32_16x16x32_bf16 v[4:7], v[166:169], v[206:209], v[4:7]
	v_mfma_f32_16x16x32_bf16 v[0:3], v[174:177], v[206:209], v[0:3]
	s_barrier
	s_setprio 0
	s_add_i32 s42, s42, 2
	s_add_u32 s38, s38, 0x100
	s_addc_u32 s39, s39, 0
	s_add_u32 s40, s40, 0x10000
	s_addc_u32 s41, s41, 0
	v_lshl_add_u64 v[136:137], v[136:137], 0, s[14:15]
	s_cmpk_gt_u32 s42, 0x7d
	v_lshl_add_u64 v[138:139], v[138:139], 0, s[14:15]
	s_cbranch_scc0 .LBB0_3793
	s_waitcnt vmcnt(0)
	s_cmpk_lt_u32 s22, 0x100
	s_cbranch_scc0 .LBB0_3796
	s_barrier
